# bf16 row epilogue of both in-projection GEMMs transposed through LDS so every global store instruction writes full 128B row segments; pre-epilogue workgroup barrier made unconditional
# speedup vs baseline: 1.0174x; 1.0174x over previous
;   DI void operator()(const f32x16 (&acc)[2][4], int mbase, int nbase, int l32, int g) const {
; #pragma unroll
;     for (int nb = 0; nb < 2; ++nb)
; #pragma unroll
;       for (int mb = 0; mb < 4; ++mb) {
;         const size_t tok = mbase + 32 * mb + l32;
;         const f32x16& c = acc[nb][mb];
; #pragma unroll
;         for (int j = 0; j < 4; j += 2) {
;           u32x2 a, b;
;           a.x = pk_bf16(c[4 * j], c[4 * j + 1]); a.y = pk_bf16(c[4 * j + 2], c[4 * j + 3]);
;           b.x = pk_bf16(c[4 * j + 4], c[4 * j + 5]); b.y = pk_bf16(c[4 * j + 6], c[4 * j + 7]);
;           store_bf8_pair(O + tok * ld + nbase + 32 * nb + 8 * j, g, a, b);
;         }
;       }
;   }
.LBB0_96:
	s_lshl_b32 s0, s56, 7
	s_add_i32 s98, s0, s50
	s_lshl_b32 s0, s51, 6
	s_or_b32 s0, s0, s66
	s_ashr_i32 s1, s0, 31
	s_lshl_b64 s[0:1], s[0:1], 1
	s_add_u32 s0, s18, s0
	s_addc_u32 s1, s19, s1
	s_mul_i32 s99, s98, 0x2200
	s_add_u32 s100, s0, s99
	s_addc_u32 s101, s1, 0
	v_and_b32_e32 v128, 63, v206
	v_lshrrev_b32_e32 v129, 3, v128
	v_and_b32_e32 v130, 7, v128
	v_lshlrev_b32_e32 v130, 4, v130
	v_mov_b32_e32 v133, 0x2200
	v_mad_u32_u24 v131, v129, v133, v130
	v_lshrrev_b32_e32 v132, 6, v206
	v_mov_b32_e32 v133, 0x1200
	v_mul_u32_u24_e32 v132, v132, v133
	v_add_u32_e32 v132, 0x12000, v132
	v_mov_b32_e32 v133, 0x90
	v_mad_u32_u24 v129, v129, v133, v132
	v_add_u32_e32 v129, v129, v130
	v_mad_u32_u24 v130, v203, v133, v132
	v_lshl_add_u32 v130, v202, 4, v130
	v_cvt_pk_bf16_f32 v112, v112, v113
	v_cvt_pk_bf16_f32 v113, v114, v115
	v_cvt_pk_bf16_f32 v114, v116, v117
	v_cvt_pk_bf16_f32 v115, v118, v119
	v_cvt_pk_bf16_f32 v120, v120, v121
	v_cvt_pk_bf16_f32 v121, v122, v123
	v_cvt_pk_bf16_f32 v122, v124, v125
	v_cvt_pk_bf16_f32 v123, v126, v127
	v_cvt_pk_bf16_f32 v48, v48, v49
	v_cvt_pk_bf16_f32 v49, v50, v51
	v_cvt_pk_bf16_f32 v50, v52, v53
	v_cvt_pk_bf16_f32 v51, v54, v55
	v_cvt_pk_bf16_f32 v56, v56, v57
	v_cvt_pk_bf16_f32 v57, v58, v59
	v_cvt_pk_bf16_f32 v58, v60, v61
	v_cvt_pk_bf16_f32 v59, v62, v63
	s_nop 1
	v_permlane32_swap_b32_e32 v112, v114
	v_permlane32_swap_b32_e32 v113, v115
	v_permlane32_swap_b32_e32 v120, v122
	v_permlane32_swap_b32_e32 v121, v123
	v_permlane32_swap_b32_e32 v48, v50
	v_permlane32_swap_b32_e32 v49, v51
	v_permlane32_swap_b32_e32 v56, v58
	v_permlane32_swap_b32_e32 v57, v59
	ds_write_b128 v130, v[112:115]
	ds_write_b128 v130, v[120:123] offset:32
	ds_write_b128 v130, v[48:51] offset:64
	ds_write_b128 v130, v[56:59] offset:96
	ds_read_b128 v[116:119], v129
	ds_read_b128 v[124:127], v129 offset:1152
	ds_read_b128 v[52:55], v129 offset:2304
	ds_read_b128 v[60:63], v129 offset:3456
	v_cvt_pk_bf16_f32 v96, v96, v97
	v_cvt_pk_bf16_f32 v97, v98, v99
	v_cvt_pk_bf16_f32 v98, v100, v101
	v_cvt_pk_bf16_f32 v99, v102, v103
	v_cvt_pk_bf16_f32 v104, v104, v105
	v_cvt_pk_bf16_f32 v105, v106, v107
	v_cvt_pk_bf16_f32 v106, v108, v109
	v_cvt_pk_bf16_f32 v107, v110, v111
	v_cvt_pk_bf16_f32 v32, v32, v33
	v_cvt_pk_bf16_f32 v33, v34, v35
	v_cvt_pk_bf16_f32 v34, v36, v37
	v_cvt_pk_bf16_f32 v35, v38, v39
	v_cvt_pk_bf16_f32 v40, v40, v41
	v_cvt_pk_bf16_f32 v41, v42, v43
	v_cvt_pk_bf16_f32 v42, v44, v45
	v_cvt_pk_bf16_f32 v43, v46, v47
	s_nop 1
	v_permlane32_swap_b32_e32 v96, v98
	v_permlane32_swap_b32_e32 v97, v99
	v_permlane32_swap_b32_e32 v104, v106
	v_permlane32_swap_b32_e32 v105, v107
	v_permlane32_swap_b32_e32 v32, v34
	v_permlane32_swap_b32_e32 v33, v35
	v_permlane32_swap_b32_e32 v40, v42
	v_permlane32_swap_b32_e32 v41, v43
	s_waitcnt lgkmcnt(3)
	global_store_dwordx4 v131, v[116:119], s[100:101]
	s_add_u32 s100, s100, 0x11000
	s_addc_u32 s101, s101, 0
	s_waitcnt lgkmcnt(2)
	global_store_dwordx4 v131, v[124:127], s[100:101]
	s_add_u32 s100, s100, 0x11000
	s_addc_u32 s101, s101, 0
	s_waitcnt lgkmcnt(1)
	global_store_dwordx4 v131, v[52:55], s[100:101]
	s_add_u32 s100, s100, 0x11000
	s_addc_u32 s101, s101, 0
	s_waitcnt lgkmcnt(0)
;   DI void operator()(const f32x16 (&acc)[2][4], int mbase, int nbase, int l32, int g) const {
; #pragma unroll
;     for (int nb = 0; nb < 2; ++nb)
; #pragma unroll
;       for (int mb = 0; mb < 4; ++mb) {
;         const size_t tok = mbase + 32 * mb + l32;
;         const f32x16& c = acc[nb][mb];
; #pragma unroll
;         for (int j = 0; j < 4; j += 2) {
;           u32x2 a, b;
;           a.x = pk_bf16(c[4 * j], c[4 * j + 1]); a.y = pk_bf16(c[4 * j + 2], c[4 * j + 3]);
;           b.x = pk_bf16(c[4 * j + 4], c[4 * j + 5]); b.y = pk_bf16(c[4 * j + 6], c[4 * j + 7]);
;           store_bf8_pair(O + tok * ld + nbase + 32 * nb + 8 * j, g, a, b);
;         }
;       }
;   }
	global_store_dwordx4 v131, v[60:63], s[100:101]
	s_add_u32 s100, s100, 0x11000
	s_addc_u32 s101, s101, 0
	ds_write_b128 v130, v[96:99]
	ds_write_b128 v130, v[104:107] offset:32
	ds_write_b128 v130, v[32:35] offset:64
	ds_write_b128 v130, v[40:43] offset:96
	ds_read_b128 v[100:103], v129
	ds_read_b128 v[108:111], v129 offset:1152
	ds_read_b128 v[36:39], v129 offset:2304
	ds_read_b128 v[44:47], v129 offset:3456
	v_cvt_pk_bf16_f32 v80, v80, v81
	v_cvt_pk_bf16_f32 v81, v82, v83
	v_cvt_pk_bf16_f32 v82, v84, v85
	v_cvt_pk_bf16_f32 v83, v86, v87
	v_cvt_pk_bf16_f32 v88, v88, v89
	v_cvt_pk_bf16_f32 v89, v90, v91
	v_cvt_pk_bf16_f32 v90, v92, v93
	v_cvt_pk_bf16_f32 v91, v94, v95
	v_cvt_pk_bf16_f32 v16, v16, v17
	v_cvt_pk_bf16_f32 v17, v18, v19
	v_cvt_pk_bf16_f32 v18, v20, v21
	v_cvt_pk_bf16_f32 v19, v22, v23
	v_cvt_pk_bf16_f32 v24, v24, v25
	v_cvt_pk_bf16_f32 v25, v26, v27
	v_cvt_pk_bf16_f32 v26, v28, v29
	v_cvt_pk_bf16_f32 v27, v30, v31
	s_nop 1
	v_permlane32_swap_b32_e32 v80, v82
	v_permlane32_swap_b32_e32 v81, v83
	v_permlane32_swap_b32_e32 v88, v90
	v_permlane32_swap_b32_e32 v89, v91
	v_permlane32_swap_b32_e32 v16, v18
	v_permlane32_swap_b32_e32 v17, v19
	v_permlane32_swap_b32_e32 v24, v26
	v_permlane32_swap_b32_e32 v25, v27
	s_waitcnt lgkmcnt(3)
	global_store_dwordx4 v131, v[100:103], s[100:101]
	s_add_u32 s100, s100, 0x11000
	s_addc_u32 s101, s101, 0
	s_waitcnt lgkmcnt(2)
	global_store_dwordx4 v131, v[108:111], s[100:101]
	s_add_u32 s100, s100, 0x11000
	s_addc_u32 s101, s101, 0
	s_waitcnt lgkmcnt(1)
	global_store_dwordx4 v131, v[36:39], s[100:101]
	s_add_u32 s100, s100, 0x11000
	s_addc_u32 s101, s101, 0
	s_waitcnt lgkmcnt(0)
	global_store_dwordx4 v131, v[44:47], s[100:101]
	s_add_u32 s100, s100, 0x11000
	s_addc_u32 s101, s101, 0
	ds_write_b128 v130, v[80:83]
	ds_write_b128 v130, v[88:91] offset:32
	ds_write_b128 v130, v[16:19] offset:64
	ds_write_b128 v130, v[24:27] offset:96
	ds_read_b128 v[84:87], v129
	ds_read_b128 v[92:95], v129 offset:1152
	ds_read_b128 v[20:23], v129 offset:2304
	ds_read_b128 v[28:31], v129 offset:3456
	v_cvt_pk_bf16_f32 v64, v64, v65
	v_cvt_pk_bf16_f32 v65, v66, v67
	v_cvt_pk_bf16_f32 v66, v68, v69
	v_cvt_pk_bf16_f32 v67, v70, v71
	v_cvt_pk_bf16_f32 v72, v72, v73
	v_cvt_pk_bf16_f32 v73, v74, v75
	v_cvt_pk_bf16_f32 v74, v76, v77
	v_cvt_pk_bf16_f32 v75, v78, v79
	v_cvt_pk_bf16_f32 v0, v0, v1
	v_cvt_pk_bf16_f32 v1, v2, v3
	v_cvt_pk_bf16_f32 v2, v4, v5
	v_cvt_pk_bf16_f32 v3, v6, v7
	v_cvt_pk_bf16_f32 v8, v8, v9
	v_cvt_pk_bf16_f32 v9, v10, v11
	v_cvt_pk_bf16_f32 v10, v12, v13
	v_cvt_pk_bf16_f32 v11, v14, v15
	s_nop 1
	v_permlane32_swap_b32_e32 v64, v66
	v_permlane32_swap_b32_e32 v65, v67
	v_permlane32_swap_b32_e32 v72, v74
	v_permlane32_swap_b32_e32 v73, v75
	v_permlane32_swap_b32_e32 v0, v2
	v_permlane32_swap_b32_e32 v1, v3
	v_permlane32_swap_b32_e32 v8, v10
	v_permlane32_swap_b32_e32 v9, v11
	s_waitcnt lgkmcnt(3)
	global_store_dwordx4 v131, v[84:87], s[100:101]
	s_add_u32 s100, s100, 0x11000
	s_addc_u32 s101, s101, 0
	s_waitcnt lgkmcnt(2)
	global_store_dwordx4 v131, v[92:95], s[100:101]
	s_add_u32 s100, s100, 0x11000
	s_addc_u32 s101, s101, 0
	s_waitcnt lgkmcnt(1)
	global_store_dwordx4 v131, v[20:23], s[100:101]
	s_add_u32 s100, s100, 0x11000
	s_addc_u32 s101, s101, 0
	s_waitcnt lgkmcnt(0)
	global_store_dwordx4 v131, v[28:31], s[100:101]
	s_add_u32 s100, s100, 0x11000
	s_addc_u32 s101, s101, 0
	ds_write_b128 v130, v[64:67]
	ds_write_b128 v130, v[72:75] offset:32
	ds_write_b128 v130, v[0:3] offset:64
	ds_write_b128 v130, v[8:11] offset:96
	ds_read_b128 v[68:71], v129
	ds_read_b128 v[76:79], v129 offset:1152
	ds_read_b128 v[4:7], v129 offset:2304
	ds_read_b128 v[12:15], v129 offset:3456
	s_waitcnt lgkmcnt(3)
	global_store_dwordx4 v131, v[68:71], s[100:101]
	s_add_u32 s100, s100, 0x11000
	s_addc_u32 s101, s101, 0
	s_waitcnt lgkmcnt(2)
	global_store_dwordx4 v131, v[76:79], s[100:101]
	s_add_u32 s100, s100, 0x11000
	s_addc_u32 s101, s101, 0
	s_waitcnt lgkmcnt(1)
	global_store_dwordx4 v131, v[4:7], s[100:101]
	s_add_u32 s100, s100, 0x11000
	s_addc_u32 s101, s101, 0
	s_waitcnt lgkmcnt(0)
	global_store_dwordx4 v131, v[12:15], s[100:101]
	s_add_u32 s100, s100, 0x11000
	s_addc_u32 s101, s101, 0

; template <bool trans>
; DI void gemm_core(const GTile& tl, const GTile& nx, bool has_next  , bool chain  , bool pre, u32x4 (&ra)[4], u32x4 (&rb)[4], char* smem, f32x16 (&acc)[2][4]) {
;     ...
;   const int nk = K / 64;
;   if (!pre) { G_LOAD(0); G_STORE(0); G_LOAD(1); }
;   for (int kt = 0; kt < nk; ++kt) {
;     __syncthreads();
;     G_COMPUTE(kt & 1, kt);
;   }
.LBB0_103:
	v_lshl_add_u64 v[190:191], s[0:1], 0, v[192:193]
	v_lshl_add_u64 v[188:189], s[6:7], 0, v[192:193]
	s_waitcnt lgkmcnt(0)
	s_barrier
	global_load_dwordx4 v[218:221], v[190:191], off offset:256
	global_load_dwordx4 v[222:225], v[188:189], off offset:256
	s_lshr_b32 s1, s33, 1
	s_and_b32 s0, s33, 0xc0
	v_and_b32_e32 v10, 31, v8
	s_and_b32 s1, s1, 0xfffff80
	v_or_b32_e32 v12, s1, v10
	v_or_b32_e32 v10, s0, v10
	v_add3_u32 v215, 16, v11, v9
	v_lshrrev_b32_e32 v8, 1, v8
	v_mul_u32_u24_e32 v242, 0x90, v10
	v_and_b32_e32 v243, 16, v8
	v_add_u32_e32 v209, 0x12000, v215
	v_mul_lo_u32 v208, v12, s45
	v_add3_u32 v205, 16, v242, v243
	v_add_u32_e32 v210, 0x1b000, v215
	ds_write_b128 v209, v[0:3]
	s_waitcnt vmcnt(6)
	ds_write_b128 v210, v[4:7]
	v_add3_u32 v204, 16, v208, v243
	ds_read_b128 v[0:3], v205 offset:36864
	ds_read_b128 v[4:7], v205 offset:41472
	ds_read_b128 v[8:11], v204
	ds_read_b128 v[12:15], v204 offset:4608
	v_lshl_add_u64 v[184:185], v[190:191], 0, s[42:43]
	v_lshl_add_u64 v[186:187], s[28:29], 0, v[192:193]
	v_lshl_add_u64 v[194:195], v[190:191], 0, s[34:35]
	v_lshl_add_u64 v[196:197], s[26:27], 0, v[192:193]
	s_setprio 1
	s_waitcnt lgkmcnt(1)
	v_mfma_f32_32x32x16_bf16 v[112:127], v[8:11], v[0:3], 0
	v_mfma_f32_32x32x16_bf16 v[48:63], v[8:11], v[4:7], 0
	s_waitcnt lgkmcnt(0)
	v_mfma_f32_32x32x16_bf16 v[96:111], v[12:15], v[0:3], 0
	v_mfma_f32_32x32x16_bf16 v[32:47], v[12:15], v[4:7], 0
	ds_read_b128 v[8:11], v204 offset:9216
	ds_read_b128 v[12:15], v204 offset:13824
	s_waitcnt lgkmcnt(1)
	v_mfma_f32_32x32x16_bf16 v[80:95], v[8:11], v[0:3], 0
	v_mfma_f32_32x32x16_bf16 v[16:31], v[8:11], v[4:7], 0
	s_waitcnt lgkmcnt(0)
	v_mfma_f32_32x32x16_bf16 v[64:79], v[12:15], v[0:3], 0
	v_mfma_f32_32x32x16_bf16 v[0:15], v[12:15], v[4:7], 0
	s_setprio 0
	global_load_dwordx4 v[226:229], v[194:195], off offset:256
	global_load_dwordx4 v[230:233], v[196:197], off offset:256
	v_add_u32_e32 v212, 0x14400, v215
	v_add_u32_e32 v211, 0x1d400, v215
	ds_write_b128 v212, v[176:179]
	s_waitcnt vmcnt(7)
	ds_write_b128 v211, v[180:183]
	ds_read_b128 v[176:179], v205 offset:36896
	ds_read_b128 v[180:183], v205 offset:41504
	ds_read_b128 v[198:201], v204 offset:32
	ds_read_b128 v[234:237], v204 offset:4640
	s_setprio 1
	s_waitcnt lgkmcnt(1)
	v_mfma_f32_32x32x16_bf16 v[112:127], v[198:201], v[176:179], v[112:127]
	v_mfma_f32_32x32x16_bf16 v[48:63], v[198:201], v[180:183], v[48:63]
	s_waitcnt lgkmcnt(0)
	v_mfma_f32_32x32x16_bf16 v[96:111], v[234:237], v[176:179], v[96:111]
	v_mfma_f32_32x32x16_bf16 v[32:47], v[234:237], v[180:183], v[32:47]
	ds_read_b128 v[198:201], v204 offset:9248
	ds_read_b128 v[234:237], v204 offset:13856
	s_waitcnt lgkmcnt(1)
	v_mfma_f32_32x32x16_bf16 v[80:95], v[198:201], v[176:179], v[80:95]
	v_mfma_f32_32x32x16_bf16 v[16:31], v[198:201], v[180:183], v[16:31]
	s_waitcnt lgkmcnt(0)
	v_mfma_f32_32x32x16_bf16 v[64:79], v[234:237], v[176:179], v[64:79]
	v_mfma_f32_32x32x16_bf16 v[0:15], v[234:237], v[180:183], v[0:15]
	s_setprio 0
	global_load_dwordx4 v[176:179], v[184:185], off offset:256
	global_load_dwordx4 v[180:183], v[186:187], off offset:256
	v_add_u32_e32 v214, 0x16800, v215
	v_add_u32_e32 v213, 0x1f800, v215
	ds_write_b128 v214, v[168:171]
	s_waitcnt vmcnt(8)
	ds_write_b128 v213, v[172:175]
	ds_read_b128 v[168:171], v205 offset:36928
	ds_read_b128 v[172:175], v205 offset:41536
	ds_read_b128 v[198:201], v204 offset:64
	ds_read_b128 v[234:237], v204 offset:4672
	s_setprio 1
	s_waitcnt lgkmcnt(1)
	v_mfma_f32_32x32x16_bf16 v[112:127], v[198:201], v[168:171], v[112:127]
	v_mfma_f32_32x32x16_bf16 v[48:63], v[198:201], v[172:175], v[48:63]
	s_waitcnt lgkmcnt(0)
	v_mfma_f32_32x32x16_bf16 v[96:111], v[234:237], v[168:171], v[96:111]
	v_mfma_f32_32x32x16_bf16 v[32:47], v[234:237], v[172:175], v[32:47]
	ds_read_b128 v[198:201], v204 offset:9280
	ds_read_b128 v[234:237], v204 offset:13888
	s_waitcnt lgkmcnt(1)
	v_mfma_f32_32x32x16_bf16 v[80:95], v[198:201], v[168:171], v[80:95]
	v_mfma_f32_32x32x16_bf16 v[16:31], v[198:201], v[172:175], v[16:31]
	s_waitcnt lgkmcnt(0)
	v_mfma_f32_32x32x16_bf16 v[64:79], v[234:237], v[168:171], v[64:79]
	v_mfma_f32_32x32x16_bf16 v[0:15], v[234:237], v[172:175], v[0:15]
	s_setprio 0
	v_add_co_u32_e32 v198, vcc, s44, v190
	v_add_u32_e32 v217, 0x18c00, v215
	s_nop 0
	v_addc_co_u32_e32 v199, vcc, 0, v191, vcc
	v_add_co_u32_e32 v200, vcc, s44, v188
	v_add_u32_e32 v216, 0x21c00, v215
	s_nop 0
	v_addc_co_u32_e32 v201, vcc, 0, v189, vcc
	global_load_dwordx4 v[168:171], v[198:199], off offset:256
	global_load_dwordx4 v[172:175], v[200:201], off offset:256
	s_waitcnt vmcnt(8)
	ds_write_b128 v217, v[164:167]
	ds_write_b128 v216, v[160:163]
	ds_read_b128 v[160:163], v205 offset:36960
	ds_read_b128 v[164:167], v205 offset:41568
	ds_read_b128 v[234:237], v204 offset:96
	ds_read_b128 v[238:241], v204 offset:4704
	s_setprio 1
	s_waitcnt lgkmcnt(1)
	v_mfma_f32_32x32x16_bf16 v[112:127], v[234:237], v[160:163], v[112:127]
	v_mfma_f32_32x32x16_bf16 v[48:63], v[234:237], v[164:167], v[48:63]
	s_waitcnt lgkmcnt(0)
	v_mfma_f32_32x32x16_bf16 v[96:111], v[238:241], v[160:163], v[96:111]
	v_mfma_f32_32x32x16_bf16 v[32:47], v[238:241], v[164:167], v[32:47]
	ds_read_b128 v[234:237], v204 offset:9312
	ds_read_b128 v[238:241], v204 offset:13920
	s_waitcnt lgkmcnt(1)
	v_mfma_f32_32x32x16_bf16 v[80:95], v[234:237], v[160:163], v[80:95]
	v_mfma_f32_32x32x16_bf16 v[16:31], v[234:237], v[164:167], v[16:31]
	s_waitcnt lgkmcnt(0)
	v_mfma_f32_32x32x16_bf16 v[64:79], v[238:241], v[160:163], v[64:79]
	v_mfma_f32_32x32x16_bf16 v[0:15], v[238:241], v[164:167], v[0:15]
	s_setprio 0
	global_load_dwordx4 v[160:163], v[190:191], off offset:384
	global_load_dwordx4 v[164:167], v[188:189], off offset:384
	s_barrier
; template <bool trans>
; DI void gemm_core(const GTile& tl, const GTile& nx, bool has_next  , bool chain  , bool pre, u32x4 (&ra)[4], u32x4 (&rb)[4], char* smem, f32x16 (&acc)[2][4]) {
;     ...
;   const int nk = K / 64;
;   if (!pre) { G_LOAD(0); G_STORE(0); G_LOAD(1); }
;   for (int kt = 0; kt < nk; ++kt) {
;     __syncthreads();
;     G_COMPUTE(kt & 1, kt);
;   }
	s_add_i32 s0, 16, 0x12000
	v_add3_u32 v192, s0, v208, v243
	s_add_i32 s0, 16, 0x1b000
	v_add3_u32 v208, s0, v242, v243
	s_waitcnt vmcnt(9)
	ds_write_b128 v215, v[218:221]
	s_waitcnt vmcnt(8)
	ds_write_b128 v215, v[222:225] offset:36864
	ds_read_b128 v[218:221], v208
	ds_read_b128 v[222:225], v208 offset:4608
	ds_read_b128 v[234:237], v192
	ds_read_b128 v[238:241], v192 offset:4608
	s_setprio 1
	s_waitcnt lgkmcnt(1)
	v_mfma_f32_32x32x16_bf16 v[112:127], v[234:237], v[218:221], v[112:127]
	v_mfma_f32_32x32x16_bf16 v[48:63], v[234:237], v[222:225], v[48:63]
	s_waitcnt lgkmcnt(0)
	v_mfma_f32_32x32x16_bf16 v[96:111], v[238:241], v[218:221], v[96:111]
	v_mfma_f32_32x32x16_bf16 v[32:47], v[238:241], v[222:225], v[32:47]
	ds_read_b128 v[234:237], v192 offset:9216
	ds_read_b128 v[238:241], v192 offset:13824
	s_waitcnt lgkmcnt(1)
	v_mfma_f32_32x32x16_bf16 v[80:95], v[234:237], v[218:221], v[80:95]
	v_mfma_f32_32x32x16_bf16 v[16:31], v[234:237], v[222:225], v[16:31]
	s_waitcnt lgkmcnt(0)
	v_mfma_f32_32x32x16_bf16 v[64:79], v[238:241], v[218:221], v[64:79]
	v_mfma_f32_32x32x16_bf16 v[0:15], v[238:241], v[222:225], v[0:15]
	s_setprio 0
	global_load_dwordx4 v[218:221], v[194:195], off offset:384
	global_load_dwordx4 v[222:225], v[196:197], off offset:384
	s_waitcnt vmcnt(9)
	ds_write_b128 v215, v[226:229] offset:9216
	s_waitcnt vmcnt(8)
	ds_write_b128 v215, v[230:233] offset:46080
	ds_read_b128 v[226:229], v208 offset:32
	ds_read_b128 v[230:233], v208 offset:4640
	ds_read_b128 v[234:237], v192 offset:32
	ds_read_b128 v[238:241], v192 offset:4640
	s_setprio 1
	s_waitcnt lgkmcnt(1)
	v_mfma_f32_32x32x16_bf16 v[112:127], v[234:237], v[226:229], v[112:127]
	v_mfma_f32_32x32x16_bf16 v[48:63], v[234:237], v[230:233], v[48:63]
	s_waitcnt lgkmcnt(0)
	v_mfma_f32_32x32x16_bf16 v[96:111], v[238:241], v[226:229], v[96:111]
	v_mfma_f32_32x32x16_bf16 v[32:47], v[238:241], v[230:233], v[32:47]
	ds_read_b128 v[234:237], v192 offset:9248
	ds_read_b128 v[238:241], v192 offset:13856
	s_waitcnt lgkmcnt(1)
	v_mfma_f32_32x32x16_bf16 v[80:95], v[234:237], v[226:229], v[80:95]
	v_mfma_f32_32x32x16_bf16 v[16:31], v[234:237], v[230:233], v[16:31]
	s_waitcnt lgkmcnt(0)
	v_mfma_f32_32x32x16_bf16 v[64:79], v[238:241], v[226:229], v[64:79]
	v_mfma_f32_32x32x16_bf16 v[0:15], v[238:241], v[230:233], v[0:15]
	s_setprio 0
	global_load_dwordx4 v[226:229], v[184:185], off offset:384
	global_load_dwordx4 v[230:233], v[186:187], off offset:384
	s_waitcnt vmcnt(9)
	ds_write_b128 v215, v[176:179] offset:18432
	s_waitcnt vmcnt(8)
	ds_write_b128 v215, v[180:183] offset:55296
	ds_read_b128 v[176:179], v208 offset:64
	ds_read_b128 v[180:183], v208 offset:4672
	ds_read_b128 v[234:237], v192 offset:64
	ds_read_b128 v[238:241], v192 offset:4672
	s_setprio 1
	s_waitcnt lgkmcnt(1)
	v_mfma_f32_32x32x16_bf16 v[112:127], v[234:237], v[176:179], v[112:127]
	v_mfma_f32_32x32x16_bf16 v[48:63], v[234:237], v[180:183], v[48:63]
	s_waitcnt lgkmcnt(0)
	v_mfma_f32_32x32x16_bf16 v[96:111], v[238:241], v[176:179], v[96:111]
	v_mfma_f32_32x32x16_bf16 v[32:47], v[238:241], v[180:183], v[32:47]
	ds_read_b128 v[234:237], v192 offset:9280
	ds_read_b128 v[238:241], v192 offset:13888
	s_waitcnt lgkmcnt(1)
	v_mfma_f32_32x32x16_bf16 v[80:95], v[234:237], v[176:179], v[80:95]
	v_mfma_f32_32x32x16_bf16 v[16:31], v[234:237], v[180:183], v[16:31]
	s_waitcnt lgkmcnt(0)
	v_mfma_f32_32x32x16_bf16 v[64:79], v[238:241], v[176:179], v[64:79]
	v_mfma_f32_32x32x16_bf16 v[0:15], v[238:241], v[180:183], v[0:15]
	s_setprio 0
	global_load_dwordx4 v[176:179], v[198:199], off offset:384
	global_load_dwordx4 v[180:183], v[200:201], off offset:384
	s_waitcnt vmcnt(9)
	ds_write_b128 v215, v[168:171] offset:27648
	s_waitcnt vmcnt(8)
	ds_write_b128 v215, v[172:175] offset:64512
	ds_read_b128 v[168:171], v208 offset:96
	ds_read_b128 v[172:175], v208 offset:4704
	ds_read_b128 v[234:237], v192 offset:96
	ds_read_b128 v[238:241], v192 offset:4704
	s_setprio 1
	s_waitcnt lgkmcnt(1)
	v_mfma_f32_32x32x16_bf16 v[112:127], v[234:237], v[168:171], v[112:127]
	v_mfma_f32_32x32x16_bf16 v[48:63], v[234:237], v[172:175], v[48:63]
	s_waitcnt lgkmcnt(0)
	v_mfma_f32_32x32x16_bf16 v[96:111], v[238:241], v[168:171], v[96:111]
	v_mfma_f32_32x32x16_bf16 v[32:47], v[238:241], v[172:175], v[32:47]
	ds_read_b128 v[234:237], v192 offset:9312
	ds_read_b128 v[238:241], v192 offset:13920
	s_waitcnt lgkmcnt(1)
	v_mfma_f32_32x32x16_bf16 v[80:95], v[234:237], v[168:171], v[80:95]
	v_mfma_f32_32x32x16_bf16 v[16:31], v[234:237], v[172:175], v[16:31]
	s_waitcnt lgkmcnt(0)
	v_mfma_f32_32x32x16_bf16 v[64:79], v[238:241], v[168:171], v[64:79]
	v_mfma_f32_32x32x16_bf16 v[0:15], v[238:241], v[172:175], v[0:15]
	s_setprio 0
	global_load_dwordx4 v[168:171], v[190:191], off offset:512
	global_load_dwordx4 v[172:175], v[188:189], off offset:512
	s_barrier
; template <bool trans>
; DI void gemm_core(const GTile& tl, const GTile& nx, bool has_next  , bool chain  , bool pre, u32x4 (&ra)[4], u32x4 (&rb)[4], char* smem, f32x16 (&acc)[2][4]) {
;     ...
;   const int nk = K / 64;
;   if (!pre) { G_LOAD(0); G_STORE(0); G_LOAD(1); }
;   for (int kt = 0; kt < nk; ++kt) {
;     __syncthreads();
;     G_COMPUTE(kt & 1, kt);
;   }
	s_waitcnt vmcnt(9)
	ds_write_b128 v209, v[160:163]
	s_waitcnt vmcnt(8)
	ds_write_b128 v210, v[164:167]
	ds_read_b128 v[160:163], v205 offset:36864
	ds_read_b128 v[164:167], v205 offset:41472
	ds_read_b128 v[234:237], v204
	ds_read_b128 v[238:241], v204 offset:4608
	s_setprio 1
	s_waitcnt lgkmcnt(1)
	v_mfma_f32_32x32x16_bf16 v[112:127], v[234:237], v[160:163], v[112:127]
	v_mfma_f32_32x32x16_bf16 v[48:63], v[234:237], v[164:167], v[48:63]
	s_waitcnt lgkmcnt(0)
	v_mfma_f32_32x32x16_bf16 v[96:111], v[238:241], v[160:163], v[96:111]
	v_mfma_f32_32x32x16_bf16 v[32:47], v[238:241], v[164:167], v[32:47]
	ds_read_b128 v[234:237], v204 offset:9216
	ds_read_b128 v[238:241], v204 offset:13824
	s_waitcnt vmcnt(7)
	ds_write_b128 v212, v[218:221]
	s_waitcnt vmcnt(6)
	ds_write_b128 v211, v[222:225]
	ds_read_b128 v[218:221], v205 offset:36896
	ds_read_b128 v[222:225], v205 offset:41504
	s_waitcnt lgkmcnt(5)
	v_mfma_f32_32x32x16_bf16 v[80:95], v[234:237], v[160:163], v[80:95]
	v_mfma_f32_32x32x16_bf16 v[16:31], v[234:237], v[164:167], v[16:31]
	ds_read_b128 v[234:237], v204 offset:32
	s_waitcnt lgkmcnt(5)
	v_mfma_f32_32x32x16_bf16 v[64:79], v[238:241], v[160:163], v[64:79]
	v_mfma_f32_32x32x16_bf16 v[0:15], v[238:241], v[164:167], v[0:15]
	ds_read_b128 v[238:241], v204 offset:4640
	s_setprio 0
	global_load_dwordx4 v[160:163], v[194:195], off offset:512
	global_load_dwordx4 v[164:167], v[196:197], off offset:512
	s_setprio 1
	s_waitcnt lgkmcnt(1)
	v_mfma_f32_32x32x16_bf16 v[112:127], v[234:237], v[218:221], v[112:127]
	v_mfma_f32_32x32x16_bf16 v[48:63], v[234:237], v[222:225], v[48:63]
	s_waitcnt lgkmcnt(0)
	v_mfma_f32_32x32x16_bf16 v[96:111], v[238:241], v[218:221], v[96:111]
	v_mfma_f32_32x32x16_bf16 v[32:47], v[238:241], v[222:225], v[32:47]
	ds_read_b128 v[234:237], v204 offset:9248
	ds_read_b128 v[238:241], v204 offset:13856
	s_waitcnt vmcnt(7)
	ds_write_b128 v214, v[226:229]
	s_waitcnt vmcnt(6)
	ds_write_b128 v213, v[230:233]
	ds_read_b128 v[226:229], v205 offset:36928
	ds_read_b128 v[230:233], v205 offset:41536
	s_waitcnt lgkmcnt(5)
	v_mfma_f32_32x32x16_bf16 v[80:95], v[234:237], v[218:221], v[80:95]
	v_mfma_f32_32x32x16_bf16 v[16:31], v[234:237], v[222:225], v[16:31]
	ds_read_b128 v[234:237], v204 offset:64
	s_waitcnt lgkmcnt(5)
	v_mfma_f32_32x32x16_bf16 v[64:79], v[238:241], v[218:221], v[64:79]
	v_mfma_f32_32x32x16_bf16 v[0:15], v[238:241], v[222:225], v[0:15]
	ds_read_b128 v[238:241], v204 offset:4672
	s_setprio 0
	global_load_dwordx4 v[218:221], v[184:185], off offset:512
	global_load_dwordx4 v[222:225], v[186:187], off offset:512
	s_setprio 1
	s_waitcnt lgkmcnt(1)
	v_mfma_f32_32x32x16_bf16 v[112:127], v[234:237], v[226:229], v[112:127]
	v_mfma_f32_32x32x16_bf16 v[48:63], v[234:237], v[230:233], v[48:63]
	s_waitcnt lgkmcnt(0)
	v_mfma_f32_32x32x16_bf16 v[96:111], v[238:241], v[226:229], v[96:111]
	v_mfma_f32_32x32x16_bf16 v[32:47], v[238:241], v[230:233], v[32:47]
	ds_read_b128 v[234:237], v204 offset:9280
	ds_read_b128 v[238:241], v204 offset:13888
	s_waitcnt vmcnt(7)
	ds_write_b128 v217, v[176:179]
	s_waitcnt vmcnt(6)
	ds_write_b128 v216, v[180:183]
	ds_read_b128 v[176:179], v205 offset:36960
	ds_read_b128 v[180:183], v205 offset:41568
	s_waitcnt lgkmcnt(5)
	v_mfma_f32_32x32x16_bf16 v[80:95], v[234:237], v[226:229], v[80:95]
	v_mfma_f32_32x32x16_bf16 v[16:31], v[234:237], v[230:233], v[16:31]
	ds_read_b128 v[234:237], v204 offset:96
	s_waitcnt lgkmcnt(5)
	v_mfma_f32_32x32x16_bf16 v[64:79], v[238:241], v[226:229], v[64:79]
	v_mfma_f32_32x32x16_bf16 v[0:15], v[238:241], v[230:233], v[0:15]
	ds_read_b128 v[238:241], v204 offset:4704
	s_setprio 0
	global_load_dwordx4 v[226:229], v[198:199], off offset:512
	global_load_dwordx4 v[230:233], v[200:201], off offset:512
	s_setprio 1
	s_waitcnt lgkmcnt(1)
	v_mfma_f32_32x32x16_bf16 v[112:127], v[234:237], v[176:179], v[112:127]
	v_mfma_f32_32x32x16_bf16 v[48:63], v[234:237], v[180:183], v[48:63]
	s_waitcnt lgkmcnt(0)
	v_mfma_f32_32x32x16_bf16 v[96:111], v[238:241], v[176:179], v[96:111]
	v_mfma_f32_32x32x16_bf16 v[32:47], v[238:241], v[180:183], v[32:47]
	ds_read_b128 v[234:237], v204 offset:9312
	ds_read_b128 v[238:241], v204 offset:13920
	s_waitcnt lgkmcnt(0)
	s_barrier
	s_waitcnt vmcnt(7)
	ds_write_b128 v215, v[168:171]
	s_waitcnt vmcnt(6)
	ds_write_b128 v215, v[172:175] offset:36864
	ds_read_b128 v[168:171], v208
	ds_read_b128 v[172:175], v208 offset:4608
	v_mfma_f32_32x32x16_bf16 v[80:95], v[234:237], v[176:179], v[80:95]
	v_mfma_f32_32x32x16_bf16 v[16:31], v[234:237], v[180:183], v[16:31]
	ds_read_b128 v[234:237], v192
	v_mfma_f32_32x32x16_bf16 v[64:79], v[238:241], v[176:179], v[64:79]
	v_mfma_f32_32x32x16_bf16 v[0:15], v[238:241], v[180:183], v[0:15]
	ds_read_b128 v[238:241], v192 offset:4608
	s_setprio 0
	global_load_dwordx4 v[176:179], v[190:191], off offset:640
	global_load_dwordx4 v[180:183], v[188:189], off offset:640
	s_setprio 1
	s_waitcnt lgkmcnt(1)
	v_mfma_f32_32x32x16_bf16 v[112:127], v[234:237], v[168:171], v[112:127]
	v_mfma_f32_32x32x16_bf16 v[48:63], v[234:237], v[172:175], v[48:63]
	s_waitcnt lgkmcnt(0)
	v_mfma_f32_32x32x16_bf16 v[96:111], v[238:241], v[168:171], v[96:111]
	v_mfma_f32_32x32x16_bf16 v[32:47], v[238:241], v[172:175], v[32:47]
	ds_read_b128 v[234:237], v192 offset:9216
	ds_read_b128 v[238:241], v192 offset:13824
	s_waitcnt vmcnt(7)
	ds_write_b128 v215, v[160:163] offset:9216
	s_waitcnt vmcnt(6)
	ds_write_b128 v215, v[164:167] offset:46080
	ds_read_b128 v[160:163], v208 offset:32
	ds_read_b128 v[164:167], v208 offset:4640
	s_waitcnt lgkmcnt(5)
	v_mfma_f32_32x32x16_bf16 v[80:95], v[234:237], v[168:171], v[80:95]
	v_mfma_f32_32x32x16_bf16 v[16:31], v[234:237], v[172:175], v[16:31]
	ds_read_b128 v[234:237], v192 offset:32
	s_waitcnt lgkmcnt(5)
; template <bool trans>
; DI void gemm_core(const GTile& tl, const GTile& nx, bool has_next  , bool chain  , bool pre, u32x4 (&ra)[4], u32x4 (&rb)[4], char* smem, f32x16 (&acc)[2][4]) {
;     ...
;   const int nk = K / 64;
;   if (!pre) { G_LOAD(0); G_STORE(0); G_LOAD(1); }
;   for (int kt = 0; kt < nk; ++kt) {
;     __syncthreads();
;     G_COMPUTE(kt & 1, kt);
;   }
	v_mfma_f32_32x32x16_bf16 v[64:79], v[238:241], v[168:171], v[64:79]
	v_mfma_f32_32x32x16_bf16 v[0:15], v[238:241], v[172:175], v[0:15]
	ds_read_b128 v[238:241], v192 offset:4640
	s_setprio 0
	global_load_dwordx4 v[168:171], v[194:195], off offset:640
	global_load_dwordx4 v[172:175], v[196:197], off offset:640
	s_setprio 1
	s_waitcnt lgkmcnt(1)
	v_mfma_f32_32x32x16_bf16 v[112:127], v[234:237], v[160:163], v[112:127]
	v_mfma_f32_32x32x16_bf16 v[48:63], v[234:237], v[164:167], v[48:63]
	s_waitcnt lgkmcnt(0)
	v_mfma_f32_32x32x16_bf16 v[96:111], v[238:241], v[160:163], v[96:111]
	v_mfma_f32_32x32x16_bf16 v[32:47], v[238:241], v[164:167], v[32:47]
	ds_read_b128 v[234:237], v192 offset:9248
	ds_read_b128 v[238:241], v192 offset:13856
	s_waitcnt vmcnt(7)
	ds_write_b128 v215, v[218:221] offset:18432
	s_waitcnt vmcnt(6)
	ds_write_b128 v215, v[222:225] offset:55296
	ds_read_b128 v[218:221], v208 offset:64
	ds_read_b128 v[222:225], v208 offset:4672
	s_waitcnt lgkmcnt(5)
	v_mfma_f32_32x32x16_bf16 v[80:95], v[234:237], v[160:163], v[80:95]
	v_mfma_f32_32x32x16_bf16 v[16:31], v[234:237], v[164:167], v[16:31]
	ds_read_b128 v[234:237], v192 offset:64
	s_waitcnt lgkmcnt(5)
	v_mfma_f32_32x32x16_bf16 v[64:79], v[238:241], v[160:163], v[64:79]
	v_mfma_f32_32x32x16_bf16 v[0:15], v[238:241], v[164:167], v[0:15]
	ds_read_b128 v[238:241], v192 offset:4672
	s_setprio 0
	global_load_dwordx4 v[160:163], v[184:185], off offset:640
	global_load_dwordx4 v[164:167], v[186:187], off offset:640
	s_setprio 1
	s_waitcnt lgkmcnt(1)
	v_mfma_f32_32x32x16_bf16 v[112:127], v[234:237], v[218:221], v[112:127]
	v_mfma_f32_32x32x16_bf16 v[48:63], v[234:237], v[222:225], v[48:63]
	s_waitcnt lgkmcnt(0)
	v_mfma_f32_32x32x16_bf16 v[96:111], v[238:241], v[218:221], v[96:111]
	v_mfma_f32_32x32x16_bf16 v[32:47], v[238:241], v[222:225], v[32:47]
	ds_read_b128 v[234:237], v192 offset:9280
	ds_read_b128 v[238:241], v192 offset:13888
	s_waitcnt vmcnt(7)
	ds_write_b128 v215, v[226:229] offset:27648
	s_waitcnt vmcnt(6)
	ds_write_b128 v215, v[230:233] offset:64512
	ds_read_b128 v[226:229], v208 offset:96
	ds_read_b128 v[230:233], v208 offset:4704
	s_waitcnt lgkmcnt(5)
	v_mfma_f32_32x32x16_bf16 v[80:95], v[234:237], v[218:221], v[80:95]
	v_mfma_f32_32x32x16_bf16 v[16:31], v[234:237], v[222:225], v[16:31]
	ds_read_b128 v[234:237], v192 offset:96
	s_waitcnt lgkmcnt(5)
	v_mfma_f32_32x32x16_bf16 v[64:79], v[238:241], v[218:221], v[64:79]
	v_mfma_f32_32x32x16_bf16 v[0:15], v[238:241], v[222:225], v[0:15]
	ds_read_b128 v[238:241], v192 offset:4704
	s_setprio 0
	global_load_dwordx4 v[218:221], v[198:199], off offset:640
	global_load_dwordx4 v[222:225], v[200:201], off offset:640
	s_setprio 1
	s_waitcnt lgkmcnt(1)
	v_mfma_f32_32x32x16_bf16 v[112:127], v[234:237], v[226:229], v[112:127]
	v_mfma_f32_32x32x16_bf16 v[48:63], v[234:237], v[230:233], v[48:63]
	s_waitcnt lgkmcnt(0)
	v_mfma_f32_32x32x16_bf16 v[96:111], v[238:241], v[226:229], v[96:111]
	v_mfma_f32_32x32x16_bf16 v[32:47], v[238:241], v[230:233], v[32:47]
	ds_read_b128 v[234:237], v192 offset:9312
	ds_read_b128 v[238:241], v192 offset:13920
	s_waitcnt lgkmcnt(0)
	s_barrier
	s_waitcnt vmcnt(7)
	ds_write_b128 v209, v[176:179]
	s_waitcnt vmcnt(6)
	ds_write_b128 v210, v[180:183]
	ds_read_b128 v[176:179], v205 offset:36864
	ds_read_b128 v[180:183], v205 offset:41472
	v_mfma_f32_32x32x16_bf16 v[80:95], v[234:237], v[226:229], v[80:95]
	v_mfma_f32_32x32x16_bf16 v[16:31], v[234:237], v[230:233], v[16:31]
	ds_read_b128 v[234:237], v204
	v_mfma_f32_32x32x16_bf16 v[64:79], v[238:241], v[226:229], v[64:79]
	v_mfma_f32_32x32x16_bf16 v[0:15], v[238:241], v[230:233], v[0:15]
	ds_read_b128 v[238:241], v204 offset:4608
	s_setprio 0
	global_load_dwordx4 v[226:229], v[190:191], off offset:768
	global_load_dwordx4 v[230:233], v[188:189], off offset:768
	s_setprio 1
	s_waitcnt lgkmcnt(1)
	v_mfma_f32_32x32x16_bf16 v[112:127], v[234:237], v[176:179], v[112:127]
	v_mfma_f32_32x32x16_bf16 v[48:63], v[234:237], v[180:183], v[48:63]
	s_waitcnt lgkmcnt(0)
	v_mfma_f32_32x32x16_bf16 v[96:111], v[238:241], v[176:179], v[96:111]
	v_mfma_f32_32x32x16_bf16 v[32:47], v[238:241], v[180:183], v[32:47]
	ds_read_b128 v[234:237], v204 offset:9216
	ds_read_b128 v[238:241], v204 offset:13824
	s_waitcnt vmcnt(7)
	ds_write_b128 v212, v[168:171]
	s_waitcnt vmcnt(6)
	ds_write_b128 v211, v[172:175]
	ds_read_b128 v[168:171], v205 offset:36896
	ds_read_b128 v[172:175], v205 offset:41504
	s_waitcnt lgkmcnt(5)
	v_mfma_f32_32x32x16_bf16 v[80:95], v[234:237], v[176:179], v[80:95]
	v_mfma_f32_32x32x16_bf16 v[16:31], v[234:237], v[180:183], v[16:31]
	ds_read_b128 v[234:237], v204 offset:32
	s_waitcnt lgkmcnt(5)
	v_mfma_f32_32x32x16_bf16 v[64:79], v[238:241], v[176:179], v[64:79]
	v_mfma_f32_32x32x16_bf16 v[0:15], v[238:241], v[180:183], v[0:15]
	ds_read_b128 v[238:241], v204 offset:4640
	s_setprio 0
	global_load_dwordx4 v[176:179], v[194:195], off offset:768
	global_load_dwordx4 v[180:183], v[196:197], off offset:768
	s_setprio 1
	s_waitcnt lgkmcnt(1)
	v_mfma_f32_32x32x16_bf16 v[112:127], v[234:237], v[168:171], v[112:127]
	v_mfma_f32_32x32x16_bf16 v[48:63], v[234:237], v[172:175], v[48:63]
	s_waitcnt lgkmcnt(0)
	v_mfma_f32_32x32x16_bf16 v[96:111], v[238:241], v[168:171], v[96:111]
	v_mfma_f32_32x32x16_bf16 v[32:47], v[238:241], v[172:175], v[32:47]
	ds_read_b128 v[234:237], v204 offset:9248
	ds_read_b128 v[238:241], v204 offset:13856
	s_waitcnt vmcnt(7)
	ds_write_b128 v214, v[160:163]
	s_waitcnt vmcnt(6)
	ds_write_b128 v213, v[164:167]
	ds_read_b128 v[160:163], v205 offset:36928
	ds_read_b128 v[164:167], v205 offset:41536
	s_waitcnt lgkmcnt(5)
; template <bool trans>
; DI void gemm_core(const GTile& tl, const GTile& nx, bool has_next  , bool chain  , bool pre, u32x4 (&ra)[4], u32x4 (&rb)[4], char* smem, f32x16 (&acc)[2][4]) {
;     ...
;   const int nk = K / 64;
;   if (!pre) { G_LOAD(0); G_STORE(0); G_LOAD(1); }
;   for (int kt = 0; kt < nk; ++kt) {
;     __syncthreads();
;     G_COMPUTE(kt & 1, kt);
;   }
	v_mfma_f32_32x32x16_bf16 v[80:95], v[234:237], v[168:171], v[80:95]
	v_mfma_f32_32x32x16_bf16 v[16:31], v[234:237], v[172:175], v[16:31]
	ds_read_b128 v[234:237], v204 offset:64
	s_waitcnt lgkmcnt(5)
	v_mfma_f32_32x32x16_bf16 v[64:79], v[238:241], v[168:171], v[64:79]
	v_mfma_f32_32x32x16_bf16 v[0:15], v[238:241], v[172:175], v[0:15]
	ds_read_b128 v[238:241], v204 offset:4672
	s_setprio 0
	global_load_dwordx4 v[168:171], v[184:185], off offset:768
	global_load_dwordx4 v[172:175], v[186:187], off offset:768
	s_setprio 1
	s_waitcnt lgkmcnt(1)
	v_mfma_f32_32x32x16_bf16 v[112:127], v[234:237], v[160:163], v[112:127]
	v_mfma_f32_32x32x16_bf16 v[48:63], v[234:237], v[164:167], v[48:63]
	s_waitcnt lgkmcnt(0)
	v_mfma_f32_32x32x16_bf16 v[96:111], v[238:241], v[160:163], v[96:111]
	v_mfma_f32_32x32x16_bf16 v[32:47], v[238:241], v[164:167], v[32:47]
	ds_read_b128 v[234:237], v204 offset:9280
	ds_read_b128 v[238:241], v204 offset:13888
	s_waitcnt vmcnt(7)
	ds_write_b128 v217, v[218:221]
	s_waitcnt vmcnt(6)
	ds_write_b128 v216, v[222:225]
	ds_read_b128 v[218:221], v205 offset:36960
	ds_read_b128 v[222:225], v205 offset:41568
	s_waitcnt lgkmcnt(5)
	v_mfma_f32_32x32x16_bf16 v[80:95], v[234:237], v[160:163], v[80:95]
	v_mfma_f32_32x32x16_bf16 v[16:31], v[234:237], v[164:167], v[16:31]
	ds_read_b128 v[234:237], v204 offset:96
	s_waitcnt lgkmcnt(5)
	v_mfma_f32_32x32x16_bf16 v[64:79], v[238:241], v[160:163], v[64:79]
	v_mfma_f32_32x32x16_bf16 v[0:15], v[238:241], v[164:167], v[0:15]
	ds_read_b128 v[238:241], v204 offset:4704
	s_setprio 0
	global_load_dwordx4 v[160:163], v[198:199], off offset:768
	global_load_dwordx4 v[164:167], v[200:201], off offset:768
	s_setprio 1
	s_waitcnt lgkmcnt(1)
	v_mfma_f32_32x32x16_bf16 v[112:127], v[234:237], v[218:221], v[112:127]
	v_mfma_f32_32x32x16_bf16 v[48:63], v[234:237], v[222:225], v[48:63]
	s_waitcnt lgkmcnt(0)
	v_mfma_f32_32x32x16_bf16 v[96:111], v[238:241], v[218:221], v[96:111]
	v_mfma_f32_32x32x16_bf16 v[32:47], v[238:241], v[222:225], v[32:47]
	ds_read_b128 v[234:237], v204 offset:9312
	ds_read_b128 v[238:241], v204 offset:13920
	s_waitcnt lgkmcnt(0)
	s_barrier
	s_waitcnt vmcnt(7)
	ds_write_b128 v215, v[226:229]
	s_waitcnt vmcnt(6)
	ds_write_b128 v215, v[230:233] offset:36864
	ds_read_b128 v[226:229], v208
	ds_read_b128 v[230:233], v208 offset:4608
	v_mfma_f32_32x32x16_bf16 v[80:95], v[234:237], v[218:221], v[80:95]
	v_mfma_f32_32x32x16_bf16 v[16:31], v[234:237], v[222:225], v[16:31]
	ds_read_b128 v[234:237], v192
	v_mfma_f32_32x32x16_bf16 v[64:79], v[238:241], v[218:221], v[64:79]
	v_mfma_f32_32x32x16_bf16 v[0:15], v[238:241], v[222:225], v[0:15]
	ds_read_b128 v[238:241], v192 offset:4608
	s_setprio 0
	global_load_dwordx4 v[218:221], v[190:191], off offset:896
	global_load_dwordx4 v[222:225], v[188:189], off offset:896
	s_setprio 1
	s_waitcnt lgkmcnt(1)
	v_mfma_f32_32x32x16_bf16 v[112:127], v[234:237], v[226:229], v[112:127]
	v_mfma_f32_32x32x16_bf16 v[48:63], v[234:237], v[230:233], v[48:63]
	s_waitcnt lgkmcnt(0)
	v_mfma_f32_32x32x16_bf16 v[96:111], v[238:241], v[226:229], v[96:111]
	v_mfma_f32_32x32x16_bf16 v[32:47], v[238:241], v[230:233], v[32:47]
	ds_read_b128 v[234:237], v192 offset:9216
	ds_read_b128 v[238:241], v192 offset:13824
	s_waitcnt vmcnt(7)
	ds_write_b128 v215, v[176:179] offset:9216
	s_waitcnt vmcnt(6)
	ds_write_b128 v215, v[180:183] offset:46080
	ds_read_b128 v[176:179], v208 offset:32
	ds_read_b128 v[180:183], v208 offset:4640
	s_waitcnt lgkmcnt(5)
	v_mfma_f32_32x32x16_bf16 v[80:95], v[234:237], v[226:229], v[80:95]
	v_mfma_f32_32x32x16_bf16 v[16:31], v[234:237], v[230:233], v[16:31]
	ds_read_b128 v[234:237], v192 offset:32
	s_waitcnt lgkmcnt(5)
	v_mfma_f32_32x32x16_bf16 v[64:79], v[238:241], v[226:229], v[64:79]
	v_mfma_f32_32x32x16_bf16 v[0:15], v[238:241], v[230:233], v[0:15]
	ds_read_b128 v[238:241], v192 offset:4640
	s_setprio 0
	global_load_dwordx4 v[226:229], v[194:195], off offset:896
	global_load_dwordx4 v[230:233], v[196:197], off offset:896
	s_setprio 1
	s_waitcnt lgkmcnt(1)
	v_mfma_f32_32x32x16_bf16 v[112:127], v[234:237], v[176:179], v[112:127]
	v_mfma_f32_32x32x16_bf16 v[48:63], v[234:237], v[180:183], v[48:63]
	s_waitcnt lgkmcnt(0)
	v_mfma_f32_32x32x16_bf16 v[96:111], v[238:241], v[176:179], v[96:111]
	v_mfma_f32_32x32x16_bf16 v[32:47], v[238:241], v[180:183], v[32:47]
	ds_read_b128 v[234:237], v192 offset:9248
	ds_read_b128 v[238:241], v192 offset:13856
	s_waitcnt vmcnt(7)
	ds_write_b128 v215, v[168:171] offset:18432
	s_waitcnt vmcnt(6)
	ds_write_b128 v215, v[172:175] offset:55296
	ds_read_b128 v[168:171], v208 offset:64
	ds_read_b128 v[172:175], v208 offset:4672
	s_waitcnt lgkmcnt(5)
	v_mfma_f32_32x32x16_bf16 v[80:95], v[234:237], v[176:179], v[80:95]
	v_mfma_f32_32x32x16_bf16 v[16:31], v[234:237], v[180:183], v[16:31]
	ds_read_b128 v[234:237], v192 offset:64
	s_waitcnt lgkmcnt(5)
	v_mfma_f32_32x32x16_bf16 v[64:79], v[238:241], v[176:179], v[64:79]
	v_mfma_f32_32x32x16_bf16 v[0:15], v[238:241], v[180:183], v[0:15]
	ds_read_b128 v[238:241], v192 offset:4672
	s_setprio 0
	global_load_dwordx4 v[176:179], v[184:185], off offset:896
	global_load_dwordx4 v[180:183], v[186:187], off offset:896
	s_setprio 1
	s_waitcnt lgkmcnt(1)
	v_mfma_f32_32x32x16_bf16 v[112:127], v[234:237], v[168:171], v[112:127]
	v_mfma_f32_32x32x16_bf16 v[48:63], v[234:237], v[172:175], v[48:63]
	s_waitcnt lgkmcnt(0)
	v_mfma_f32_32x32x16_bf16 v[96:111], v[238:241], v[168:171], v[96:111]
	v_mfma_f32_32x32x16_bf16 v[32:47], v[238:241], v[172:175], v[32:47]
	ds_read_b128 v[234:237], v192 offset:9280
	ds_read_b128 v[238:241], v192 offset:13888
	s_waitcnt vmcnt(7)
	ds_write_b128 v215, v[160:163] offset:27648
	s_waitcnt vmcnt(6)
	ds_write_b128 v215, v[164:167] offset:64512
	ds_read_b128 v[160:163], v208 offset:96
	ds_read_b128 v[164:167], v208 offset:4704
	s_waitcnt lgkmcnt(5)
	v_mfma_f32_32x32x16_bf16 v[80:95], v[234:237], v[168:171], v[80:95]
	v_mfma_f32_32x32x16_bf16 v[16:31], v[234:237], v[172:175], v[16:31]
	ds_read_b128 v[234:237], v192 offset:96
	s_waitcnt lgkmcnt(5)
	v_mfma_f32_32x32x16_bf16 v[64:79], v[238:241], v[168:171], v[64:79]
	v_mfma_f32_32x32x16_bf16 v[0:15], v[238:241], v[172:175], v[0:15]
	ds_read_b128 v[238:241], v192 offset:4704
	s_setprio 0
	global_load_dwordx4 v[168:171], v[198:199], off offset:896
	global_load_dwordx4 v[172:175], v[200:201], off offset:896
	s_setprio 1
	s_waitcnt lgkmcnt(1)
	v_mfma_f32_32x32x16_bf16 v[112:127], v[234:237], v[160:163], v[112:127]
	v_mfma_f32_32x32x16_bf16 v[48:63], v[234:237], v[164:167], v[48:63]
	s_waitcnt lgkmcnt(0)
	v_mfma_f32_32x32x16_bf16 v[96:111], v[238:241], v[160:163], v[96:111]
	v_mfma_f32_32x32x16_bf16 v[32:47], v[238:241], v[164:167], v[32:47]
	ds_read_b128 v[234:237], v192 offset:9312
	ds_read_b128 v[238:241], v192 offset:13920
	s_waitcnt lgkmcnt(0)
	s_barrier
; template <bool trans>
; DI void gemm_core(const GTile& tl, const GTile& nx, bool has_next  , bool chain  , bool pre, u32x4 (&ra)[4], u32x4 (&rb)[4], char* smem, f32x16 (&acc)[2][4]) {
;     ...
;   const int nk = K / 64;
;   if (!pre) { G_LOAD(0); G_STORE(0); G_LOAD(1); }
;   for (int kt = 0; kt < nk; ++kt) {
;     __syncthreads();
;     G_COMPUTE(kt & 1, kt);
;   }
	s_waitcnt vmcnt(7)
	ds_write_b128 v209, v[218:221]
	s_waitcnt vmcnt(6)
	ds_write_b128 v210, v[222:225]
	ds_read_b128 v[218:221], v205 offset:36864
	ds_read_b128 v[222:225], v205 offset:41472
	v_mfma_f32_32x32x16_bf16 v[80:95], v[234:237], v[160:163], v[80:95]
	v_mfma_f32_32x32x16_bf16 v[16:31], v[234:237], v[164:167], v[16:31]
	ds_read_b128 v[234:237], v204
	v_mfma_f32_32x32x16_bf16 v[64:79], v[238:241], v[160:163], v[64:79]
	v_mfma_f32_32x32x16_bf16 v[0:15], v[238:241], v[164:167], v[0:15]
	ds_read_b128 v[238:241], v204 offset:4608
	s_setprio 0
	global_load_dwordx4 v[160:163], v[190:191], off offset:1024
	global_load_dwordx4 v[164:167], v[188:189], off offset:1024
	s_setprio 1
	s_waitcnt lgkmcnt(1)
	v_mfma_f32_32x32x16_bf16 v[112:127], v[234:237], v[218:221], v[112:127]
	v_mfma_f32_32x32x16_bf16 v[48:63], v[234:237], v[222:225], v[48:63]
	s_waitcnt lgkmcnt(0)
	v_mfma_f32_32x32x16_bf16 v[96:111], v[238:241], v[218:221], v[96:111]
	v_mfma_f32_32x32x16_bf16 v[32:47], v[238:241], v[222:225], v[32:47]
	ds_read_b128 v[234:237], v204 offset:9216
	ds_read_b128 v[238:241], v204 offset:13824
	s_waitcnt vmcnt(7)
	ds_write_b128 v212, v[226:229]
	s_waitcnt vmcnt(6)
	ds_write_b128 v211, v[230:233]
	ds_read_b128 v[226:229], v205 offset:36896
	ds_read_b128 v[230:233], v205 offset:41504
	s_waitcnt lgkmcnt(5)
	v_mfma_f32_32x32x16_bf16 v[80:95], v[234:237], v[218:221], v[80:95]
	v_mfma_f32_32x32x16_bf16 v[16:31], v[234:237], v[222:225], v[16:31]
	ds_read_b128 v[234:237], v204 offset:32
	s_waitcnt lgkmcnt(5)
	v_mfma_f32_32x32x16_bf16 v[64:79], v[238:241], v[218:221], v[64:79]
	v_mfma_f32_32x32x16_bf16 v[0:15], v[238:241], v[222:225], v[0:15]
	ds_read_b128 v[238:241], v204 offset:4640
	s_setprio 0
	global_load_dwordx4 v[218:221], v[194:195], off offset:1024
	global_load_dwordx4 v[222:225], v[196:197], off offset:1024
	s_setprio 1
	s_waitcnt lgkmcnt(1)
	v_mfma_f32_32x32x16_bf16 v[112:127], v[234:237], v[226:229], v[112:127]
	v_mfma_f32_32x32x16_bf16 v[48:63], v[234:237], v[230:233], v[48:63]
	s_waitcnt lgkmcnt(0)
	v_mfma_f32_32x32x16_bf16 v[96:111], v[238:241], v[226:229], v[96:111]
	v_mfma_f32_32x32x16_bf16 v[32:47], v[238:241], v[230:233], v[32:47]
	ds_read_b128 v[234:237], v204 offset:9248
	ds_read_b128 v[238:241], v204 offset:13856
	s_waitcnt vmcnt(7)
	ds_write_b128 v214, v[176:179]
	s_waitcnt vmcnt(6)
	ds_write_b128 v213, v[180:183]
	ds_read_b128 v[176:179], v205 offset:36928
	ds_read_b128 v[180:183], v205 offset:41536
	s_waitcnt lgkmcnt(5)
	v_mfma_f32_32x32x16_bf16 v[80:95], v[234:237], v[226:229], v[80:95]
	v_mfma_f32_32x32x16_bf16 v[16:31], v[234:237], v[230:233], v[16:31]
	ds_read_b128 v[234:237], v204 offset:64
	s_waitcnt lgkmcnt(5)
	v_mfma_f32_32x32x16_bf16 v[64:79], v[238:241], v[226:229], v[64:79]
	v_mfma_f32_32x32x16_bf16 v[0:15], v[238:241], v[230:233], v[0:15]
	ds_read_b128 v[238:241], v204 offset:4672
	s_setprio 0
	global_load_dwordx4 v[226:229], v[184:185], off offset:1024
	global_load_dwordx4 v[230:233], v[186:187], off offset:1024
	s_setprio 1
	s_waitcnt lgkmcnt(1)
	v_mfma_f32_32x32x16_bf16 v[112:127], v[234:237], v[176:179], v[112:127]
	v_mfma_f32_32x32x16_bf16 v[48:63], v[234:237], v[180:183], v[48:63]
	s_waitcnt lgkmcnt(0)
	v_mfma_f32_32x32x16_bf16 v[96:111], v[238:241], v[176:179], v[96:111]
	v_mfma_f32_32x32x16_bf16 v[32:47], v[238:241], v[180:183], v[32:47]
	ds_read_b128 v[234:237], v204 offset:9280
	ds_read_b128 v[238:241], v204 offset:13888
	s_waitcnt vmcnt(7)
	ds_write_b128 v217, v[168:171]
	s_waitcnt vmcnt(6)
	ds_write_b128 v216, v[172:175]
	ds_read_b128 v[168:171], v205 offset:36960
	ds_read_b128 v[172:175], v205 offset:41568
	s_waitcnt lgkmcnt(5)
	v_mfma_f32_32x32x16_bf16 v[80:95], v[234:237], v[176:179], v[80:95]
	v_mfma_f32_32x32x16_bf16 v[16:31], v[234:237], v[180:183], v[16:31]
	ds_read_b128 v[234:237], v204 offset:96
	s_waitcnt lgkmcnt(5)
	v_mfma_f32_32x32x16_bf16 v[64:79], v[238:241], v[176:179], v[64:79]
	v_mfma_f32_32x32x16_bf16 v[0:15], v[238:241], v[180:183], v[0:15]
	ds_read_b128 v[238:241], v204 offset:4704
	s_setprio 0
	global_load_dwordx4 v[176:179], v[198:199], off offset:1024
	global_load_dwordx4 v[180:183], v[200:201], off offset:1024
	s_setprio 1
	s_waitcnt lgkmcnt(1)
	v_mfma_f32_32x32x16_bf16 v[112:127], v[234:237], v[168:171], v[112:127]
	v_mfma_f32_32x32x16_bf16 v[48:63], v[234:237], v[172:175], v[48:63]
	s_waitcnt lgkmcnt(0)
	v_mfma_f32_32x32x16_bf16 v[96:111], v[238:241], v[168:171], v[96:111]
	v_mfma_f32_32x32x16_bf16 v[32:47], v[238:241], v[172:175], v[32:47]
	ds_read_b128 v[234:237], v204 offset:9312
	ds_read_b128 v[238:241], v204 offset:13920
	s_waitcnt lgkmcnt(0)
	s_barrier
; template <bool trans>
; DI void gemm_core(const GTile& tl, const GTile& nx, bool has_next  , bool chain  , bool pre, u32x4 (&ra)[4], u32x4 (&rb)[4], char* smem, f32x16 (&acc)[2][4]) {
;     ...
;   const int nk = K / 64;
;   if (!pre) { G_LOAD(0); G_STORE(0); G_LOAD(1); }
;   for (int kt = 0; kt < nk; ++kt) {
;     __syncthreads();
;     G_COMPUTE(kt & 1, kt);
;   }
	s_waitcnt vmcnt(7)
	ds_write_b128 v215, v[160:163]
	s_waitcnt vmcnt(6)
	ds_write_b128 v215, v[164:167] offset:36864
	ds_read_b128 v[160:163], v208
	ds_read_b128 v[164:167], v208 offset:4608
	v_mfma_f32_32x32x16_bf16 v[80:95], v[234:237], v[168:171], v[80:95]
	v_mfma_f32_32x32x16_bf16 v[16:31], v[234:237], v[172:175], v[16:31]
	ds_read_b128 v[234:237], v192
	v_mfma_f32_32x32x16_bf16 v[64:79], v[238:241], v[168:171], v[64:79]
	v_mfma_f32_32x32x16_bf16 v[0:15], v[238:241], v[172:175], v[0:15]
	ds_read_b128 v[238:241], v192 offset:4608
	s_setprio 0
	global_load_dwordx4 v[168:171], v[190:191], off offset:1152
	global_load_dwordx4 v[172:175], v[188:189], off offset:1152
	s_setprio 1
	s_waitcnt lgkmcnt(1)
	v_mfma_f32_32x32x16_bf16 v[112:127], v[234:237], v[160:163], v[112:127]
	v_mfma_f32_32x32x16_bf16 v[48:63], v[234:237], v[164:167], v[48:63]
	s_waitcnt lgkmcnt(0)
	v_mfma_f32_32x32x16_bf16 v[96:111], v[238:241], v[160:163], v[96:111]
	v_mfma_f32_32x32x16_bf16 v[32:47], v[238:241], v[164:167], v[32:47]
	ds_read_b128 v[234:237], v192 offset:9216
	ds_read_b128 v[238:241], v192 offset:13824
	s_waitcnt vmcnt(7)
	ds_write_b128 v215, v[218:221] offset:9216
	s_waitcnt vmcnt(6)
	ds_write_b128 v215, v[222:225] offset:46080
	ds_read_b128 v[218:221], v208 offset:32
	ds_read_b128 v[222:225], v208 offset:4640
	s_waitcnt lgkmcnt(5)
	v_mfma_f32_32x32x16_bf16 v[80:95], v[234:237], v[160:163], v[80:95]
	v_mfma_f32_32x32x16_bf16 v[16:31], v[234:237], v[164:167], v[16:31]
	ds_read_b128 v[234:237], v192 offset:32
	s_waitcnt lgkmcnt(5)
	v_mfma_f32_32x32x16_bf16 v[64:79], v[238:241], v[160:163], v[64:79]
	v_mfma_f32_32x32x16_bf16 v[0:15], v[238:241], v[164:167], v[0:15]
	ds_read_b128 v[238:241], v192 offset:4640
	s_setprio 0
	global_load_dwordx4 v[160:163], v[194:195], off offset:1152
	global_load_dwordx4 v[164:167], v[196:197], off offset:1152
	s_setprio 1
	s_waitcnt lgkmcnt(1)
	v_mfma_f32_32x32x16_bf16 v[112:127], v[234:237], v[218:221], v[112:127]
	v_mfma_f32_32x32x16_bf16 v[48:63], v[234:237], v[222:225], v[48:63]
	s_waitcnt lgkmcnt(0)
	v_mfma_f32_32x32x16_bf16 v[96:111], v[238:241], v[218:221], v[96:111]
	v_mfma_f32_32x32x16_bf16 v[32:47], v[238:241], v[222:225], v[32:47]
	ds_read_b128 v[234:237], v192 offset:9248
	ds_read_b128 v[238:241], v192 offset:13856
	s_waitcnt vmcnt(7)
	ds_write_b128 v215, v[226:229] offset:18432
	s_waitcnt vmcnt(6)
	ds_write_b128 v215, v[230:233] offset:55296
	ds_read_b128 v[226:229], v208 offset:64
	ds_read_b128 v[230:233], v208 offset:4672
	s_waitcnt lgkmcnt(5)
	v_mfma_f32_32x32x16_bf16 v[80:95], v[234:237], v[218:221], v[80:95]
	v_mfma_f32_32x32x16_bf16 v[16:31], v[234:237], v[222:225], v[16:31]
	ds_read_b128 v[234:237], v192 offset:64
	s_waitcnt lgkmcnt(5)
	v_mfma_f32_32x32x16_bf16 v[64:79], v[238:241], v[218:221], v[64:79]
	v_mfma_f32_32x32x16_bf16 v[0:15], v[238:241], v[222:225], v[0:15]
	ds_read_b128 v[238:241], v192 offset:4672
	s_setprio 0
	global_load_dwordx4 v[218:221], v[184:185], off offset:1152
	global_load_dwordx4 v[222:225], v[186:187], off offset:1152
	s_setprio 1
	s_waitcnt lgkmcnt(1)
	v_mfma_f32_32x32x16_bf16 v[112:127], v[234:237], v[226:229], v[112:127]
	v_mfma_f32_32x32x16_bf16 v[48:63], v[234:237], v[230:233], v[48:63]
	s_waitcnt lgkmcnt(0)
	v_mfma_f32_32x32x16_bf16 v[96:111], v[238:241], v[226:229], v[96:111]
	v_mfma_f32_32x32x16_bf16 v[32:47], v[238:241], v[230:233], v[32:47]
	ds_read_b128 v[234:237], v192 offset:9280
	ds_read_b128 v[238:241], v192 offset:13888
	s_waitcnt vmcnt(7)
	ds_write_b128 v215, v[176:179] offset:27648
	s_waitcnt vmcnt(6)
	ds_write_b128 v215, v[180:183] offset:64512
	ds_read_b128 v[176:179], v208 offset:96
	ds_read_b128 v[180:183], v208 offset:4704
	s_waitcnt lgkmcnt(5)
	v_mfma_f32_32x32x16_bf16 v[80:95], v[234:237], v[226:229], v[80:95]
	v_mfma_f32_32x32x16_bf16 v[16:31], v[234:237], v[230:233], v[16:31]
	ds_read_b128 v[234:237], v192 offset:96
	s_waitcnt lgkmcnt(5)
	v_mfma_f32_32x32x16_bf16 v[64:79], v[238:241], v[226:229], v[64:79]
	v_mfma_f32_32x32x16_bf16 v[0:15], v[238:241], v[230:233], v[0:15]
	ds_read_b128 v[238:241], v192 offset:4704
	s_setprio 0
	global_load_dwordx4 v[226:229], v[198:199], off offset:1152
	global_load_dwordx4 v[230:233], v[200:201], off offset:1152
	s_setprio 1
	s_waitcnt lgkmcnt(1)
	v_mfma_f32_32x32x16_bf16 v[112:127], v[234:237], v[176:179], v[112:127]
	v_mfma_f32_32x32x16_bf16 v[48:63], v[234:237], v[180:183], v[48:63]
	s_waitcnt lgkmcnt(0)
	v_mfma_f32_32x32x16_bf16 v[96:111], v[238:241], v[176:179], v[96:111]
	v_mfma_f32_32x32x16_bf16 v[32:47], v[238:241], v[180:183], v[32:47]
	ds_read_b128 v[234:237], v192 offset:9312
	ds_read_b128 v[238:241], v192 offset:13920
	s_waitcnt lgkmcnt(0)
	s_barrier
; template <bool trans>
; DI void gemm_core(const GTile& tl, const GTile& nx, bool has_next  , bool chain  , bool pre, u32x4 (&ra)[4], u32x4 (&rb)[4], char* smem, f32x16 (&acc)[2][4]) {
;     ...
;   const int nk = K / 64;
;   if (!pre) { G_LOAD(0); G_STORE(0); G_LOAD(1); }
;   for (int kt = 0; kt < nk; ++kt) {
;     __syncthreads();
;     G_COMPUTE(kt & 1, kt);
;   }
	s_waitcnt vmcnt(7)
	ds_write_b128 v209, v[168:171]
	s_waitcnt vmcnt(6)
	ds_write_b128 v210, v[172:175]
	ds_read_b128 v[168:171], v205 offset:36864
	ds_read_b128 v[172:175], v205 offset:41472
	v_mfma_f32_32x32x16_bf16 v[80:95], v[234:237], v[176:179], v[80:95]
	v_mfma_f32_32x32x16_bf16 v[16:31], v[234:237], v[180:183], v[16:31]
	ds_read_b128 v[234:237], v204
	v_mfma_f32_32x32x16_bf16 v[64:79], v[238:241], v[176:179], v[64:79]
	v_mfma_f32_32x32x16_bf16 v[0:15], v[238:241], v[180:183], v[0:15]
	ds_read_b128 v[238:241], v204 offset:4608
	s_setprio 0
	global_load_dwordx4 v[176:179], v[190:191], off offset:1280
	global_load_dwordx4 v[180:183], v[188:189], off offset:1280
	s_setprio 1
	s_waitcnt lgkmcnt(1)
	v_mfma_f32_32x32x16_bf16 v[112:127], v[234:237], v[168:171], v[112:127]
	v_mfma_f32_32x32x16_bf16 v[48:63], v[234:237], v[172:175], v[48:63]
	s_waitcnt lgkmcnt(0)
	v_mfma_f32_32x32x16_bf16 v[96:111], v[238:241], v[168:171], v[96:111]
	v_mfma_f32_32x32x16_bf16 v[32:47], v[238:241], v[172:175], v[32:47]
	ds_read_b128 v[234:237], v204 offset:9216
	ds_read_b128 v[238:241], v204 offset:13824
	s_waitcnt vmcnt(7)
	ds_write_b128 v212, v[160:163]
	s_waitcnt vmcnt(6)
	ds_write_b128 v211, v[164:167]
	ds_read_b128 v[160:163], v205 offset:36896
	ds_read_b128 v[164:167], v205 offset:41504
	s_waitcnt lgkmcnt(5)
	v_mfma_f32_32x32x16_bf16 v[80:95], v[234:237], v[168:171], v[80:95]
	v_mfma_f32_32x32x16_bf16 v[16:31], v[234:237], v[172:175], v[16:31]
	ds_read_b128 v[234:237], v204 offset:32
	s_waitcnt lgkmcnt(5)
	v_mfma_f32_32x32x16_bf16 v[64:79], v[238:241], v[168:171], v[64:79]
	v_mfma_f32_32x32x16_bf16 v[0:15], v[238:241], v[172:175], v[0:15]
	ds_read_b128 v[238:241], v204 offset:4640
	s_setprio 0
	global_load_dwordx4 v[168:171], v[194:195], off offset:1280
	global_load_dwordx4 v[172:175], v[196:197], off offset:1280
	s_setprio 1
	s_waitcnt lgkmcnt(1)
	v_mfma_f32_32x32x16_bf16 v[112:127], v[234:237], v[160:163], v[112:127]
	v_mfma_f32_32x32x16_bf16 v[48:63], v[234:237], v[164:167], v[48:63]
	s_waitcnt lgkmcnt(0)
	v_mfma_f32_32x32x16_bf16 v[96:111], v[238:241], v[160:163], v[96:111]
	v_mfma_f32_32x32x16_bf16 v[32:47], v[238:241], v[164:167], v[32:47]
	ds_read_b128 v[234:237], v204 offset:9248
	ds_read_b128 v[238:241], v204 offset:13856
	s_waitcnt vmcnt(7)
	ds_write_b128 v214, v[218:221]
	s_waitcnt vmcnt(6)
	ds_write_b128 v213, v[222:225]
	ds_read_b128 v[218:221], v205 offset:36928
	ds_read_b128 v[222:225], v205 offset:41536
	s_waitcnt lgkmcnt(5)
	v_mfma_f32_32x32x16_bf16 v[80:95], v[234:237], v[160:163], v[80:95]
	v_mfma_f32_32x32x16_bf16 v[16:31], v[234:237], v[164:167], v[16:31]
	ds_read_b128 v[234:237], v204 offset:64
	s_waitcnt lgkmcnt(5)
	v_mfma_f32_32x32x16_bf16 v[64:79], v[238:241], v[160:163], v[64:79]
	v_mfma_f32_32x32x16_bf16 v[0:15], v[238:241], v[164:167], v[0:15]
	ds_read_b128 v[238:241], v204 offset:4672
	s_setprio 0
	global_load_dwordx4 v[160:163], v[184:185], off offset:1280
	global_load_dwordx4 v[164:167], v[186:187], off offset:1280
	s_setprio 1
	s_waitcnt lgkmcnt(1)
	v_mfma_f32_32x32x16_bf16 v[112:127], v[234:237], v[218:221], v[112:127]
	v_mfma_f32_32x32x16_bf16 v[48:63], v[234:237], v[222:225], v[48:63]
	s_waitcnt lgkmcnt(0)
	v_mfma_f32_32x32x16_bf16 v[96:111], v[238:241], v[218:221], v[96:111]
	v_mfma_f32_32x32x16_bf16 v[32:47], v[238:241], v[222:225], v[32:47]
	ds_read_b128 v[234:237], v204 offset:9280
	ds_read_b128 v[238:241], v204 offset:13888
	s_waitcnt vmcnt(7)
	ds_write_b128 v217, v[226:229]
	s_waitcnt vmcnt(6)
	ds_write_b128 v216, v[230:233]
	ds_read_b128 v[226:229], v205 offset:36960
	ds_read_b128 v[230:233], v205 offset:41568
	s_waitcnt lgkmcnt(5)
	v_mfma_f32_32x32x16_bf16 v[80:95], v[234:237], v[218:221], v[80:95]
	v_mfma_f32_32x32x16_bf16 v[16:31], v[234:237], v[222:225], v[16:31]
	ds_read_b128 v[234:237], v204 offset:96
	s_waitcnt lgkmcnt(5)
	v_mfma_f32_32x32x16_bf16 v[64:79], v[238:241], v[218:221], v[64:79]
	v_mfma_f32_32x32x16_bf16 v[0:15], v[238:241], v[222:225], v[0:15]
	ds_read_b128 v[238:241], v204 offset:4704
	s_setprio 0
	global_load_dwordx4 v[218:221], v[198:199], off offset:1280
	global_load_dwordx4 v[222:225], v[200:201], off offset:1280
	s_setprio 1
	s_waitcnt lgkmcnt(1)
	v_mfma_f32_32x32x16_bf16 v[112:127], v[234:237], v[226:229], v[112:127]
	v_mfma_f32_32x32x16_bf16 v[48:63], v[234:237], v[230:233], v[48:63]
	s_waitcnt lgkmcnt(0)
	v_mfma_f32_32x32x16_bf16 v[96:111], v[238:241], v[226:229], v[96:111]
	v_mfma_f32_32x32x16_bf16 v[32:47], v[238:241], v[230:233], v[32:47]
	ds_read_b128 v[234:237], v204 offset:9312
	ds_read_b128 v[238:241], v204 offset:13920
	s_waitcnt lgkmcnt(0)
	s_barrier
; template <bool trans>
; DI void gemm_core(const GTile& tl, const GTile& nx, bool has_next  , bool chain  , bool pre, u32x4 (&ra)[4], u32x4 (&rb)[4], char* smem, f32x16 (&acc)[2][4]) {
;     ...
;   const int nk = K / 64;
;   if (!pre) { G_LOAD(0); G_STORE(0); G_LOAD(1); }
;   for (int kt = 0; kt < nk; ++kt) {
;     __syncthreads();
;     G_COMPUTE(kt & 1, kt);
;   }
	s_waitcnt vmcnt(7)
	ds_write_b128 v215, v[176:179]
	s_waitcnt vmcnt(6)
	ds_write_b128 v215, v[180:183] offset:36864
	ds_read_b128 v[176:179], v208
	ds_read_b128 v[180:183], v208 offset:4608
	v_mfma_f32_32x32x16_bf16 v[80:95], v[234:237], v[226:229], v[80:95]
	v_mfma_f32_32x32x16_bf16 v[16:31], v[234:237], v[230:233], v[16:31]
	ds_read_b128 v[234:237], v192
	v_mfma_f32_32x32x16_bf16 v[64:79], v[238:241], v[226:229], v[64:79]
	v_mfma_f32_32x32x16_bf16 v[0:15], v[238:241], v[230:233], v[0:15]
	ds_read_b128 v[238:241], v192 offset:4608
	s_setprio 0
	global_load_dwordx4 v[226:229], v[190:191], off offset:1408
	global_load_dwordx4 v[230:233], v[188:189], off offset:1408
	s_setprio 1
	s_waitcnt lgkmcnt(1)
	v_mfma_f32_32x32x16_bf16 v[112:127], v[234:237], v[176:179], v[112:127]
	v_mfma_f32_32x32x16_bf16 v[48:63], v[234:237], v[180:183], v[48:63]
	s_waitcnt lgkmcnt(0)
	v_mfma_f32_32x32x16_bf16 v[96:111], v[238:241], v[176:179], v[96:111]
	v_mfma_f32_32x32x16_bf16 v[32:47], v[238:241], v[180:183], v[32:47]
	ds_read_b128 v[234:237], v192 offset:9216
	ds_read_b128 v[238:241], v192 offset:13824
	s_waitcnt vmcnt(7)
	ds_write_b128 v215, v[168:171] offset:9216
	s_waitcnt vmcnt(6)
	ds_write_b128 v215, v[172:175] offset:46080
	ds_read_b128 v[168:171], v208 offset:32
	ds_read_b128 v[172:175], v208 offset:4640
	s_waitcnt lgkmcnt(5)
	v_mfma_f32_32x32x16_bf16 v[80:95], v[234:237], v[176:179], v[80:95]
	v_mfma_f32_32x32x16_bf16 v[16:31], v[234:237], v[180:183], v[16:31]
	ds_read_b128 v[234:237], v192 offset:32
	s_waitcnt lgkmcnt(5)
	v_mfma_f32_32x32x16_bf16 v[64:79], v[238:241], v[176:179], v[64:79]
	v_mfma_f32_32x32x16_bf16 v[0:15], v[238:241], v[180:183], v[0:15]
	ds_read_b128 v[238:241], v192 offset:4640
	s_setprio 0
	global_load_dwordx4 v[176:179], v[194:195], off offset:1408
	global_load_dwordx4 v[180:183], v[196:197], off offset:1408
	s_setprio 1
	s_waitcnt lgkmcnt(1)
	v_mfma_f32_32x32x16_bf16 v[112:127], v[234:237], v[168:171], v[112:127]
	v_mfma_f32_32x32x16_bf16 v[48:63], v[234:237], v[172:175], v[48:63]
	s_waitcnt lgkmcnt(0)
	v_mfma_f32_32x32x16_bf16 v[96:111], v[238:241], v[168:171], v[96:111]
	v_mfma_f32_32x32x16_bf16 v[32:47], v[238:241], v[172:175], v[32:47]
	ds_read_b128 v[234:237], v192 offset:9248
	ds_read_b128 v[238:241], v192 offset:13856
	s_waitcnt vmcnt(7)
	ds_write_b128 v215, v[160:163] offset:18432
	s_waitcnt vmcnt(6)
	ds_write_b128 v215, v[164:167] offset:55296
	ds_read_b128 v[160:163], v208 offset:64
	ds_read_b128 v[164:167], v208 offset:4672
	s_waitcnt lgkmcnt(5)
	v_mfma_f32_32x32x16_bf16 v[80:95], v[234:237], v[168:171], v[80:95]
	v_mfma_f32_32x32x16_bf16 v[16:31], v[234:237], v[172:175], v[16:31]
	ds_read_b128 v[234:237], v192 offset:64
	s_waitcnt lgkmcnt(5)
	v_mfma_f32_32x32x16_bf16 v[64:79], v[238:241], v[168:171], v[64:79]
	v_mfma_f32_32x32x16_bf16 v[0:15], v[238:241], v[172:175], v[0:15]
	ds_read_b128 v[238:241], v192 offset:4672
	s_setprio 0
	global_load_dwordx4 v[168:171], v[184:185], off offset:1408
	global_load_dwordx4 v[172:175], v[186:187], off offset:1408
	s_setprio 1
	s_waitcnt lgkmcnt(1)
	v_mfma_f32_32x32x16_bf16 v[112:127], v[234:237], v[160:163], v[112:127]
	v_mfma_f32_32x32x16_bf16 v[48:63], v[234:237], v[164:167], v[48:63]
	s_waitcnt lgkmcnt(0)
	v_mfma_f32_32x32x16_bf16 v[96:111], v[238:241], v[160:163], v[96:111]
	v_mfma_f32_32x32x16_bf16 v[32:47], v[238:241], v[164:167], v[32:47]
	ds_read_b128 v[234:237], v192 offset:9280
	ds_read_b128 v[238:241], v192 offset:13888
	s_waitcnt vmcnt(7)
	ds_write_b128 v215, v[218:221] offset:27648
	s_waitcnt vmcnt(6)
	ds_write_b128 v215, v[222:225] offset:64512
	ds_read_b128 v[218:221], v208 offset:96
	ds_read_b128 v[222:225], v208 offset:4704
	s_waitcnt lgkmcnt(5)
	v_mfma_f32_32x32x16_bf16 v[80:95], v[234:237], v[160:163], v[80:95]
	v_mfma_f32_32x32x16_bf16 v[16:31], v[234:237], v[164:167], v[16:31]
	ds_read_b128 v[234:237], v192 offset:96
	s_waitcnt lgkmcnt(5)
	v_mfma_f32_32x32x16_bf16 v[64:79], v[238:241], v[160:163], v[64:79]
	v_mfma_f32_32x32x16_bf16 v[0:15], v[238:241], v[164:167], v[0:15]
	ds_read_b128 v[238:241], v192 offset:4704
	s_setprio 0
	global_load_dwordx4 v[160:163], v[198:199], off offset:1408
	global_load_dwordx4 v[164:167], v[200:201], off offset:1408
	s_setprio 1
	s_waitcnt lgkmcnt(1)
	v_mfma_f32_32x32x16_bf16 v[112:127], v[234:237], v[218:221], v[112:127]
	v_mfma_f32_32x32x16_bf16 v[48:63], v[234:237], v[222:225], v[48:63]
	s_waitcnt lgkmcnt(0)
	v_mfma_f32_32x32x16_bf16 v[96:111], v[238:241], v[218:221], v[96:111]
	v_mfma_f32_32x32x16_bf16 v[32:47], v[238:241], v[222:225], v[32:47]
	ds_read_b128 v[234:237], v192 offset:9312
	ds_read_b128 v[238:241], v192 offset:13920
	s_waitcnt lgkmcnt(0)
	s_barrier
; template <bool trans>
; DI void gemm_core(const GTile& tl, const GTile& nx, bool has_next  , bool chain  , bool pre, u32x4 (&ra)[4], u32x4 (&rb)[4], char* smem, f32x16 (&acc)[2][4]) {
;     ...
;   const int nk = K / 64;
;   if (!pre) { G_LOAD(0); G_STORE(0); G_LOAD(1); }
;   for (int kt = 0; kt < nk; ++kt) {
;     __syncthreads();
;     G_COMPUTE(kt & 1, kt);
;   }
	s_waitcnt vmcnt(7)
	ds_write_b128 v209, v[226:229]
	s_waitcnt vmcnt(6)
	ds_write_b128 v210, v[230:233]
	ds_read_b128 v[226:229], v205 offset:36864
	ds_read_b128 v[230:233], v205 offset:41472
	v_mfma_f32_32x32x16_bf16 v[80:95], v[234:237], v[218:221], v[80:95]
	v_mfma_f32_32x32x16_bf16 v[16:31], v[234:237], v[222:225], v[16:31]
	ds_read_b128 v[234:237], v204
	v_mfma_f32_32x32x16_bf16 v[64:79], v[238:241], v[218:221], v[64:79]
	v_mfma_f32_32x32x16_bf16 v[0:15], v[238:241], v[222:225], v[0:15]
	ds_read_b128 v[238:241], v204 offset:4608
	s_setprio 0
	global_load_dwordx4 v[218:221], v[190:191], off offset:1536
	global_load_dwordx4 v[222:225], v[188:189], off offset:1536
	s_setprio 1
	s_waitcnt lgkmcnt(1)
	v_mfma_f32_32x32x16_bf16 v[112:127], v[234:237], v[226:229], v[112:127]
	v_mfma_f32_32x32x16_bf16 v[48:63], v[234:237], v[230:233], v[48:63]
	s_waitcnt lgkmcnt(0)
	v_mfma_f32_32x32x16_bf16 v[96:111], v[238:241], v[226:229], v[96:111]
	v_mfma_f32_32x32x16_bf16 v[32:47], v[238:241], v[230:233], v[32:47]
	ds_read_b128 v[234:237], v204 offset:9216
	ds_read_b128 v[238:241], v204 offset:13824
	s_waitcnt vmcnt(7)
	ds_write_b128 v212, v[176:179]
	s_waitcnt vmcnt(6)
	ds_write_b128 v211, v[180:183]
	ds_read_b128 v[176:179], v205 offset:36896
	ds_read_b128 v[180:183], v205 offset:41504
	s_waitcnt lgkmcnt(5)
	v_mfma_f32_32x32x16_bf16 v[80:95], v[234:237], v[226:229], v[80:95]
	v_mfma_f32_32x32x16_bf16 v[16:31], v[234:237], v[230:233], v[16:31]
	ds_read_b128 v[234:237], v204 offset:32
	s_waitcnt lgkmcnt(5)
	v_mfma_f32_32x32x16_bf16 v[64:79], v[238:241], v[226:229], v[64:79]
	v_mfma_f32_32x32x16_bf16 v[0:15], v[238:241], v[230:233], v[0:15]
	ds_read_b128 v[238:241], v204 offset:4640
	s_setprio 0
	global_load_dwordx4 v[226:229], v[194:195], off offset:1536
	global_load_dwordx4 v[230:233], v[196:197], off offset:1536
	s_setprio 1
	s_waitcnt lgkmcnt(1)
	v_mfma_f32_32x32x16_bf16 v[112:127], v[234:237], v[176:179], v[112:127]
	v_mfma_f32_32x32x16_bf16 v[48:63], v[234:237], v[180:183], v[48:63]
	s_waitcnt lgkmcnt(0)
	v_mfma_f32_32x32x16_bf16 v[96:111], v[238:241], v[176:179], v[96:111]
	v_mfma_f32_32x32x16_bf16 v[32:47], v[238:241], v[180:183], v[32:47]
	ds_read_b128 v[234:237], v204 offset:9248
	ds_read_b128 v[238:241], v204 offset:13856
	s_waitcnt vmcnt(7)
	ds_write_b128 v214, v[168:171]
	s_waitcnt vmcnt(6)
	ds_write_b128 v213, v[172:175]
	ds_read_b128 v[168:171], v205 offset:36928
	ds_read_b128 v[172:175], v205 offset:41536
	s_waitcnt lgkmcnt(5)
	v_mfma_f32_32x32x16_bf16 v[80:95], v[234:237], v[176:179], v[80:95]
	v_mfma_f32_32x32x16_bf16 v[16:31], v[234:237], v[180:183], v[16:31]
	ds_read_b128 v[234:237], v204 offset:64
	s_waitcnt lgkmcnt(5)
	v_mfma_f32_32x32x16_bf16 v[64:79], v[238:241], v[176:179], v[64:79]
	v_mfma_f32_32x32x16_bf16 v[0:15], v[238:241], v[180:183], v[0:15]
	ds_read_b128 v[238:241], v204 offset:4672
	s_setprio 0
	global_load_dwordx4 v[176:179], v[184:185], off offset:1536
	global_load_dwordx4 v[180:183], v[186:187], off offset:1536
	s_setprio 1
	s_waitcnt lgkmcnt(1)
	v_mfma_f32_32x32x16_bf16 v[112:127], v[234:237], v[168:171], v[112:127]
	v_mfma_f32_32x32x16_bf16 v[48:63], v[234:237], v[172:175], v[48:63]
	s_waitcnt lgkmcnt(0)
	v_mfma_f32_32x32x16_bf16 v[96:111], v[238:241], v[168:171], v[96:111]
	v_mfma_f32_32x32x16_bf16 v[32:47], v[238:241], v[172:175], v[32:47]
	ds_read_b128 v[234:237], v204 offset:9280
	ds_read_b128 v[238:241], v204 offset:13888
	s_waitcnt vmcnt(7)
	ds_write_b128 v217, v[160:163]
	s_waitcnt vmcnt(6)
	ds_write_b128 v216, v[164:167]
	ds_read_b128 v[160:163], v205 offset:36960
	ds_read_b128 v[164:167], v205 offset:41568
	s_waitcnt lgkmcnt(5)
	v_mfma_f32_32x32x16_bf16 v[80:95], v[234:237], v[168:171], v[80:95]
	v_mfma_f32_32x32x16_bf16 v[16:31], v[234:237], v[172:175], v[16:31]
	ds_read_b128 v[234:237], v204 offset:96
	s_waitcnt lgkmcnt(5)
	v_mfma_f32_32x32x16_bf16 v[64:79], v[238:241], v[168:171], v[64:79]
	v_mfma_f32_32x32x16_bf16 v[0:15], v[238:241], v[172:175], v[0:15]
	ds_read_b128 v[238:241], v204 offset:4704
	s_setprio 0
	global_load_dwordx4 v[168:171], v[198:199], off offset:1536
	global_load_dwordx4 v[172:175], v[200:201], off offset:1536
	s_setprio 1
	s_waitcnt lgkmcnt(1)
	v_mfma_f32_32x32x16_bf16 v[112:127], v[234:237], v[160:163], v[112:127]
	v_mfma_f32_32x32x16_bf16 v[48:63], v[234:237], v[164:167], v[48:63]
	s_waitcnt lgkmcnt(0)
	v_mfma_f32_32x32x16_bf16 v[96:111], v[238:241], v[160:163], v[96:111]
	v_mfma_f32_32x32x16_bf16 v[32:47], v[238:241], v[164:167], v[32:47]
	ds_read_b128 v[234:237], v204 offset:9312
	ds_read_b128 v[238:241], v204 offset:13920
	s_waitcnt lgkmcnt(0)
	s_barrier
; template <bool trans>
; DI void gemm_core(const GTile& tl, const GTile& nx, bool has_next  , bool chain  , bool pre, u32x4 (&ra)[4], u32x4 (&rb)[4], char* smem, f32x16 (&acc)[2][4]) {
;     ...
;   const int nk = K / 64;
;   if (!pre) { G_LOAD(0); G_STORE(0); G_LOAD(1); }
;   for (int kt = 0; kt < nk; ++kt) {
;     __syncthreads();
;     G_COMPUTE(kt & 1, kt);
;   }
	s_waitcnt vmcnt(7)
	ds_write_b128 v215, v[218:221]
	s_waitcnt vmcnt(6)
	ds_write_b128 v215, v[222:225] offset:36864
	ds_read_b128 v[218:221], v208
	ds_read_b128 v[222:225], v208 offset:4608
	v_mfma_f32_32x32x16_bf16 v[80:95], v[234:237], v[160:163], v[80:95]
	v_mfma_f32_32x32x16_bf16 v[16:31], v[234:237], v[164:167], v[16:31]
	ds_read_b128 v[234:237], v192
	v_mfma_f32_32x32x16_bf16 v[64:79], v[238:241], v[160:163], v[64:79]
	v_mfma_f32_32x32x16_bf16 v[0:15], v[238:241], v[164:167], v[0:15]
	ds_read_b128 v[238:241], v192 offset:4608
	s_setprio 0
	global_load_dwordx4 v[160:163], v[190:191], off offset:1664
	global_load_dwordx4 v[164:167], v[188:189], off offset:1664
	s_setprio 1
	s_waitcnt lgkmcnt(1)
	v_mfma_f32_32x32x16_bf16 v[112:127], v[234:237], v[218:221], v[112:127]
	v_mfma_f32_32x32x16_bf16 v[48:63], v[234:237], v[222:225], v[48:63]
	s_waitcnt lgkmcnt(0)
	v_mfma_f32_32x32x16_bf16 v[96:111], v[238:241], v[218:221], v[96:111]
	v_mfma_f32_32x32x16_bf16 v[32:47], v[238:241], v[222:225], v[32:47]
	ds_read_b128 v[234:237], v192 offset:9216
	ds_read_b128 v[238:241], v192 offset:13824
	s_waitcnt vmcnt(7)
	ds_write_b128 v215, v[226:229] offset:9216
	s_waitcnt vmcnt(6)
	ds_write_b128 v215, v[230:233] offset:46080
	ds_read_b128 v[226:229], v208 offset:32
	ds_read_b128 v[230:233], v208 offset:4640
	s_waitcnt lgkmcnt(5)
	v_mfma_f32_32x32x16_bf16 v[80:95], v[234:237], v[218:221], v[80:95]
	v_mfma_f32_32x32x16_bf16 v[16:31], v[234:237], v[222:225], v[16:31]
	ds_read_b128 v[234:237], v192 offset:32
	s_waitcnt lgkmcnt(5)
	v_mfma_f32_32x32x16_bf16 v[64:79], v[238:241], v[218:221], v[64:79]
	v_mfma_f32_32x32x16_bf16 v[0:15], v[238:241], v[222:225], v[0:15]
	ds_read_b128 v[238:241], v192 offset:4640
	s_setprio 0
	global_load_dwordx4 v[218:221], v[194:195], off offset:1664
	global_load_dwordx4 v[222:225], v[196:197], off offset:1664
	s_setprio 1
	s_waitcnt lgkmcnt(1)
	v_mfma_f32_32x32x16_bf16 v[112:127], v[234:237], v[226:229], v[112:127]
	v_mfma_f32_32x32x16_bf16 v[48:63], v[234:237], v[230:233], v[48:63]
	s_waitcnt lgkmcnt(0)
	v_mfma_f32_32x32x16_bf16 v[96:111], v[238:241], v[226:229], v[96:111]
	v_mfma_f32_32x32x16_bf16 v[32:47], v[238:241], v[230:233], v[32:47]
	ds_read_b128 v[234:237], v192 offset:9248
	ds_read_b128 v[238:241], v192 offset:13856
	s_waitcnt vmcnt(7)
	ds_write_b128 v215, v[176:179] offset:18432
	s_waitcnt vmcnt(6)
	ds_write_b128 v215, v[180:183] offset:55296
	ds_read_b128 v[176:179], v208 offset:64
	ds_read_b128 v[180:183], v208 offset:4672
	s_waitcnt lgkmcnt(5)
	v_mfma_f32_32x32x16_bf16 v[80:95], v[234:237], v[226:229], v[80:95]
	v_mfma_f32_32x32x16_bf16 v[16:31], v[234:237], v[230:233], v[16:31]
	ds_read_b128 v[234:237], v192 offset:64
	s_waitcnt lgkmcnt(5)
	v_mfma_f32_32x32x16_bf16 v[64:79], v[238:241], v[226:229], v[64:79]
	v_mfma_f32_32x32x16_bf16 v[0:15], v[238:241], v[230:233], v[0:15]
	ds_read_b128 v[238:241], v192 offset:4672
	s_setprio 0
	global_load_dwordx4 v[226:229], v[184:185], off offset:1664
	global_load_dwordx4 v[230:233], v[186:187], off offset:1664
	s_setprio 1
	s_waitcnt lgkmcnt(1)
	v_mfma_f32_32x32x16_bf16 v[112:127], v[234:237], v[176:179], v[112:127]
	v_mfma_f32_32x32x16_bf16 v[48:63], v[234:237], v[180:183], v[48:63]
	s_waitcnt lgkmcnt(0)
	v_mfma_f32_32x32x16_bf16 v[96:111], v[238:241], v[176:179], v[96:111]
	v_mfma_f32_32x32x16_bf16 v[32:47], v[238:241], v[180:183], v[32:47]
	ds_read_b128 v[234:237], v192 offset:9280
	ds_read_b128 v[238:241], v192 offset:13888
	s_waitcnt vmcnt(7)
	ds_write_b128 v215, v[168:171] offset:27648
	s_waitcnt vmcnt(6)
	ds_write_b128 v215, v[172:175] offset:64512
	ds_read_b128 v[168:171], v208 offset:96
	ds_read_b128 v[172:175], v208 offset:4704
	s_waitcnt lgkmcnt(5)
	v_mfma_f32_32x32x16_bf16 v[80:95], v[234:237], v[176:179], v[80:95]
	v_mfma_f32_32x32x16_bf16 v[16:31], v[234:237], v[180:183], v[16:31]
	ds_read_b128 v[234:237], v192 offset:96
	s_waitcnt lgkmcnt(5)
	v_mfma_f32_32x32x16_bf16 v[64:79], v[238:241], v[176:179], v[64:79]
	v_mfma_f32_32x32x16_bf16 v[0:15], v[238:241], v[180:183], v[0:15]
	ds_read_b128 v[238:241], v192 offset:4704
	s_setprio 0
	global_load_dwordx4 v[176:179], v[198:199], off offset:1664
	global_load_dwordx4 v[180:183], v[200:201], off offset:1664
	s_setprio 1
	s_waitcnt lgkmcnt(1)
	v_mfma_f32_32x32x16_bf16 v[112:127], v[234:237], v[168:171], v[112:127]
	v_mfma_f32_32x32x16_bf16 v[48:63], v[234:237], v[172:175], v[48:63]
	s_waitcnt lgkmcnt(0)
	v_mfma_f32_32x32x16_bf16 v[96:111], v[238:241], v[168:171], v[96:111]
	v_mfma_f32_32x32x16_bf16 v[32:47], v[238:241], v[172:175], v[32:47]
	ds_read_b128 v[234:237], v192 offset:9312
	ds_read_b128 v[238:241], v192 offset:13920
	s_waitcnt lgkmcnt(0)
	s_barrier
; template <bool trans>
; DI void gemm_core(const GTile& tl, const GTile& nx, bool has_next  , bool chain  , bool pre, u32x4 (&ra)[4], u32x4 (&rb)[4], char* smem, f32x16 (&acc)[2][4]) {
;     ...
;   const int nk = K / 64;
;   if (!pre) { G_LOAD(0); G_STORE(0); G_LOAD(1); }
;   for (int kt = 0; kt < nk; ++kt) {
;     __syncthreads();
;     G_COMPUTE(kt & 1, kt);
;   }
	s_waitcnt vmcnt(7)
	ds_write_b128 v209, v[160:163]
	s_waitcnt vmcnt(6)
	ds_write_b128 v210, v[164:167]
	ds_read_b128 v[160:163], v205 offset:36864
	ds_read_b128 v[164:167], v205 offset:41472
	v_mfma_f32_32x32x16_bf16 v[80:95], v[234:237], v[168:171], v[80:95]
	v_mfma_f32_32x32x16_bf16 v[16:31], v[234:237], v[172:175], v[16:31]
	ds_read_b128 v[234:237], v204
	v_mfma_f32_32x32x16_bf16 v[64:79], v[238:241], v[168:171], v[64:79]
	v_mfma_f32_32x32x16_bf16 v[0:15], v[238:241], v[172:175], v[0:15]
	ds_read_b128 v[238:241], v204 offset:4608
	s_setprio 0
	global_load_dwordx4 v[168:171], v[190:191], off offset:1792
	global_load_dwordx4 v[172:175], v[188:189], off offset:1792
	s_setprio 1
	s_waitcnt lgkmcnt(1)
	v_mfma_f32_32x32x16_bf16 v[112:127], v[234:237], v[160:163], v[112:127]
	v_mfma_f32_32x32x16_bf16 v[48:63], v[234:237], v[164:167], v[48:63]
	s_waitcnt lgkmcnt(0)
	v_mfma_f32_32x32x16_bf16 v[96:111], v[238:241], v[160:163], v[96:111]
	v_mfma_f32_32x32x16_bf16 v[32:47], v[238:241], v[164:167], v[32:47]
	ds_read_b128 v[234:237], v204 offset:9216
	ds_read_b128 v[238:241], v204 offset:13824
	s_waitcnt vmcnt(7)
	ds_write_b128 v212, v[218:221]
	s_waitcnt vmcnt(6)
	ds_write_b128 v211, v[222:225]
	ds_read_b128 v[218:221], v205 offset:36896
	ds_read_b128 v[222:225], v205 offset:41504
	s_waitcnt lgkmcnt(5)
	v_mfma_f32_32x32x16_bf16 v[80:95], v[234:237], v[160:163], v[80:95]
	v_mfma_f32_32x32x16_bf16 v[16:31], v[234:237], v[164:167], v[16:31]
	ds_read_b128 v[234:237], v204 offset:32
	s_waitcnt lgkmcnt(5)
	v_mfma_f32_32x32x16_bf16 v[64:79], v[238:241], v[160:163], v[64:79]
	v_mfma_f32_32x32x16_bf16 v[0:15], v[238:241], v[164:167], v[0:15]
	ds_read_b128 v[238:241], v204 offset:4640
	s_setprio 0
	global_load_dwordx4 v[160:163], v[194:195], off offset:1792
	global_load_dwordx4 v[164:167], v[196:197], off offset:1792
	s_setprio 1
	s_waitcnt lgkmcnt(1)
	v_mfma_f32_32x32x16_bf16 v[112:127], v[234:237], v[218:221], v[112:127]
	v_mfma_f32_32x32x16_bf16 v[48:63], v[234:237], v[222:225], v[48:63]
	s_waitcnt lgkmcnt(0)
	v_mfma_f32_32x32x16_bf16 v[96:111], v[238:241], v[218:221], v[96:111]
	v_mfma_f32_32x32x16_bf16 v[32:47], v[238:241], v[222:225], v[32:47]
	ds_read_b128 v[234:237], v204 offset:9248
	ds_read_b128 v[238:241], v204 offset:13856
	s_waitcnt vmcnt(7)
	ds_write_b128 v214, v[226:229]
	s_waitcnt vmcnt(6)
	ds_write_b128 v213, v[230:233]
	ds_read_b128 v[226:229], v205 offset:36928
	ds_read_b128 v[230:233], v205 offset:41536
	s_waitcnt lgkmcnt(5)
	v_mfma_f32_32x32x16_bf16 v[80:95], v[234:237], v[218:221], v[80:95]
	v_mfma_f32_32x32x16_bf16 v[16:31], v[234:237], v[222:225], v[16:31]
	ds_read_b128 v[234:237], v204 offset:64
	s_waitcnt lgkmcnt(5)
	v_mfma_f32_32x32x16_bf16 v[64:79], v[238:241], v[218:221], v[64:79]
	v_mfma_f32_32x32x16_bf16 v[0:15], v[238:241], v[222:225], v[0:15]
	ds_read_b128 v[238:241], v204 offset:4672
	s_setprio 0
	global_load_dwordx4 v[218:221], v[184:185], off offset:1792
	global_load_dwordx4 v[222:225], v[186:187], off offset:1792
	s_setprio 1
	s_waitcnt lgkmcnt(1)
	v_mfma_f32_32x32x16_bf16 v[112:127], v[234:237], v[226:229], v[112:127]
	v_mfma_f32_32x32x16_bf16 v[48:63], v[234:237], v[230:233], v[48:63]
	s_waitcnt lgkmcnt(0)
	v_mfma_f32_32x32x16_bf16 v[96:111], v[238:241], v[226:229], v[96:111]
	v_mfma_f32_32x32x16_bf16 v[32:47], v[238:241], v[230:233], v[32:47]
	ds_read_b128 v[234:237], v204 offset:9280
	ds_read_b128 v[238:241], v204 offset:13888
	s_waitcnt vmcnt(7)
	ds_write_b128 v217, v[176:179]
	s_waitcnt vmcnt(6)
	ds_write_b128 v216, v[180:183]
	ds_read_b128 v[176:179], v205 offset:36960
	ds_read_b128 v[180:183], v205 offset:41568
	s_waitcnt lgkmcnt(5)
	v_mfma_f32_32x32x16_bf16 v[80:95], v[234:237], v[226:229], v[80:95]
	v_mfma_f32_32x32x16_bf16 v[16:31], v[234:237], v[230:233], v[16:31]
	ds_read_b128 v[234:237], v204 offset:96
	s_waitcnt lgkmcnt(5)
	v_mfma_f32_32x32x16_bf16 v[64:79], v[238:241], v[226:229], v[64:79]
	v_mfma_f32_32x32x16_bf16 v[0:15], v[238:241], v[230:233], v[0:15]
	ds_read_b128 v[238:241], v204 offset:4704
	s_setprio 0
	global_load_dwordx4 v[226:229], v[198:199], off offset:1792
	global_load_dwordx4 v[230:233], v[200:201], off offset:1792
	s_setprio 1
	s_waitcnt lgkmcnt(1)
	v_mfma_f32_32x32x16_bf16 v[112:127], v[234:237], v[176:179], v[112:127]
	v_mfma_f32_32x32x16_bf16 v[48:63], v[234:237], v[180:183], v[48:63]
	s_waitcnt lgkmcnt(0)
	v_mfma_f32_32x32x16_bf16 v[96:111], v[238:241], v[176:179], v[96:111]
	v_mfma_f32_32x32x16_bf16 v[32:47], v[238:241], v[180:183], v[32:47]
	ds_read_b128 v[234:237], v204 offset:9312
	ds_read_b128 v[238:241], v204 offset:13920
	s_waitcnt lgkmcnt(0)
	s_barrier
; template <bool trans>
; DI void gemm_core(const GTile& tl, const GTile& nx, bool has_next  , bool chain  , bool pre, u32x4 (&ra)[4], u32x4 (&rb)[4], char* smem, f32x16 (&acc)[2][4]) {
;     ...
;   const int nk = K / 64;
;   if (!pre) { G_LOAD(0); G_STORE(0); G_LOAD(1); }
;   for (int kt = 0; kt < nk; ++kt) {
;     __syncthreads();
;     G_COMPUTE(kt & 1, kt);
;   }
	s_waitcnt vmcnt(7)
	ds_write_b128 v215, v[168:171]
	s_waitcnt vmcnt(6)
	ds_write_b128 v215, v[172:175] offset:36864
	ds_read_b128 v[168:171], v208
	ds_read_b128 v[172:175], v208 offset:4608
	v_mfma_f32_32x32x16_bf16 v[80:95], v[234:237], v[176:179], v[80:95]
	v_mfma_f32_32x32x16_bf16 v[16:31], v[234:237], v[180:183], v[16:31]
	ds_read_b128 v[234:237], v192
	v_mfma_f32_32x32x16_bf16 v[64:79], v[238:241], v[176:179], v[64:79]
	v_mfma_f32_32x32x16_bf16 v[0:15], v[238:241], v[180:183], v[0:15]
	ds_read_b128 v[238:241], v192 offset:4608
	s_setprio 0
	global_load_dwordx4 v[176:179], v[190:191], off offset:1920
	global_load_dwordx4 v[180:183], v[188:189], off offset:1920
	s_setprio 1
	s_waitcnt lgkmcnt(1)
	v_mfma_f32_32x32x16_bf16 v[112:127], v[234:237], v[168:171], v[112:127]
	v_mfma_f32_32x32x16_bf16 v[48:63], v[234:237], v[172:175], v[48:63]
	s_waitcnt lgkmcnt(0)
	v_mfma_f32_32x32x16_bf16 v[96:111], v[238:241], v[168:171], v[96:111]
	v_mfma_f32_32x32x16_bf16 v[32:47], v[238:241], v[172:175], v[32:47]
	ds_read_b128 v[234:237], v192 offset:9216
	ds_read_b128 v[238:241], v192 offset:13824
	s_waitcnt vmcnt(7)
	ds_write_b128 v215, v[160:163] offset:9216
	s_waitcnt vmcnt(6)
	ds_write_b128 v215, v[164:167] offset:46080
	ds_read_b128 v[160:163], v208 offset:32
	ds_read_b128 v[164:167], v208 offset:4640
	s_waitcnt lgkmcnt(5)
	v_mfma_f32_32x32x16_bf16 v[80:95], v[234:237], v[168:171], v[80:95]
	v_mfma_f32_32x32x16_bf16 v[16:31], v[234:237], v[172:175], v[16:31]
	ds_read_b128 v[234:237], v192 offset:32
	s_waitcnt lgkmcnt(5)
	v_mfma_f32_32x32x16_bf16 v[64:79], v[238:241], v[168:171], v[64:79]
	v_mfma_f32_32x32x16_bf16 v[0:15], v[238:241], v[172:175], v[0:15]
	ds_read_b128 v[238:241], v192 offset:4640
	s_setprio 0
	global_load_dwordx4 v[168:171], v[194:195], off offset:1920
	global_load_dwordx4 v[172:175], v[196:197], off offset:1920
	s_setprio 1
	s_waitcnt lgkmcnt(1)
	v_mfma_f32_32x32x16_bf16 v[112:127], v[234:237], v[160:163], v[112:127]
	v_mfma_f32_32x32x16_bf16 v[48:63], v[234:237], v[164:167], v[48:63]
	s_waitcnt lgkmcnt(0)
	v_mfma_f32_32x32x16_bf16 v[96:111], v[238:241], v[160:163], v[96:111]
	v_mfma_f32_32x32x16_bf16 v[32:47], v[238:241], v[164:167], v[32:47]
	ds_read_b128 v[234:237], v192 offset:9248
	ds_read_b128 v[238:241], v192 offset:13856
	s_waitcnt vmcnt(7)
	ds_write_b128 v215, v[218:221] offset:18432
	s_waitcnt vmcnt(6)
	ds_write_b128 v215, v[222:225] offset:55296
	ds_read_b128 v[218:221], v208 offset:64
	ds_read_b128 v[222:225], v208 offset:4672
	s_waitcnt lgkmcnt(5)
	v_mfma_f32_32x32x16_bf16 v[80:95], v[234:237], v[160:163], v[80:95]
	v_mfma_f32_32x32x16_bf16 v[16:31], v[234:237], v[164:167], v[16:31]
	ds_read_b128 v[234:237], v192 offset:64
	s_waitcnt lgkmcnt(5)
	v_mfma_f32_32x32x16_bf16 v[64:79], v[238:241], v[160:163], v[64:79]
	v_mfma_f32_32x32x16_bf16 v[0:15], v[238:241], v[164:167], v[0:15]
	ds_read_b128 v[238:241], v192 offset:4672
	s_setprio 0
	global_load_dwordx4 v[160:163], v[184:185], off offset:1920
	global_load_dwordx4 v[164:167], v[186:187], off offset:1920
	s_setprio 1
	s_waitcnt lgkmcnt(1)
	v_mfma_f32_32x32x16_bf16 v[112:127], v[234:237], v[218:221], v[112:127]
	v_mfma_f32_32x32x16_bf16 v[48:63], v[234:237], v[222:225], v[48:63]
	s_waitcnt lgkmcnt(0)
	v_mfma_f32_32x32x16_bf16 v[96:111], v[238:241], v[218:221], v[96:111]
	v_mfma_f32_32x32x16_bf16 v[32:47], v[238:241], v[222:225], v[32:47]
	ds_read_b128 v[234:237], v192 offset:9280
	ds_read_b128 v[238:241], v192 offset:13888
	s_waitcnt vmcnt(7)
	ds_write_b128 v215, v[226:229] offset:27648
	s_waitcnt vmcnt(6)
	ds_write_b128 v215, v[230:233] offset:64512
	ds_read_b128 v[226:229], v208 offset:96
	ds_read_b128 v[230:233], v208 offset:4704
	s_waitcnt lgkmcnt(5)
	v_mfma_f32_32x32x16_bf16 v[80:95], v[234:237], v[218:221], v[80:95]
	v_mfma_f32_32x32x16_bf16 v[16:31], v[234:237], v[222:225], v[16:31]
	ds_read_b128 v[234:237], v192 offset:96
	s_waitcnt lgkmcnt(5)
	v_mfma_f32_32x32x16_bf16 v[64:79], v[238:241], v[218:221], v[64:79]
	v_mfma_f32_32x32x16_bf16 v[0:15], v[238:241], v[222:225], v[0:15]
	ds_read_b128 v[238:241], v192 offset:4704
	s_setprio 0
	global_load_dwordx4 v[218:221], v[198:199], off offset:1920
	global_load_dwordx4 v[222:225], v[200:201], off offset:1920
	s_setprio 1
	s_waitcnt lgkmcnt(1)
	v_mfma_f32_32x32x16_bf16 v[112:127], v[234:237], v[226:229], v[112:127]
	v_mfma_f32_32x32x16_bf16 v[48:63], v[234:237], v[230:233], v[48:63]
	s_waitcnt lgkmcnt(0)
	v_mfma_f32_32x32x16_bf16 v[96:111], v[238:241], v[226:229], v[96:111]
	v_mfma_f32_32x32x16_bf16 v[32:47], v[238:241], v[230:233], v[32:47]
	ds_read_b128 v[234:237], v192 offset:9312
	ds_read_b128 v[238:241], v192 offset:13920
	s_waitcnt lgkmcnt(0)
	s_barrier
; template <bool trans>
; DI void gemm_core(const GTile& tl, const GTile& nx, bool has_next  , bool chain  , bool pre, u32x4 (&ra)[4], u32x4 (&rb)[4], char* smem, f32x16 (&acc)[2][4]) {
;     ...
;   const int nk = K / 64;
;   if (!pre) { G_LOAD(0); G_STORE(0); G_LOAD(1); }
;   for (int kt = 0; kt < nk; ++kt) {
;     __syncthreads();
;     G_COMPUTE(kt & 1, kt);
;   }
	s_waitcnt vmcnt(7)
	ds_write_b128 v209, v[176:179]
	s_waitcnt vmcnt(6)
	ds_write_b128 v210, v[180:183]
	ds_read_b128 v[176:179], v205 offset:36864
	ds_read_b128 v[180:183], v205 offset:41472
	v_mfma_f32_32x32x16_bf16 v[80:95], v[234:237], v[226:229], v[80:95]
	v_mfma_f32_32x32x16_bf16 v[16:31], v[234:237], v[230:233], v[16:31]
	ds_read_b128 v[234:237], v204
	v_mfma_f32_32x32x16_bf16 v[64:79], v[238:241], v[226:229], v[64:79]
	v_mfma_f32_32x32x16_bf16 v[0:15], v[238:241], v[230:233], v[0:15]
	ds_read_b128 v[238:241], v204 offset:4608
	s_setprio 0
	global_load_dwordx4 v[226:229], v[190:191], off offset:2048
	global_load_dwordx4 v[230:233], v[188:189], off offset:2048
	s_setprio 1
	s_waitcnt lgkmcnt(1)
	v_mfma_f32_32x32x16_bf16 v[112:127], v[234:237], v[176:179], v[112:127]
	v_mfma_f32_32x32x16_bf16 v[48:63], v[234:237], v[180:183], v[48:63]
	s_waitcnt lgkmcnt(0)
	v_mfma_f32_32x32x16_bf16 v[96:111], v[238:241], v[176:179], v[96:111]
	v_mfma_f32_32x32x16_bf16 v[32:47], v[238:241], v[180:183], v[32:47]
	ds_read_b128 v[234:237], v204 offset:9216
	ds_read_b128 v[238:241], v204 offset:13824
	s_waitcnt vmcnt(7)
	ds_write_b128 v212, v[168:171]
	s_waitcnt vmcnt(6)
	ds_write_b128 v211, v[172:175]
	ds_read_b128 v[168:171], v205 offset:36896
	ds_read_b128 v[172:175], v205 offset:41504
	s_waitcnt lgkmcnt(5)
	v_mfma_f32_32x32x16_bf16 v[80:95], v[234:237], v[176:179], v[80:95]
	v_mfma_f32_32x32x16_bf16 v[16:31], v[234:237], v[180:183], v[16:31]
	ds_read_b128 v[234:237], v204 offset:32
	s_waitcnt lgkmcnt(5)
	v_mfma_f32_32x32x16_bf16 v[64:79], v[238:241], v[176:179], v[64:79]
	v_mfma_f32_32x32x16_bf16 v[0:15], v[238:241], v[180:183], v[0:15]
	ds_read_b128 v[238:241], v204 offset:4640
	s_setprio 0
	global_load_dwordx4 v[176:179], v[194:195], off offset:2048
	global_load_dwordx4 v[180:183], v[196:197], off offset:2048
	s_setprio 1
	s_waitcnt lgkmcnt(1)
	v_mfma_f32_32x32x16_bf16 v[112:127], v[234:237], v[168:171], v[112:127]
	v_mfma_f32_32x32x16_bf16 v[48:63], v[234:237], v[172:175], v[48:63]
	s_waitcnt lgkmcnt(0)
	v_mfma_f32_32x32x16_bf16 v[96:111], v[238:241], v[168:171], v[96:111]
	v_mfma_f32_32x32x16_bf16 v[32:47], v[238:241], v[172:175], v[32:47]
	ds_read_b128 v[234:237], v204 offset:9248
	ds_read_b128 v[238:241], v204 offset:13856
	s_waitcnt vmcnt(7)
	ds_write_b128 v214, v[160:163]
	s_waitcnt vmcnt(6)
	ds_write_b128 v213, v[164:167]
	ds_read_b128 v[160:163], v205 offset:36928
	ds_read_b128 v[164:167], v205 offset:41536
	s_waitcnt lgkmcnt(5)
	v_mfma_f32_32x32x16_bf16 v[80:95], v[234:237], v[168:171], v[80:95]
	v_mfma_f32_32x32x16_bf16 v[16:31], v[234:237], v[172:175], v[16:31]
	ds_read_b128 v[234:237], v204 offset:64
	s_waitcnt lgkmcnt(5)
	v_mfma_f32_32x32x16_bf16 v[64:79], v[238:241], v[168:171], v[64:79]
	v_mfma_f32_32x32x16_bf16 v[0:15], v[238:241], v[172:175], v[0:15]
	ds_read_b128 v[238:241], v204 offset:4672
	s_setprio 0
	global_load_dwordx4 v[168:171], v[184:185], off offset:2048
	global_load_dwordx4 v[172:175], v[186:187], off offset:2048
	s_setprio 1
	s_waitcnt lgkmcnt(1)
	v_mfma_f32_32x32x16_bf16 v[112:127], v[234:237], v[160:163], v[112:127]
	v_mfma_f32_32x32x16_bf16 v[48:63], v[234:237], v[164:167], v[48:63]
	s_waitcnt lgkmcnt(0)
	v_mfma_f32_32x32x16_bf16 v[96:111], v[238:241], v[160:163], v[96:111]
	v_mfma_f32_32x32x16_bf16 v[32:47], v[238:241], v[164:167], v[32:47]
	ds_read_b128 v[234:237], v204 offset:9280
	ds_read_b128 v[238:241], v204 offset:13888
	s_waitcnt vmcnt(7)
	ds_write_b128 v217, v[218:221]
	s_waitcnt vmcnt(6)
	ds_write_b128 v216, v[222:225]
	ds_read_b128 v[218:221], v205 offset:36960
	ds_read_b128 v[222:225], v205 offset:41568
	s_waitcnt lgkmcnt(5)
	v_mfma_f32_32x32x16_bf16 v[80:95], v[234:237], v[160:163], v[80:95]
	v_mfma_f32_32x32x16_bf16 v[16:31], v[234:237], v[164:167], v[16:31]
	ds_read_b128 v[234:237], v204 offset:96
	s_waitcnt lgkmcnt(5)
	v_mfma_f32_32x32x16_bf16 v[64:79], v[238:241], v[160:163], v[64:79]
	v_mfma_f32_32x32x16_bf16 v[0:15], v[238:241], v[164:167], v[0:15]
	ds_read_b128 v[238:241], v204 offset:4704
	s_setprio 0
	global_load_dwordx4 v[160:163], v[198:199], off offset:2048
	global_load_dwordx4 v[164:167], v[200:201], off offset:2048
	s_setprio 1
	s_waitcnt lgkmcnt(1)
	v_mfma_f32_32x32x16_bf16 v[112:127], v[234:237], v[218:221], v[112:127]
	v_mfma_f32_32x32x16_bf16 v[48:63], v[234:237], v[222:225], v[48:63]
	s_waitcnt lgkmcnt(0)
	v_mfma_f32_32x32x16_bf16 v[96:111], v[238:241], v[218:221], v[96:111]
	v_mfma_f32_32x32x16_bf16 v[32:47], v[238:241], v[222:225], v[32:47]
	ds_read_b128 v[234:237], v204 offset:9312
	ds_read_b128 v[238:241], v204 offset:13920
	s_waitcnt lgkmcnt(0)
	s_barrier
; template <bool trans>
; DI void gemm_core(const GTile& tl, const GTile& nx, bool has_next  , bool chain  , bool pre, u32x4 (&ra)[4], u32x4 (&rb)[4], char* smem, f32x16 (&acc)[2][4]) {
;     ...
;   const int nk = K / 64;
;   if (!pre) { G_LOAD(0); G_STORE(0); G_LOAD(1); }
;   for (int kt = 0; kt < nk; ++kt) {
;     __syncthreads();
;     G_COMPUTE(kt & 1, kt);
;   }
	s_waitcnt vmcnt(7)
	ds_write_b128 v215, v[226:229]
	s_waitcnt vmcnt(6)
	ds_write_b128 v215, v[230:233] offset:36864
	ds_read_b128 v[226:229], v208
	ds_read_b128 v[230:233], v208 offset:4608
	v_mfma_f32_32x32x16_bf16 v[80:95], v[234:237], v[218:221], v[80:95]
	v_mfma_f32_32x32x16_bf16 v[16:31], v[234:237], v[222:225], v[16:31]
	ds_read_b128 v[234:237], v192
	v_mfma_f32_32x32x16_bf16 v[64:79], v[238:241], v[218:221], v[64:79]
	v_mfma_f32_32x32x16_bf16 v[0:15], v[238:241], v[222:225], v[0:15]
	ds_read_b128 v[238:241], v192 offset:4608
	s_setprio 0
	global_load_dwordx4 v[218:221], v[190:191], off offset:2176
	global_load_dwordx4 v[222:225], v[188:189], off offset:2176
	s_setprio 1
	s_waitcnt lgkmcnt(1)
	v_mfma_f32_32x32x16_bf16 v[112:127], v[234:237], v[226:229], v[112:127]
	v_mfma_f32_32x32x16_bf16 v[48:63], v[234:237], v[230:233], v[48:63]
	s_waitcnt lgkmcnt(0)
	v_mfma_f32_32x32x16_bf16 v[96:111], v[238:241], v[226:229], v[96:111]
	v_mfma_f32_32x32x16_bf16 v[32:47], v[238:241], v[230:233], v[32:47]
	ds_read_b128 v[234:237], v192 offset:9216
	ds_read_b128 v[238:241], v192 offset:13824
	s_waitcnt vmcnt(7)
	ds_write_b128 v215, v[176:179] offset:9216
	s_waitcnt vmcnt(6)
	ds_write_b128 v215, v[180:183] offset:46080
	ds_read_b128 v[176:179], v208 offset:32
	ds_read_b128 v[180:183], v208 offset:4640
	s_waitcnt lgkmcnt(5)
	v_mfma_f32_32x32x16_bf16 v[80:95], v[234:237], v[226:229], v[80:95]
	v_mfma_f32_32x32x16_bf16 v[16:31], v[234:237], v[230:233], v[16:31]
	ds_read_b128 v[234:237], v192 offset:32
	s_waitcnt lgkmcnt(5)
	v_mfma_f32_32x32x16_bf16 v[64:79], v[238:241], v[226:229], v[64:79]
	v_mfma_f32_32x32x16_bf16 v[0:15], v[238:241], v[230:233], v[0:15]
	ds_read_b128 v[238:241], v192 offset:4640
	s_setprio 0
	global_load_dwordx4 v[226:229], v[194:195], off offset:2176
	global_load_dwordx4 v[230:233], v[196:197], off offset:2176
	s_setprio 1
	s_waitcnt lgkmcnt(1)
	v_mfma_f32_32x32x16_bf16 v[112:127], v[234:237], v[176:179], v[112:127]
	v_mfma_f32_32x32x16_bf16 v[48:63], v[234:237], v[180:183], v[48:63]
	s_waitcnt lgkmcnt(0)
	v_mfma_f32_32x32x16_bf16 v[96:111], v[238:241], v[176:179], v[96:111]
	v_mfma_f32_32x32x16_bf16 v[32:47], v[238:241], v[180:183], v[32:47]
	ds_read_b128 v[234:237], v192 offset:9248
	ds_read_b128 v[238:241], v192 offset:13856
	s_waitcnt vmcnt(7)
	ds_write_b128 v215, v[168:171] offset:18432
	s_waitcnt vmcnt(6)
	ds_write_b128 v215, v[172:175] offset:55296
	ds_read_b128 v[168:171], v208 offset:64
	ds_read_b128 v[172:175], v208 offset:4672
	s_waitcnt lgkmcnt(5)
	v_mfma_f32_32x32x16_bf16 v[80:95], v[234:237], v[176:179], v[80:95]
	v_mfma_f32_32x32x16_bf16 v[16:31], v[234:237], v[180:183], v[16:31]
	ds_read_b128 v[234:237], v192 offset:64
	s_waitcnt lgkmcnt(5)
	v_mfma_f32_32x32x16_bf16 v[64:79], v[238:241], v[176:179], v[64:79]
	v_mfma_f32_32x32x16_bf16 v[0:15], v[238:241], v[180:183], v[0:15]
	ds_read_b128 v[238:241], v192 offset:4672
	s_setprio 0
	global_load_dwordx4 v[176:179], v[184:185], off offset:2176
	global_load_dwordx4 v[180:183], v[186:187], off offset:2176
	s_setprio 1
	s_waitcnt lgkmcnt(1)
	v_mfma_f32_32x32x16_bf16 v[112:127], v[234:237], v[168:171], v[112:127]
	v_mfma_f32_32x32x16_bf16 v[48:63], v[234:237], v[172:175], v[48:63]
	s_waitcnt lgkmcnt(0)
	v_mfma_f32_32x32x16_bf16 v[96:111], v[238:241], v[168:171], v[96:111]
	v_mfma_f32_32x32x16_bf16 v[32:47], v[238:241], v[172:175], v[32:47]
	ds_read_b128 v[234:237], v192 offset:9280
	ds_read_b128 v[238:241], v192 offset:13888
	s_waitcnt vmcnt(7)
	ds_write_b128 v215, v[160:163] offset:27648
	s_waitcnt vmcnt(6)
	ds_write_b128 v215, v[164:167] offset:64512
	ds_read_b128 v[160:163], v208 offset:96
	ds_read_b128 v[164:167], v208 offset:4704
	s_waitcnt lgkmcnt(5)
	v_mfma_f32_32x32x16_bf16 v[80:95], v[234:237], v[168:171], v[80:95]
	v_mfma_f32_32x32x16_bf16 v[16:31], v[234:237], v[172:175], v[16:31]
	ds_read_b128 v[234:237], v192 offset:96
	s_waitcnt lgkmcnt(5)
	v_mfma_f32_32x32x16_bf16 v[64:79], v[238:241], v[168:171], v[64:79]
	v_mfma_f32_32x32x16_bf16 v[0:15], v[238:241], v[172:175], v[0:15]
	ds_read_b128 v[238:241], v192 offset:4704
	s_setprio 0
	global_load_dwordx4 v[168:171], v[198:199], off offset:2176
	global_load_dwordx4 v[172:175], v[200:201], off offset:2176
	s_setprio 1
	s_waitcnt lgkmcnt(1)
	v_mfma_f32_32x32x16_bf16 v[112:127], v[234:237], v[160:163], v[112:127]
	v_mfma_f32_32x32x16_bf16 v[48:63], v[234:237], v[164:167], v[48:63]
	s_waitcnt lgkmcnt(0)
	v_mfma_f32_32x32x16_bf16 v[96:111], v[238:241], v[160:163], v[96:111]
	v_mfma_f32_32x32x16_bf16 v[32:47], v[238:241], v[164:167], v[32:47]
	ds_read_b128 v[234:237], v192 offset:9312
	ds_read_b128 v[238:241], v192 offset:13920
	s_waitcnt lgkmcnt(0)
	s_barrier
; template <bool trans>
; DI void gemm_core(const GTile& tl, const GTile& nx, bool has_next  , bool chain  , bool pre, u32x4 (&ra)[4], u32x4 (&rb)[4], char* smem, f32x16 (&acc)[2][4]) {
;     ...
;   const int nk = K / 64;
;   if (!pre) { G_LOAD(0); G_STORE(0); G_LOAD(1); }
;   for (int kt = 0; kt < nk; ++kt) {
;     __syncthreads();
;     G_COMPUTE(kt & 1, kt);
;   }
	s_waitcnt vmcnt(7)
	ds_write_b128 v209, v[218:221]
	s_waitcnt vmcnt(6)
	ds_write_b128 v210, v[222:225]
	ds_read_b128 v[218:221], v205 offset:36864
	ds_read_b128 v[222:225], v205 offset:41472
	v_mfma_f32_32x32x16_bf16 v[80:95], v[234:237], v[160:163], v[80:95]
	v_mfma_f32_32x32x16_bf16 v[16:31], v[234:237], v[164:167], v[16:31]
	ds_read_b128 v[234:237], v204
	v_mfma_f32_32x32x16_bf16 v[64:79], v[238:241], v[160:163], v[64:79]
	v_mfma_f32_32x32x16_bf16 v[0:15], v[238:241], v[164:167], v[0:15]
	ds_read_b128 v[238:241], v204 offset:4608
	s_setprio 0
	global_load_dwordx4 v[160:163], v[190:191], off offset:2304
	global_load_dwordx4 v[164:167], v[188:189], off offset:2304
	s_setprio 1
	s_waitcnt lgkmcnt(1)
	v_mfma_f32_32x32x16_bf16 v[112:127], v[234:237], v[218:221], v[112:127]
	v_mfma_f32_32x32x16_bf16 v[48:63], v[234:237], v[222:225], v[48:63]
	s_waitcnt lgkmcnt(0)
	v_mfma_f32_32x32x16_bf16 v[96:111], v[238:241], v[218:221], v[96:111]
	v_mfma_f32_32x32x16_bf16 v[32:47], v[238:241], v[222:225], v[32:47]
	ds_read_b128 v[234:237], v204 offset:9216
	ds_read_b128 v[238:241], v204 offset:13824
	s_waitcnt vmcnt(7)
	ds_write_b128 v212, v[226:229]
	s_waitcnt vmcnt(6)
	ds_write_b128 v211, v[230:233]
	ds_read_b128 v[226:229], v205 offset:36896
	ds_read_b128 v[230:233], v205 offset:41504
	s_waitcnt lgkmcnt(5)
	v_mfma_f32_32x32x16_bf16 v[80:95], v[234:237], v[218:221], v[80:95]
	v_mfma_f32_32x32x16_bf16 v[16:31], v[234:237], v[222:225], v[16:31]
	ds_read_b128 v[234:237], v204 offset:32
	s_waitcnt lgkmcnt(5)
	v_mfma_f32_32x32x16_bf16 v[64:79], v[238:241], v[218:221], v[64:79]
	v_mfma_f32_32x32x16_bf16 v[0:15], v[238:241], v[222:225], v[0:15]
	ds_read_b128 v[238:241], v204 offset:4640
	s_setprio 0
	global_load_dwordx4 v[218:221], v[194:195], off offset:2304
	global_load_dwordx4 v[222:225], v[196:197], off offset:2304
	s_setprio 1
	s_waitcnt lgkmcnt(1)
	v_mfma_f32_32x32x16_bf16 v[112:127], v[234:237], v[226:229], v[112:127]
	v_mfma_f32_32x32x16_bf16 v[48:63], v[234:237], v[230:233], v[48:63]
	s_waitcnt lgkmcnt(0)
	v_mfma_f32_32x32x16_bf16 v[96:111], v[238:241], v[226:229], v[96:111]
	v_mfma_f32_32x32x16_bf16 v[32:47], v[238:241], v[230:233], v[32:47]
	ds_read_b128 v[234:237], v204 offset:9248
	ds_read_b128 v[238:241], v204 offset:13856
	s_waitcnt vmcnt(7)
	ds_write_b128 v214, v[176:179]
	s_waitcnt vmcnt(6)
	ds_write_b128 v213, v[180:183]
	ds_read_b128 v[176:179], v205 offset:36928
	ds_read_b128 v[180:183], v205 offset:41536
	s_waitcnt lgkmcnt(5)
	v_mfma_f32_32x32x16_bf16 v[80:95], v[234:237], v[226:229], v[80:95]
	v_mfma_f32_32x32x16_bf16 v[16:31], v[234:237], v[230:233], v[16:31]
	ds_read_b128 v[234:237], v204 offset:64
	s_waitcnt lgkmcnt(5)
	v_mfma_f32_32x32x16_bf16 v[64:79], v[238:241], v[226:229], v[64:79]
	v_mfma_f32_32x32x16_bf16 v[0:15], v[238:241], v[230:233], v[0:15]
	ds_read_b128 v[238:241], v204 offset:4672
	s_setprio 0
	global_load_dwordx4 v[226:229], v[184:185], off offset:2304
	global_load_dwordx4 v[230:233], v[186:187], off offset:2304
	s_setprio 1
	s_waitcnt lgkmcnt(1)
	v_mfma_f32_32x32x16_bf16 v[112:127], v[234:237], v[176:179], v[112:127]
	v_mfma_f32_32x32x16_bf16 v[48:63], v[234:237], v[180:183], v[48:63]
	s_waitcnt lgkmcnt(0)
	v_mfma_f32_32x32x16_bf16 v[96:111], v[238:241], v[176:179], v[96:111]
	v_mfma_f32_32x32x16_bf16 v[32:47], v[238:241], v[180:183], v[32:47]
	ds_read_b128 v[234:237], v204 offset:9280
	ds_read_b128 v[238:241], v204 offset:13888
	s_waitcnt vmcnt(7)
	ds_write_b128 v217, v[168:171]
	s_waitcnt vmcnt(6)
	ds_write_b128 v216, v[172:175]
	ds_read_b128 v[168:171], v205 offset:36960
	ds_read_b128 v[172:175], v205 offset:41568
	s_waitcnt lgkmcnt(5)
	v_mfma_f32_32x32x16_bf16 v[80:95], v[234:237], v[176:179], v[80:95]
	v_mfma_f32_32x32x16_bf16 v[16:31], v[234:237], v[180:183], v[16:31]
	ds_read_b128 v[234:237], v204 offset:96
	s_waitcnt lgkmcnt(5)
	v_mfma_f32_32x32x16_bf16 v[64:79], v[238:241], v[176:179], v[64:79]
	v_mfma_f32_32x32x16_bf16 v[0:15], v[238:241], v[180:183], v[0:15]
	ds_read_b128 v[238:241], v204 offset:4704
	s_setprio 0
	global_load_dwordx4 v[176:179], v[198:199], off offset:2304
	global_load_dwordx4 v[180:183], v[200:201], off offset:2304
	s_setprio 1
	s_waitcnt lgkmcnt(1)
	v_mfma_f32_32x32x16_bf16 v[112:127], v[234:237], v[168:171], v[112:127]
	v_mfma_f32_32x32x16_bf16 v[48:63], v[234:237], v[172:175], v[48:63]
	s_waitcnt lgkmcnt(0)
	v_mfma_f32_32x32x16_bf16 v[96:111], v[238:241], v[168:171], v[96:111]
	v_mfma_f32_32x32x16_bf16 v[32:47], v[238:241], v[172:175], v[32:47]
	ds_read_b128 v[234:237], v204 offset:9312
	ds_read_b128 v[238:241], v204 offset:13920
	s_waitcnt lgkmcnt(0)
	s_barrier
; template <bool trans>
; DI void gemm_core(const GTile& tl, const GTile& nx, bool has_next  , bool chain  , bool pre, u32x4 (&ra)[4], u32x4 (&rb)[4], char* smem, f32x16 (&acc)[2][4]) {
;     ...
;   const int nk = K / 64;
;   if (!pre) { G_LOAD(0); G_STORE(0); G_LOAD(1); }
;   for (int kt = 0; kt < nk; ++kt) {
;     __syncthreads();
;     G_COMPUTE(kt & 1, kt);
;   }
	s_waitcnt vmcnt(7)
	ds_write_b128 v215, v[160:163]
	s_waitcnt vmcnt(6)
	ds_write_b128 v215, v[164:167] offset:36864
	ds_read_b128 v[160:163], v208
	ds_read_b128 v[164:167], v208 offset:4608
	v_mfma_f32_32x32x16_bf16 v[80:95], v[234:237], v[168:171], v[80:95]
	v_mfma_f32_32x32x16_bf16 v[16:31], v[234:237], v[172:175], v[16:31]
	ds_read_b128 v[234:237], v192
	v_mfma_f32_32x32x16_bf16 v[64:79], v[238:241], v[168:171], v[64:79]
	v_mfma_f32_32x32x16_bf16 v[0:15], v[238:241], v[172:175], v[0:15]
	ds_read_b128 v[238:241], v192 offset:4608
	s_setprio 0
	global_load_dwordx4 v[168:171], v[190:191], off offset:2432
	global_load_dwordx4 v[172:175], v[188:189], off offset:2432
	s_setprio 1
	s_waitcnt lgkmcnt(1)
	v_mfma_f32_32x32x16_bf16 v[112:127], v[234:237], v[160:163], v[112:127]
	v_mfma_f32_32x32x16_bf16 v[48:63], v[234:237], v[164:167], v[48:63]
	s_waitcnt lgkmcnt(0)
	v_mfma_f32_32x32x16_bf16 v[96:111], v[238:241], v[160:163], v[96:111]
	v_mfma_f32_32x32x16_bf16 v[32:47], v[238:241], v[164:167], v[32:47]
	ds_read_b128 v[234:237], v192 offset:9216
	ds_read_b128 v[238:241], v192 offset:13824
	s_waitcnt vmcnt(7)
	ds_write_b128 v215, v[218:221] offset:9216
	s_waitcnt vmcnt(6)
	ds_write_b128 v215, v[222:225] offset:46080
	ds_read_b128 v[218:221], v208 offset:32
	ds_read_b128 v[222:225], v208 offset:4640
	s_waitcnt lgkmcnt(5)
	v_mfma_f32_32x32x16_bf16 v[80:95], v[234:237], v[160:163], v[80:95]
	v_mfma_f32_32x32x16_bf16 v[16:31], v[234:237], v[164:167], v[16:31]
	ds_read_b128 v[234:237], v192 offset:32
	s_waitcnt lgkmcnt(5)
	v_mfma_f32_32x32x16_bf16 v[64:79], v[238:241], v[160:163], v[64:79]
	v_mfma_f32_32x32x16_bf16 v[0:15], v[238:241], v[164:167], v[0:15]
	ds_read_b128 v[238:241], v192 offset:4640
	s_setprio 0
	global_load_dwordx4 v[160:163], v[194:195], off offset:2432
	global_load_dwordx4 v[164:167], v[196:197], off offset:2432
	s_setprio 1
	s_waitcnt lgkmcnt(1)
	v_mfma_f32_32x32x16_bf16 v[112:127], v[234:237], v[218:221], v[112:127]
	v_mfma_f32_32x32x16_bf16 v[48:63], v[234:237], v[222:225], v[48:63]
	s_waitcnt lgkmcnt(0)
	v_mfma_f32_32x32x16_bf16 v[96:111], v[238:241], v[218:221], v[96:111]
	v_mfma_f32_32x32x16_bf16 v[32:47], v[238:241], v[222:225], v[32:47]
	ds_read_b128 v[234:237], v192 offset:9248
	ds_read_b128 v[238:241], v192 offset:13856
	s_waitcnt vmcnt(7)
	ds_write_b128 v215, v[226:229] offset:18432
	s_waitcnt vmcnt(6)
	ds_write_b128 v215, v[230:233] offset:55296
	ds_read_b128 v[226:229], v208 offset:64
	ds_read_b128 v[230:233], v208 offset:4672
	s_waitcnt lgkmcnt(5)
	v_mfma_f32_32x32x16_bf16 v[80:95], v[234:237], v[218:221], v[80:95]
	v_mfma_f32_32x32x16_bf16 v[16:31], v[234:237], v[222:225], v[16:31]
	ds_read_b128 v[234:237], v192 offset:64
	s_waitcnt lgkmcnt(5)
	v_mfma_f32_32x32x16_bf16 v[64:79], v[238:241], v[218:221], v[64:79]
	v_mfma_f32_32x32x16_bf16 v[0:15], v[238:241], v[222:225], v[0:15]
	ds_read_b128 v[238:241], v192 offset:4672
	s_setprio 0
	global_load_dwordx4 v[218:221], v[184:185], off offset:2432
	global_load_dwordx4 v[222:225], v[186:187], off offset:2432
	s_setprio 1
	s_waitcnt lgkmcnt(1)
	v_mfma_f32_32x32x16_bf16 v[112:127], v[234:237], v[226:229], v[112:127]
	v_mfma_f32_32x32x16_bf16 v[48:63], v[234:237], v[230:233], v[48:63]
	s_waitcnt lgkmcnt(0)
	v_mfma_f32_32x32x16_bf16 v[96:111], v[238:241], v[226:229], v[96:111]
	v_mfma_f32_32x32x16_bf16 v[32:47], v[238:241], v[230:233], v[32:47]
	ds_read_b128 v[234:237], v192 offset:9280
	ds_read_b128 v[238:241], v192 offset:13888
	s_waitcnt vmcnt(7)
	ds_write_b128 v215, v[176:179] offset:27648
	s_waitcnt vmcnt(6)
	ds_write_b128 v215, v[180:183] offset:64512
	ds_read_b128 v[176:179], v208 offset:96
	ds_read_b128 v[180:183], v208 offset:4704
	s_waitcnt lgkmcnt(5)
	v_mfma_f32_32x32x16_bf16 v[80:95], v[234:237], v[226:229], v[80:95]
	v_mfma_f32_32x32x16_bf16 v[16:31], v[234:237], v[230:233], v[16:31]
	ds_read_b128 v[234:237], v192 offset:96
	s_waitcnt lgkmcnt(5)
	v_mfma_f32_32x32x16_bf16 v[64:79], v[238:241], v[226:229], v[64:79]
	v_mfma_f32_32x32x16_bf16 v[0:15], v[238:241], v[230:233], v[0:15]
	ds_read_b128 v[238:241], v192 offset:4704
	s_setprio 0
	global_load_dwordx4 v[226:229], v[198:199], off offset:2432
	global_load_dwordx4 v[230:233], v[200:201], off offset:2432
	s_setprio 1
	s_waitcnt lgkmcnt(1)
	v_mfma_f32_32x32x16_bf16 v[112:127], v[234:237], v[176:179], v[112:127]
	v_mfma_f32_32x32x16_bf16 v[48:63], v[234:237], v[180:183], v[48:63]
	s_waitcnt lgkmcnt(0)
	v_mfma_f32_32x32x16_bf16 v[96:111], v[238:241], v[176:179], v[96:111]
	v_mfma_f32_32x32x16_bf16 v[32:47], v[238:241], v[180:183], v[32:47]
	ds_read_b128 v[234:237], v192 offset:9312
	ds_read_b128 v[238:241], v192 offset:13920
	s_waitcnt lgkmcnt(0)
	s_barrier
; template <bool trans>
; DI void gemm_core(const GTile& tl, const GTile& nx, bool has_next  , bool chain  , bool pre, u32x4 (&ra)[4], u32x4 (&rb)[4], char* smem, f32x16 (&acc)[2][4]) {
;     ...
;   const int nk = K / 64;
;   if (!pre) { G_LOAD(0); G_STORE(0); G_LOAD(1); }
;   for (int kt = 0; kt < nk; ++kt) {
;     __syncthreads();
;     G_COMPUTE(kt & 1, kt);
;   }
	s_waitcnt vmcnt(7)
	ds_write_b128 v209, v[168:171]
	s_waitcnt vmcnt(6)
	ds_write_b128 v210, v[172:175]
	ds_read_b128 v[168:171], v205 offset:36864
	ds_read_b128 v[172:175], v205 offset:41472
	v_mfma_f32_32x32x16_bf16 v[80:95], v[234:237], v[176:179], v[80:95]
	v_mfma_f32_32x32x16_bf16 v[16:31], v[234:237], v[180:183], v[16:31]
	ds_read_b128 v[234:237], v204
	v_mfma_f32_32x32x16_bf16 v[64:79], v[238:241], v[176:179], v[64:79]
	v_mfma_f32_32x32x16_bf16 v[0:15], v[238:241], v[180:183], v[0:15]
	ds_read_b128 v[238:241], v204 offset:4608
	s_setprio 0
	global_load_dwordx4 v[176:179], v[190:191], off offset:2560
	global_load_dwordx4 v[180:183], v[188:189], off offset:2560
	s_setprio 1
	s_waitcnt lgkmcnt(1)
	v_mfma_f32_32x32x16_bf16 v[112:127], v[234:237], v[168:171], v[112:127]
	v_mfma_f32_32x32x16_bf16 v[48:63], v[234:237], v[172:175], v[48:63]
	s_waitcnt lgkmcnt(0)
	v_mfma_f32_32x32x16_bf16 v[96:111], v[238:241], v[168:171], v[96:111]
	v_mfma_f32_32x32x16_bf16 v[32:47], v[238:241], v[172:175], v[32:47]
	ds_read_b128 v[234:237], v204 offset:9216
	ds_read_b128 v[238:241], v204 offset:13824
	s_waitcnt vmcnt(7)
	ds_write_b128 v212, v[160:163]
	s_waitcnt vmcnt(6)
	ds_write_b128 v211, v[164:167]
	ds_read_b128 v[160:163], v205 offset:36896
	ds_read_b128 v[164:167], v205 offset:41504
	s_waitcnt lgkmcnt(5)
	v_mfma_f32_32x32x16_bf16 v[80:95], v[234:237], v[168:171], v[80:95]
	v_mfma_f32_32x32x16_bf16 v[16:31], v[234:237], v[172:175], v[16:31]
	ds_read_b128 v[234:237], v204 offset:32
	s_waitcnt lgkmcnt(5)
	v_mfma_f32_32x32x16_bf16 v[64:79], v[238:241], v[168:171], v[64:79]
	v_mfma_f32_32x32x16_bf16 v[0:15], v[238:241], v[172:175], v[0:15]
	ds_read_b128 v[238:241], v204 offset:4640
	s_setprio 0
	global_load_dwordx4 v[168:171], v[194:195], off offset:2560
	global_load_dwordx4 v[172:175], v[196:197], off offset:2560
	s_setprio 1
	s_waitcnt lgkmcnt(1)
	v_mfma_f32_32x32x16_bf16 v[112:127], v[234:237], v[160:163], v[112:127]
	v_mfma_f32_32x32x16_bf16 v[48:63], v[234:237], v[164:167], v[48:63]
	s_waitcnt lgkmcnt(0)
	v_mfma_f32_32x32x16_bf16 v[96:111], v[238:241], v[160:163], v[96:111]
	v_mfma_f32_32x32x16_bf16 v[32:47], v[238:241], v[164:167], v[32:47]
	ds_read_b128 v[234:237], v204 offset:9248
	ds_read_b128 v[238:241], v204 offset:13856
	s_waitcnt vmcnt(7)
	ds_write_b128 v214, v[218:221]
	s_waitcnt vmcnt(6)
	ds_write_b128 v213, v[222:225]
	ds_read_b128 v[218:221], v205 offset:36928
	ds_read_b128 v[222:225], v205 offset:41536
	s_waitcnt lgkmcnt(5)
	v_mfma_f32_32x32x16_bf16 v[80:95], v[234:237], v[160:163], v[80:95]
	v_mfma_f32_32x32x16_bf16 v[16:31], v[234:237], v[164:167], v[16:31]
	ds_read_b128 v[234:237], v204 offset:64
	s_waitcnt lgkmcnt(5)
	v_mfma_f32_32x32x16_bf16 v[64:79], v[238:241], v[160:163], v[64:79]
	v_mfma_f32_32x32x16_bf16 v[0:15], v[238:241], v[164:167], v[0:15]
	ds_read_b128 v[238:241], v204 offset:4672
	s_setprio 0
	global_load_dwordx4 v[160:163], v[184:185], off offset:2560
	global_load_dwordx4 v[164:167], v[186:187], off offset:2560
	s_setprio 1
	s_waitcnt lgkmcnt(1)
	v_mfma_f32_32x32x16_bf16 v[112:127], v[234:237], v[218:221], v[112:127]
	v_mfma_f32_32x32x16_bf16 v[48:63], v[234:237], v[222:225], v[48:63]
	s_waitcnt lgkmcnt(0)
	v_mfma_f32_32x32x16_bf16 v[96:111], v[238:241], v[218:221], v[96:111]
	v_mfma_f32_32x32x16_bf16 v[32:47], v[238:241], v[222:225], v[32:47]
	ds_read_b128 v[234:237], v204 offset:9280
	ds_read_b128 v[238:241], v204 offset:13888
	s_waitcnt vmcnt(7)
	ds_write_b128 v217, v[226:229]
	s_waitcnt vmcnt(6)
	ds_write_b128 v216, v[230:233]
	ds_read_b128 v[226:229], v205 offset:36960
	ds_read_b128 v[230:233], v205 offset:41568
	s_waitcnt lgkmcnt(5)
	v_mfma_f32_32x32x16_bf16 v[80:95], v[234:237], v[218:221], v[80:95]
	v_mfma_f32_32x32x16_bf16 v[16:31], v[234:237], v[222:225], v[16:31]
	ds_read_b128 v[234:237], v204 offset:96
	s_waitcnt lgkmcnt(5)
	v_mfma_f32_32x32x16_bf16 v[64:79], v[238:241], v[218:221], v[64:79]
	v_mfma_f32_32x32x16_bf16 v[0:15], v[238:241], v[222:225], v[0:15]
	ds_read_b128 v[238:241], v204 offset:4704
	s_setprio 0
	global_load_dwordx4 v[218:221], v[198:199], off offset:2560
	global_load_dwordx4 v[222:225], v[200:201], off offset:2560
	s_setprio 1
	s_waitcnt lgkmcnt(1)
	v_mfma_f32_32x32x16_bf16 v[112:127], v[234:237], v[226:229], v[112:127]
	v_mfma_f32_32x32x16_bf16 v[48:63], v[234:237], v[230:233], v[48:63]
	s_waitcnt lgkmcnt(0)
	v_mfma_f32_32x32x16_bf16 v[96:111], v[238:241], v[226:229], v[96:111]
	v_mfma_f32_32x32x16_bf16 v[32:47], v[238:241], v[230:233], v[32:47]
	ds_read_b128 v[234:237], v204 offset:9312
	ds_read_b128 v[238:241], v204 offset:13920
	s_waitcnt lgkmcnt(0)
	s_barrier
; template <bool trans>
; DI void gemm_core(const GTile& tl, const GTile& nx, bool has_next  , bool chain  , bool pre, u32x4 (&ra)[4], u32x4 (&rb)[4], char* smem, f32x16 (&acc)[2][4]) {
;     ...
;   const int nk = K / 64;
;   if (!pre) { G_LOAD(0); G_STORE(0); G_LOAD(1); }
;   for (int kt = 0; kt < nk; ++kt) {
;     __syncthreads();
;     G_COMPUTE(kt & 1, kt);
;   }
	s_waitcnt vmcnt(7)
	ds_write_b128 v215, v[176:179]
	s_waitcnt vmcnt(6)
	ds_write_b128 v215, v[180:183] offset:36864
	ds_read_b128 v[176:179], v208
	ds_read_b128 v[180:183], v208 offset:4608
	v_mfma_f32_32x32x16_bf16 v[80:95], v[234:237], v[226:229], v[80:95]
	v_mfma_f32_32x32x16_bf16 v[16:31], v[234:237], v[230:233], v[16:31]
	ds_read_b128 v[234:237], v192
	v_mfma_f32_32x32x16_bf16 v[64:79], v[238:241], v[226:229], v[64:79]
	v_mfma_f32_32x32x16_bf16 v[0:15], v[238:241], v[230:233], v[0:15]
	ds_read_b128 v[238:241], v192 offset:4608
	s_setprio 0
	global_load_dwordx4 v[226:229], v[190:191], off offset:2688
	global_load_dwordx4 v[230:233], v[188:189], off offset:2688
	s_setprio 1
	s_waitcnt lgkmcnt(1)
	v_mfma_f32_32x32x16_bf16 v[112:127], v[234:237], v[176:179], v[112:127]
	v_mfma_f32_32x32x16_bf16 v[48:63], v[234:237], v[180:183], v[48:63]
	s_waitcnt lgkmcnt(0)
	v_mfma_f32_32x32x16_bf16 v[96:111], v[238:241], v[176:179], v[96:111]
	v_mfma_f32_32x32x16_bf16 v[32:47], v[238:241], v[180:183], v[32:47]
	ds_read_b128 v[234:237], v192 offset:9216
	ds_read_b128 v[238:241], v192 offset:13824
	s_waitcnt vmcnt(7)
	ds_write_b128 v215, v[168:171] offset:9216
	s_waitcnt vmcnt(6)
	ds_write_b128 v215, v[172:175] offset:46080
	ds_read_b128 v[168:171], v208 offset:32
	ds_read_b128 v[172:175], v208 offset:4640
	s_waitcnt lgkmcnt(5)
	v_mfma_f32_32x32x16_bf16 v[80:95], v[234:237], v[176:179], v[80:95]
	v_mfma_f32_32x32x16_bf16 v[16:31], v[234:237], v[180:183], v[16:31]
	ds_read_b128 v[234:237], v192 offset:32
	s_waitcnt lgkmcnt(5)
	v_mfma_f32_32x32x16_bf16 v[64:79], v[238:241], v[176:179], v[64:79]
	v_mfma_f32_32x32x16_bf16 v[0:15], v[238:241], v[180:183], v[0:15]
	ds_read_b128 v[238:241], v192 offset:4640
	s_setprio 0
	global_load_dwordx4 v[176:179], v[194:195], off offset:2688
	global_load_dwordx4 v[180:183], v[196:197], off offset:2688
	s_setprio 1
	s_waitcnt lgkmcnt(1)
	v_mfma_f32_32x32x16_bf16 v[112:127], v[234:237], v[168:171], v[112:127]
	v_mfma_f32_32x32x16_bf16 v[48:63], v[234:237], v[172:175], v[48:63]
	s_waitcnt lgkmcnt(0)
	v_mfma_f32_32x32x16_bf16 v[96:111], v[238:241], v[168:171], v[96:111]
	v_mfma_f32_32x32x16_bf16 v[32:47], v[238:241], v[172:175], v[32:47]
	ds_read_b128 v[234:237], v192 offset:9248
	ds_read_b128 v[238:241], v192 offset:13856
	s_waitcnt vmcnt(7)
	ds_write_b128 v215, v[160:163] offset:18432
	s_waitcnt vmcnt(6)
	ds_write_b128 v215, v[164:167] offset:55296
	ds_read_b128 v[160:163], v208 offset:64
	ds_read_b128 v[164:167], v208 offset:4672
	s_waitcnt lgkmcnt(5)
	v_mfma_f32_32x32x16_bf16 v[80:95], v[234:237], v[168:171], v[80:95]
	v_mfma_f32_32x32x16_bf16 v[16:31], v[234:237], v[172:175], v[16:31]
	ds_read_b128 v[234:237], v192 offset:64
	s_waitcnt lgkmcnt(5)
	v_mfma_f32_32x32x16_bf16 v[64:79], v[238:241], v[168:171], v[64:79]
	v_mfma_f32_32x32x16_bf16 v[0:15], v[238:241], v[172:175], v[0:15]
	ds_read_b128 v[238:241], v192 offset:4672
	s_setprio 0
	global_load_dwordx4 v[168:171], v[184:185], off offset:2688
	global_load_dwordx4 v[172:175], v[186:187], off offset:2688
	s_setprio 1
	s_waitcnt lgkmcnt(1)
	v_mfma_f32_32x32x16_bf16 v[112:127], v[234:237], v[160:163], v[112:127]
	v_mfma_f32_32x32x16_bf16 v[48:63], v[234:237], v[164:167], v[48:63]
	s_waitcnt lgkmcnt(0)
	v_mfma_f32_32x32x16_bf16 v[96:111], v[238:241], v[160:163], v[96:111]
	v_mfma_f32_32x32x16_bf16 v[32:47], v[238:241], v[164:167], v[32:47]
	ds_read_b128 v[234:237], v192 offset:9280
	ds_read_b128 v[238:241], v192 offset:13888
	s_waitcnt vmcnt(7)
	ds_write_b128 v215, v[218:221] offset:27648
	s_waitcnt vmcnt(6)
	ds_write_b128 v215, v[222:225] offset:64512
	ds_read_b128 v[218:221], v208 offset:96
	ds_read_b128 v[222:225], v208 offset:4704
	s_waitcnt lgkmcnt(5)
	v_mfma_f32_32x32x16_bf16 v[80:95], v[234:237], v[160:163], v[80:95]
	v_mfma_f32_32x32x16_bf16 v[16:31], v[234:237], v[164:167], v[16:31]
	ds_read_b128 v[234:237], v192 offset:96
	s_waitcnt lgkmcnt(5)
	v_mfma_f32_32x32x16_bf16 v[64:79], v[238:241], v[160:163], v[64:79]
	v_mfma_f32_32x32x16_bf16 v[0:15], v[238:241], v[164:167], v[0:15]
	ds_read_b128 v[238:241], v192 offset:4704
	s_setprio 0
	global_load_dwordx4 v[160:163], v[198:199], off offset:2688
	global_load_dwordx4 v[164:167], v[200:201], off offset:2688
	s_setprio 1
	s_waitcnt lgkmcnt(1)
	v_mfma_f32_32x32x16_bf16 v[112:127], v[234:237], v[218:221], v[112:127]
	v_mfma_f32_32x32x16_bf16 v[48:63], v[234:237], v[222:225], v[48:63]
	s_waitcnt lgkmcnt(0)
	v_mfma_f32_32x32x16_bf16 v[96:111], v[238:241], v[218:221], v[96:111]
	v_mfma_f32_32x32x16_bf16 v[32:47], v[238:241], v[222:225], v[32:47]
	ds_read_b128 v[234:237], v192 offset:9312
	ds_read_b128 v[238:241], v192 offset:13920
	s_waitcnt lgkmcnt(0)
	s_barrier
; template <bool trans>
; DI void gemm_core(const GTile& tl, const GTile& nx, bool has_next  , bool chain  , bool pre, u32x4 (&ra)[4], u32x4 (&rb)[4], char* smem, f32x16 (&acc)[2][4]) {
;     ...
;   const int nk = K / 64;
;   if (!pre) { G_LOAD(0); G_STORE(0); G_LOAD(1); }
;   for (int kt = 0; kt < nk; ++kt) {
;     __syncthreads();
;     G_COMPUTE(kt & 1, kt);
;   }
	s_waitcnt vmcnt(7)
	ds_write_b128 v209, v[226:229]
	s_waitcnt vmcnt(6)
	ds_write_b128 v210, v[230:233]
	ds_read_b128 v[226:229], v205 offset:36864
	ds_read_b128 v[230:233], v205 offset:41472
	v_mfma_f32_32x32x16_bf16 v[80:95], v[234:237], v[218:221], v[80:95]
	v_mfma_f32_32x32x16_bf16 v[16:31], v[234:237], v[222:225], v[16:31]
	ds_read_b128 v[234:237], v204
	v_mfma_f32_32x32x16_bf16 v[64:79], v[238:241], v[218:221], v[64:79]
	v_mfma_f32_32x32x16_bf16 v[0:15], v[238:241], v[222:225], v[0:15]
	ds_read_b128 v[238:241], v204 offset:4608
	s_setprio 0
	global_load_dwordx4 v[218:221], v[190:191], off offset:2816
	global_load_dwordx4 v[222:225], v[188:189], off offset:2816
	s_setprio 1
	s_waitcnt lgkmcnt(1)
	v_mfma_f32_32x32x16_bf16 v[112:127], v[234:237], v[226:229], v[112:127]
	v_mfma_f32_32x32x16_bf16 v[48:63], v[234:237], v[230:233], v[48:63]
	s_waitcnt lgkmcnt(0)
	v_mfma_f32_32x32x16_bf16 v[96:111], v[238:241], v[226:229], v[96:111]
	v_mfma_f32_32x32x16_bf16 v[32:47], v[238:241], v[230:233], v[32:47]
	ds_read_b128 v[234:237], v204 offset:9216
	ds_read_b128 v[238:241], v204 offset:13824
	s_waitcnt vmcnt(7)
	ds_write_b128 v212, v[176:179]
	s_waitcnt vmcnt(6)
	ds_write_b128 v211, v[180:183]
	ds_read_b128 v[176:179], v205 offset:36896
	ds_read_b128 v[180:183], v205 offset:41504
	s_waitcnt lgkmcnt(5)
	v_mfma_f32_32x32x16_bf16 v[80:95], v[234:237], v[226:229], v[80:95]
	v_mfma_f32_32x32x16_bf16 v[16:31], v[234:237], v[230:233], v[16:31]
	ds_read_b128 v[234:237], v204 offset:32
	s_waitcnt lgkmcnt(5)
	v_mfma_f32_32x32x16_bf16 v[64:79], v[238:241], v[226:229], v[64:79]
	v_mfma_f32_32x32x16_bf16 v[0:15], v[238:241], v[230:233], v[0:15]
	ds_read_b128 v[238:241], v204 offset:4640
	s_setprio 0
	global_load_dwordx4 v[226:229], v[194:195], off offset:2816
	global_load_dwordx4 v[230:233], v[196:197], off offset:2816
	s_setprio 1
	s_waitcnt lgkmcnt(1)
	v_mfma_f32_32x32x16_bf16 v[112:127], v[234:237], v[176:179], v[112:127]
	v_mfma_f32_32x32x16_bf16 v[48:63], v[234:237], v[180:183], v[48:63]
	s_waitcnt lgkmcnt(0)
	v_mfma_f32_32x32x16_bf16 v[96:111], v[238:241], v[176:179], v[96:111]
	v_mfma_f32_32x32x16_bf16 v[32:47], v[238:241], v[180:183], v[32:47]
	ds_read_b128 v[234:237], v204 offset:9248
	ds_read_b128 v[238:241], v204 offset:13856
	s_waitcnt vmcnt(7)
	ds_write_b128 v214, v[168:171]
	s_waitcnt vmcnt(6)
	ds_write_b128 v213, v[172:175]
	ds_read_b128 v[168:171], v205 offset:36928
	ds_read_b128 v[172:175], v205 offset:41536
	s_waitcnt lgkmcnt(5)
	v_mfma_f32_32x32x16_bf16 v[80:95], v[234:237], v[176:179], v[80:95]
	v_mfma_f32_32x32x16_bf16 v[16:31], v[234:237], v[180:183], v[16:31]
	ds_read_b128 v[234:237], v204 offset:64
	s_waitcnt lgkmcnt(5)
	v_mfma_f32_32x32x16_bf16 v[64:79], v[238:241], v[176:179], v[64:79]
	v_mfma_f32_32x32x16_bf16 v[0:15], v[238:241], v[180:183], v[0:15]
	ds_read_b128 v[238:241], v204 offset:4672
	s_setprio 0
	global_load_dwordx4 v[176:179], v[184:185], off offset:2816
	global_load_dwordx4 v[180:183], v[186:187], off offset:2816
	s_setprio 1
	s_waitcnt lgkmcnt(1)
	v_mfma_f32_32x32x16_bf16 v[112:127], v[234:237], v[168:171], v[112:127]
	v_mfma_f32_32x32x16_bf16 v[48:63], v[234:237], v[172:175], v[48:63]
	s_waitcnt lgkmcnt(0)
	v_mfma_f32_32x32x16_bf16 v[96:111], v[238:241], v[168:171], v[96:111]
	v_mfma_f32_32x32x16_bf16 v[32:47], v[238:241], v[172:175], v[32:47]
	ds_read_b128 v[234:237], v204 offset:9280
	ds_read_b128 v[238:241], v204 offset:13888
	s_waitcnt vmcnt(7)
	ds_write_b128 v217, v[160:163]
	s_waitcnt vmcnt(6)
	ds_write_b128 v216, v[164:167]
	ds_read_b128 v[160:163], v205 offset:36960
	ds_read_b128 v[164:167], v205 offset:41568
	s_waitcnt lgkmcnt(5)
	v_mfma_f32_32x32x16_bf16 v[80:95], v[234:237], v[168:171], v[80:95]
	v_mfma_f32_32x32x16_bf16 v[16:31], v[234:237], v[172:175], v[16:31]
	ds_read_b128 v[234:237], v204 offset:96
	s_waitcnt lgkmcnt(5)
	v_mfma_f32_32x32x16_bf16 v[64:79], v[238:241], v[168:171], v[64:79]
	v_mfma_f32_32x32x16_bf16 v[0:15], v[238:241], v[172:175], v[0:15]
	ds_read_b128 v[238:241], v204 offset:4704
	s_setprio 0
	global_load_dwordx4 v[168:171], v[198:199], off offset:2816
	global_load_dwordx4 v[172:175], v[200:201], off offset:2816
	s_setprio 1
	s_waitcnt lgkmcnt(1)
	v_mfma_f32_32x32x16_bf16 v[112:127], v[234:237], v[160:163], v[112:127]
	v_mfma_f32_32x32x16_bf16 v[48:63], v[234:237], v[164:167], v[48:63]
	s_waitcnt lgkmcnt(0)
	v_mfma_f32_32x32x16_bf16 v[96:111], v[238:241], v[160:163], v[96:111]
	v_mfma_f32_32x32x16_bf16 v[32:47], v[238:241], v[164:167], v[32:47]
	ds_read_b128 v[234:237], v204 offset:9312
	ds_read_b128 v[238:241], v204 offset:13920
	s_waitcnt lgkmcnt(0)
	s_barrier
; template <bool trans>
; DI void gemm_core(const GTile& tl, const GTile& nx, bool has_next  , bool chain  , bool pre, u32x4 (&ra)[4], u32x4 (&rb)[4], char* smem, f32x16 (&acc)[2][4]) {
;     ...
;   const int nk = K / 64;
;   if (!pre) { G_LOAD(0); G_STORE(0); G_LOAD(1); }
;   for (int kt = 0; kt < nk; ++kt) {
;     __syncthreads();
;     G_COMPUTE(kt & 1, kt);
;   }
	s_waitcnt vmcnt(7)
	ds_write_b128 v215, v[218:221]
	s_waitcnt vmcnt(6)
	ds_write_b128 v215, v[222:225] offset:36864
	ds_read_b128 v[218:221], v208
	ds_read_b128 v[222:225], v208 offset:4608
	v_mfma_f32_32x32x16_bf16 v[80:95], v[234:237], v[160:163], v[80:95]
	v_mfma_f32_32x32x16_bf16 v[16:31], v[234:237], v[164:167], v[16:31]
	ds_read_b128 v[234:237], v192
	v_mfma_f32_32x32x16_bf16 v[64:79], v[238:241], v[160:163], v[64:79]
	v_mfma_f32_32x32x16_bf16 v[0:15], v[238:241], v[164:167], v[0:15]
	ds_read_b128 v[238:241], v192 offset:4608
	s_setprio 0
	global_load_dwordx4 v[160:163], v[190:191], off offset:2944
	global_load_dwordx4 v[164:167], v[188:189], off offset:2944
	s_setprio 1
	s_waitcnt lgkmcnt(1)
	v_mfma_f32_32x32x16_bf16 v[112:127], v[234:237], v[218:221], v[112:127]
	v_mfma_f32_32x32x16_bf16 v[48:63], v[234:237], v[222:225], v[48:63]
	s_waitcnt lgkmcnt(0)
	v_mfma_f32_32x32x16_bf16 v[96:111], v[238:241], v[218:221], v[96:111]
	v_mfma_f32_32x32x16_bf16 v[32:47], v[238:241], v[222:225], v[32:47]
	ds_read_b128 v[234:237], v192 offset:9216
	ds_read_b128 v[238:241], v192 offset:13824
	s_waitcnt vmcnt(7)
	ds_write_b128 v215, v[226:229] offset:9216
	s_waitcnt vmcnt(6)
	ds_write_b128 v215, v[230:233] offset:46080
	ds_read_b128 v[226:229], v208 offset:32
	ds_read_b128 v[230:233], v208 offset:4640
	s_waitcnt lgkmcnt(5)
	v_mfma_f32_32x32x16_bf16 v[80:95], v[234:237], v[218:221], v[80:95]
	v_mfma_f32_32x32x16_bf16 v[16:31], v[234:237], v[222:225], v[16:31]
	ds_read_b128 v[234:237], v192 offset:32
	s_waitcnt lgkmcnt(5)
	v_mfma_f32_32x32x16_bf16 v[64:79], v[238:241], v[218:221], v[64:79]
	v_mfma_f32_32x32x16_bf16 v[0:15], v[238:241], v[222:225], v[0:15]
	ds_read_b128 v[238:241], v192 offset:4640
	s_setprio 0
	global_load_dwordx4 v[218:221], v[194:195], off offset:2944
	global_load_dwordx4 v[222:225], v[196:197], off offset:2944
	s_setprio 1
	s_waitcnt lgkmcnt(1)
	v_mfma_f32_32x32x16_bf16 v[112:127], v[234:237], v[226:229], v[112:127]
	v_mfma_f32_32x32x16_bf16 v[48:63], v[234:237], v[230:233], v[48:63]
	s_waitcnt lgkmcnt(0)
	v_mfma_f32_32x32x16_bf16 v[96:111], v[238:241], v[226:229], v[96:111]
	v_mfma_f32_32x32x16_bf16 v[32:47], v[238:241], v[230:233], v[32:47]
	ds_read_b128 v[234:237], v192 offset:9248
	ds_read_b128 v[238:241], v192 offset:13856
	s_waitcnt vmcnt(7)
	ds_write_b128 v215, v[176:179] offset:18432
	s_waitcnt vmcnt(6)
	ds_write_b128 v215, v[180:183] offset:55296
	ds_read_b128 v[176:179], v208 offset:64
	ds_read_b128 v[180:183], v208 offset:4672
	s_waitcnt lgkmcnt(5)
	v_mfma_f32_32x32x16_bf16 v[80:95], v[234:237], v[226:229], v[80:95]
	v_mfma_f32_32x32x16_bf16 v[16:31], v[234:237], v[230:233], v[16:31]
	ds_read_b128 v[234:237], v192 offset:64
	s_waitcnt lgkmcnt(5)
	v_mfma_f32_32x32x16_bf16 v[64:79], v[238:241], v[226:229], v[64:79]
	v_mfma_f32_32x32x16_bf16 v[0:15], v[238:241], v[230:233], v[0:15]
	ds_read_b128 v[238:241], v192 offset:4672
	s_setprio 0
	global_load_dwordx4 v[226:229], v[184:185], off offset:2944
	global_load_dwordx4 v[230:233], v[186:187], off offset:2944
	s_setprio 1
	s_waitcnt lgkmcnt(1)
	v_mfma_f32_32x32x16_bf16 v[112:127], v[234:237], v[176:179], v[112:127]
	v_mfma_f32_32x32x16_bf16 v[48:63], v[234:237], v[180:183], v[48:63]
	s_waitcnt lgkmcnt(0)
	v_mfma_f32_32x32x16_bf16 v[96:111], v[238:241], v[176:179], v[96:111]
	v_mfma_f32_32x32x16_bf16 v[32:47], v[238:241], v[180:183], v[32:47]
	ds_read_b128 v[234:237], v192 offset:9280
	ds_read_b128 v[238:241], v192 offset:13888
	s_waitcnt vmcnt(7)
	ds_write_b128 v215, v[168:171] offset:27648
	s_waitcnt vmcnt(6)
	ds_write_b128 v215, v[172:175] offset:64512
	ds_read_b128 v[168:171], v208 offset:96
	ds_read_b128 v[172:175], v208 offset:4704
	s_waitcnt lgkmcnt(5)
	v_mfma_f32_32x32x16_bf16 v[80:95], v[234:237], v[176:179], v[80:95]
	v_mfma_f32_32x32x16_bf16 v[16:31], v[234:237], v[180:183], v[16:31]
	ds_read_b128 v[234:237], v192 offset:96
	s_waitcnt lgkmcnt(5)
	v_mfma_f32_32x32x16_bf16 v[64:79], v[238:241], v[176:179], v[64:79]
	v_mfma_f32_32x32x16_bf16 v[0:15], v[238:241], v[180:183], v[0:15]
	ds_read_b128 v[238:241], v192 offset:4704
	s_setprio 0
	global_load_dwordx4 v[176:179], v[198:199], off offset:2944
	global_load_dwordx4 v[180:183], v[200:201], off offset:2944
	s_setprio 1
	s_waitcnt lgkmcnt(1)
	v_mfma_f32_32x32x16_bf16 v[112:127], v[234:237], v[168:171], v[112:127]
	v_mfma_f32_32x32x16_bf16 v[48:63], v[234:237], v[172:175], v[48:63]
	s_waitcnt lgkmcnt(0)
	v_mfma_f32_32x32x16_bf16 v[96:111], v[238:241], v[168:171], v[96:111]
	v_mfma_f32_32x32x16_bf16 v[32:47], v[238:241], v[172:175], v[32:47]
	ds_read_b128 v[234:237], v192 offset:9312
	ds_read_b128 v[238:241], v192 offset:13920
	s_waitcnt lgkmcnt(0)
	s_barrier
; template <bool trans>
; DI void gemm_core(const GTile& tl, const GTile& nx, bool has_next  , bool chain  , bool pre, u32x4 (&ra)[4], u32x4 (&rb)[4], char* smem, f32x16 (&acc)[2][4]) {
;     ...
;   const int nk = K / 64;
;   if (!pre) { G_LOAD(0); G_STORE(0); G_LOAD(1); }
;   for (int kt = 0; kt < nk; ++kt) {
;     __syncthreads();
;     G_COMPUTE(kt & 1, kt);
;   }
	s_waitcnt vmcnt(7)
	ds_write_b128 v209, v[160:163]
	s_waitcnt vmcnt(6)
	ds_write_b128 v210, v[164:167]
	ds_read_b128 v[160:163], v205 offset:36864
	ds_read_b128 v[164:167], v205 offset:41472
	v_mfma_f32_32x32x16_bf16 v[80:95], v[234:237], v[168:171], v[80:95]
	v_mfma_f32_32x32x16_bf16 v[16:31], v[234:237], v[172:175], v[16:31]
	ds_read_b128 v[234:237], v204
	v_mfma_f32_32x32x16_bf16 v[64:79], v[238:241], v[168:171], v[64:79]
	v_mfma_f32_32x32x16_bf16 v[0:15], v[238:241], v[172:175], v[0:15]
	ds_read_b128 v[238:241], v204 offset:4608
	s_setprio 0
	global_load_dwordx4 v[168:171], v[190:191], off offset:3072
	global_load_dwordx4 v[172:175], v[188:189], off offset:3072
	s_setprio 1
	s_waitcnt lgkmcnt(1)
	v_mfma_f32_32x32x16_bf16 v[112:127], v[234:237], v[160:163], v[112:127]
	v_mfma_f32_32x32x16_bf16 v[48:63], v[234:237], v[164:167], v[48:63]
	s_waitcnt lgkmcnt(0)
	v_mfma_f32_32x32x16_bf16 v[96:111], v[238:241], v[160:163], v[96:111]
	v_mfma_f32_32x32x16_bf16 v[32:47], v[238:241], v[164:167], v[32:47]
	ds_read_b128 v[234:237], v204 offset:9216
	ds_read_b128 v[238:241], v204 offset:13824
	s_waitcnt vmcnt(7)
	ds_write_b128 v212, v[218:221]
	s_waitcnt vmcnt(6)
	ds_write_b128 v211, v[222:225]
	ds_read_b128 v[218:221], v205 offset:36896
	ds_read_b128 v[222:225], v205 offset:41504
	s_waitcnt lgkmcnt(5)
	v_mfma_f32_32x32x16_bf16 v[80:95], v[234:237], v[160:163], v[80:95]
	v_mfma_f32_32x32x16_bf16 v[16:31], v[234:237], v[164:167], v[16:31]
	ds_read_b128 v[234:237], v204 offset:32
	s_waitcnt lgkmcnt(5)
	v_mfma_f32_32x32x16_bf16 v[64:79], v[238:241], v[160:163], v[64:79]
	v_mfma_f32_32x32x16_bf16 v[0:15], v[238:241], v[164:167], v[0:15]
	ds_read_b128 v[238:241], v204 offset:4640
	s_setprio 0
	global_load_dwordx4 v[160:163], v[194:195], off offset:3072
	global_load_dwordx4 v[164:167], v[196:197], off offset:3072
	s_setprio 1
	s_waitcnt lgkmcnt(1)
	v_mfma_f32_32x32x16_bf16 v[112:127], v[234:237], v[218:221], v[112:127]
	v_mfma_f32_32x32x16_bf16 v[48:63], v[234:237], v[222:225], v[48:63]
	s_waitcnt lgkmcnt(0)
	v_mfma_f32_32x32x16_bf16 v[96:111], v[238:241], v[218:221], v[96:111]
	v_mfma_f32_32x32x16_bf16 v[32:47], v[238:241], v[222:225], v[32:47]
	ds_read_b128 v[234:237], v204 offset:9248
	ds_read_b128 v[238:241], v204 offset:13856
	s_waitcnt vmcnt(7)
	ds_write_b128 v214, v[226:229]
	s_waitcnt vmcnt(6)
	ds_write_b128 v213, v[230:233]
	ds_read_b128 v[226:229], v205 offset:36928
	ds_read_b128 v[230:233], v205 offset:41536
	s_waitcnt lgkmcnt(5)
	v_mfma_f32_32x32x16_bf16 v[80:95], v[234:237], v[218:221], v[80:95]
	v_mfma_f32_32x32x16_bf16 v[16:31], v[234:237], v[222:225], v[16:31]
	ds_read_b128 v[234:237], v204 offset:64
	s_waitcnt lgkmcnt(5)
	v_mfma_f32_32x32x16_bf16 v[64:79], v[238:241], v[218:221], v[64:79]
	v_mfma_f32_32x32x16_bf16 v[0:15], v[238:241], v[222:225], v[0:15]
	ds_read_b128 v[238:241], v204 offset:4672
	s_setprio 0
	global_load_dwordx4 v[218:221], v[184:185], off offset:3072
	global_load_dwordx4 v[222:225], v[186:187], off offset:3072
	s_setprio 1
	s_waitcnt lgkmcnt(1)
	v_mfma_f32_32x32x16_bf16 v[112:127], v[234:237], v[226:229], v[112:127]
	v_mfma_f32_32x32x16_bf16 v[48:63], v[234:237], v[230:233], v[48:63]
	s_waitcnt lgkmcnt(0)
	v_mfma_f32_32x32x16_bf16 v[96:111], v[238:241], v[226:229], v[96:111]
	v_mfma_f32_32x32x16_bf16 v[32:47], v[238:241], v[230:233], v[32:47]
	ds_read_b128 v[234:237], v204 offset:9280
	ds_read_b128 v[238:241], v204 offset:13888
	s_waitcnt vmcnt(7)
	ds_write_b128 v217, v[176:179]
	s_waitcnt vmcnt(6)
	ds_write_b128 v216, v[180:183]
	ds_read_b128 v[176:179], v205 offset:36960
	ds_read_b128 v[180:183], v205 offset:41568
	s_waitcnt lgkmcnt(5)
	v_mfma_f32_32x32x16_bf16 v[80:95], v[234:237], v[226:229], v[80:95]
	v_mfma_f32_32x32x16_bf16 v[16:31], v[234:237], v[230:233], v[16:31]
	ds_read_b128 v[234:237], v204 offset:96
	s_waitcnt lgkmcnt(5)
	v_mfma_f32_32x32x16_bf16 v[64:79], v[238:241], v[226:229], v[64:79]
	v_mfma_f32_32x32x16_bf16 v[0:15], v[238:241], v[230:233], v[0:15]
	ds_read_b128 v[238:241], v204 offset:4704
	s_setprio 0
	global_load_dwordx4 v[226:229], v[198:199], off offset:3072
	global_load_dwordx4 v[230:233], v[200:201], off offset:3072
	s_setprio 1
	s_waitcnt lgkmcnt(1)
	v_mfma_f32_32x32x16_bf16 v[112:127], v[234:237], v[176:179], v[112:127]
	v_mfma_f32_32x32x16_bf16 v[48:63], v[234:237], v[180:183], v[48:63]
	s_waitcnt lgkmcnt(0)
	v_mfma_f32_32x32x16_bf16 v[96:111], v[238:241], v[176:179], v[96:111]
	v_mfma_f32_32x32x16_bf16 v[32:47], v[238:241], v[180:183], v[32:47]
	ds_read_b128 v[234:237], v204 offset:9312
	ds_read_b128 v[238:241], v204 offset:13920
	s_waitcnt lgkmcnt(0)
	s_barrier
; template <bool trans>
; DI void gemm_core(const GTile& tl, const GTile& nx, bool has_next  , bool chain  , bool pre, u32x4 (&ra)[4], u32x4 (&rb)[4], char* smem, f32x16 (&acc)[2][4]) {
;     ...
;   const int nk = K / 64;
;   if (!pre) { G_LOAD(0); G_STORE(0); G_LOAD(1); }
;   for (int kt = 0; kt < nk; ++kt) {
;     __syncthreads();
;     G_COMPUTE(kt & 1, kt);
;   }
	s_waitcnt vmcnt(7)
	ds_write_b128 v215, v[168:171]
	s_waitcnt vmcnt(6)
	ds_write_b128 v215, v[172:175] offset:36864
	ds_read_b128 v[168:171], v208
	ds_read_b128 v[172:175], v208 offset:4608
	v_mfma_f32_32x32x16_bf16 v[80:95], v[234:237], v[176:179], v[80:95]
	v_mfma_f32_32x32x16_bf16 v[16:31], v[234:237], v[180:183], v[16:31]
	ds_read_b128 v[234:237], v192
	v_mfma_f32_32x32x16_bf16 v[64:79], v[238:241], v[176:179], v[64:79]
	v_mfma_f32_32x32x16_bf16 v[0:15], v[238:241], v[180:183], v[0:15]
	ds_read_b128 v[238:241], v192 offset:4608
	s_setprio 0
	global_load_dwordx4 v[176:179], v[190:191], off offset:3200
	global_load_dwordx4 v[180:183], v[188:189], off offset:3200
	s_setprio 1
	s_waitcnt lgkmcnt(1)
	v_mfma_f32_32x32x16_bf16 v[112:127], v[234:237], v[168:171], v[112:127]
	v_mfma_f32_32x32x16_bf16 v[48:63], v[234:237], v[172:175], v[48:63]
	s_waitcnt lgkmcnt(0)
	v_mfma_f32_32x32x16_bf16 v[96:111], v[238:241], v[168:171], v[96:111]
	v_mfma_f32_32x32x16_bf16 v[32:47], v[238:241], v[172:175], v[32:47]
	ds_read_b128 v[234:237], v192 offset:9216
	ds_read_b128 v[238:241], v192 offset:13824
	s_waitcnt vmcnt(7)
	ds_write_b128 v215, v[160:163] offset:9216
	s_waitcnt vmcnt(6)
	ds_write_b128 v215, v[164:167] offset:46080
	ds_read_b128 v[160:163], v208 offset:32
	ds_read_b128 v[164:167], v208 offset:4640
	s_waitcnt lgkmcnt(5)
	v_mfma_f32_32x32x16_bf16 v[80:95], v[234:237], v[168:171], v[80:95]
	v_mfma_f32_32x32x16_bf16 v[16:31], v[234:237], v[172:175], v[16:31]
	ds_read_b128 v[234:237], v192 offset:32
	s_waitcnt lgkmcnt(5)
	v_mfma_f32_32x32x16_bf16 v[64:79], v[238:241], v[168:171], v[64:79]
	v_mfma_f32_32x32x16_bf16 v[0:15], v[238:241], v[172:175], v[0:15]
	ds_read_b128 v[238:241], v192 offset:4640
	s_setprio 0
	global_load_dwordx4 v[168:171], v[194:195], off offset:3200
	global_load_dwordx4 v[172:175], v[196:197], off offset:3200
	s_setprio 1
	s_waitcnt lgkmcnt(1)
	v_mfma_f32_32x32x16_bf16 v[112:127], v[234:237], v[160:163], v[112:127]
	v_mfma_f32_32x32x16_bf16 v[48:63], v[234:237], v[164:167], v[48:63]
	s_waitcnt lgkmcnt(0)
	v_mfma_f32_32x32x16_bf16 v[96:111], v[238:241], v[160:163], v[96:111]
	v_mfma_f32_32x32x16_bf16 v[32:47], v[238:241], v[164:167], v[32:47]
	ds_read_b128 v[234:237], v192 offset:9248
	ds_read_b128 v[238:241], v192 offset:13856
	s_waitcnt vmcnt(7)
	ds_write_b128 v215, v[218:221] offset:18432
	s_waitcnt vmcnt(6)
	ds_write_b128 v215, v[222:225] offset:55296
	ds_read_b128 v[218:221], v208 offset:64
	ds_read_b128 v[222:225], v208 offset:4672
	s_waitcnt lgkmcnt(5)
	v_mfma_f32_32x32x16_bf16 v[80:95], v[234:237], v[160:163], v[80:95]
	v_mfma_f32_32x32x16_bf16 v[16:31], v[234:237], v[164:167], v[16:31]
	ds_read_b128 v[234:237], v192 offset:64
	s_waitcnt lgkmcnt(5)
	v_mfma_f32_32x32x16_bf16 v[64:79], v[238:241], v[160:163], v[64:79]
	v_mfma_f32_32x32x16_bf16 v[0:15], v[238:241], v[164:167], v[0:15]
	ds_read_b128 v[238:241], v192 offset:4672
	s_setprio 0
	global_load_dwordx4 v[160:163], v[184:185], off offset:3200
	global_load_dwordx4 v[164:167], v[186:187], off offset:3200
	s_setprio 1
	s_waitcnt lgkmcnt(1)
	v_mfma_f32_32x32x16_bf16 v[112:127], v[234:237], v[218:221], v[112:127]
	v_mfma_f32_32x32x16_bf16 v[48:63], v[234:237], v[222:225], v[48:63]
	s_waitcnt lgkmcnt(0)
	v_mfma_f32_32x32x16_bf16 v[96:111], v[238:241], v[218:221], v[96:111]
	v_mfma_f32_32x32x16_bf16 v[32:47], v[238:241], v[222:225], v[32:47]
	ds_read_b128 v[234:237], v192 offset:9280
	ds_read_b128 v[238:241], v192 offset:13888
	s_waitcnt vmcnt(7)
	ds_write_b128 v215, v[226:229] offset:27648
	s_waitcnt vmcnt(6)
	ds_write_b128 v215, v[230:233] offset:64512
	ds_read_b128 v[226:229], v208 offset:96
	ds_read_b128 v[230:233], v208 offset:4704
	s_waitcnt lgkmcnt(5)
	v_mfma_f32_32x32x16_bf16 v[80:95], v[234:237], v[218:221], v[80:95]
	v_mfma_f32_32x32x16_bf16 v[16:31], v[234:237], v[222:225], v[16:31]
	ds_read_b128 v[234:237], v192 offset:96
	s_waitcnt lgkmcnt(5)
	v_mfma_f32_32x32x16_bf16 v[64:79], v[238:241], v[218:221], v[64:79]
	v_mfma_f32_32x32x16_bf16 v[0:15], v[238:241], v[222:225], v[0:15]
	ds_read_b128 v[238:241], v192 offset:4704
	s_setprio 0
	global_load_dwordx4 v[218:221], v[198:199], off offset:3200
	global_load_dwordx4 v[222:225], v[200:201], off offset:3200
	s_setprio 1
	s_waitcnt lgkmcnt(1)
	v_mfma_f32_32x32x16_bf16 v[112:127], v[234:237], v[226:229], v[112:127]
	v_mfma_f32_32x32x16_bf16 v[48:63], v[234:237], v[230:233], v[48:63]
	s_waitcnt lgkmcnt(0)
	v_mfma_f32_32x32x16_bf16 v[96:111], v[238:241], v[226:229], v[96:111]
	v_mfma_f32_32x32x16_bf16 v[32:47], v[238:241], v[230:233], v[32:47]
	ds_read_b128 v[234:237], v192 offset:9312
	ds_read_b128 v[238:241], v192 offset:13920
	s_waitcnt lgkmcnt(0)
	s_barrier
; template <bool trans>
; DI void gemm_core(const GTile& tl, const GTile& nx, bool has_next  , bool chain  , bool pre, u32x4 (&ra)[4], u32x4 (&rb)[4], char* smem, f32x16 (&acc)[2][4]) {
;     ...
;   const int nk = K / 64;
;   if (!pre) { G_LOAD(0); G_STORE(0); G_LOAD(1); }
;   for (int kt = 0; kt < nk; ++kt) {
;     __syncthreads();
;     G_COMPUTE(kt & 1, kt);
;   }
	s_waitcnt vmcnt(7)
	ds_write_b128 v209, v[176:179]
	s_waitcnt vmcnt(6)
	ds_write_b128 v210, v[180:183]
	ds_read_b128 v[176:179], v205 offset:36864
	ds_read_b128 v[180:183], v205 offset:41472
	v_mfma_f32_32x32x16_bf16 v[80:95], v[234:237], v[226:229], v[80:95]
	v_mfma_f32_32x32x16_bf16 v[16:31], v[234:237], v[230:233], v[16:31]
	ds_read_b128 v[234:237], v204
	v_mfma_f32_32x32x16_bf16 v[64:79], v[238:241], v[226:229], v[64:79]
	v_mfma_f32_32x32x16_bf16 v[0:15], v[238:241], v[230:233], v[0:15]
	ds_read_b128 v[238:241], v204 offset:4608
	s_setprio 0
	global_load_dwordx4 v[226:229], v[190:191], off offset:3328
	global_load_dwordx4 v[230:233], v[188:189], off offset:3328
	s_setprio 1
	s_waitcnt lgkmcnt(1)
	v_mfma_f32_32x32x16_bf16 v[112:127], v[234:237], v[176:179], v[112:127]
	v_mfma_f32_32x32x16_bf16 v[48:63], v[234:237], v[180:183], v[48:63]
	s_waitcnt lgkmcnt(0)
	v_mfma_f32_32x32x16_bf16 v[96:111], v[238:241], v[176:179], v[96:111]
	v_mfma_f32_32x32x16_bf16 v[32:47], v[238:241], v[180:183], v[32:47]
	ds_read_b128 v[234:237], v204 offset:9216
	ds_read_b128 v[238:241], v204 offset:13824
	s_waitcnt vmcnt(7)
	ds_write_b128 v212, v[168:171]
	s_waitcnt vmcnt(6)
	ds_write_b128 v211, v[172:175]
	ds_read_b128 v[168:171], v205 offset:36896
	ds_read_b128 v[172:175], v205 offset:41504
	s_waitcnt lgkmcnt(5)
	v_mfma_f32_32x32x16_bf16 v[80:95], v[234:237], v[176:179], v[80:95]
	v_mfma_f32_32x32x16_bf16 v[16:31], v[234:237], v[180:183], v[16:31]
	ds_read_b128 v[234:237], v204 offset:32
	s_waitcnt lgkmcnt(5)
	v_mfma_f32_32x32x16_bf16 v[64:79], v[238:241], v[176:179], v[64:79]
	v_mfma_f32_32x32x16_bf16 v[0:15], v[238:241], v[180:183], v[0:15]
	ds_read_b128 v[238:241], v204 offset:4640
	s_setprio 0
	global_load_dwordx4 v[176:179], v[194:195], off offset:3328
	global_load_dwordx4 v[180:183], v[196:197], off offset:3328
	s_setprio 1
	s_waitcnt lgkmcnt(1)
	v_mfma_f32_32x32x16_bf16 v[112:127], v[234:237], v[168:171], v[112:127]
	v_mfma_f32_32x32x16_bf16 v[48:63], v[234:237], v[172:175], v[48:63]
	s_waitcnt lgkmcnt(0)
	v_mfma_f32_32x32x16_bf16 v[96:111], v[238:241], v[168:171], v[96:111]
	v_mfma_f32_32x32x16_bf16 v[32:47], v[238:241], v[172:175], v[32:47]
	ds_read_b128 v[234:237], v204 offset:9248
	ds_read_b128 v[238:241], v204 offset:13856
	s_waitcnt vmcnt(7)
	ds_write_b128 v214, v[160:163]
	s_waitcnt vmcnt(6)
	ds_write_b128 v213, v[164:167]
	ds_read_b128 v[160:163], v205 offset:36928
	ds_read_b128 v[164:167], v205 offset:41536
	s_waitcnt lgkmcnt(5)
	v_mfma_f32_32x32x16_bf16 v[80:95], v[234:237], v[168:171], v[80:95]
	v_mfma_f32_32x32x16_bf16 v[16:31], v[234:237], v[172:175], v[16:31]
	ds_read_b128 v[234:237], v204 offset:64
	s_waitcnt lgkmcnt(5)
	v_mfma_f32_32x32x16_bf16 v[64:79], v[238:241], v[168:171], v[64:79]
	v_mfma_f32_32x32x16_bf16 v[0:15], v[238:241], v[172:175], v[0:15]
	ds_read_b128 v[238:241], v204 offset:4672
	s_setprio 0
	global_load_dwordx4 v[168:171], v[184:185], off offset:3328
	global_load_dwordx4 v[172:175], v[186:187], off offset:3328
	s_setprio 1
	s_waitcnt lgkmcnt(1)
	v_mfma_f32_32x32x16_bf16 v[112:127], v[234:237], v[160:163], v[112:127]
	v_mfma_f32_32x32x16_bf16 v[48:63], v[234:237], v[164:167], v[48:63]
	s_waitcnt lgkmcnt(0)
	v_mfma_f32_32x32x16_bf16 v[96:111], v[238:241], v[160:163], v[96:111]
	v_mfma_f32_32x32x16_bf16 v[32:47], v[238:241], v[164:167], v[32:47]
	ds_read_b128 v[234:237], v204 offset:9280
	ds_read_b128 v[238:241], v204 offset:13888
	s_waitcnt vmcnt(7)
	ds_write_b128 v217, v[218:221]
	s_waitcnt vmcnt(6)
	ds_write_b128 v216, v[222:225]
	ds_read_b128 v[218:221], v205 offset:36960
	ds_read_b128 v[222:225], v205 offset:41568
	s_waitcnt lgkmcnt(5)
	v_mfma_f32_32x32x16_bf16 v[80:95], v[234:237], v[160:163], v[80:95]
	v_mfma_f32_32x32x16_bf16 v[16:31], v[234:237], v[164:167], v[16:31]
	ds_read_b128 v[234:237], v204 offset:96
	s_waitcnt lgkmcnt(5)
	v_mfma_f32_32x32x16_bf16 v[64:79], v[238:241], v[160:163], v[64:79]
	v_mfma_f32_32x32x16_bf16 v[0:15], v[238:241], v[164:167], v[0:15]
	ds_read_b128 v[238:241], v204 offset:4704
	s_setprio 0
	global_load_dwordx4 v[160:163], v[198:199], off offset:3328
	global_load_dwordx4 v[164:167], v[200:201], off offset:3328
	s_setprio 1
	s_waitcnt lgkmcnt(1)
	v_mfma_f32_32x32x16_bf16 v[112:127], v[234:237], v[218:221], v[112:127]
	v_mfma_f32_32x32x16_bf16 v[48:63], v[234:237], v[222:225], v[48:63]
	s_waitcnt lgkmcnt(0)
	v_mfma_f32_32x32x16_bf16 v[96:111], v[238:241], v[218:221], v[96:111]
	v_mfma_f32_32x32x16_bf16 v[32:47], v[238:241], v[222:225], v[32:47]
	ds_read_b128 v[234:237], v204 offset:9312
	ds_read_b128 v[238:241], v204 offset:13920
	s_waitcnt lgkmcnt(0)
	s_barrier
; template <bool trans>
; DI void gemm_core(const GTile& tl, const GTile& nx, bool has_next  , bool chain  , bool pre, u32x4 (&ra)[4], u32x4 (&rb)[4], char* smem, f32x16 (&acc)[2][4]) {
;     ...
;   const int nk = K / 64;
;   if (!pre) { G_LOAD(0); G_STORE(0); G_LOAD(1); }
;   for (int kt = 0; kt < nk; ++kt) {
;     __syncthreads();
;     G_COMPUTE(kt & 1, kt);
;   }
	s_waitcnt vmcnt(7)
	ds_write_b128 v215, v[226:229]
	s_waitcnt vmcnt(6)
	ds_write_b128 v215, v[230:233] offset:36864
	ds_read_b128 v[226:229], v208
	ds_read_b128 v[230:233], v208 offset:4608
	v_mfma_f32_32x32x16_bf16 v[80:95], v[234:237], v[218:221], v[80:95]
	v_mfma_f32_32x32x16_bf16 v[16:31], v[234:237], v[222:225], v[16:31]
	ds_read_b128 v[234:237], v192
	v_mfma_f32_32x32x16_bf16 v[64:79], v[238:241], v[218:221], v[64:79]
	v_mfma_f32_32x32x16_bf16 v[0:15], v[238:241], v[222:225], v[0:15]
	ds_read_b128 v[238:241], v192 offset:4608
	s_setprio 0
	global_load_dwordx4 v[218:221], v[190:191], off offset:3456
	global_load_dwordx4 v[222:225], v[188:189], off offset:3456
	s_setprio 1
	s_waitcnt lgkmcnt(1)
	v_mfma_f32_32x32x16_bf16 v[112:127], v[234:237], v[226:229], v[112:127]
	v_mfma_f32_32x32x16_bf16 v[48:63], v[234:237], v[230:233], v[48:63]
	s_waitcnt lgkmcnt(0)
	v_mfma_f32_32x32x16_bf16 v[96:111], v[238:241], v[226:229], v[96:111]
	v_mfma_f32_32x32x16_bf16 v[32:47], v[238:241], v[230:233], v[32:47]
	ds_read_b128 v[234:237], v192 offset:9216
	ds_read_b128 v[238:241], v192 offset:13824
	s_waitcnt vmcnt(7)
	ds_write_b128 v215, v[176:179] offset:9216
	s_waitcnt vmcnt(6)
	ds_write_b128 v215, v[180:183] offset:46080
	ds_read_b128 v[176:179], v208 offset:32
	ds_read_b128 v[180:183], v208 offset:4640
	s_waitcnt lgkmcnt(5)
	v_mfma_f32_32x32x16_bf16 v[80:95], v[234:237], v[226:229], v[80:95]
	v_mfma_f32_32x32x16_bf16 v[16:31], v[234:237], v[230:233], v[16:31]
	ds_read_b128 v[234:237], v192 offset:32
	s_waitcnt lgkmcnt(5)
	v_mfma_f32_32x32x16_bf16 v[64:79], v[238:241], v[226:229], v[64:79]
	v_mfma_f32_32x32x16_bf16 v[0:15], v[238:241], v[230:233], v[0:15]
	ds_read_b128 v[238:241], v192 offset:4640
	s_setprio 0
	global_load_dwordx4 v[226:229], v[194:195], off offset:3456
	global_load_dwordx4 v[230:233], v[196:197], off offset:3456
	s_setprio 1
	s_waitcnt lgkmcnt(1)
	v_mfma_f32_32x32x16_bf16 v[112:127], v[234:237], v[176:179], v[112:127]
	v_mfma_f32_32x32x16_bf16 v[48:63], v[234:237], v[180:183], v[48:63]
	s_waitcnt lgkmcnt(0)
	v_mfma_f32_32x32x16_bf16 v[96:111], v[238:241], v[176:179], v[96:111]
	v_mfma_f32_32x32x16_bf16 v[32:47], v[238:241], v[180:183], v[32:47]
	ds_read_b128 v[234:237], v192 offset:9248
	ds_read_b128 v[238:241], v192 offset:13856
	s_waitcnt vmcnt(7)
	ds_write_b128 v215, v[168:171] offset:18432
	s_waitcnt vmcnt(6)
	ds_write_b128 v215, v[172:175] offset:55296
	ds_read_b128 v[168:171], v208 offset:64
	ds_read_b128 v[172:175], v208 offset:4672
	s_waitcnt lgkmcnt(5)
	v_mfma_f32_32x32x16_bf16 v[80:95], v[234:237], v[176:179], v[80:95]
	v_mfma_f32_32x32x16_bf16 v[16:31], v[234:237], v[180:183], v[16:31]
	ds_read_b128 v[234:237], v192 offset:64
	s_waitcnt lgkmcnt(5)
	v_mfma_f32_32x32x16_bf16 v[64:79], v[238:241], v[176:179], v[64:79]
	v_mfma_f32_32x32x16_bf16 v[0:15], v[238:241], v[180:183], v[0:15]
	ds_read_b128 v[238:241], v192 offset:4672
	s_setprio 0
	global_load_dwordx4 v[176:179], v[184:185], off offset:3456
	global_load_dwordx4 v[180:183], v[186:187], off offset:3456
	s_setprio 1
	s_waitcnt lgkmcnt(1)
	v_mfma_f32_32x32x16_bf16 v[112:127], v[234:237], v[168:171], v[112:127]
	v_mfma_f32_32x32x16_bf16 v[48:63], v[234:237], v[172:175], v[48:63]
	s_waitcnt lgkmcnt(0)
	v_mfma_f32_32x32x16_bf16 v[96:111], v[238:241], v[168:171], v[96:111]
	v_mfma_f32_32x32x16_bf16 v[32:47], v[238:241], v[172:175], v[32:47]
	ds_read_b128 v[234:237], v192 offset:9280
	ds_read_b128 v[238:241], v192 offset:13888
	s_waitcnt vmcnt(7)
	ds_write_b128 v215, v[160:163] offset:27648
	s_waitcnt vmcnt(6)
	ds_write_b128 v215, v[164:167] offset:64512
	ds_read_b128 v[160:163], v208 offset:96
	ds_read_b128 v[164:167], v208 offset:4704
	s_waitcnt lgkmcnt(5)
	v_mfma_f32_32x32x16_bf16 v[80:95], v[234:237], v[168:171], v[80:95]
	v_mfma_f32_32x32x16_bf16 v[16:31], v[234:237], v[172:175], v[16:31]
	ds_read_b128 v[234:237], v192 offset:96
	s_waitcnt lgkmcnt(5)
	v_mfma_f32_32x32x16_bf16 v[64:79], v[238:241], v[168:171], v[64:79]
	v_mfma_f32_32x32x16_bf16 v[0:15], v[238:241], v[172:175], v[0:15]
	ds_read_b128 v[238:241], v192 offset:4704
	s_setprio 0
	global_load_dwordx4 v[168:171], v[198:199], off offset:3456
	global_load_dwordx4 v[172:175], v[200:201], off offset:3456
	s_setprio 1
	s_waitcnt lgkmcnt(1)
	v_mfma_f32_32x32x16_bf16 v[112:127], v[234:237], v[160:163], v[112:127]
	v_mfma_f32_32x32x16_bf16 v[48:63], v[234:237], v[164:167], v[48:63]
	s_waitcnt lgkmcnt(0)
	v_mfma_f32_32x32x16_bf16 v[96:111], v[238:241], v[160:163], v[96:111]
	v_mfma_f32_32x32x16_bf16 v[32:47], v[238:241], v[164:167], v[32:47]
	ds_read_b128 v[234:237], v192 offset:9312
	ds_read_b128 v[238:241], v192 offset:13920
	s_waitcnt lgkmcnt(0)
	s_barrier
; template <bool trans>
; DI void gemm_core(const GTile& tl, const GTile& nx, bool has_next  , bool chain  , bool pre, u32x4 (&ra)[4], u32x4 (&rb)[4], char* smem, f32x16 (&acc)[2][4]) {
;     ...
;   const int nk = K / 64;
;   if (!pre) { G_LOAD(0); G_STORE(0); G_LOAD(1); }
;   for (int kt = 0; kt < nk; ++kt) {
;     __syncthreads();
;     G_COMPUTE(kt & 1, kt);
;   }
	s_waitcnt vmcnt(7)
	ds_write_b128 v209, v[218:221]
	s_waitcnt vmcnt(6)
	ds_write_b128 v210, v[222:225]
	ds_read_b128 v[218:221], v205 offset:36864
	ds_read_b128 v[222:225], v205 offset:41472
	v_mfma_f32_32x32x16_bf16 v[80:95], v[234:237], v[160:163], v[80:95]
	v_mfma_f32_32x32x16_bf16 v[16:31], v[234:237], v[164:167], v[16:31]
	ds_read_b128 v[234:237], v204
	v_mfma_f32_32x32x16_bf16 v[64:79], v[238:241], v[160:163], v[64:79]
	v_mfma_f32_32x32x16_bf16 v[0:15], v[238:241], v[164:167], v[0:15]
	ds_read_b128 v[238:241], v204 offset:4608
	s_setprio 0
	global_load_dwordx4 v[160:163], v[190:191], off offset:3584
	global_load_dwordx4 v[164:167], v[188:189], off offset:3584
	s_setprio 1
	s_waitcnt lgkmcnt(1)
	v_mfma_f32_32x32x16_bf16 v[112:127], v[234:237], v[218:221], v[112:127]
	v_mfma_f32_32x32x16_bf16 v[48:63], v[234:237], v[222:225], v[48:63]
	s_waitcnt lgkmcnt(0)
	v_mfma_f32_32x32x16_bf16 v[96:111], v[238:241], v[218:221], v[96:111]
	v_mfma_f32_32x32x16_bf16 v[32:47], v[238:241], v[222:225], v[32:47]
	ds_read_b128 v[234:237], v204 offset:9216
	ds_read_b128 v[238:241], v204 offset:13824
	s_waitcnt vmcnt(7)
	ds_write_b128 v212, v[226:229]
	s_waitcnt vmcnt(6)
	ds_write_b128 v211, v[230:233]
	ds_read_b128 v[226:229], v205 offset:36896
	ds_read_b128 v[230:233], v205 offset:41504
	s_waitcnt lgkmcnt(5)
	v_mfma_f32_32x32x16_bf16 v[80:95], v[234:237], v[218:221], v[80:95]
	v_mfma_f32_32x32x16_bf16 v[16:31], v[234:237], v[222:225], v[16:31]
	ds_read_b128 v[234:237], v204 offset:32
	s_waitcnt lgkmcnt(5)
	v_mfma_f32_32x32x16_bf16 v[64:79], v[238:241], v[218:221], v[64:79]
	v_mfma_f32_32x32x16_bf16 v[0:15], v[238:241], v[222:225], v[0:15]
	ds_read_b128 v[238:241], v204 offset:4640
	s_setprio 0
	global_load_dwordx4 v[218:221], v[194:195], off offset:3584
	global_load_dwordx4 v[222:225], v[196:197], off offset:3584
	s_setprio 1
	s_waitcnt lgkmcnt(1)
	v_mfma_f32_32x32x16_bf16 v[112:127], v[234:237], v[226:229], v[112:127]
	v_mfma_f32_32x32x16_bf16 v[48:63], v[234:237], v[230:233], v[48:63]
	s_waitcnt lgkmcnt(0)
	v_mfma_f32_32x32x16_bf16 v[96:111], v[238:241], v[226:229], v[96:111]
	v_mfma_f32_32x32x16_bf16 v[32:47], v[238:241], v[230:233], v[32:47]
	ds_read_b128 v[234:237], v204 offset:9248
	ds_read_b128 v[238:241], v204 offset:13856
	s_waitcnt vmcnt(7)
	ds_write_b128 v214, v[176:179]
	s_waitcnt vmcnt(6)
	ds_write_b128 v213, v[180:183]
	ds_read_b128 v[176:179], v205 offset:36928
	ds_read_b128 v[180:183], v205 offset:41536
	s_waitcnt lgkmcnt(5)
	v_mfma_f32_32x32x16_bf16 v[80:95], v[234:237], v[226:229], v[80:95]
	v_mfma_f32_32x32x16_bf16 v[16:31], v[234:237], v[230:233], v[16:31]
	ds_read_b128 v[234:237], v204 offset:64
	s_waitcnt lgkmcnt(5)
	v_mfma_f32_32x32x16_bf16 v[64:79], v[238:241], v[226:229], v[64:79]
	v_mfma_f32_32x32x16_bf16 v[0:15], v[238:241], v[230:233], v[0:15]
	ds_read_b128 v[238:241], v204 offset:4672
	s_setprio 0
	global_load_dwordx4 v[226:229], v[184:185], off offset:3584
	global_load_dwordx4 v[230:233], v[186:187], off offset:3584
	s_setprio 1
	s_waitcnt lgkmcnt(1)
	v_mfma_f32_32x32x16_bf16 v[112:127], v[234:237], v[176:179], v[112:127]
	v_mfma_f32_32x32x16_bf16 v[48:63], v[234:237], v[180:183], v[48:63]
	s_waitcnt lgkmcnt(0)
	v_mfma_f32_32x32x16_bf16 v[96:111], v[238:241], v[176:179], v[96:111]
	v_mfma_f32_32x32x16_bf16 v[32:47], v[238:241], v[180:183], v[32:47]
	ds_read_b128 v[234:237], v204 offset:9280
	ds_read_b128 v[238:241], v204 offset:13888
	s_waitcnt vmcnt(7)
	ds_write_b128 v217, v[168:171]
	s_waitcnt vmcnt(6)
	ds_write_b128 v216, v[172:175]
	ds_read_b128 v[168:171], v205 offset:36960
	ds_read_b128 v[172:175], v205 offset:41568
	s_waitcnt lgkmcnt(5)
	v_mfma_f32_32x32x16_bf16 v[80:95], v[234:237], v[176:179], v[80:95]
	v_mfma_f32_32x32x16_bf16 v[16:31], v[234:237], v[180:183], v[16:31]
	ds_read_b128 v[234:237], v204 offset:96
	s_waitcnt lgkmcnt(5)
	v_mfma_f32_32x32x16_bf16 v[64:79], v[238:241], v[176:179], v[64:79]
	v_mfma_f32_32x32x16_bf16 v[0:15], v[238:241], v[180:183], v[0:15]
	ds_read_b128 v[238:241], v204 offset:4704
	s_setprio 0
	global_load_dwordx4 v[176:179], v[198:199], off offset:3584
	global_load_dwordx4 v[180:183], v[200:201], off offset:3584
	s_setprio 1
	s_waitcnt lgkmcnt(1)
	v_mfma_f32_32x32x16_bf16 v[112:127], v[234:237], v[168:171], v[112:127]
	v_mfma_f32_32x32x16_bf16 v[48:63], v[234:237], v[172:175], v[48:63]
	s_waitcnt lgkmcnt(0)
	v_mfma_f32_32x32x16_bf16 v[96:111], v[238:241], v[168:171], v[96:111]
	v_mfma_f32_32x32x16_bf16 v[32:47], v[238:241], v[172:175], v[32:47]
	ds_read_b128 v[234:237], v204 offset:9312
	ds_read_b128 v[238:241], v204 offset:13920
	s_waitcnt lgkmcnt(0)
	s_barrier
; template <bool trans>
; DI void gemm_core(const GTile& tl, const GTile& nx, bool has_next  , bool chain  , bool pre, u32x4 (&ra)[4], u32x4 (&rb)[4], char* smem, f32x16 (&acc)[2][4]) {
;     ...
;   const int nk = K / 64;
;   if (!pre) { G_LOAD(0); G_STORE(0); G_LOAD(1); }
;   for (int kt = 0; kt < nk; ++kt) {
;     __syncthreads();
;     G_COMPUTE(kt & 1, kt);
;   }
	s_waitcnt vmcnt(7)
	ds_write_b128 v215, v[160:163]
	s_waitcnt vmcnt(6)
	ds_write_b128 v215, v[164:167] offset:36864
	ds_read_b128 v[160:163], v208
	ds_read_b128 v[164:167], v208 offset:4608
	v_mfma_f32_32x32x16_bf16 v[80:95], v[234:237], v[168:171], v[80:95]
	v_mfma_f32_32x32x16_bf16 v[16:31], v[234:237], v[172:175], v[16:31]
	ds_read_b128 v[234:237], v192
	v_mfma_f32_32x32x16_bf16 v[64:79], v[238:241], v[168:171], v[64:79]
	v_mfma_f32_32x32x16_bf16 v[0:15], v[238:241], v[172:175], v[0:15]
	ds_read_b128 v[238:241], v192 offset:4608
	s_setprio 0
	global_load_dwordx4 v[168:171], v[190:191], off offset:3712
	global_load_dwordx4 v[172:175], v[188:189], off offset:3712
	s_setprio 1
	s_waitcnt lgkmcnt(1)
	v_mfma_f32_32x32x16_bf16 v[112:127], v[234:237], v[160:163], v[112:127]
	v_mfma_f32_32x32x16_bf16 v[48:63], v[234:237], v[164:167], v[48:63]
	s_waitcnt lgkmcnt(0)
	v_mfma_f32_32x32x16_bf16 v[96:111], v[238:241], v[160:163], v[96:111]
	v_mfma_f32_32x32x16_bf16 v[32:47], v[238:241], v[164:167], v[32:47]
	ds_read_b128 v[234:237], v192 offset:9216
	ds_read_b128 v[238:241], v192 offset:13824
	s_waitcnt vmcnt(7)
	ds_write_b128 v215, v[218:221] offset:9216
	s_waitcnt vmcnt(6)
	ds_write_b128 v215, v[222:225] offset:46080
	ds_read_b128 v[218:221], v208 offset:32
	ds_read_b128 v[222:225], v208 offset:4640
	s_waitcnt lgkmcnt(5)
	v_mfma_f32_32x32x16_bf16 v[80:95], v[234:237], v[160:163], v[80:95]
	v_mfma_f32_32x32x16_bf16 v[16:31], v[234:237], v[164:167], v[16:31]
	ds_read_b128 v[234:237], v192 offset:32
	s_waitcnt lgkmcnt(5)
	v_mfma_f32_32x32x16_bf16 v[64:79], v[238:241], v[160:163], v[64:79]
	v_mfma_f32_32x32x16_bf16 v[0:15], v[238:241], v[164:167], v[0:15]
	ds_read_b128 v[238:241], v192 offset:4640
	s_setprio 0
	global_load_dwordx4 v[160:163], v[194:195], off offset:3712
	global_load_dwordx4 v[164:167], v[196:197], off offset:3712
	s_setprio 1
	s_waitcnt lgkmcnt(1)
	v_mfma_f32_32x32x16_bf16 v[112:127], v[234:237], v[218:221], v[112:127]
	v_mfma_f32_32x32x16_bf16 v[48:63], v[234:237], v[222:225], v[48:63]
	s_waitcnt lgkmcnt(0)
	v_mfma_f32_32x32x16_bf16 v[96:111], v[238:241], v[218:221], v[96:111]
	v_mfma_f32_32x32x16_bf16 v[32:47], v[238:241], v[222:225], v[32:47]
	ds_read_b128 v[234:237], v192 offset:9248
	ds_read_b128 v[238:241], v192 offset:13856
	s_waitcnt vmcnt(7)
	ds_write_b128 v215, v[226:229] offset:18432
	s_waitcnt vmcnt(6)
	ds_write_b128 v215, v[230:233] offset:55296
	ds_read_b128 v[226:229], v208 offset:64
	ds_read_b128 v[230:233], v208 offset:4672
	s_waitcnt lgkmcnt(5)
	v_mfma_f32_32x32x16_bf16 v[80:95], v[234:237], v[218:221], v[80:95]
	v_mfma_f32_32x32x16_bf16 v[16:31], v[234:237], v[222:225], v[16:31]
	ds_read_b128 v[234:237], v192 offset:64
	s_waitcnt lgkmcnt(5)
	v_mfma_f32_32x32x16_bf16 v[64:79], v[238:241], v[218:221], v[64:79]
	v_mfma_f32_32x32x16_bf16 v[0:15], v[238:241], v[222:225], v[0:15]
	ds_read_b128 v[238:241], v192 offset:4672
	s_setprio 0
	global_load_dwordx4 v[218:221], v[184:185], off offset:3712
	global_load_dwordx4 v[222:225], v[186:187], off offset:3712
	s_setprio 1
	s_waitcnt lgkmcnt(1)
	v_mfma_f32_32x32x16_bf16 v[112:127], v[234:237], v[226:229], v[112:127]
	v_mfma_f32_32x32x16_bf16 v[48:63], v[234:237], v[230:233], v[48:63]
	s_waitcnt lgkmcnt(0)
	v_mfma_f32_32x32x16_bf16 v[96:111], v[238:241], v[226:229], v[96:111]
	v_mfma_f32_32x32x16_bf16 v[32:47], v[238:241], v[230:233], v[32:47]
	ds_read_b128 v[234:237], v192 offset:9280
	ds_read_b128 v[238:241], v192 offset:13888
	s_waitcnt vmcnt(7)
	ds_write_b128 v215, v[176:179] offset:27648
	s_waitcnt vmcnt(6)
	ds_write_b128 v215, v[180:183] offset:64512
	ds_read_b128 v[176:179], v208 offset:96
	ds_read_b128 v[180:183], v208 offset:4704
	s_waitcnt lgkmcnt(5)
	v_mfma_f32_32x32x16_bf16 v[80:95], v[234:237], v[226:229], v[80:95]
	v_mfma_f32_32x32x16_bf16 v[16:31], v[234:237], v[230:233], v[16:31]
	ds_read_b128 v[234:237], v192 offset:96
	s_waitcnt lgkmcnt(5)
	v_mfma_f32_32x32x16_bf16 v[64:79], v[238:241], v[226:229], v[64:79]
	v_mfma_f32_32x32x16_bf16 v[0:15], v[238:241], v[230:233], v[0:15]
	ds_read_b128 v[238:241], v192 offset:4704
	s_setprio 0
	global_load_dwordx4 v[226:229], v[198:199], off offset:3712
	global_load_dwordx4 v[230:233], v[200:201], off offset:3712
	s_setprio 1
	s_waitcnt lgkmcnt(1)
	v_mfma_f32_32x32x16_bf16 v[112:127], v[234:237], v[176:179], v[112:127]
	v_mfma_f32_32x32x16_bf16 v[48:63], v[234:237], v[180:183], v[48:63]
	s_waitcnt lgkmcnt(0)
	v_mfma_f32_32x32x16_bf16 v[96:111], v[238:241], v[176:179], v[96:111]
	v_mfma_f32_32x32x16_bf16 v[32:47], v[238:241], v[180:183], v[32:47]
	ds_read_b128 v[234:237], v192 offset:9312
	ds_read_b128 v[238:241], v192 offset:13920
	s_waitcnt lgkmcnt(0)
	s_barrier
; template <bool trans>
; DI void gemm_core(const GTile& tl, const GTile& nx, bool has_next  , bool chain  , bool pre, u32x4 (&ra)[4], u32x4 (&rb)[4], char* smem, f32x16 (&acc)[2][4]) {
;     ...
;   const int nk = K / 64;
;   if (!pre) { G_LOAD(0); G_STORE(0); G_LOAD(1); }
;   for (int kt = 0; kt < nk; ++kt) {
;     __syncthreads();
;     G_COMPUTE(kt & 1, kt);
;   }
	s_waitcnt vmcnt(7)
	ds_write_b128 v209, v[168:171]
	s_waitcnt vmcnt(6)
	ds_write_b128 v210, v[172:175]
	ds_read_b128 v[168:171], v205 offset:36864
	ds_read_b128 v[172:175], v205 offset:41472
	v_mfma_f32_32x32x16_bf16 v[80:95], v[234:237], v[176:179], v[80:95]
	v_mfma_f32_32x32x16_bf16 v[16:31], v[234:237], v[180:183], v[16:31]
	ds_read_b128 v[234:237], v204
	v_mfma_f32_32x32x16_bf16 v[64:79], v[238:241], v[176:179], v[64:79]
	v_mfma_f32_32x32x16_bf16 v[0:15], v[238:241], v[180:183], v[0:15]
	ds_read_b128 v[238:241], v204 offset:4608
	s_setprio 0
	global_load_dwordx4 v[176:179], v[190:191], off offset:3840
	global_load_dwordx4 v[180:183], v[188:189], off offset:3840
	s_setprio 1
	s_waitcnt lgkmcnt(1)
	v_mfma_f32_32x32x16_bf16 v[112:127], v[234:237], v[168:171], v[112:127]
	v_mfma_f32_32x32x16_bf16 v[48:63], v[234:237], v[172:175], v[48:63]
	s_waitcnt lgkmcnt(0)
	v_mfma_f32_32x32x16_bf16 v[96:111], v[238:241], v[168:171], v[96:111]
	v_mfma_f32_32x32x16_bf16 v[32:47], v[238:241], v[172:175], v[32:47]
	ds_read_b128 v[234:237], v204 offset:9216
	ds_read_b128 v[238:241], v204 offset:13824
	s_waitcnt lgkmcnt(1)
	v_mfma_f32_32x32x16_bf16 v[80:95], v[234:237], v[168:171], v[80:95]
	v_mfma_f32_32x32x16_bf16 v[16:31], v[234:237], v[172:175], v[16:31]
	s_waitcnt lgkmcnt(0)
	v_mfma_f32_32x32x16_bf16 v[64:79], v[238:241], v[168:171], v[64:79]
	v_mfma_f32_32x32x16_bf16 v[0:15], v[238:241], v[172:175], v[0:15]
	s_setprio 0
	global_load_dwordx4 v[234:237], v[194:195], off offset:3840
	global_load_dwordx4 v[238:241], v[196:197], off offset:3840
	s_waitcnt vmcnt(9)
	ds_write_b128 v212, v[160:163]
	s_waitcnt vmcnt(8)
	ds_write_b128 v211, v[164:167]
	ds_read_b128 v[160:163], v205 offset:36896
	ds_read_b128 v[164:167], v205 offset:41504
	ds_read_b128 v[168:171], v204 offset:32
	ds_read_b128 v[172:175], v204 offset:4640
	s_setprio 1
	s_waitcnt lgkmcnt(1)
	v_mfma_f32_32x32x16_bf16 v[112:127], v[168:171], v[160:163], v[112:127]
	v_mfma_f32_32x32x16_bf16 v[48:63], v[168:171], v[164:167], v[48:63]
	s_waitcnt lgkmcnt(0)
	v_mfma_f32_32x32x16_bf16 v[96:111], v[172:175], v[160:163], v[96:111]
	v_mfma_f32_32x32x16_bf16 v[32:47], v[172:175], v[164:167], v[32:47]
	ds_read_b128 v[168:171], v204 offset:9248
	ds_read_b128 v[172:175], v204 offset:13856
	s_waitcnt lgkmcnt(1)
	v_mfma_f32_32x32x16_bf16 v[80:95], v[168:171], v[160:163], v[80:95]
	v_mfma_f32_32x32x16_bf16 v[16:31], v[168:171], v[164:167], v[16:31]
	s_waitcnt lgkmcnt(0)
	v_mfma_f32_32x32x16_bf16 v[64:79], v[172:175], v[160:163], v[64:79]
	v_mfma_f32_32x32x16_bf16 v[0:15], v[172:175], v[164:167], v[0:15]
	s_setprio 0
	global_load_dwordx4 v[242:245], v[184:185], off offset:3840
	global_load_dwordx4 v[246:249], v[186:187], off offset:3840
	s_waitcnt vmcnt(9)
	ds_write_b128 v214, v[218:221]
	s_waitcnt vmcnt(8)
	ds_write_b128 v213, v[222:225]
	ds_read_b128 v[160:163], v205 offset:36928
	ds_read_b128 v[164:167], v205 offset:41536
	ds_read_b128 v[168:171], v204 offset:64
	ds_read_b128 v[172:175], v204 offset:4672
	s_setprio 1
	s_waitcnt lgkmcnt(1)
	v_mfma_f32_32x32x16_bf16 v[112:127], v[168:171], v[160:163], v[112:127]
	v_mfma_f32_32x32x16_bf16 v[48:63], v[168:171], v[164:167], v[48:63]
	s_waitcnt lgkmcnt(0)
	v_mfma_f32_32x32x16_bf16 v[96:111], v[172:175], v[160:163], v[96:111]
	v_mfma_f32_32x32x16_bf16 v[32:47], v[172:175], v[164:167], v[32:47]
	ds_read_b128 v[168:171], v204 offset:9280
	ds_read_b128 v[172:175], v204 offset:13888
	s_waitcnt lgkmcnt(1)
	v_mfma_f32_32x32x16_bf16 v[80:95], v[168:171], v[160:163], v[80:95]
	v_mfma_f32_32x32x16_bf16 v[16:31], v[168:171], v[164:167], v[16:31]
	s_waitcnt lgkmcnt(0)
	v_mfma_f32_32x32x16_bf16 v[64:79], v[172:175], v[160:163], v[64:79]
	v_mfma_f32_32x32x16_bf16 v[0:15], v[172:175], v[164:167], v[0:15]
	s_setprio 0
	global_load_dwordx4 v[218:221], v[198:199], off offset:3840
	global_load_dwordx4 v[222:225], v[200:201], off offset:3840
	s_waitcnt vmcnt(9)
	ds_write_b128 v217, v[226:229]
	s_waitcnt vmcnt(8)
	ds_write_b128 v216, v[230:233]
	ds_read_b128 v[160:163], v205 offset:36960
	ds_read_b128 v[164:167], v205 offset:41568
	ds_read_b128 v[168:171], v204 offset:96
	ds_read_b128 v[172:175], v204 offset:4704
	s_setprio 1
	s_waitcnt lgkmcnt(1)
	v_mfma_f32_32x32x16_bf16 v[112:127], v[168:171], v[160:163], v[112:127]
	v_mfma_f32_32x32x16_bf16 v[48:63], v[168:171], v[164:167], v[48:63]
	s_waitcnt lgkmcnt(0)
	v_mfma_f32_32x32x16_bf16 v[96:111], v[172:175], v[160:163], v[96:111]
	v_mfma_f32_32x32x16_bf16 v[32:47], v[172:175], v[164:167], v[32:47]
	ds_read_b128 v[168:171], v204 offset:9312
	ds_read_b128 v[172:175], v204 offset:13920
	s_waitcnt lgkmcnt(1)
	v_mfma_f32_32x32x16_bf16 v[80:95], v[168:171], v[160:163], v[80:95]
	v_mfma_f32_32x32x16_bf16 v[16:31], v[168:171], v[164:167], v[16:31]
	s_waitcnt lgkmcnt(0)
	v_mfma_f32_32x32x16_bf16 v[64:79], v[172:175], v[160:163], v[64:79]
	v_mfma_f32_32x32x16_bf16 v[0:15], v[172:175], v[164:167], v[0:15]
	s_setprio 0
	global_load_dwordx4 v[160:163], v[190:191], off offset:3968
	global_load_dwordx4 v[164:167], v[188:189], off offset:3968
	s_barrier
; template <bool trans>
; DI void gemm_core(const GTile& tl, const GTile& nx, bool has_next  , bool chain  , bool pre, u32x4 (&ra)[4], u32x4 (&rb)[4], char* smem, f32x16 (&acc)[2][4]) {
;     ...
;   const int nk = K / 64;
;   if (!pre) { G_LOAD(0); G_STORE(0); G_LOAD(1); }
;   for (int kt = 0; kt < nk; ++kt) {
;     __syncthreads();
;     G_COMPUTE(kt & 1, kt);
;   }
	s_waitcnt vmcnt(9)
	ds_write_b128 v215, v[176:179]
	s_waitcnt vmcnt(8)
	ds_write_b128 v215, v[180:183] offset:36864
	ds_read_b128 v[168:171], v208
	ds_read_b128 v[172:175], v208 offset:4608
	ds_read_b128 v[176:179], v192
	ds_read_b128 v[180:183], v192 offset:4608
	s_setprio 1
	s_waitcnt lgkmcnt(1)
	v_mfma_f32_32x32x16_bf16 v[112:127], v[176:179], v[168:171], v[112:127]
	v_mfma_f32_32x32x16_bf16 v[48:63], v[176:179], v[172:175], v[48:63]
	s_waitcnt lgkmcnt(0)
	v_mfma_f32_32x32x16_bf16 v[96:111], v[180:183], v[168:171], v[96:111]
	v_mfma_f32_32x32x16_bf16 v[32:47], v[180:183], v[172:175], v[32:47]
	ds_read_b128 v[176:179], v192 offset:9216
	ds_read_b128 v[180:183], v192 offset:13824
	s_waitcnt lgkmcnt(1)
	v_mfma_f32_32x32x16_bf16 v[80:95], v[176:179], v[168:171], v[80:95]
	v_mfma_f32_32x32x16_bf16 v[16:31], v[176:179], v[172:175], v[16:31]
	s_waitcnt lgkmcnt(0)
	v_mfma_f32_32x32x16_bf16 v[64:79], v[180:183], v[168:171], v[64:79]
	v_mfma_f32_32x32x16_bf16 v[0:15], v[180:183], v[172:175], v[0:15]
	s_setprio 0
	global_load_dwordx4 v[168:171], v[194:195], off offset:3968
	global_load_dwordx4 v[172:175], v[196:197], off offset:3968
	s_waitcnt vmcnt(9)
	ds_write_b128 v215, v[234:237] offset:9216
	s_waitcnt vmcnt(8)
	ds_write_b128 v215, v[238:241] offset:46080
	ds_read_b128 v[176:179], v208 offset:32
	ds_read_b128 v[180:183], v208 offset:4640
	ds_read_b128 v[188:191], v192 offset:32
	ds_read_b128 v[194:197], v192 offset:4640
	s_setprio 1
	s_waitcnt lgkmcnt(1)
	v_mfma_f32_32x32x16_bf16 v[112:127], v[188:191], v[176:179], v[112:127]
	v_mfma_f32_32x32x16_bf16 v[48:63], v[188:191], v[180:183], v[48:63]
	s_waitcnt lgkmcnt(0)
	v_mfma_f32_32x32x16_bf16 v[96:111], v[194:197], v[176:179], v[96:111]
	v_mfma_f32_32x32x16_bf16 v[32:47], v[194:197], v[180:183], v[32:47]
	ds_read_b128 v[188:191], v192 offset:9248
	ds_read_b128 v[194:197], v192 offset:13856
	s_waitcnt lgkmcnt(1)
	v_mfma_f32_32x32x16_bf16 v[80:95], v[188:191], v[176:179], v[80:95]
	v_mfma_f32_32x32x16_bf16 v[16:31], v[188:191], v[180:183], v[16:31]
	s_waitcnt lgkmcnt(0)
	v_mfma_f32_32x32x16_bf16 v[64:79], v[194:197], v[176:179], v[64:79]
	v_mfma_f32_32x32x16_bf16 v[0:15], v[194:197], v[180:183], v[0:15]
	s_setprio 0
	global_load_dwordx4 v[176:179], v[184:185], off offset:3968
	global_load_dwordx4 v[180:183], v[186:187], off offset:3968
	s_waitcnt vmcnt(9)
	ds_write_b128 v215, v[242:245] offset:18432
	s_waitcnt vmcnt(8)
	ds_write_b128 v215, v[246:249] offset:55296
	ds_read_b128 v[184:187], v208 offset:64
	ds_read_b128 v[188:191], v208 offset:4672
	ds_read_b128 v[194:197], v192 offset:64
	ds_read_b128 v[226:229], v192 offset:4672
	s_setprio 1
	s_waitcnt lgkmcnt(1)
	v_mfma_f32_32x32x16_bf16 v[112:127], v[194:197], v[184:187], v[112:127]
	v_mfma_f32_32x32x16_bf16 v[48:63], v[194:197], v[188:191], v[48:63]
	s_waitcnt lgkmcnt(0)
	v_mfma_f32_32x32x16_bf16 v[96:111], v[226:229], v[184:187], v[96:111]
	v_mfma_f32_32x32x16_bf16 v[32:47], v[226:229], v[188:191], v[32:47]
	ds_read_b128 v[194:197], v192 offset:9280
	ds_read_b128 v[226:229], v192 offset:13888
	s_waitcnt lgkmcnt(1)
	v_mfma_f32_32x32x16_bf16 v[80:95], v[194:197], v[184:187], v[80:95]
	v_mfma_f32_32x32x16_bf16 v[16:31], v[194:197], v[188:191], v[16:31]
	s_waitcnt lgkmcnt(0)
	v_mfma_f32_32x32x16_bf16 v[64:79], v[226:229], v[184:187], v[64:79]
	v_mfma_f32_32x32x16_bf16 v[0:15], v[226:229], v[188:191], v[0:15]
	s_setprio 0
	global_load_dwordx4 v[184:187], v[198:199], off offset:3968
	global_load_dwordx4 v[188:191], v[200:201], off offset:3968
	s_waitcnt vmcnt(9)
	ds_write_b128 v215, v[218:221] offset:27648
	s_waitcnt vmcnt(8)
	ds_write_b128 v215, v[222:225] offset:64512
	ds_read_b128 v[194:197], v208 offset:96
	ds_read_b128 v[198:201], v208 offset:4704
	ds_read_b128 v[218:221], v192 offset:96
	ds_read_b128 v[222:225], v192 offset:4704
	s_setprio 1
	s_waitcnt lgkmcnt(1)
	v_mfma_f32_32x32x16_bf16 v[112:127], v[218:221], v[194:197], v[112:127]
	v_mfma_f32_32x32x16_bf16 v[48:63], v[218:221], v[198:201], v[48:63]
	s_waitcnt lgkmcnt(0)
	v_mfma_f32_32x32x16_bf16 v[96:111], v[222:225], v[194:197], v[96:111]
	v_mfma_f32_32x32x16_bf16 v[32:47], v[222:225], v[198:201], v[32:47]
	ds_read_b128 v[218:221], v192 offset:9312
	ds_read_b128 v[222:225], v192 offset:13920
	s_waitcnt lgkmcnt(1)
	v_mfma_f32_32x32x16_bf16 v[80:95], v[218:221], v[194:197], v[80:95]
	v_mfma_f32_32x32x16_bf16 v[16:31], v[218:221], v[198:201], v[16:31]
	s_waitcnt lgkmcnt(0)
	v_mfma_f32_32x32x16_bf16 v[64:79], v[222:225], v[194:197], v[64:79]
	v_mfma_f32_32x32x16_bf16 v[0:15], v[222:225], v[198:201], v[0:15]
	s_setprio 0
	s_barrier
; template <bool trans>
; DI void gemm_core(const GTile& tl, const GTile& nx, bool has_next  , bool chain  , bool pre, u32x4 (&ra)[4], u32x4 (&rb)[4], char* smem, f32x16 (&acc)[2][4]) {
;     ...
;   const int nk = K / 64;
;   if (!pre) { G_LOAD(0); G_STORE(0); G_LOAD(1); }
;   for (int kt = 0; kt < nk; ++kt) {
;     __syncthreads();
;     G_COMPUTE(kt & 1, kt);
;   }
	s_waitcnt vmcnt(7)
	ds_write_b128 v209, v[160:163]
	s_waitcnt vmcnt(6)
	ds_write_b128 v210, v[164:167]
	ds_read_b128 v[194:197], v205 offset:36864
	ds_read_b128 v[198:201], v205 offset:41472
	ds_read_b128 v[218:221], v204
	ds_read_b128 v[222:225], v204 offset:4608
	s_setprio 1
	s_waitcnt lgkmcnt(1)
	v_mfma_f32_32x32x16_bf16 v[112:127], v[218:221], v[194:197], v[112:127]
	v_mfma_f32_32x32x16_bf16 v[48:63], v[218:221], v[198:201], v[48:63]
	s_waitcnt lgkmcnt(0)
	v_mfma_f32_32x32x16_bf16 v[96:111], v[222:225], v[194:197], v[96:111]
	v_mfma_f32_32x32x16_bf16 v[32:47], v[222:225], v[198:201], v[32:47]
	ds_read_b128 v[218:221], v204 offset:9216
	ds_read_b128 v[222:225], v204 offset:13824
	s_waitcnt lgkmcnt(1)
	v_mfma_f32_32x32x16_bf16 v[80:95], v[218:221], v[194:197], v[80:95]
	v_mfma_f32_32x32x16_bf16 v[16:31], v[218:221], v[198:201], v[16:31]
	s_waitcnt lgkmcnt(0)
	v_mfma_f32_32x32x16_bf16 v[64:79], v[222:225], v[194:197], v[64:79]
	v_mfma_f32_32x32x16_bf16 v[0:15], v[222:225], v[198:201], v[0:15]
	s_setprio 0
	s_waitcnt vmcnt(5)
	ds_write_b128 v212, v[168:171]
	s_waitcnt vmcnt(4)
	ds_write_b128 v211, v[172:175]
	ds_read_b128 v[194:197], v205 offset:36896
	ds_read_b128 v[198:201], v205 offset:41504
	ds_read_b128 v[218:221], v204 offset:32
	ds_read_b128 v[222:225], v204 offset:4640
	s_setprio 1
	s_waitcnt lgkmcnt(1)
	v_mfma_f32_32x32x16_bf16 v[112:127], v[218:221], v[194:197], v[112:127]
	v_mfma_f32_32x32x16_bf16 v[48:63], v[218:221], v[198:201], v[48:63]
	s_waitcnt lgkmcnt(0)
	v_mfma_f32_32x32x16_bf16 v[96:111], v[222:225], v[194:197], v[96:111]
	v_mfma_f32_32x32x16_bf16 v[32:47], v[222:225], v[198:201], v[32:47]
	ds_read_b128 v[218:221], v204 offset:9248
	ds_read_b128 v[222:225], v204 offset:13856
	s_waitcnt lgkmcnt(1)
	v_mfma_f32_32x32x16_bf16 v[80:95], v[218:221], v[194:197], v[80:95]
	v_mfma_f32_32x32x16_bf16 v[16:31], v[218:221], v[198:201], v[16:31]
	s_waitcnt lgkmcnt(0)
	v_mfma_f32_32x32x16_bf16 v[64:79], v[222:225], v[194:197], v[64:79]
	v_mfma_f32_32x32x16_bf16 v[0:15], v[222:225], v[198:201], v[0:15]
	s_setprio 0
	s_waitcnt vmcnt(3)
	ds_write_b128 v214, v[176:179]
	s_waitcnt vmcnt(2)
	ds_write_b128 v213, v[180:183]
	ds_read_b128 v[194:197], v205 offset:36928
	ds_read_b128 v[198:201], v205 offset:41536
	ds_read_b128 v[210:213], v204 offset:64
	ds_read_b128 v[218:221], v204 offset:4672
	s_setprio 1
	s_waitcnt lgkmcnt(1)
	v_mfma_f32_32x32x16_bf16 v[112:127], v[210:213], v[194:197], v[112:127]
	v_mfma_f32_32x32x16_bf16 v[48:63], v[210:213], v[198:201], v[48:63]
	s_waitcnt lgkmcnt(0)
	v_mfma_f32_32x32x16_bf16 v[96:111], v[218:221], v[194:197], v[96:111]
	v_mfma_f32_32x32x16_bf16 v[32:47], v[218:221], v[198:201], v[32:47]
	ds_read_b128 v[210:213], v204 offset:9280
	ds_read_b128 v[218:221], v204 offset:13888
	s_waitcnt lgkmcnt(1)
	v_mfma_f32_32x32x16_bf16 v[80:95], v[210:213], v[194:197], v[80:95]
	v_mfma_f32_32x32x16_bf16 v[16:31], v[210:213], v[198:201], v[16:31]
	s_waitcnt lgkmcnt(0)
	v_mfma_f32_32x32x16_bf16 v[64:79], v[218:221], v[194:197], v[64:79]
	v_mfma_f32_32x32x16_bf16 v[0:15], v[218:221], v[198:201], v[0:15]
	s_setprio 0
	s_waitcnt vmcnt(1)
	ds_write_b128 v217, v[184:187]
	s_waitcnt vmcnt(0)
	ds_write_b128 v216, v[188:191]
	ds_read_b128 v[194:197], v205 offset:36960
	ds_read_b128 v[198:201], v205 offset:41568
	ds_read_b128 v[210:213], v204 offset:96
	ds_read_b128 v[214:217], v204 offset:4704
	s_setprio 1
	s_waitcnt lgkmcnt(1)
	v_mfma_f32_32x32x16_bf16 v[112:127], v[210:213], v[194:197], v[112:127]
	v_mfma_f32_32x32x16_bf16 v[48:63], v[210:213], v[198:201], v[48:63]
	s_waitcnt lgkmcnt(0)
	v_mfma_f32_32x32x16_bf16 v[96:111], v[214:217], v[194:197], v[96:111]
	v_mfma_f32_32x32x16_bf16 v[32:47], v[214:217], v[198:201], v[32:47]
	ds_read_b128 v[210:213], v204 offset:9312
	ds_read_b128 v[214:217], v204 offset:13920
	s_waitcnt lgkmcnt(1)
	v_mfma_f32_32x32x16_bf16 v[80:95], v[210:213], v[194:197], v[80:95]
	v_mfma_f32_32x32x16_bf16 v[16:31], v[210:213], v[198:201], v[16:31]
	s_waitcnt lgkmcnt(0)
	v_mfma_f32_32x32x16_bf16 v[64:79], v[214:217], v[194:197], v[64:79]
	v_mfma_f32_32x32x16_bf16 v[0:15], v[214:217], v[198:201], v[0:15]
	s_setprio 0
	s_barrier
; template <bool trans>
; DI void gemm_core(const GTile& tl, const GTile& nx, bool has_next  , bool chain  , bool pre, u32x4 (&ra)[4], u32x4 (&rb)[4], char* smem, f32x16 (&acc)[2][4]) {
;     ...
;   const int nk = K / 64;
;   if (!pre) { G_LOAD(0); G_STORE(0); G_LOAD(1); }
;   for (int kt = 0; kt < nk; ++kt) {
;     __syncthreads();
;     G_COMPUTE(kt & 1, kt);
;   }
;   if (!has_next) __syncthreads();
	ds_read_b128 v[194:197], v208
	ds_read_b128 v[198:201], v208 offset:4608
	ds_read_b128 v[210:213], v192
	ds_read_b128 v[214:217], v192 offset:4608
	s_setprio 1
	s_waitcnt lgkmcnt(1)
	v_mfma_f32_32x32x16_bf16 v[112:127], v[210:213], v[194:197], v[112:127]
	v_mfma_f32_32x32x16_bf16 v[48:63], v[210:213], v[198:201], v[48:63]
	s_waitcnt lgkmcnt(0)
	v_mfma_f32_32x32x16_bf16 v[96:111], v[214:217], v[194:197], v[96:111]
	v_mfma_f32_32x32x16_bf16 v[32:47], v[214:217], v[198:201], v[32:47]
	ds_read_b128 v[210:213], v192 offset:9216
	ds_read_b128 v[214:217], v192 offset:13824
	s_waitcnt lgkmcnt(1)
	v_mfma_f32_32x32x16_bf16 v[80:95], v[210:213], v[194:197], v[80:95]
	v_mfma_f32_32x32x16_bf16 v[16:31], v[210:213], v[198:201], v[16:31]
	s_waitcnt lgkmcnt(0)
	v_mfma_f32_32x32x16_bf16 v[64:79], v[214:217], v[194:197], v[64:79]
	v_mfma_f32_32x32x16_bf16 v[0:15], v[214:217], v[198:201], v[0:15]
	s_setprio 0
	ds_read_b128 v[194:197], v208 offset:32
	ds_read_b128 v[198:201], v208 offset:4640
	ds_read_b128 v[210:213], v192 offset:32
	ds_read_b128 v[214:217], v192 offset:4640
	s_setprio 1
	s_waitcnt lgkmcnt(1)
	v_mfma_f32_32x32x16_bf16 v[112:127], v[210:213], v[194:197], v[112:127]
	v_mfma_f32_32x32x16_bf16 v[48:63], v[210:213], v[198:201], v[48:63]
	s_waitcnt lgkmcnt(0)
	v_mfma_f32_32x32x16_bf16 v[96:111], v[214:217], v[194:197], v[96:111]
	v_mfma_f32_32x32x16_bf16 v[32:47], v[214:217], v[198:201], v[32:47]
	ds_read_b128 v[210:213], v192 offset:9248
	ds_read_b128 v[214:217], v192 offset:13856
	s_waitcnt lgkmcnt(1)
	v_mfma_f32_32x32x16_bf16 v[80:95], v[210:213], v[194:197], v[80:95]
	v_mfma_f32_32x32x16_bf16 v[16:31], v[210:213], v[198:201], v[16:31]
	s_waitcnt lgkmcnt(0)
	v_mfma_f32_32x32x16_bf16 v[64:79], v[214:217], v[194:197], v[64:79]
	v_mfma_f32_32x32x16_bf16 v[0:15], v[214:217], v[198:201], v[0:15]
	s_setprio 0
	ds_read_b128 v[194:197], v208 offset:64
	ds_read_b128 v[198:201], v208 offset:4672
	ds_read_b128 v[210:213], v192 offset:64
	ds_read_b128 v[214:217], v192 offset:4672
	s_setprio 1
	s_waitcnt lgkmcnt(1)
	v_mfma_f32_32x32x16_bf16 v[112:127], v[210:213], v[194:197], v[112:127]
	v_mfma_f32_32x32x16_bf16 v[48:63], v[210:213], v[198:201], v[48:63]
	s_waitcnt lgkmcnt(0)
	v_mfma_f32_32x32x16_bf16 v[96:111], v[214:217], v[194:197], v[96:111]
	v_mfma_f32_32x32x16_bf16 v[32:47], v[214:217], v[198:201], v[32:47]
	ds_read_b128 v[210:213], v192 offset:9280
	ds_read_b128 v[214:217], v192 offset:13888
	s_waitcnt lgkmcnt(1)
	v_mfma_f32_32x32x16_bf16 v[80:95], v[210:213], v[194:197], v[80:95]
	v_mfma_f32_32x32x16_bf16 v[16:31], v[210:213], v[198:201], v[16:31]
	s_waitcnt lgkmcnt(0)
	v_mfma_f32_32x32x16_bf16 v[64:79], v[214:217], v[194:197], v[64:79]
	v_mfma_f32_32x32x16_bf16 v[0:15], v[214:217], v[198:201], v[0:15]
	s_setprio 0
	ds_read_b128 v[194:197], v208 offset:96
	ds_read_b128 v[198:201], v208 offset:4704
	ds_read_b128 v[208:211], v192 offset:96
	ds_read_b128 v[212:215], v192 offset:4704
	s_setprio 1
	s_waitcnt lgkmcnt(1)
	v_mfma_f32_32x32x16_bf16 v[112:127], v[208:211], v[194:197], v[112:127]
	v_mfma_f32_32x32x16_bf16 v[48:63], v[208:211], v[198:201], v[48:63]
	s_waitcnt lgkmcnt(0)
	v_mfma_f32_32x32x16_bf16 v[96:111], v[212:215], v[194:197], v[96:111]
	v_mfma_f32_32x32x16_bf16 v[32:47], v[212:215], v[198:201], v[32:47]
	ds_read_b128 v[208:211], v192 offset:9312
	ds_read_b128 v[212:215], v192 offset:13920
	s_waitcnt lgkmcnt(1)
	v_mfma_f32_32x32x16_bf16 v[80:95], v[208:211], v[194:197], v[80:95]
	v_mfma_f32_32x32x16_bf16 v[16:31], v[208:211], v[198:201], v[16:31]
	s_waitcnt lgkmcnt(0)
	v_mfma_f32_32x32x16_bf16 v[64:79], v[212:215], v[194:197], v[64:79]
	v_mfma_f32_32x32x16_bf16 v[0:15], v[212:215], v[198:201], v[0:15]
	s_setprio 0
	s_andn2_b64 vcc, exec, s[48:49]
	s_barrier

; template <bool trans>
; DI void gemm_core(const GTile& tl, const GTile& nx, bool has_next  , bool chain  , bool pre, u32x4 (&ra)[4], u32x4 (&rb)[4], char* smem, f32x16 (&acc)[2][4]) {
;     ...
;   if (!has_next) __syncthreads();
.LBB0_127:
	ds_read_b128 v[128:131], v150 offset:96
	ds_read_b128 v[132:135], v150 offset:4704
	ds_read_b128 v[136:139], v149 offset:96
	ds_read_b128 v[140:143], v149 offset:4704
	s_setprio 1
	s_waitcnt lgkmcnt(1)
	v_mfma_f32_32x32x16_bf16 v[112:127], v[128:131], v[136:139], v[112:127]
	v_mfma_f32_32x32x16_bf16 v[48:63], v[132:135], v[136:139], v[48:63]
	s_waitcnt lgkmcnt(0)
	v_mfma_f32_32x32x16_bf16 v[96:111], v[128:131], v[140:143], v[96:111]
	v_mfma_f32_32x32x16_bf16 v[32:47], v[132:135], v[140:143], v[32:47]
	ds_read_b128 v[136:139], v149 offset:9312
	ds_read_b128 v[140:143], v149 offset:13920
	s_waitcnt lgkmcnt(1)
	v_mfma_f32_32x32x16_bf16 v[80:95], v[128:131], v[136:139], v[80:95]
	v_mfma_f32_32x32x16_bf16 v[16:31], v[132:135], v[136:139], v[16:31]
	s_waitcnt lgkmcnt(0)
	v_mfma_f32_32x32x16_bf16 v[64:79], v[128:131], v[140:143], v[64:79]
	v_mfma_f32_32x32x16_bf16 v[0:15], v[132:135], v[140:143], v[0:15]
	s_setprio 0
	s_andn2_b64 vcc, exec, s[48:49]
	s_barrier
	s_branch .LBB0_96

; template <bool trans>
; DI void gemm_core(const GTile& tl, const GTile& nx, bool has_next  , bool chain  , bool pre, u32x4 (&ra)[4], u32x4 (&rb)[4], char* smem, f32x16 (&acc)[2][4]) {
;     ...
;   const int lrow = tid >> 3, kc = tid & 7;
;   const unsigned aoff = (unsigned)(lrow * lda + kc * 8) * 2u, boff = (unsigned)(lrow * ldb + kc * 8) * 2u;
;   const char* ag = (const char*)(A + (size_t)m0 * lda);
;   const char* bg = (const char*)(Bt + (size_t)n0 * ldb);
;   const unsigned aoffn = (unsigned)(lrow * nx.lda + kc * 8) * 2u, boffn = (unsigned)(lrow * nx.ldb + kc * 8) * 2u;
;   const char* agn = (const char*)(nx.A + (size_t)nx.m0 * nx.lda);
;   const char* bgn = (const char*)(nx.Bt + (size_t)nx.n0 * nx.ldb);
;     ...
;   const int nk = K / 64;
;   if (!pre) { G_LOAD(0); G_STORE(0); G_LOAD(1); }
;   for (int kt = 0; kt < nk; ++kt) {
;     __syncthreads();
;     G_COMPUTE(kt & 1, kt);
;   }
.LBB0_882:
	v_lshl_add_u64 v[190:191], s[2:3], 0, v[192:193]
	v_lshl_add_u64 v[188:189], s[16:17], 0, v[192:193]
	s_waitcnt lgkmcnt(0)
	s_barrier
	global_load_dwordx4 v[218:221], v[190:191], off offset:256
	global_load_dwordx4 v[222:225], v[188:189], off offset:256
	s_lshr_b32 s3, s33, 1
	s_and_b32 s2, s33, 0xc0
	v_and_b32_e32 v10, 31, v8
	s_and_b32 s3, s3, 0xfffff80
	v_or_b32_e32 v12, s3, v10
	v_or_b32_e32 v10, s2, v10
	v_add3_u32 v215, 16, v11, v9
	v_lshrrev_b32_e32 v8, 1, v8
	v_mul_u32_u24_e32 v208, 0x90, v10
	v_and_b32_e32 v242, 16, v8
	v_add_u32_e32 v209, 0x12000, v215
	v_mul_lo_u32 v205, v12, s54
	v_add3_u32 v204, 16, v208, v242
	v_add_u32_e32 v210, 0x1b000, v215
	ds_write_b128 v209, v[0:3]
	s_waitcnt vmcnt(5)
	ds_write_b128 v210, v[4:7]
	v_add3_u32 v192, 16, v205, v242
	ds_read_b128 v[0:3], v204 offset:36864
	ds_read_b128 v[4:7], v204 offset:41472
	ds_read_b128 v[8:11], v192
	ds_read_b128 v[12:15], v192 offset:4608
	v_lshl_add_u64 v[184:185], v[190:191], 0, s[14:15]
	v_lshl_add_u64 v[186:187], v[188:189], 0, s[14:15]
	v_lshl_add_u64 v[194:195], v[190:191], 0, s[12:13]
	v_lshl_add_u64 v[196:197], v[188:189], 0, s[12:13]
	s_setprio 1
	s_waitcnt lgkmcnt(1)
	v_mfma_f32_32x32x16_bf16 v[112:127], v[8:11], v[0:3], 0
	v_mfma_f32_32x32x16_bf16 v[48:63], v[8:11], v[4:7], 0
	s_waitcnt lgkmcnt(0)
	v_mfma_f32_32x32x16_bf16 v[96:111], v[12:15], v[0:3], 0
	v_mfma_f32_32x32x16_bf16 v[32:47], v[12:15], v[4:7], 0
	ds_read_b128 v[8:11], v192 offset:9216
	ds_read_b128 v[12:15], v192 offset:13824
	s_waitcnt lgkmcnt(1)
	v_mfma_f32_32x32x16_bf16 v[80:95], v[8:11], v[0:3], 0
	v_mfma_f32_32x32x16_bf16 v[16:31], v[8:11], v[4:7], 0
	s_waitcnt lgkmcnt(0)
	v_mfma_f32_32x32x16_bf16 v[64:79], v[12:15], v[0:3], 0
	v_mfma_f32_32x32x16_bf16 v[0:15], v[12:15], v[4:7], 0
	s_setprio 0
	global_load_dwordx4 v[226:229], v[194:195], off offset:256
	global_load_dwordx4 v[230:233], v[196:197], off offset:256
	v_add_u32_e32 v212, 0x14400, v215
	v_add_u32_e32 v211, 0x1d400, v215
	ds_write_b128 v212, v[176:179]
	s_waitcnt vmcnt(6)
	ds_write_b128 v211, v[180:183]
	ds_read_b128 v[176:179], v204 offset:36896
	ds_read_b128 v[180:183], v204 offset:41504
	ds_read_b128 v[198:201], v192 offset:32
	ds_read_b128 v[234:237], v192 offset:4640
	s_setprio 1
	s_waitcnt lgkmcnt(1)
	v_mfma_f32_32x32x16_bf16 v[112:127], v[198:201], v[176:179], v[112:127]
	v_mfma_f32_32x32x16_bf16 v[48:63], v[198:201], v[180:183], v[48:63]
	s_waitcnt lgkmcnt(0)
	v_mfma_f32_32x32x16_bf16 v[96:111], v[234:237], v[176:179], v[96:111]
	v_mfma_f32_32x32x16_bf16 v[32:47], v[234:237], v[180:183], v[32:47]
	ds_read_b128 v[198:201], v192 offset:9248
	ds_read_b128 v[234:237], v192 offset:13856
	s_waitcnt lgkmcnt(1)
	v_mfma_f32_32x32x16_bf16 v[80:95], v[198:201], v[176:179], v[80:95]
	v_mfma_f32_32x32x16_bf16 v[16:31], v[198:201], v[180:183], v[16:31]
	s_waitcnt lgkmcnt(0)
	v_mfma_f32_32x32x16_bf16 v[64:79], v[234:237], v[176:179], v[64:79]
	v_mfma_f32_32x32x16_bf16 v[0:15], v[234:237], v[180:183], v[0:15]
	s_setprio 0
	global_load_dwordx4 v[176:179], v[184:185], off offset:256
	global_load_dwordx4 v[180:183], v[186:187], off offset:256
	v_add_u32_e32 v214, 0x16800, v215
	v_add_u32_e32 v213, 0x1f800, v215
	ds_write_b128 v214, v[168:171]
	s_waitcnt vmcnt(7)
	ds_write_b128 v213, v[172:175]
	ds_read_b128 v[168:171], v204 offset:36928
	ds_read_b128 v[172:175], v204 offset:41536
	ds_read_b128 v[198:201], v192 offset:64
	ds_read_b128 v[234:237], v192 offset:4672
	s_setprio 1
	s_waitcnt lgkmcnt(1)
	v_mfma_f32_32x32x16_bf16 v[112:127], v[198:201], v[168:171], v[112:127]
	v_mfma_f32_32x32x16_bf16 v[48:63], v[198:201], v[172:175], v[48:63]
	s_waitcnt lgkmcnt(0)
	v_mfma_f32_32x32x16_bf16 v[96:111], v[234:237], v[168:171], v[96:111]
	v_mfma_f32_32x32x16_bf16 v[32:47], v[234:237], v[172:175], v[32:47]
	ds_read_b128 v[198:201], v192 offset:9280
	ds_read_b128 v[234:237], v192 offset:13888
	s_waitcnt lgkmcnt(1)
	v_mfma_f32_32x32x16_bf16 v[80:95], v[198:201], v[168:171], v[80:95]
	v_mfma_f32_32x32x16_bf16 v[16:31], v[198:201], v[172:175], v[16:31]
	s_waitcnt lgkmcnt(0)
	v_mfma_f32_32x32x16_bf16 v[64:79], v[234:237], v[168:171], v[64:79]
	v_mfma_f32_32x32x16_bf16 v[0:15], v[234:237], v[172:175], v[0:15]
	s_setprio 0
	v_add_co_u32_e32 v198, vcc, s53, v190
	v_add_u32_e32 v217, 0x18c00, v215
	s_nop 0
	v_addc_co_u32_e32 v199, vcc, 0, v191, vcc
	v_add_co_u32_e32 v200, vcc, s53, v188
	v_add_u32_e32 v216, 0x21c00, v215
	s_nop 0
	v_addc_co_u32_e32 v201, vcc, 0, v189, vcc
	global_load_dwordx4 v[168:171], v[198:199], off offset:256
	global_load_dwordx4 v[172:175], v[200:201], off offset:256
	ds_write_b128 v217, v[160:163]
	s_waitcnt vmcnt(8)
	ds_write_b128 v216, v[164:167]
	ds_read_b128 v[160:163], v204 offset:36960
	ds_read_b128 v[164:167], v204 offset:41568
	ds_read_b128 v[234:237], v192 offset:96
	ds_read_b128 v[238:241], v192 offset:4704
	s_setprio 1
	s_waitcnt lgkmcnt(1)
	v_mfma_f32_32x32x16_bf16 v[112:127], v[234:237], v[160:163], v[112:127]
	v_mfma_f32_32x32x16_bf16 v[48:63], v[234:237], v[164:167], v[48:63]
	s_waitcnt lgkmcnt(0)
	v_mfma_f32_32x32x16_bf16 v[96:111], v[238:241], v[160:163], v[96:111]
	v_mfma_f32_32x32x16_bf16 v[32:47], v[238:241], v[164:167], v[32:47]
	ds_read_b128 v[234:237], v192 offset:9312
	ds_read_b128 v[238:241], v192 offset:13920
	s_waitcnt lgkmcnt(1)
	v_mfma_f32_32x32x16_bf16 v[80:95], v[234:237], v[160:163], v[80:95]
	v_mfma_f32_32x32x16_bf16 v[16:31], v[234:237], v[164:167], v[16:31]
	s_waitcnt lgkmcnt(0)
	v_mfma_f32_32x32x16_bf16 v[64:79], v[238:241], v[160:163], v[64:79]
	v_mfma_f32_32x32x16_bf16 v[0:15], v[238:241], v[164:167], v[0:15]
	s_setprio 0
	global_load_dwordx4 v[160:163], v[190:191], off offset:384
	global_load_dwordx4 v[164:167], v[188:189], off offset:384
	s_barrier
; template <bool trans>
; DI void gemm_core(const GTile& tl, const GTile& nx, bool has_next  , bool chain  , bool pre, u32x4 (&ra)[4], u32x4 (&rb)[4], char* smem, f32x16 (&acc)[2][4]) {
;     ...
;   const int nk = K / 64;
;   if (!pre) { G_LOAD(0); G_STORE(0); G_LOAD(1); }
;   for (int kt = 0; kt < nk; ++kt) {
;     __syncthreads();
;     G_COMPUTE(kt & 1, kt);
;   }
	s_add_i32 s2, 16, 0x12000
	v_add3_u32 v205, s2, v205, v242
	s_add_i32 s2, 16, 0x1b000
	v_add3_u32 v208, s2, v208, v242
	s_waitcnt vmcnt(9)
	ds_write_b128 v215, v[218:221]
	s_waitcnt vmcnt(8)
	ds_write_b128 v215, v[222:225] offset:36864
	ds_read_b128 v[218:221], v208
	ds_read_b128 v[222:225], v208 offset:4608
	ds_read_b128 v[234:237], v205
	ds_read_b128 v[238:241], v205 offset:4608
	s_setprio 1
	s_waitcnt lgkmcnt(1)
	v_mfma_f32_32x32x16_bf16 v[112:127], v[234:237], v[218:221], v[112:127]
	v_mfma_f32_32x32x16_bf16 v[48:63], v[234:237], v[222:225], v[48:63]
	s_waitcnt lgkmcnt(0)
	v_mfma_f32_32x32x16_bf16 v[96:111], v[238:241], v[218:221], v[96:111]
	v_mfma_f32_32x32x16_bf16 v[32:47], v[238:241], v[222:225], v[32:47]
	ds_read_b128 v[234:237], v205 offset:9216
	ds_read_b128 v[238:241], v205 offset:13824
	s_waitcnt lgkmcnt(1)
	v_mfma_f32_32x32x16_bf16 v[80:95], v[234:237], v[218:221], v[80:95]
	v_mfma_f32_32x32x16_bf16 v[16:31], v[234:237], v[222:225], v[16:31]
	s_waitcnt lgkmcnt(0)
	v_mfma_f32_32x32x16_bf16 v[64:79], v[238:241], v[218:221], v[64:79]
	v_mfma_f32_32x32x16_bf16 v[0:15], v[238:241], v[222:225], v[0:15]
	s_setprio 0
	global_load_dwordx4 v[218:221], v[194:195], off offset:384
	global_load_dwordx4 v[222:225], v[196:197], off offset:384
	s_waitcnt vmcnt(9)
	ds_write_b128 v215, v[226:229] offset:9216
	s_waitcnt vmcnt(8)
	ds_write_b128 v215, v[230:233] offset:46080
	ds_read_b128 v[226:229], v208 offset:32
	ds_read_b128 v[230:233], v208 offset:4640
	ds_read_b128 v[234:237], v205 offset:32
	ds_read_b128 v[238:241], v205 offset:4640
	s_setprio 1
	s_waitcnt lgkmcnt(1)
	v_mfma_f32_32x32x16_bf16 v[112:127], v[234:237], v[226:229], v[112:127]
	v_mfma_f32_32x32x16_bf16 v[48:63], v[234:237], v[230:233], v[48:63]
	s_waitcnt lgkmcnt(0)
	v_mfma_f32_32x32x16_bf16 v[96:111], v[238:241], v[226:229], v[96:111]
	v_mfma_f32_32x32x16_bf16 v[32:47], v[238:241], v[230:233], v[32:47]
	ds_read_b128 v[234:237], v205 offset:9248
	ds_read_b128 v[238:241], v205 offset:13856
	s_waitcnt lgkmcnt(1)
	v_mfma_f32_32x32x16_bf16 v[80:95], v[234:237], v[226:229], v[80:95]
	v_mfma_f32_32x32x16_bf16 v[16:31], v[234:237], v[230:233], v[16:31]
	s_waitcnt lgkmcnt(0)
	v_mfma_f32_32x32x16_bf16 v[64:79], v[238:241], v[226:229], v[64:79]
	v_mfma_f32_32x32x16_bf16 v[0:15], v[238:241], v[230:233], v[0:15]
	s_setprio 0
	global_load_dwordx4 v[226:229], v[184:185], off offset:384
	global_load_dwordx4 v[230:233], v[186:187], off offset:384
	s_waitcnt vmcnt(9)
	ds_write_b128 v215, v[176:179] offset:18432
	s_waitcnt vmcnt(8)
	ds_write_b128 v215, v[180:183] offset:55296
	ds_read_b128 v[176:179], v208 offset:64
	ds_read_b128 v[180:183], v208 offset:4672
	ds_read_b128 v[234:237], v205 offset:64
	ds_read_b128 v[238:241], v205 offset:4672
	s_setprio 1
	s_waitcnt lgkmcnt(1)
	v_mfma_f32_32x32x16_bf16 v[112:127], v[234:237], v[176:179], v[112:127]
	v_mfma_f32_32x32x16_bf16 v[48:63], v[234:237], v[180:183], v[48:63]
	s_waitcnt lgkmcnt(0)
	v_mfma_f32_32x32x16_bf16 v[96:111], v[238:241], v[176:179], v[96:111]
	v_mfma_f32_32x32x16_bf16 v[32:47], v[238:241], v[180:183], v[32:47]
	ds_read_b128 v[234:237], v205 offset:9280
	ds_read_b128 v[238:241], v205 offset:13888
	s_waitcnt lgkmcnt(1)
	v_mfma_f32_32x32x16_bf16 v[80:95], v[234:237], v[176:179], v[80:95]
	v_mfma_f32_32x32x16_bf16 v[16:31], v[234:237], v[180:183], v[16:31]
	s_waitcnt lgkmcnt(0)
	v_mfma_f32_32x32x16_bf16 v[64:79], v[238:241], v[176:179], v[64:79]
	v_mfma_f32_32x32x16_bf16 v[0:15], v[238:241], v[180:183], v[0:15]
	s_setprio 0
	global_load_dwordx4 v[176:179], v[198:199], off offset:384
	global_load_dwordx4 v[180:183], v[200:201], off offset:384
	s_waitcnt vmcnt(9)
	ds_write_b128 v215, v[168:171] offset:27648
	s_waitcnt vmcnt(8)
	ds_write_b128 v215, v[172:175] offset:64512
	ds_read_b128 v[168:171], v208 offset:96
	ds_read_b128 v[172:175], v208 offset:4704
	ds_read_b128 v[234:237], v205 offset:96
	ds_read_b128 v[238:241], v205 offset:4704
	s_setprio 1
	s_waitcnt lgkmcnt(1)
	v_mfma_f32_32x32x16_bf16 v[112:127], v[234:237], v[168:171], v[112:127]
	v_mfma_f32_32x32x16_bf16 v[48:63], v[234:237], v[172:175], v[48:63]
	s_waitcnt lgkmcnt(0)
	v_mfma_f32_32x32x16_bf16 v[96:111], v[238:241], v[168:171], v[96:111]
	v_mfma_f32_32x32x16_bf16 v[32:47], v[238:241], v[172:175], v[32:47]
	ds_read_b128 v[234:237], v205 offset:9312
	ds_read_b128 v[238:241], v205 offset:13920
	s_waitcnt lgkmcnt(1)
	v_mfma_f32_32x32x16_bf16 v[80:95], v[234:237], v[168:171], v[80:95]
	v_mfma_f32_32x32x16_bf16 v[16:31], v[234:237], v[172:175], v[16:31]
	s_waitcnt lgkmcnt(0)
	v_mfma_f32_32x32x16_bf16 v[64:79], v[238:241], v[168:171], v[64:79]
	v_mfma_f32_32x32x16_bf16 v[0:15], v[238:241], v[172:175], v[0:15]
	s_setprio 0
	global_load_dwordx4 v[168:171], v[190:191], off offset:512
	global_load_dwordx4 v[172:175], v[188:189], off offset:512
	s_barrier
; template <bool trans>
; DI void gemm_core(const GTile& tl, const GTile& nx, bool has_next  , bool chain  , bool pre, u32x4 (&ra)[4], u32x4 (&rb)[4], char* smem, f32x16 (&acc)[2][4]) {
;     ...
;   const int nk = K / 64;
;   if (!pre) { G_LOAD(0); G_STORE(0); G_LOAD(1); }
;   for (int kt = 0; kt < nk; ++kt) {
;     __syncthreads();
;     G_COMPUTE(kt & 1, kt);
;   }
	s_waitcnt vmcnt(9)
	ds_write_b128 v209, v[160:163]
	s_waitcnt vmcnt(8)
	ds_write_b128 v210, v[164:167]
	ds_read_b128 v[160:163], v204 offset:36864
	ds_read_b128 v[164:167], v204 offset:41472
	ds_read_b128 v[234:237], v192
	ds_read_b128 v[238:241], v192 offset:4608
	s_setprio 1
	s_waitcnt lgkmcnt(1)
	v_mfma_f32_32x32x16_bf16 v[112:127], v[234:237], v[160:163], v[112:127]
	v_mfma_f32_32x32x16_bf16 v[48:63], v[234:237], v[164:167], v[48:63]
	s_waitcnt lgkmcnt(0)
	v_mfma_f32_32x32x16_bf16 v[96:111], v[238:241], v[160:163], v[96:111]
	v_mfma_f32_32x32x16_bf16 v[32:47], v[238:241], v[164:167], v[32:47]
	ds_read_b128 v[234:237], v192 offset:9216
	ds_read_b128 v[238:241], v192 offset:13824
	s_waitcnt vmcnt(7)
	ds_write_b128 v212, v[218:221]
	s_waitcnt vmcnt(6)
	ds_write_b128 v211, v[222:225]
	ds_read_b128 v[218:221], v204 offset:36896
	ds_read_b128 v[222:225], v204 offset:41504
	s_waitcnt lgkmcnt(5)
	v_mfma_f32_32x32x16_bf16 v[80:95], v[234:237], v[160:163], v[80:95]
	v_mfma_f32_32x32x16_bf16 v[16:31], v[234:237], v[164:167], v[16:31]
	ds_read_b128 v[234:237], v192 offset:32
	s_waitcnt lgkmcnt(5)
	v_mfma_f32_32x32x16_bf16 v[64:79], v[238:241], v[160:163], v[64:79]
	v_mfma_f32_32x32x16_bf16 v[0:15], v[238:241], v[164:167], v[0:15]
	ds_read_b128 v[238:241], v192 offset:4640
	s_setprio 0
	global_load_dwordx4 v[160:163], v[194:195], off offset:512
	global_load_dwordx4 v[164:167], v[196:197], off offset:512
	s_setprio 1
	s_waitcnt lgkmcnt(1)
	v_mfma_f32_32x32x16_bf16 v[112:127], v[234:237], v[218:221], v[112:127]
	v_mfma_f32_32x32x16_bf16 v[48:63], v[234:237], v[222:225], v[48:63]
	s_waitcnt lgkmcnt(0)
	v_mfma_f32_32x32x16_bf16 v[96:111], v[238:241], v[218:221], v[96:111]
	v_mfma_f32_32x32x16_bf16 v[32:47], v[238:241], v[222:225], v[32:47]
	ds_read_b128 v[234:237], v192 offset:9248
	ds_read_b128 v[238:241], v192 offset:13856
	s_waitcnt vmcnt(7)
	ds_write_b128 v214, v[226:229]
	s_waitcnt vmcnt(6)
	ds_write_b128 v213, v[230:233]
	ds_read_b128 v[226:229], v204 offset:36928
	ds_read_b128 v[230:233], v204 offset:41536
	s_waitcnt lgkmcnt(5)
	v_mfma_f32_32x32x16_bf16 v[80:95], v[234:237], v[218:221], v[80:95]
	v_mfma_f32_32x32x16_bf16 v[16:31], v[234:237], v[222:225], v[16:31]
	ds_read_b128 v[234:237], v192 offset:64
	s_waitcnt lgkmcnt(5)
	v_mfma_f32_32x32x16_bf16 v[64:79], v[238:241], v[218:221], v[64:79]
	v_mfma_f32_32x32x16_bf16 v[0:15], v[238:241], v[222:225], v[0:15]
	ds_read_b128 v[238:241], v192 offset:4672
	s_setprio 0
	global_load_dwordx4 v[218:221], v[184:185], off offset:512
	global_load_dwordx4 v[222:225], v[186:187], off offset:512
	s_setprio 1
	s_waitcnt lgkmcnt(1)
	v_mfma_f32_32x32x16_bf16 v[112:127], v[234:237], v[226:229], v[112:127]
	v_mfma_f32_32x32x16_bf16 v[48:63], v[234:237], v[230:233], v[48:63]
	s_waitcnt lgkmcnt(0)
	v_mfma_f32_32x32x16_bf16 v[96:111], v[238:241], v[226:229], v[96:111]
	v_mfma_f32_32x32x16_bf16 v[32:47], v[238:241], v[230:233], v[32:47]
	ds_read_b128 v[234:237], v192 offset:9280
	ds_read_b128 v[238:241], v192 offset:13888
	s_waitcnt vmcnt(7)
	ds_write_b128 v217, v[176:179]
	s_waitcnt vmcnt(6)
	ds_write_b128 v216, v[180:183]
	ds_read_b128 v[176:179], v204 offset:36960
	ds_read_b128 v[180:183], v204 offset:41568
	s_waitcnt lgkmcnt(5)
	v_mfma_f32_32x32x16_bf16 v[80:95], v[234:237], v[226:229], v[80:95]
	v_mfma_f32_32x32x16_bf16 v[16:31], v[234:237], v[230:233], v[16:31]
	ds_read_b128 v[234:237], v192 offset:96
	s_waitcnt lgkmcnt(5)
	v_mfma_f32_32x32x16_bf16 v[64:79], v[238:241], v[226:229], v[64:79]
	v_mfma_f32_32x32x16_bf16 v[0:15], v[238:241], v[230:233], v[0:15]
	ds_read_b128 v[238:241], v192 offset:4704
	s_setprio 0
	global_load_dwordx4 v[226:229], v[198:199], off offset:512
	global_load_dwordx4 v[230:233], v[200:201], off offset:512
	s_setprio 1
	s_waitcnt lgkmcnt(1)
	v_mfma_f32_32x32x16_bf16 v[112:127], v[234:237], v[176:179], v[112:127]
	v_mfma_f32_32x32x16_bf16 v[48:63], v[234:237], v[180:183], v[48:63]
	s_waitcnt lgkmcnt(0)
	v_mfma_f32_32x32x16_bf16 v[96:111], v[238:241], v[176:179], v[96:111]
	v_mfma_f32_32x32x16_bf16 v[32:47], v[238:241], v[180:183], v[32:47]
	ds_read_b128 v[234:237], v192 offset:9312
	ds_read_b128 v[238:241], v192 offset:13920
	s_waitcnt lgkmcnt(0)
	s_barrier
	s_waitcnt vmcnt(7)
	ds_write_b128 v215, v[168:171]
	s_waitcnt vmcnt(6)
	ds_write_b128 v215, v[172:175] offset:36864
	ds_read_b128 v[168:171], v208
	ds_read_b128 v[172:175], v208 offset:4608
	v_mfma_f32_32x32x16_bf16 v[80:95], v[234:237], v[176:179], v[80:95]
	v_mfma_f32_32x32x16_bf16 v[16:31], v[234:237], v[180:183], v[16:31]
	ds_read_b128 v[234:237], v205
	v_mfma_f32_32x32x16_bf16 v[64:79], v[238:241], v[176:179], v[64:79]
	v_mfma_f32_32x32x16_bf16 v[0:15], v[238:241], v[180:183], v[0:15]
	ds_read_b128 v[238:241], v205 offset:4608
	s_setprio 0
	global_load_dwordx4 v[176:179], v[190:191], off offset:640
	global_load_dwordx4 v[180:183], v[188:189], off offset:640
	s_setprio 1
	s_waitcnt lgkmcnt(1)
	v_mfma_f32_32x32x16_bf16 v[112:127], v[234:237], v[168:171], v[112:127]
	v_mfma_f32_32x32x16_bf16 v[48:63], v[234:237], v[172:175], v[48:63]
	s_waitcnt lgkmcnt(0)
	v_mfma_f32_32x32x16_bf16 v[96:111], v[238:241], v[168:171], v[96:111]
	v_mfma_f32_32x32x16_bf16 v[32:47], v[238:241], v[172:175], v[32:47]
	ds_read_b128 v[234:237], v205 offset:9216
	ds_read_b128 v[238:241], v205 offset:13824
	s_waitcnt vmcnt(7)
	ds_write_b128 v215, v[160:163] offset:9216
	s_waitcnt vmcnt(6)
	ds_write_b128 v215, v[164:167] offset:46080
	ds_read_b128 v[160:163], v208 offset:32
	ds_read_b128 v[164:167], v208 offset:4640
	s_waitcnt lgkmcnt(5)
	v_mfma_f32_32x32x16_bf16 v[80:95], v[234:237], v[168:171], v[80:95]
	v_mfma_f32_32x32x16_bf16 v[16:31], v[234:237], v[172:175], v[16:31]
	ds_read_b128 v[234:237], v205 offset:32
	s_waitcnt lgkmcnt(5)
; template <bool trans>
; DI void gemm_core(const GTile& tl, const GTile& nx, bool has_next  , bool chain  , bool pre, u32x4 (&ra)[4], u32x4 (&rb)[4], char* smem, f32x16 (&acc)[2][4]) {
;     ...
;   const int nk = K / 64;
;   if (!pre) { G_LOAD(0); G_STORE(0); G_LOAD(1); }
;   for (int kt = 0; kt < nk; ++kt) {
;     __syncthreads();
;     G_COMPUTE(kt & 1, kt);
;   }
	v_mfma_f32_32x32x16_bf16 v[64:79], v[238:241], v[168:171], v[64:79]
	v_mfma_f32_32x32x16_bf16 v[0:15], v[238:241], v[172:175], v[0:15]
	ds_read_b128 v[238:241], v205 offset:4640
	s_setprio 0
	global_load_dwordx4 v[168:171], v[194:195], off offset:640
	global_load_dwordx4 v[172:175], v[196:197], off offset:640
	s_setprio 1
	s_waitcnt lgkmcnt(1)
	v_mfma_f32_32x32x16_bf16 v[112:127], v[234:237], v[160:163], v[112:127]
	v_mfma_f32_32x32x16_bf16 v[48:63], v[234:237], v[164:167], v[48:63]
	s_waitcnt lgkmcnt(0)
	v_mfma_f32_32x32x16_bf16 v[96:111], v[238:241], v[160:163], v[96:111]
	v_mfma_f32_32x32x16_bf16 v[32:47], v[238:241], v[164:167], v[32:47]
	ds_read_b128 v[234:237], v205 offset:9248
	ds_read_b128 v[238:241], v205 offset:13856
	s_waitcnt vmcnt(7)
	ds_write_b128 v215, v[218:221] offset:18432
	s_waitcnt vmcnt(6)
	ds_write_b128 v215, v[222:225] offset:55296
	ds_read_b128 v[218:221], v208 offset:64
	ds_read_b128 v[222:225], v208 offset:4672
	s_waitcnt lgkmcnt(5)
	v_mfma_f32_32x32x16_bf16 v[80:95], v[234:237], v[160:163], v[80:95]
	v_mfma_f32_32x32x16_bf16 v[16:31], v[234:237], v[164:167], v[16:31]
	ds_read_b128 v[234:237], v205 offset:64
	s_waitcnt lgkmcnt(5)
	v_mfma_f32_32x32x16_bf16 v[64:79], v[238:241], v[160:163], v[64:79]
	v_mfma_f32_32x32x16_bf16 v[0:15], v[238:241], v[164:167], v[0:15]
	ds_read_b128 v[238:241], v205 offset:4672
	s_setprio 0
	global_load_dwordx4 v[160:163], v[184:185], off offset:640
	global_load_dwordx4 v[164:167], v[186:187], off offset:640
	s_setprio 1
	s_waitcnt lgkmcnt(1)
	v_mfma_f32_32x32x16_bf16 v[112:127], v[234:237], v[218:221], v[112:127]
	v_mfma_f32_32x32x16_bf16 v[48:63], v[234:237], v[222:225], v[48:63]
	s_waitcnt lgkmcnt(0)
	v_mfma_f32_32x32x16_bf16 v[96:111], v[238:241], v[218:221], v[96:111]
	v_mfma_f32_32x32x16_bf16 v[32:47], v[238:241], v[222:225], v[32:47]
	ds_read_b128 v[234:237], v205 offset:9280
	ds_read_b128 v[238:241], v205 offset:13888
	s_waitcnt vmcnt(7)
	ds_write_b128 v215, v[226:229] offset:27648
	s_waitcnt vmcnt(6)
	ds_write_b128 v215, v[230:233] offset:64512
	ds_read_b128 v[226:229], v208 offset:96
	ds_read_b128 v[230:233], v208 offset:4704
	s_waitcnt lgkmcnt(5)
	v_mfma_f32_32x32x16_bf16 v[80:95], v[234:237], v[218:221], v[80:95]
	v_mfma_f32_32x32x16_bf16 v[16:31], v[234:237], v[222:225], v[16:31]
	ds_read_b128 v[234:237], v205 offset:96
	s_waitcnt lgkmcnt(5)
	v_mfma_f32_32x32x16_bf16 v[64:79], v[238:241], v[218:221], v[64:79]
	v_mfma_f32_32x32x16_bf16 v[0:15], v[238:241], v[222:225], v[0:15]
	ds_read_b128 v[238:241], v205 offset:4704
	s_setprio 0
	global_load_dwordx4 v[218:221], v[198:199], off offset:640
	global_load_dwordx4 v[222:225], v[200:201], off offset:640
	s_setprio 1
	s_waitcnt lgkmcnt(1)
	v_mfma_f32_32x32x16_bf16 v[112:127], v[234:237], v[226:229], v[112:127]
	v_mfma_f32_32x32x16_bf16 v[48:63], v[234:237], v[230:233], v[48:63]
	s_waitcnt lgkmcnt(0)
	v_mfma_f32_32x32x16_bf16 v[96:111], v[238:241], v[226:229], v[96:111]
	v_mfma_f32_32x32x16_bf16 v[32:47], v[238:241], v[230:233], v[32:47]
	ds_read_b128 v[234:237], v205 offset:9312
	ds_read_b128 v[238:241], v205 offset:13920
	s_waitcnt lgkmcnt(0)
	s_barrier
	s_waitcnt vmcnt(7)
	ds_write_b128 v209, v[176:179]
	s_waitcnt vmcnt(6)
	ds_write_b128 v210, v[180:183]
	ds_read_b128 v[176:179], v204 offset:36864
	ds_read_b128 v[180:183], v204 offset:41472
	v_mfma_f32_32x32x16_bf16 v[80:95], v[234:237], v[226:229], v[80:95]
	v_mfma_f32_32x32x16_bf16 v[16:31], v[234:237], v[230:233], v[16:31]
	ds_read_b128 v[234:237], v192
	v_mfma_f32_32x32x16_bf16 v[64:79], v[238:241], v[226:229], v[64:79]
	v_mfma_f32_32x32x16_bf16 v[0:15], v[238:241], v[230:233], v[0:15]
	ds_read_b128 v[238:241], v192 offset:4608
	s_setprio 0
	global_load_dwordx4 v[226:229], v[190:191], off offset:768
	global_load_dwordx4 v[230:233], v[188:189], off offset:768
	s_setprio 1
	s_waitcnt lgkmcnt(1)
	v_mfma_f32_32x32x16_bf16 v[112:127], v[234:237], v[176:179], v[112:127]
	v_mfma_f32_32x32x16_bf16 v[48:63], v[234:237], v[180:183], v[48:63]
	s_waitcnt lgkmcnt(0)
	v_mfma_f32_32x32x16_bf16 v[96:111], v[238:241], v[176:179], v[96:111]
	v_mfma_f32_32x32x16_bf16 v[32:47], v[238:241], v[180:183], v[32:47]
	ds_read_b128 v[234:237], v192 offset:9216
	ds_read_b128 v[238:241], v192 offset:13824
	s_waitcnt vmcnt(7)
	ds_write_b128 v212, v[168:171]
	s_waitcnt vmcnt(6)
	ds_write_b128 v211, v[172:175]
	ds_read_b128 v[168:171], v204 offset:36896
	ds_read_b128 v[172:175], v204 offset:41504
	s_waitcnt lgkmcnt(5)
	v_mfma_f32_32x32x16_bf16 v[80:95], v[234:237], v[176:179], v[80:95]
	v_mfma_f32_32x32x16_bf16 v[16:31], v[234:237], v[180:183], v[16:31]
	ds_read_b128 v[234:237], v192 offset:32
	s_waitcnt lgkmcnt(5)
	v_mfma_f32_32x32x16_bf16 v[64:79], v[238:241], v[176:179], v[64:79]
	v_mfma_f32_32x32x16_bf16 v[0:15], v[238:241], v[180:183], v[0:15]
	ds_read_b128 v[238:241], v192 offset:4640
	s_setprio 0
	global_load_dwordx4 v[176:179], v[194:195], off offset:768
	global_load_dwordx4 v[180:183], v[196:197], off offset:768
	s_setprio 1
	s_waitcnt lgkmcnt(1)
	v_mfma_f32_32x32x16_bf16 v[112:127], v[234:237], v[168:171], v[112:127]
	v_mfma_f32_32x32x16_bf16 v[48:63], v[234:237], v[172:175], v[48:63]
	s_waitcnt lgkmcnt(0)
	v_mfma_f32_32x32x16_bf16 v[96:111], v[238:241], v[168:171], v[96:111]
	v_mfma_f32_32x32x16_bf16 v[32:47], v[238:241], v[172:175], v[32:47]
	ds_read_b128 v[234:237], v192 offset:9248
	ds_read_b128 v[238:241], v192 offset:13856
	s_waitcnt vmcnt(7)
	ds_write_b128 v214, v[160:163]
	s_waitcnt vmcnt(6)
	ds_write_b128 v213, v[164:167]
	ds_read_b128 v[160:163], v204 offset:36928
	ds_read_b128 v[164:167], v204 offset:41536
	s_waitcnt lgkmcnt(5)
; template <bool trans>
; DI void gemm_core(const GTile& tl, const GTile& nx, bool has_next  , bool chain  , bool pre, u32x4 (&ra)[4], u32x4 (&rb)[4], char* smem, f32x16 (&acc)[2][4]) {
;     ...
;   const int nk = K / 64;
;   if (!pre) { G_LOAD(0); G_STORE(0); G_LOAD(1); }
;   for (int kt = 0; kt < nk; ++kt) {
;     __syncthreads();
;     G_COMPUTE(kt & 1, kt);
;   }
	v_mfma_f32_32x32x16_bf16 v[80:95], v[234:237], v[168:171], v[80:95]
	v_mfma_f32_32x32x16_bf16 v[16:31], v[234:237], v[172:175], v[16:31]
	ds_read_b128 v[234:237], v192 offset:64
	s_waitcnt lgkmcnt(5)
	v_mfma_f32_32x32x16_bf16 v[64:79], v[238:241], v[168:171], v[64:79]
	v_mfma_f32_32x32x16_bf16 v[0:15], v[238:241], v[172:175], v[0:15]
	ds_read_b128 v[238:241], v192 offset:4672
	s_setprio 0
	global_load_dwordx4 v[168:171], v[184:185], off offset:768
	global_load_dwordx4 v[172:175], v[186:187], off offset:768
	s_setprio 1
	s_waitcnt lgkmcnt(1)
	v_mfma_f32_32x32x16_bf16 v[112:127], v[234:237], v[160:163], v[112:127]
	v_mfma_f32_32x32x16_bf16 v[48:63], v[234:237], v[164:167], v[48:63]
	s_waitcnt lgkmcnt(0)
	v_mfma_f32_32x32x16_bf16 v[96:111], v[238:241], v[160:163], v[96:111]
	v_mfma_f32_32x32x16_bf16 v[32:47], v[238:241], v[164:167], v[32:47]
	ds_read_b128 v[234:237], v192 offset:9280
	ds_read_b128 v[238:241], v192 offset:13888
	s_waitcnt vmcnt(7)
	ds_write_b128 v217, v[218:221]
	s_waitcnt vmcnt(6)
	ds_write_b128 v216, v[222:225]
	ds_read_b128 v[218:221], v204 offset:36960
	ds_read_b128 v[222:225], v204 offset:41568
	s_waitcnt lgkmcnt(5)
	v_mfma_f32_32x32x16_bf16 v[80:95], v[234:237], v[160:163], v[80:95]
	v_mfma_f32_32x32x16_bf16 v[16:31], v[234:237], v[164:167], v[16:31]
	ds_read_b128 v[234:237], v192 offset:96
	s_waitcnt lgkmcnt(5)
	v_mfma_f32_32x32x16_bf16 v[64:79], v[238:241], v[160:163], v[64:79]
	v_mfma_f32_32x32x16_bf16 v[0:15], v[238:241], v[164:167], v[0:15]
	ds_read_b128 v[238:241], v192 offset:4704
	s_setprio 0
	global_load_dwordx4 v[160:163], v[198:199], off offset:768
	global_load_dwordx4 v[164:167], v[200:201], off offset:768
	s_setprio 1
	s_waitcnt lgkmcnt(1)
	v_mfma_f32_32x32x16_bf16 v[112:127], v[234:237], v[218:221], v[112:127]
	v_mfma_f32_32x32x16_bf16 v[48:63], v[234:237], v[222:225], v[48:63]
	s_waitcnt lgkmcnt(0)
	v_mfma_f32_32x32x16_bf16 v[96:111], v[238:241], v[218:221], v[96:111]
	v_mfma_f32_32x32x16_bf16 v[32:47], v[238:241], v[222:225], v[32:47]
	ds_read_b128 v[234:237], v192 offset:9312
	ds_read_b128 v[238:241], v192 offset:13920
	s_waitcnt lgkmcnt(0)
	s_barrier
	s_waitcnt vmcnt(7)
	ds_write_b128 v215, v[226:229]
	s_waitcnt vmcnt(6)
	ds_write_b128 v215, v[230:233] offset:36864
	ds_read_b128 v[226:229], v208
	ds_read_b128 v[230:233], v208 offset:4608
	v_mfma_f32_32x32x16_bf16 v[80:95], v[234:237], v[218:221], v[80:95]
	v_mfma_f32_32x32x16_bf16 v[16:31], v[234:237], v[222:225], v[16:31]
	ds_read_b128 v[234:237], v205
	v_mfma_f32_32x32x16_bf16 v[64:79], v[238:241], v[218:221], v[64:79]
	v_mfma_f32_32x32x16_bf16 v[0:15], v[238:241], v[222:225], v[0:15]
	ds_read_b128 v[238:241], v205 offset:4608
	s_setprio 0
	global_load_dwordx4 v[218:221], v[190:191], off offset:896
	global_load_dwordx4 v[222:225], v[188:189], off offset:896
	s_setprio 1
	s_waitcnt lgkmcnt(1)
	v_mfma_f32_32x32x16_bf16 v[112:127], v[234:237], v[226:229], v[112:127]
	v_mfma_f32_32x32x16_bf16 v[48:63], v[234:237], v[230:233], v[48:63]
	s_waitcnt lgkmcnt(0)
	v_mfma_f32_32x32x16_bf16 v[96:111], v[238:241], v[226:229], v[96:111]
	v_mfma_f32_32x32x16_bf16 v[32:47], v[238:241], v[230:233], v[32:47]
	ds_read_b128 v[234:237], v205 offset:9216
	ds_read_b128 v[238:241], v205 offset:13824
	s_waitcnt vmcnt(7)
	ds_write_b128 v215, v[176:179] offset:9216
	s_waitcnt vmcnt(6)
	ds_write_b128 v215, v[180:183] offset:46080
	ds_read_b128 v[176:179], v208 offset:32
	ds_read_b128 v[180:183], v208 offset:4640
	s_waitcnt lgkmcnt(5)
	v_mfma_f32_32x32x16_bf16 v[80:95], v[234:237], v[226:229], v[80:95]
	v_mfma_f32_32x32x16_bf16 v[16:31], v[234:237], v[230:233], v[16:31]
	ds_read_b128 v[234:237], v205 offset:32
	s_waitcnt lgkmcnt(5)
	v_mfma_f32_32x32x16_bf16 v[64:79], v[238:241], v[226:229], v[64:79]
	v_mfma_f32_32x32x16_bf16 v[0:15], v[238:241], v[230:233], v[0:15]
	ds_read_b128 v[238:241], v205 offset:4640
	s_setprio 0
	global_load_dwordx4 v[226:229], v[194:195], off offset:896
	global_load_dwordx4 v[230:233], v[196:197], off offset:896
	s_setprio 1
	s_waitcnt lgkmcnt(1)
	v_mfma_f32_32x32x16_bf16 v[112:127], v[234:237], v[176:179], v[112:127]
	v_mfma_f32_32x32x16_bf16 v[48:63], v[234:237], v[180:183], v[48:63]
	s_waitcnt lgkmcnt(0)
	v_mfma_f32_32x32x16_bf16 v[96:111], v[238:241], v[176:179], v[96:111]
	v_mfma_f32_32x32x16_bf16 v[32:47], v[238:241], v[180:183], v[32:47]
	ds_read_b128 v[234:237], v205 offset:9248
	ds_read_b128 v[238:241], v205 offset:13856
	s_waitcnt vmcnt(7)
	ds_write_b128 v215, v[168:171] offset:18432
	s_waitcnt vmcnt(6)
	ds_write_b128 v215, v[172:175] offset:55296
	ds_read_b128 v[168:171], v208 offset:64
	ds_read_b128 v[172:175], v208 offset:4672
	s_waitcnt lgkmcnt(5)
	v_mfma_f32_32x32x16_bf16 v[80:95], v[234:237], v[176:179], v[80:95]
	v_mfma_f32_32x32x16_bf16 v[16:31], v[234:237], v[180:183], v[16:31]
	ds_read_b128 v[234:237], v205 offset:64
	s_waitcnt lgkmcnt(5)
	v_mfma_f32_32x32x16_bf16 v[64:79], v[238:241], v[176:179], v[64:79]
	v_mfma_f32_32x32x16_bf16 v[0:15], v[238:241], v[180:183], v[0:15]
	ds_read_b128 v[238:241], v205 offset:4672
	s_setprio 0
	global_load_dwordx4 v[176:179], v[184:185], off offset:896
	global_load_dwordx4 v[180:183], v[186:187], off offset:896
	s_setprio 1
	s_waitcnt lgkmcnt(1)
	v_mfma_f32_32x32x16_bf16 v[112:127], v[234:237], v[168:171], v[112:127]
	v_mfma_f32_32x32x16_bf16 v[48:63], v[234:237], v[172:175], v[48:63]
	s_waitcnt lgkmcnt(0)
	v_mfma_f32_32x32x16_bf16 v[96:111], v[238:241], v[168:171], v[96:111]
	v_mfma_f32_32x32x16_bf16 v[32:47], v[238:241], v[172:175], v[32:47]
	ds_read_b128 v[234:237], v205 offset:9280
	ds_read_b128 v[238:241], v205 offset:13888
	s_waitcnt vmcnt(7)
	ds_write_b128 v215, v[160:163] offset:27648
	s_waitcnt vmcnt(6)
	ds_write_b128 v215, v[164:167] offset:64512
	ds_read_b128 v[160:163], v208 offset:96
	ds_read_b128 v[164:167], v208 offset:4704
	s_waitcnt lgkmcnt(5)
	v_mfma_f32_32x32x16_bf16 v[80:95], v[234:237], v[168:171], v[80:95]
	v_mfma_f32_32x32x16_bf16 v[16:31], v[234:237], v[172:175], v[16:31]
	ds_read_b128 v[234:237], v205 offset:96
	s_waitcnt lgkmcnt(5)
	v_mfma_f32_32x32x16_bf16 v[64:79], v[238:241], v[168:171], v[64:79]
	v_mfma_f32_32x32x16_bf16 v[0:15], v[238:241], v[172:175], v[0:15]
	ds_read_b128 v[238:241], v205 offset:4704
	s_setprio 0
	global_load_dwordx4 v[168:171], v[198:199], off offset:896
	global_load_dwordx4 v[172:175], v[200:201], off offset:896
	s_setprio 1
	s_waitcnt lgkmcnt(1)
	v_mfma_f32_32x32x16_bf16 v[112:127], v[234:237], v[160:163], v[112:127]
	v_mfma_f32_32x32x16_bf16 v[48:63], v[234:237], v[164:167], v[48:63]
	s_waitcnt lgkmcnt(0)
	v_mfma_f32_32x32x16_bf16 v[96:111], v[238:241], v[160:163], v[96:111]
	v_mfma_f32_32x32x16_bf16 v[32:47], v[238:241], v[164:167], v[32:47]
	ds_read_b128 v[234:237], v205 offset:9312
	ds_read_b128 v[238:241], v205 offset:13920
	s_waitcnt lgkmcnt(0)
	s_barrier
; template <bool trans>
; DI void gemm_core(const GTile& tl, const GTile& nx, bool has_next  , bool chain  , bool pre, u32x4 (&ra)[4], u32x4 (&rb)[4], char* smem, f32x16 (&acc)[2][4]) {
;     ...
;   const int nk = K / 64;
;   if (!pre) { G_LOAD(0); G_STORE(0); G_LOAD(1); }
;   for (int kt = 0; kt < nk; ++kt) {
;     __syncthreads();
;     G_COMPUTE(kt & 1, kt);
;   }
	s_waitcnt vmcnt(7)
	ds_write_b128 v209, v[218:221]
	s_waitcnt vmcnt(6)
	ds_write_b128 v210, v[222:225]
	ds_read_b128 v[218:221], v204 offset:36864
	ds_read_b128 v[222:225], v204 offset:41472
	v_mfma_f32_32x32x16_bf16 v[80:95], v[234:237], v[160:163], v[80:95]
	v_mfma_f32_32x32x16_bf16 v[16:31], v[234:237], v[164:167], v[16:31]
	ds_read_b128 v[234:237], v192
	v_mfma_f32_32x32x16_bf16 v[64:79], v[238:241], v[160:163], v[64:79]
	v_mfma_f32_32x32x16_bf16 v[0:15], v[238:241], v[164:167], v[0:15]
	ds_read_b128 v[238:241], v192 offset:4608
	s_setprio 0
	global_load_dwordx4 v[160:163], v[190:191], off offset:1024
	global_load_dwordx4 v[164:167], v[188:189], off offset:1024
	s_setprio 1
	s_waitcnt lgkmcnt(1)
	v_mfma_f32_32x32x16_bf16 v[112:127], v[234:237], v[218:221], v[112:127]
	v_mfma_f32_32x32x16_bf16 v[48:63], v[234:237], v[222:225], v[48:63]
	s_waitcnt lgkmcnt(0)
	v_mfma_f32_32x32x16_bf16 v[96:111], v[238:241], v[218:221], v[96:111]
	v_mfma_f32_32x32x16_bf16 v[32:47], v[238:241], v[222:225], v[32:47]
	ds_read_b128 v[234:237], v192 offset:9216
	ds_read_b128 v[238:241], v192 offset:13824
	s_waitcnt vmcnt(7)
	ds_write_b128 v212, v[226:229]
	s_waitcnt vmcnt(6)
	ds_write_b128 v211, v[230:233]
	ds_read_b128 v[226:229], v204 offset:36896
	ds_read_b128 v[230:233], v204 offset:41504
	s_waitcnt lgkmcnt(5)
	v_mfma_f32_32x32x16_bf16 v[80:95], v[234:237], v[218:221], v[80:95]
	v_mfma_f32_32x32x16_bf16 v[16:31], v[234:237], v[222:225], v[16:31]
	ds_read_b128 v[234:237], v192 offset:32
	s_waitcnt lgkmcnt(5)
	v_mfma_f32_32x32x16_bf16 v[64:79], v[238:241], v[218:221], v[64:79]
	v_mfma_f32_32x32x16_bf16 v[0:15], v[238:241], v[222:225], v[0:15]
	ds_read_b128 v[238:241], v192 offset:4640
	s_setprio 0
	global_load_dwordx4 v[218:221], v[194:195], off offset:1024
	global_load_dwordx4 v[222:225], v[196:197], off offset:1024
	s_setprio 1
	s_waitcnt lgkmcnt(1)
	v_mfma_f32_32x32x16_bf16 v[112:127], v[234:237], v[226:229], v[112:127]
	v_mfma_f32_32x32x16_bf16 v[48:63], v[234:237], v[230:233], v[48:63]
	s_waitcnt lgkmcnt(0)
	v_mfma_f32_32x32x16_bf16 v[96:111], v[238:241], v[226:229], v[96:111]
	v_mfma_f32_32x32x16_bf16 v[32:47], v[238:241], v[230:233], v[32:47]
	ds_read_b128 v[234:237], v192 offset:9248
	ds_read_b128 v[238:241], v192 offset:13856
	s_waitcnt vmcnt(7)
	ds_write_b128 v214, v[176:179]
	s_waitcnt vmcnt(6)
	ds_write_b128 v213, v[180:183]
	ds_read_b128 v[176:179], v204 offset:36928
	ds_read_b128 v[180:183], v204 offset:41536
	s_waitcnt lgkmcnt(5)
	v_mfma_f32_32x32x16_bf16 v[80:95], v[234:237], v[226:229], v[80:95]
	v_mfma_f32_32x32x16_bf16 v[16:31], v[234:237], v[230:233], v[16:31]
	ds_read_b128 v[234:237], v192 offset:64
	s_waitcnt lgkmcnt(5)
	v_mfma_f32_32x32x16_bf16 v[64:79], v[238:241], v[226:229], v[64:79]
	v_mfma_f32_32x32x16_bf16 v[0:15], v[238:241], v[230:233], v[0:15]
	ds_read_b128 v[238:241], v192 offset:4672
	s_setprio 0
	global_load_dwordx4 v[226:229], v[184:185], off offset:1024
	global_load_dwordx4 v[230:233], v[186:187], off offset:1024
	s_setprio 1
	s_waitcnt lgkmcnt(1)
	v_mfma_f32_32x32x16_bf16 v[112:127], v[234:237], v[176:179], v[112:127]
	v_mfma_f32_32x32x16_bf16 v[48:63], v[234:237], v[180:183], v[48:63]
	s_waitcnt lgkmcnt(0)
	v_mfma_f32_32x32x16_bf16 v[96:111], v[238:241], v[176:179], v[96:111]
	v_mfma_f32_32x32x16_bf16 v[32:47], v[238:241], v[180:183], v[32:47]
	ds_read_b128 v[234:237], v192 offset:9280
	ds_read_b128 v[238:241], v192 offset:13888
	s_waitcnt vmcnt(7)
	ds_write_b128 v217, v[168:171]
	s_waitcnt vmcnt(6)
	ds_write_b128 v216, v[172:175]
	ds_read_b128 v[168:171], v204 offset:36960
	ds_read_b128 v[172:175], v204 offset:41568
	s_waitcnt lgkmcnt(5)
	v_mfma_f32_32x32x16_bf16 v[80:95], v[234:237], v[176:179], v[80:95]
	v_mfma_f32_32x32x16_bf16 v[16:31], v[234:237], v[180:183], v[16:31]
	ds_read_b128 v[234:237], v192 offset:96
	s_waitcnt lgkmcnt(5)
	v_mfma_f32_32x32x16_bf16 v[64:79], v[238:241], v[176:179], v[64:79]
	v_mfma_f32_32x32x16_bf16 v[0:15], v[238:241], v[180:183], v[0:15]
	ds_read_b128 v[238:241], v192 offset:4704
	s_setprio 0
	global_load_dwordx4 v[176:179], v[198:199], off offset:1024
	global_load_dwordx4 v[180:183], v[200:201], off offset:1024
	s_setprio 1
	s_waitcnt lgkmcnt(1)
	v_mfma_f32_32x32x16_bf16 v[112:127], v[234:237], v[168:171], v[112:127]
	v_mfma_f32_32x32x16_bf16 v[48:63], v[234:237], v[172:175], v[48:63]
	s_waitcnt lgkmcnt(0)
	v_mfma_f32_32x32x16_bf16 v[96:111], v[238:241], v[168:171], v[96:111]
	v_mfma_f32_32x32x16_bf16 v[32:47], v[238:241], v[172:175], v[32:47]
	ds_read_b128 v[234:237], v192 offset:9312
	ds_read_b128 v[238:241], v192 offset:13920
	s_waitcnt lgkmcnt(0)
	s_barrier
; template <bool trans>
; DI void gemm_core(const GTile& tl, const GTile& nx, bool has_next  , bool chain  , bool pre, u32x4 (&ra)[4], u32x4 (&rb)[4], char* smem, f32x16 (&acc)[2][4]) {
;     ...
;   const int nk = K / 64;
;   if (!pre) { G_LOAD(0); G_STORE(0); G_LOAD(1); }
;   for (int kt = 0; kt < nk; ++kt) {
;     __syncthreads();
;     G_COMPUTE(kt & 1, kt);
;   }
	s_waitcnt vmcnt(7)
	ds_write_b128 v215, v[160:163]
	s_waitcnt vmcnt(6)
	ds_write_b128 v215, v[164:167] offset:36864
	ds_read_b128 v[160:163], v208
	ds_read_b128 v[164:167], v208 offset:4608
	v_mfma_f32_32x32x16_bf16 v[80:95], v[234:237], v[168:171], v[80:95]
	v_mfma_f32_32x32x16_bf16 v[16:31], v[234:237], v[172:175], v[16:31]
	ds_read_b128 v[234:237], v205
	v_mfma_f32_32x32x16_bf16 v[64:79], v[238:241], v[168:171], v[64:79]
	v_mfma_f32_32x32x16_bf16 v[0:15], v[238:241], v[172:175], v[0:15]
	ds_read_b128 v[238:241], v205 offset:4608
	s_setprio 0
	global_load_dwordx4 v[168:171], v[190:191], off offset:1152
	global_load_dwordx4 v[172:175], v[188:189], off offset:1152
	s_setprio 1
	s_waitcnt lgkmcnt(1)
	v_mfma_f32_32x32x16_bf16 v[112:127], v[234:237], v[160:163], v[112:127]
	v_mfma_f32_32x32x16_bf16 v[48:63], v[234:237], v[164:167], v[48:63]
	s_waitcnt lgkmcnt(0)
	v_mfma_f32_32x32x16_bf16 v[96:111], v[238:241], v[160:163], v[96:111]
	v_mfma_f32_32x32x16_bf16 v[32:47], v[238:241], v[164:167], v[32:47]
	ds_read_b128 v[234:237], v205 offset:9216
	ds_read_b128 v[238:241], v205 offset:13824
	s_waitcnt vmcnt(7)
	ds_write_b128 v215, v[218:221] offset:9216
	s_waitcnt vmcnt(6)
	ds_write_b128 v215, v[222:225] offset:46080
	ds_read_b128 v[218:221], v208 offset:32
	ds_read_b128 v[222:225], v208 offset:4640
	s_waitcnt lgkmcnt(5)
	v_mfma_f32_32x32x16_bf16 v[80:95], v[234:237], v[160:163], v[80:95]
	v_mfma_f32_32x32x16_bf16 v[16:31], v[234:237], v[164:167], v[16:31]
	ds_read_b128 v[234:237], v205 offset:32
	s_waitcnt lgkmcnt(5)
	v_mfma_f32_32x32x16_bf16 v[64:79], v[238:241], v[160:163], v[64:79]
	v_mfma_f32_32x32x16_bf16 v[0:15], v[238:241], v[164:167], v[0:15]
	ds_read_b128 v[238:241], v205 offset:4640
	s_setprio 0
	global_load_dwordx4 v[160:163], v[194:195], off offset:1152
	global_load_dwordx4 v[164:167], v[196:197], off offset:1152
	s_setprio 1
	s_waitcnt lgkmcnt(1)
	v_mfma_f32_32x32x16_bf16 v[112:127], v[234:237], v[218:221], v[112:127]
	v_mfma_f32_32x32x16_bf16 v[48:63], v[234:237], v[222:225], v[48:63]
	s_waitcnt lgkmcnt(0)
	v_mfma_f32_32x32x16_bf16 v[96:111], v[238:241], v[218:221], v[96:111]
	v_mfma_f32_32x32x16_bf16 v[32:47], v[238:241], v[222:225], v[32:47]
	ds_read_b128 v[234:237], v205 offset:9248
	ds_read_b128 v[238:241], v205 offset:13856
	s_waitcnt vmcnt(7)
	ds_write_b128 v215, v[226:229] offset:18432
	s_waitcnt vmcnt(6)
	ds_write_b128 v215, v[230:233] offset:55296
	ds_read_b128 v[226:229], v208 offset:64
	ds_read_b128 v[230:233], v208 offset:4672
	s_waitcnt lgkmcnt(5)
	v_mfma_f32_32x32x16_bf16 v[80:95], v[234:237], v[218:221], v[80:95]
	v_mfma_f32_32x32x16_bf16 v[16:31], v[234:237], v[222:225], v[16:31]
	ds_read_b128 v[234:237], v205 offset:64
	s_waitcnt lgkmcnt(5)
	v_mfma_f32_32x32x16_bf16 v[64:79], v[238:241], v[218:221], v[64:79]
	v_mfma_f32_32x32x16_bf16 v[0:15], v[238:241], v[222:225], v[0:15]
	ds_read_b128 v[238:241], v205 offset:4672
	s_setprio 0
	global_load_dwordx4 v[218:221], v[184:185], off offset:1152
	global_load_dwordx4 v[222:225], v[186:187], off offset:1152
	s_setprio 1
	s_waitcnt lgkmcnt(1)
	v_mfma_f32_32x32x16_bf16 v[112:127], v[234:237], v[226:229], v[112:127]
	v_mfma_f32_32x32x16_bf16 v[48:63], v[234:237], v[230:233], v[48:63]
	s_waitcnt lgkmcnt(0)
	v_mfma_f32_32x32x16_bf16 v[96:111], v[238:241], v[226:229], v[96:111]
	v_mfma_f32_32x32x16_bf16 v[32:47], v[238:241], v[230:233], v[32:47]
	ds_read_b128 v[234:237], v205 offset:9280
	ds_read_b128 v[238:241], v205 offset:13888
	s_waitcnt vmcnt(7)
	ds_write_b128 v215, v[176:179] offset:27648
	s_waitcnt vmcnt(6)
	ds_write_b128 v215, v[180:183] offset:64512
	ds_read_b128 v[176:179], v208 offset:96
	ds_read_b128 v[180:183], v208 offset:4704
	s_waitcnt lgkmcnt(5)
	v_mfma_f32_32x32x16_bf16 v[80:95], v[234:237], v[226:229], v[80:95]
	v_mfma_f32_32x32x16_bf16 v[16:31], v[234:237], v[230:233], v[16:31]
	ds_read_b128 v[234:237], v205 offset:96
	s_waitcnt lgkmcnt(5)
	v_mfma_f32_32x32x16_bf16 v[64:79], v[238:241], v[226:229], v[64:79]
	v_mfma_f32_32x32x16_bf16 v[0:15], v[238:241], v[230:233], v[0:15]
	ds_read_b128 v[238:241], v205 offset:4704
	s_setprio 0
	global_load_dwordx4 v[226:229], v[198:199], off offset:1152
	global_load_dwordx4 v[230:233], v[200:201], off offset:1152
	s_setprio 1
	s_waitcnt lgkmcnt(1)
	v_mfma_f32_32x32x16_bf16 v[112:127], v[234:237], v[176:179], v[112:127]
	v_mfma_f32_32x32x16_bf16 v[48:63], v[234:237], v[180:183], v[48:63]
	s_waitcnt lgkmcnt(0)
	v_mfma_f32_32x32x16_bf16 v[96:111], v[238:241], v[176:179], v[96:111]
	v_mfma_f32_32x32x16_bf16 v[32:47], v[238:241], v[180:183], v[32:47]
	ds_read_b128 v[234:237], v205 offset:9312
	ds_read_b128 v[238:241], v205 offset:13920
	s_waitcnt lgkmcnt(0)
	s_barrier
; template <bool trans>
; DI void gemm_core(const GTile& tl, const GTile& nx, bool has_next  , bool chain  , bool pre, u32x4 (&ra)[4], u32x4 (&rb)[4], char* smem, f32x16 (&acc)[2][4]) {
;     ...
;   const int nk = K / 64;
;   if (!pre) { G_LOAD(0); G_STORE(0); G_LOAD(1); }
;   for (int kt = 0; kt < nk; ++kt) {
;     __syncthreads();
;     G_COMPUTE(kt & 1, kt);
;   }
	s_waitcnt vmcnt(7)
	ds_write_b128 v209, v[168:171]
	s_waitcnt vmcnt(6)
	ds_write_b128 v210, v[172:175]
	ds_read_b128 v[168:171], v204 offset:36864
	ds_read_b128 v[172:175], v204 offset:41472
	v_mfma_f32_32x32x16_bf16 v[80:95], v[234:237], v[176:179], v[80:95]
	v_mfma_f32_32x32x16_bf16 v[16:31], v[234:237], v[180:183], v[16:31]
	ds_read_b128 v[234:237], v192
	v_mfma_f32_32x32x16_bf16 v[64:79], v[238:241], v[176:179], v[64:79]
	v_mfma_f32_32x32x16_bf16 v[0:15], v[238:241], v[180:183], v[0:15]
	ds_read_b128 v[238:241], v192 offset:4608
	s_setprio 0
	global_load_dwordx4 v[176:179], v[190:191], off offset:1280
	global_load_dwordx4 v[180:183], v[188:189], off offset:1280
	s_setprio 1
	s_waitcnt lgkmcnt(1)
	v_mfma_f32_32x32x16_bf16 v[112:127], v[234:237], v[168:171], v[112:127]
	v_mfma_f32_32x32x16_bf16 v[48:63], v[234:237], v[172:175], v[48:63]
	s_waitcnt lgkmcnt(0)
	v_mfma_f32_32x32x16_bf16 v[96:111], v[238:241], v[168:171], v[96:111]
	v_mfma_f32_32x32x16_bf16 v[32:47], v[238:241], v[172:175], v[32:47]
	ds_read_b128 v[234:237], v192 offset:9216
	ds_read_b128 v[238:241], v192 offset:13824
	s_waitcnt vmcnt(7)
	ds_write_b128 v212, v[160:163]
	s_waitcnt vmcnt(6)
	ds_write_b128 v211, v[164:167]
	ds_read_b128 v[160:163], v204 offset:36896
	ds_read_b128 v[164:167], v204 offset:41504
	s_waitcnt lgkmcnt(5)
	v_mfma_f32_32x32x16_bf16 v[80:95], v[234:237], v[168:171], v[80:95]
	v_mfma_f32_32x32x16_bf16 v[16:31], v[234:237], v[172:175], v[16:31]
	ds_read_b128 v[234:237], v192 offset:32
	s_waitcnt lgkmcnt(5)
	v_mfma_f32_32x32x16_bf16 v[64:79], v[238:241], v[168:171], v[64:79]
	v_mfma_f32_32x32x16_bf16 v[0:15], v[238:241], v[172:175], v[0:15]
	ds_read_b128 v[238:241], v192 offset:4640
	s_setprio 0
	global_load_dwordx4 v[168:171], v[194:195], off offset:1280
	global_load_dwordx4 v[172:175], v[196:197], off offset:1280
	s_setprio 1
	s_waitcnt lgkmcnt(1)
	v_mfma_f32_32x32x16_bf16 v[112:127], v[234:237], v[160:163], v[112:127]
	v_mfma_f32_32x32x16_bf16 v[48:63], v[234:237], v[164:167], v[48:63]
	s_waitcnt lgkmcnt(0)
	v_mfma_f32_32x32x16_bf16 v[96:111], v[238:241], v[160:163], v[96:111]
	v_mfma_f32_32x32x16_bf16 v[32:47], v[238:241], v[164:167], v[32:47]
	ds_read_b128 v[234:237], v192 offset:9248
	ds_read_b128 v[238:241], v192 offset:13856
	s_waitcnt vmcnt(7)
	ds_write_b128 v214, v[218:221]
	s_waitcnt vmcnt(6)
	ds_write_b128 v213, v[222:225]
	ds_read_b128 v[218:221], v204 offset:36928
	ds_read_b128 v[222:225], v204 offset:41536
	s_waitcnt lgkmcnt(5)
	v_mfma_f32_32x32x16_bf16 v[80:95], v[234:237], v[160:163], v[80:95]
	v_mfma_f32_32x32x16_bf16 v[16:31], v[234:237], v[164:167], v[16:31]
	ds_read_b128 v[234:237], v192 offset:64
	s_waitcnt lgkmcnt(5)
	v_mfma_f32_32x32x16_bf16 v[64:79], v[238:241], v[160:163], v[64:79]
	v_mfma_f32_32x32x16_bf16 v[0:15], v[238:241], v[164:167], v[0:15]
	ds_read_b128 v[238:241], v192 offset:4672
	s_setprio 0
	global_load_dwordx4 v[160:163], v[184:185], off offset:1280
	global_load_dwordx4 v[164:167], v[186:187], off offset:1280
	s_setprio 1
	s_waitcnt lgkmcnt(1)
	v_mfma_f32_32x32x16_bf16 v[112:127], v[234:237], v[218:221], v[112:127]
	v_mfma_f32_32x32x16_bf16 v[48:63], v[234:237], v[222:225], v[48:63]
	s_waitcnt lgkmcnt(0)
	v_mfma_f32_32x32x16_bf16 v[96:111], v[238:241], v[218:221], v[96:111]
	v_mfma_f32_32x32x16_bf16 v[32:47], v[238:241], v[222:225], v[32:47]
	ds_read_b128 v[234:237], v192 offset:9280
	ds_read_b128 v[238:241], v192 offset:13888
	s_waitcnt vmcnt(7)
	ds_write_b128 v217, v[226:229]
	s_waitcnt vmcnt(6)
	ds_write_b128 v216, v[230:233]
	ds_read_b128 v[226:229], v204 offset:36960
	ds_read_b128 v[230:233], v204 offset:41568
	s_waitcnt lgkmcnt(5)
	v_mfma_f32_32x32x16_bf16 v[80:95], v[234:237], v[218:221], v[80:95]
	v_mfma_f32_32x32x16_bf16 v[16:31], v[234:237], v[222:225], v[16:31]
	ds_read_b128 v[234:237], v192 offset:96
	s_waitcnt lgkmcnt(5)
	v_mfma_f32_32x32x16_bf16 v[64:79], v[238:241], v[218:221], v[64:79]
	v_mfma_f32_32x32x16_bf16 v[0:15], v[238:241], v[222:225], v[0:15]
	ds_read_b128 v[238:241], v192 offset:4704
	s_setprio 0
	global_load_dwordx4 v[218:221], v[198:199], off offset:1280
	global_load_dwordx4 v[222:225], v[200:201], off offset:1280
	s_setprio 1
	s_waitcnt lgkmcnt(1)
	v_mfma_f32_32x32x16_bf16 v[112:127], v[234:237], v[226:229], v[112:127]
	v_mfma_f32_32x32x16_bf16 v[48:63], v[234:237], v[230:233], v[48:63]
	s_waitcnt lgkmcnt(0)
	v_mfma_f32_32x32x16_bf16 v[96:111], v[238:241], v[226:229], v[96:111]
	v_mfma_f32_32x32x16_bf16 v[32:47], v[238:241], v[230:233], v[32:47]
	ds_read_b128 v[234:237], v192 offset:9312
	ds_read_b128 v[238:241], v192 offset:13920
	s_waitcnt lgkmcnt(0)
	s_barrier
; template <bool trans>
; DI void gemm_core(const GTile& tl, const GTile& nx, bool has_next  , bool chain  , bool pre, u32x4 (&ra)[4], u32x4 (&rb)[4], char* smem, f32x16 (&acc)[2][4]) {
;     ...
;   const int nk = K / 64;
;   if (!pre) { G_LOAD(0); G_STORE(0); G_LOAD(1); }
;   for (int kt = 0; kt < nk; ++kt) {
;     __syncthreads();
;     G_COMPUTE(kt & 1, kt);
;   }
	s_waitcnt vmcnt(7)
	ds_write_b128 v215, v[176:179]
	s_waitcnt vmcnt(6)
	ds_write_b128 v215, v[180:183] offset:36864
	ds_read_b128 v[176:179], v208
	ds_read_b128 v[180:183], v208 offset:4608
	v_mfma_f32_32x32x16_bf16 v[80:95], v[234:237], v[226:229], v[80:95]
	v_mfma_f32_32x32x16_bf16 v[16:31], v[234:237], v[230:233], v[16:31]
	ds_read_b128 v[234:237], v205
	v_mfma_f32_32x32x16_bf16 v[64:79], v[238:241], v[226:229], v[64:79]
	v_mfma_f32_32x32x16_bf16 v[0:15], v[238:241], v[230:233], v[0:15]
	ds_read_b128 v[238:241], v205 offset:4608
	s_setprio 0
	global_load_dwordx4 v[226:229], v[190:191], off offset:1408
	global_load_dwordx4 v[230:233], v[188:189], off offset:1408
	s_setprio 1
	s_waitcnt lgkmcnt(1)
	v_mfma_f32_32x32x16_bf16 v[112:127], v[234:237], v[176:179], v[112:127]
	v_mfma_f32_32x32x16_bf16 v[48:63], v[234:237], v[180:183], v[48:63]
	s_waitcnt lgkmcnt(0)
	v_mfma_f32_32x32x16_bf16 v[96:111], v[238:241], v[176:179], v[96:111]
	v_mfma_f32_32x32x16_bf16 v[32:47], v[238:241], v[180:183], v[32:47]
	ds_read_b128 v[234:237], v205 offset:9216
	ds_read_b128 v[238:241], v205 offset:13824
	s_waitcnt vmcnt(7)
	ds_write_b128 v215, v[168:171] offset:9216
	s_waitcnt vmcnt(6)
	ds_write_b128 v215, v[172:175] offset:46080
	ds_read_b128 v[168:171], v208 offset:32
	ds_read_b128 v[172:175], v208 offset:4640
	s_waitcnt lgkmcnt(5)
	v_mfma_f32_32x32x16_bf16 v[80:95], v[234:237], v[176:179], v[80:95]
	v_mfma_f32_32x32x16_bf16 v[16:31], v[234:237], v[180:183], v[16:31]
	ds_read_b128 v[234:237], v205 offset:32
	s_waitcnt lgkmcnt(5)
	v_mfma_f32_32x32x16_bf16 v[64:79], v[238:241], v[176:179], v[64:79]
	v_mfma_f32_32x32x16_bf16 v[0:15], v[238:241], v[180:183], v[0:15]
	ds_read_b128 v[238:241], v205 offset:4640
	s_setprio 0
	global_load_dwordx4 v[176:179], v[194:195], off offset:1408
	global_load_dwordx4 v[180:183], v[196:197], off offset:1408
	s_setprio 1
	s_waitcnt lgkmcnt(1)
	v_mfma_f32_32x32x16_bf16 v[112:127], v[234:237], v[168:171], v[112:127]
	v_mfma_f32_32x32x16_bf16 v[48:63], v[234:237], v[172:175], v[48:63]
	s_waitcnt lgkmcnt(0)
	v_mfma_f32_32x32x16_bf16 v[96:111], v[238:241], v[168:171], v[96:111]
	v_mfma_f32_32x32x16_bf16 v[32:47], v[238:241], v[172:175], v[32:47]
	ds_read_b128 v[234:237], v205 offset:9248
	ds_read_b128 v[238:241], v205 offset:13856
	s_waitcnt vmcnt(7)
	ds_write_b128 v215, v[160:163] offset:18432
	s_waitcnt vmcnt(6)
	ds_write_b128 v215, v[164:167] offset:55296
	ds_read_b128 v[160:163], v208 offset:64
	ds_read_b128 v[164:167], v208 offset:4672
	s_waitcnt lgkmcnt(5)
	v_mfma_f32_32x32x16_bf16 v[80:95], v[234:237], v[168:171], v[80:95]
	v_mfma_f32_32x32x16_bf16 v[16:31], v[234:237], v[172:175], v[16:31]
	ds_read_b128 v[234:237], v205 offset:64
	s_waitcnt lgkmcnt(5)
	v_mfma_f32_32x32x16_bf16 v[64:79], v[238:241], v[168:171], v[64:79]
	v_mfma_f32_32x32x16_bf16 v[0:15], v[238:241], v[172:175], v[0:15]
	ds_read_b128 v[238:241], v205 offset:4672
	s_setprio 0
	global_load_dwordx4 v[168:171], v[184:185], off offset:1408
	global_load_dwordx4 v[172:175], v[186:187], off offset:1408
	s_setprio 1
	s_waitcnt lgkmcnt(1)
	v_mfma_f32_32x32x16_bf16 v[112:127], v[234:237], v[160:163], v[112:127]
	v_mfma_f32_32x32x16_bf16 v[48:63], v[234:237], v[164:167], v[48:63]
	s_waitcnt lgkmcnt(0)
	v_mfma_f32_32x32x16_bf16 v[96:111], v[238:241], v[160:163], v[96:111]
	v_mfma_f32_32x32x16_bf16 v[32:47], v[238:241], v[164:167], v[32:47]
	ds_read_b128 v[234:237], v205 offset:9280
	ds_read_b128 v[238:241], v205 offset:13888
	s_waitcnt vmcnt(7)
	ds_write_b128 v215, v[218:221] offset:27648
	s_waitcnt vmcnt(6)
	ds_write_b128 v215, v[222:225] offset:64512
	ds_read_b128 v[218:221], v208 offset:96
	ds_read_b128 v[222:225], v208 offset:4704
	s_waitcnt lgkmcnt(5)
	v_mfma_f32_32x32x16_bf16 v[80:95], v[234:237], v[160:163], v[80:95]
	v_mfma_f32_32x32x16_bf16 v[16:31], v[234:237], v[164:167], v[16:31]
	ds_read_b128 v[234:237], v205 offset:96
	s_waitcnt lgkmcnt(5)
	v_mfma_f32_32x32x16_bf16 v[64:79], v[238:241], v[160:163], v[64:79]
	v_mfma_f32_32x32x16_bf16 v[0:15], v[238:241], v[164:167], v[0:15]
	ds_read_b128 v[238:241], v205 offset:4704
	s_setprio 0
	global_load_dwordx4 v[160:163], v[198:199], off offset:1408
	global_load_dwordx4 v[164:167], v[200:201], off offset:1408
	s_setprio 1
	s_waitcnt lgkmcnt(1)
	v_mfma_f32_32x32x16_bf16 v[112:127], v[234:237], v[218:221], v[112:127]
	v_mfma_f32_32x32x16_bf16 v[48:63], v[234:237], v[222:225], v[48:63]
	s_waitcnt lgkmcnt(0)
	v_mfma_f32_32x32x16_bf16 v[96:111], v[238:241], v[218:221], v[96:111]
	v_mfma_f32_32x32x16_bf16 v[32:47], v[238:241], v[222:225], v[32:47]
	ds_read_b128 v[234:237], v205 offset:9312
	ds_read_b128 v[238:241], v205 offset:13920
	s_waitcnt lgkmcnt(0)
	s_barrier
; template <bool trans>
; DI void gemm_core(const GTile& tl, const GTile& nx, bool has_next  , bool chain  , bool pre, u32x4 (&ra)[4], u32x4 (&rb)[4], char* smem, f32x16 (&acc)[2][4]) {
;     ...
;   const int nk = K / 64;
;   if (!pre) { G_LOAD(0); G_STORE(0); G_LOAD(1); }
;   for (int kt = 0; kt < nk; ++kt) {
;     __syncthreads();
;     G_COMPUTE(kt & 1, kt);
;   }
	s_waitcnt vmcnt(7)
	ds_write_b128 v209, v[226:229]
	s_waitcnt vmcnt(6)
	ds_write_b128 v210, v[230:233]
	ds_read_b128 v[226:229], v204 offset:36864
	ds_read_b128 v[230:233], v204 offset:41472
	v_mfma_f32_32x32x16_bf16 v[80:95], v[234:237], v[218:221], v[80:95]
	v_mfma_f32_32x32x16_bf16 v[16:31], v[234:237], v[222:225], v[16:31]
	ds_read_b128 v[234:237], v192
	v_mfma_f32_32x32x16_bf16 v[64:79], v[238:241], v[218:221], v[64:79]
	v_mfma_f32_32x32x16_bf16 v[0:15], v[238:241], v[222:225], v[0:15]
	ds_read_b128 v[238:241], v192 offset:4608
	s_setprio 0
	global_load_dwordx4 v[218:221], v[190:191], off offset:1536
	global_load_dwordx4 v[222:225], v[188:189], off offset:1536
	s_setprio 1
	s_waitcnt lgkmcnt(1)
	v_mfma_f32_32x32x16_bf16 v[112:127], v[234:237], v[226:229], v[112:127]
	v_mfma_f32_32x32x16_bf16 v[48:63], v[234:237], v[230:233], v[48:63]
	s_waitcnt lgkmcnt(0)
	v_mfma_f32_32x32x16_bf16 v[96:111], v[238:241], v[226:229], v[96:111]
	v_mfma_f32_32x32x16_bf16 v[32:47], v[238:241], v[230:233], v[32:47]
	ds_read_b128 v[234:237], v192 offset:9216
	ds_read_b128 v[238:241], v192 offset:13824
	s_waitcnt vmcnt(7)
	ds_write_b128 v212, v[176:179]
	s_waitcnt vmcnt(6)
	ds_write_b128 v211, v[180:183]
	ds_read_b128 v[176:179], v204 offset:36896
	ds_read_b128 v[180:183], v204 offset:41504
	s_waitcnt lgkmcnt(5)
	v_mfma_f32_32x32x16_bf16 v[80:95], v[234:237], v[226:229], v[80:95]
	v_mfma_f32_32x32x16_bf16 v[16:31], v[234:237], v[230:233], v[16:31]
	ds_read_b128 v[234:237], v192 offset:32
	s_waitcnt lgkmcnt(5)
	v_mfma_f32_32x32x16_bf16 v[64:79], v[238:241], v[226:229], v[64:79]
	v_mfma_f32_32x32x16_bf16 v[0:15], v[238:241], v[230:233], v[0:15]
	ds_read_b128 v[238:241], v192 offset:4640
	s_setprio 0
	global_load_dwordx4 v[226:229], v[194:195], off offset:1536
	global_load_dwordx4 v[230:233], v[196:197], off offset:1536
	s_setprio 1
	s_waitcnt lgkmcnt(1)
	v_mfma_f32_32x32x16_bf16 v[112:127], v[234:237], v[176:179], v[112:127]
	v_mfma_f32_32x32x16_bf16 v[48:63], v[234:237], v[180:183], v[48:63]
	s_waitcnt lgkmcnt(0)
	v_mfma_f32_32x32x16_bf16 v[96:111], v[238:241], v[176:179], v[96:111]
	v_mfma_f32_32x32x16_bf16 v[32:47], v[238:241], v[180:183], v[32:47]
	ds_read_b128 v[234:237], v192 offset:9248
	ds_read_b128 v[238:241], v192 offset:13856
	s_waitcnt vmcnt(7)
	ds_write_b128 v214, v[168:171]
	s_waitcnt vmcnt(6)
	ds_write_b128 v213, v[172:175]
	ds_read_b128 v[168:171], v204 offset:36928
	ds_read_b128 v[172:175], v204 offset:41536
	s_waitcnt lgkmcnt(5)
	v_mfma_f32_32x32x16_bf16 v[80:95], v[234:237], v[176:179], v[80:95]
	v_mfma_f32_32x32x16_bf16 v[16:31], v[234:237], v[180:183], v[16:31]
	ds_read_b128 v[234:237], v192 offset:64
	s_waitcnt lgkmcnt(5)
	v_mfma_f32_32x32x16_bf16 v[64:79], v[238:241], v[176:179], v[64:79]
	v_mfma_f32_32x32x16_bf16 v[0:15], v[238:241], v[180:183], v[0:15]
	ds_read_b128 v[238:241], v192 offset:4672
	s_setprio 0
	global_load_dwordx4 v[176:179], v[184:185], off offset:1536
	global_load_dwordx4 v[180:183], v[186:187], off offset:1536
	s_setprio 1
	s_waitcnt lgkmcnt(1)
	v_mfma_f32_32x32x16_bf16 v[112:127], v[234:237], v[168:171], v[112:127]
	v_mfma_f32_32x32x16_bf16 v[48:63], v[234:237], v[172:175], v[48:63]
	s_waitcnt lgkmcnt(0)
	v_mfma_f32_32x32x16_bf16 v[96:111], v[238:241], v[168:171], v[96:111]
	v_mfma_f32_32x32x16_bf16 v[32:47], v[238:241], v[172:175], v[32:47]
	ds_read_b128 v[234:237], v192 offset:9280
	ds_read_b128 v[238:241], v192 offset:13888
	s_waitcnt vmcnt(7)
	ds_write_b128 v217, v[160:163]
	s_waitcnt vmcnt(6)
	ds_write_b128 v216, v[164:167]
	ds_read_b128 v[160:163], v204 offset:36960
	ds_read_b128 v[164:167], v204 offset:41568
	s_waitcnt lgkmcnt(5)
	v_mfma_f32_32x32x16_bf16 v[80:95], v[234:237], v[168:171], v[80:95]
	v_mfma_f32_32x32x16_bf16 v[16:31], v[234:237], v[172:175], v[16:31]
	ds_read_b128 v[234:237], v192 offset:96
	s_waitcnt lgkmcnt(5)
	v_mfma_f32_32x32x16_bf16 v[64:79], v[238:241], v[168:171], v[64:79]
	v_mfma_f32_32x32x16_bf16 v[0:15], v[238:241], v[172:175], v[0:15]
	ds_read_b128 v[238:241], v192 offset:4704
	s_setprio 0
	global_load_dwordx4 v[168:171], v[198:199], off offset:1536
	global_load_dwordx4 v[172:175], v[200:201], off offset:1536
	s_setprio 1
	s_waitcnt lgkmcnt(1)
	v_mfma_f32_32x32x16_bf16 v[112:127], v[234:237], v[160:163], v[112:127]
	v_mfma_f32_32x32x16_bf16 v[48:63], v[234:237], v[164:167], v[48:63]
	s_waitcnt lgkmcnt(0)
	v_mfma_f32_32x32x16_bf16 v[96:111], v[238:241], v[160:163], v[96:111]
	v_mfma_f32_32x32x16_bf16 v[32:47], v[238:241], v[164:167], v[32:47]
	ds_read_b128 v[234:237], v192 offset:9312
	ds_read_b128 v[238:241], v192 offset:13920
	s_waitcnt lgkmcnt(0)
	s_barrier
; template <bool trans>
; DI void gemm_core(const GTile& tl, const GTile& nx, bool has_next  , bool chain  , bool pre, u32x4 (&ra)[4], u32x4 (&rb)[4], char* smem, f32x16 (&acc)[2][4]) {
;     ...
;   const int nk = K / 64;
;   if (!pre) { G_LOAD(0); G_STORE(0); G_LOAD(1); }
;   for (int kt = 0; kt < nk; ++kt) {
;     __syncthreads();
;     G_COMPUTE(kt & 1, kt);
;   }
	s_waitcnt vmcnt(7)
	ds_write_b128 v215, v[218:221]
	s_waitcnt vmcnt(6)
	ds_write_b128 v215, v[222:225] offset:36864
	ds_read_b128 v[218:221], v208
	ds_read_b128 v[222:225], v208 offset:4608
	v_mfma_f32_32x32x16_bf16 v[80:95], v[234:237], v[160:163], v[80:95]
	v_mfma_f32_32x32x16_bf16 v[16:31], v[234:237], v[164:167], v[16:31]
	ds_read_b128 v[234:237], v205
	v_mfma_f32_32x32x16_bf16 v[64:79], v[238:241], v[160:163], v[64:79]
	v_mfma_f32_32x32x16_bf16 v[0:15], v[238:241], v[164:167], v[0:15]
	ds_read_b128 v[238:241], v205 offset:4608
	s_setprio 0
	global_load_dwordx4 v[160:163], v[190:191], off offset:1664
	global_load_dwordx4 v[164:167], v[188:189], off offset:1664
	s_setprio 1
	s_waitcnt lgkmcnt(1)
	v_mfma_f32_32x32x16_bf16 v[112:127], v[234:237], v[218:221], v[112:127]
	v_mfma_f32_32x32x16_bf16 v[48:63], v[234:237], v[222:225], v[48:63]
	s_waitcnt lgkmcnt(0)
	v_mfma_f32_32x32x16_bf16 v[96:111], v[238:241], v[218:221], v[96:111]
	v_mfma_f32_32x32x16_bf16 v[32:47], v[238:241], v[222:225], v[32:47]
	ds_read_b128 v[234:237], v205 offset:9216
	ds_read_b128 v[238:241], v205 offset:13824
	s_waitcnt vmcnt(7)
	ds_write_b128 v215, v[226:229] offset:9216
	s_waitcnt vmcnt(6)
	ds_write_b128 v215, v[230:233] offset:46080
	ds_read_b128 v[226:229], v208 offset:32
	ds_read_b128 v[230:233], v208 offset:4640
	s_waitcnt lgkmcnt(5)
	v_mfma_f32_32x32x16_bf16 v[80:95], v[234:237], v[218:221], v[80:95]
	v_mfma_f32_32x32x16_bf16 v[16:31], v[234:237], v[222:225], v[16:31]
	ds_read_b128 v[234:237], v205 offset:32
	s_waitcnt lgkmcnt(5)
	v_mfma_f32_32x32x16_bf16 v[64:79], v[238:241], v[218:221], v[64:79]
	v_mfma_f32_32x32x16_bf16 v[0:15], v[238:241], v[222:225], v[0:15]
	ds_read_b128 v[238:241], v205 offset:4640
	s_setprio 0
	global_load_dwordx4 v[218:221], v[194:195], off offset:1664
	global_load_dwordx4 v[222:225], v[196:197], off offset:1664
	s_setprio 1
	s_waitcnt lgkmcnt(1)
	v_mfma_f32_32x32x16_bf16 v[112:127], v[234:237], v[226:229], v[112:127]
	v_mfma_f32_32x32x16_bf16 v[48:63], v[234:237], v[230:233], v[48:63]
	s_waitcnt lgkmcnt(0)
	v_mfma_f32_32x32x16_bf16 v[96:111], v[238:241], v[226:229], v[96:111]
	v_mfma_f32_32x32x16_bf16 v[32:47], v[238:241], v[230:233], v[32:47]
	ds_read_b128 v[234:237], v205 offset:9248
	ds_read_b128 v[238:241], v205 offset:13856
	s_waitcnt vmcnt(7)
	ds_write_b128 v215, v[176:179] offset:18432
	s_waitcnt vmcnt(6)
	ds_write_b128 v215, v[180:183] offset:55296
	ds_read_b128 v[176:179], v208 offset:64
	ds_read_b128 v[180:183], v208 offset:4672
	s_waitcnt lgkmcnt(5)
	v_mfma_f32_32x32x16_bf16 v[80:95], v[234:237], v[226:229], v[80:95]
	v_mfma_f32_32x32x16_bf16 v[16:31], v[234:237], v[230:233], v[16:31]
	ds_read_b128 v[234:237], v205 offset:64
	s_waitcnt lgkmcnt(5)
	v_mfma_f32_32x32x16_bf16 v[64:79], v[238:241], v[226:229], v[64:79]
	v_mfma_f32_32x32x16_bf16 v[0:15], v[238:241], v[230:233], v[0:15]
	ds_read_b128 v[238:241], v205 offset:4672
	s_setprio 0
	global_load_dwordx4 v[226:229], v[184:185], off offset:1664
	global_load_dwordx4 v[230:233], v[186:187], off offset:1664
	s_setprio 1
	s_waitcnt lgkmcnt(1)
	v_mfma_f32_32x32x16_bf16 v[112:127], v[234:237], v[176:179], v[112:127]
	v_mfma_f32_32x32x16_bf16 v[48:63], v[234:237], v[180:183], v[48:63]
	s_waitcnt lgkmcnt(0)
	v_mfma_f32_32x32x16_bf16 v[96:111], v[238:241], v[176:179], v[96:111]
	v_mfma_f32_32x32x16_bf16 v[32:47], v[238:241], v[180:183], v[32:47]
	ds_read_b128 v[234:237], v205 offset:9280
	ds_read_b128 v[238:241], v205 offset:13888
	s_waitcnt vmcnt(7)
	ds_write_b128 v215, v[168:171] offset:27648
	s_waitcnt vmcnt(6)
	ds_write_b128 v215, v[172:175] offset:64512
	ds_read_b128 v[168:171], v208 offset:96
	ds_read_b128 v[172:175], v208 offset:4704
	s_waitcnt lgkmcnt(5)
	v_mfma_f32_32x32x16_bf16 v[80:95], v[234:237], v[176:179], v[80:95]
	v_mfma_f32_32x32x16_bf16 v[16:31], v[234:237], v[180:183], v[16:31]
	ds_read_b128 v[234:237], v205 offset:96
	s_waitcnt lgkmcnt(5)
	v_mfma_f32_32x32x16_bf16 v[64:79], v[238:241], v[176:179], v[64:79]
	v_mfma_f32_32x32x16_bf16 v[0:15], v[238:241], v[180:183], v[0:15]
	ds_read_b128 v[238:241], v205 offset:4704
	s_setprio 0
	global_load_dwordx4 v[176:179], v[198:199], off offset:1664
	global_load_dwordx4 v[180:183], v[200:201], off offset:1664
	s_setprio 1
	s_waitcnt lgkmcnt(1)
	v_mfma_f32_32x32x16_bf16 v[112:127], v[234:237], v[168:171], v[112:127]
	v_mfma_f32_32x32x16_bf16 v[48:63], v[234:237], v[172:175], v[48:63]
	s_waitcnt lgkmcnt(0)
	v_mfma_f32_32x32x16_bf16 v[96:111], v[238:241], v[168:171], v[96:111]
	v_mfma_f32_32x32x16_bf16 v[32:47], v[238:241], v[172:175], v[32:47]
	ds_read_b128 v[234:237], v205 offset:9312
	ds_read_b128 v[238:241], v205 offset:13920
	s_waitcnt lgkmcnt(0)
	s_barrier
; template <bool trans>
; DI void gemm_core(const GTile& tl, const GTile& nx, bool has_next  , bool chain  , bool pre, u32x4 (&ra)[4], u32x4 (&rb)[4], char* smem, f32x16 (&acc)[2][4]) {
;     ...
;   const int nk = K / 64;
;   if (!pre) { G_LOAD(0); G_STORE(0); G_LOAD(1); }
;   for (int kt = 0; kt < nk; ++kt) {
;     __syncthreads();
;     G_COMPUTE(kt & 1, kt);
;   }
	s_waitcnt vmcnt(7)
	ds_write_b128 v209, v[160:163]
	s_waitcnt vmcnt(6)
	ds_write_b128 v210, v[164:167]
	ds_read_b128 v[160:163], v204 offset:36864
	ds_read_b128 v[164:167], v204 offset:41472
	v_mfma_f32_32x32x16_bf16 v[80:95], v[234:237], v[168:171], v[80:95]
	v_mfma_f32_32x32x16_bf16 v[16:31], v[234:237], v[172:175], v[16:31]
	ds_read_b128 v[234:237], v192
	v_mfma_f32_32x32x16_bf16 v[64:79], v[238:241], v[168:171], v[64:79]
	v_mfma_f32_32x32x16_bf16 v[0:15], v[238:241], v[172:175], v[0:15]
	ds_read_b128 v[238:241], v192 offset:4608
	s_setprio 0
	global_load_dwordx4 v[168:171], v[190:191], off offset:1792
	global_load_dwordx4 v[172:175], v[188:189], off offset:1792
	s_setprio 1
	s_waitcnt lgkmcnt(1)
	v_mfma_f32_32x32x16_bf16 v[112:127], v[234:237], v[160:163], v[112:127]
	v_mfma_f32_32x32x16_bf16 v[48:63], v[234:237], v[164:167], v[48:63]
	s_waitcnt lgkmcnt(0)
	v_mfma_f32_32x32x16_bf16 v[96:111], v[238:241], v[160:163], v[96:111]
	v_mfma_f32_32x32x16_bf16 v[32:47], v[238:241], v[164:167], v[32:47]
	ds_read_b128 v[234:237], v192 offset:9216
	ds_read_b128 v[238:241], v192 offset:13824
	s_waitcnt vmcnt(7)
	ds_write_b128 v212, v[218:221]
	s_waitcnt vmcnt(6)
	ds_write_b128 v211, v[222:225]
	ds_read_b128 v[218:221], v204 offset:36896
	ds_read_b128 v[222:225], v204 offset:41504
	s_waitcnt lgkmcnt(5)
	v_mfma_f32_32x32x16_bf16 v[80:95], v[234:237], v[160:163], v[80:95]
	v_mfma_f32_32x32x16_bf16 v[16:31], v[234:237], v[164:167], v[16:31]
	ds_read_b128 v[234:237], v192 offset:32
	s_waitcnt lgkmcnt(5)
	v_mfma_f32_32x32x16_bf16 v[64:79], v[238:241], v[160:163], v[64:79]
	v_mfma_f32_32x32x16_bf16 v[0:15], v[238:241], v[164:167], v[0:15]
	ds_read_b128 v[238:241], v192 offset:4640
	s_setprio 0
	global_load_dwordx4 v[160:163], v[194:195], off offset:1792
	global_load_dwordx4 v[164:167], v[196:197], off offset:1792
	s_setprio 1
	s_waitcnt lgkmcnt(1)
	v_mfma_f32_32x32x16_bf16 v[112:127], v[234:237], v[218:221], v[112:127]
	v_mfma_f32_32x32x16_bf16 v[48:63], v[234:237], v[222:225], v[48:63]
	s_waitcnt lgkmcnt(0)
	v_mfma_f32_32x32x16_bf16 v[96:111], v[238:241], v[218:221], v[96:111]
	v_mfma_f32_32x32x16_bf16 v[32:47], v[238:241], v[222:225], v[32:47]
	ds_read_b128 v[234:237], v192 offset:9248
	ds_read_b128 v[238:241], v192 offset:13856
	s_waitcnt vmcnt(7)
	ds_write_b128 v214, v[226:229]
	s_waitcnt vmcnt(6)
	ds_write_b128 v213, v[230:233]
	ds_read_b128 v[226:229], v204 offset:36928
	ds_read_b128 v[230:233], v204 offset:41536
	s_waitcnt lgkmcnt(5)
	v_mfma_f32_32x32x16_bf16 v[80:95], v[234:237], v[218:221], v[80:95]
	v_mfma_f32_32x32x16_bf16 v[16:31], v[234:237], v[222:225], v[16:31]
	ds_read_b128 v[234:237], v192 offset:64
	s_waitcnt lgkmcnt(5)
	v_mfma_f32_32x32x16_bf16 v[64:79], v[238:241], v[218:221], v[64:79]
	v_mfma_f32_32x32x16_bf16 v[0:15], v[238:241], v[222:225], v[0:15]
	ds_read_b128 v[238:241], v192 offset:4672
	s_setprio 0
	global_load_dwordx4 v[218:221], v[184:185], off offset:1792
	global_load_dwordx4 v[222:225], v[186:187], off offset:1792
	s_setprio 1
	s_waitcnt lgkmcnt(1)
	v_mfma_f32_32x32x16_bf16 v[112:127], v[234:237], v[226:229], v[112:127]
	v_mfma_f32_32x32x16_bf16 v[48:63], v[234:237], v[230:233], v[48:63]
	s_waitcnt lgkmcnt(0)
	v_mfma_f32_32x32x16_bf16 v[96:111], v[238:241], v[226:229], v[96:111]
	v_mfma_f32_32x32x16_bf16 v[32:47], v[238:241], v[230:233], v[32:47]
	ds_read_b128 v[234:237], v192 offset:9280
	ds_read_b128 v[238:241], v192 offset:13888
	s_waitcnt vmcnt(7)
	ds_write_b128 v217, v[176:179]
	s_waitcnt vmcnt(6)
	ds_write_b128 v216, v[180:183]
	ds_read_b128 v[176:179], v204 offset:36960
	ds_read_b128 v[180:183], v204 offset:41568
	s_waitcnt lgkmcnt(5)
	v_mfma_f32_32x32x16_bf16 v[80:95], v[234:237], v[226:229], v[80:95]
	v_mfma_f32_32x32x16_bf16 v[16:31], v[234:237], v[230:233], v[16:31]
	ds_read_b128 v[234:237], v192 offset:96
	s_waitcnt lgkmcnt(5)
	v_mfma_f32_32x32x16_bf16 v[64:79], v[238:241], v[226:229], v[64:79]
	v_mfma_f32_32x32x16_bf16 v[0:15], v[238:241], v[230:233], v[0:15]
	ds_read_b128 v[238:241], v192 offset:4704
	s_setprio 0
	global_load_dwordx4 v[226:229], v[198:199], off offset:1792
	global_load_dwordx4 v[230:233], v[200:201], off offset:1792
	s_setprio 1
	s_waitcnt lgkmcnt(1)
	v_mfma_f32_32x32x16_bf16 v[112:127], v[234:237], v[176:179], v[112:127]
	v_mfma_f32_32x32x16_bf16 v[48:63], v[234:237], v[180:183], v[48:63]
	s_waitcnt lgkmcnt(0)
	v_mfma_f32_32x32x16_bf16 v[96:111], v[238:241], v[176:179], v[96:111]
	v_mfma_f32_32x32x16_bf16 v[32:47], v[238:241], v[180:183], v[32:47]
	ds_read_b128 v[234:237], v192 offset:9312
	ds_read_b128 v[238:241], v192 offset:13920
	s_waitcnt lgkmcnt(0)
	s_barrier
; template <bool trans>
; DI void gemm_core(const GTile& tl, const GTile& nx, bool has_next  , bool chain  , bool pre, u32x4 (&ra)[4], u32x4 (&rb)[4], char* smem, f32x16 (&acc)[2][4]) {
;     ...
;   const int nk = K / 64;
;   if (!pre) { G_LOAD(0); G_STORE(0); G_LOAD(1); }
;   for (int kt = 0; kt < nk; ++kt) {
;     __syncthreads();
;     G_COMPUTE(kt & 1, kt);
;   }
	s_waitcnt vmcnt(7)
	ds_write_b128 v215, v[168:171]
	s_waitcnt vmcnt(6)
	ds_write_b128 v215, v[172:175] offset:36864
	ds_read_b128 v[168:171], v208
	ds_read_b128 v[172:175], v208 offset:4608
	v_mfma_f32_32x32x16_bf16 v[80:95], v[234:237], v[176:179], v[80:95]
	v_mfma_f32_32x32x16_bf16 v[16:31], v[234:237], v[180:183], v[16:31]
	ds_read_b128 v[234:237], v205
	v_mfma_f32_32x32x16_bf16 v[64:79], v[238:241], v[176:179], v[64:79]
	v_mfma_f32_32x32x16_bf16 v[0:15], v[238:241], v[180:183], v[0:15]
	ds_read_b128 v[238:241], v205 offset:4608
	s_setprio 0
	global_load_dwordx4 v[176:179], v[190:191], off offset:1920
	global_load_dwordx4 v[180:183], v[188:189], off offset:1920
	s_setprio 1
	s_waitcnt lgkmcnt(1)
	v_mfma_f32_32x32x16_bf16 v[112:127], v[234:237], v[168:171], v[112:127]
	v_mfma_f32_32x32x16_bf16 v[48:63], v[234:237], v[172:175], v[48:63]
	s_waitcnt lgkmcnt(0)
	v_mfma_f32_32x32x16_bf16 v[96:111], v[238:241], v[168:171], v[96:111]
	v_mfma_f32_32x32x16_bf16 v[32:47], v[238:241], v[172:175], v[32:47]
	ds_read_b128 v[234:237], v205 offset:9216
	ds_read_b128 v[238:241], v205 offset:13824
	s_waitcnt vmcnt(7)
	ds_write_b128 v215, v[160:163] offset:9216
	s_waitcnt vmcnt(6)
	ds_write_b128 v215, v[164:167] offset:46080
	ds_read_b128 v[160:163], v208 offset:32
	ds_read_b128 v[164:167], v208 offset:4640
	s_waitcnt lgkmcnt(5)
	v_mfma_f32_32x32x16_bf16 v[80:95], v[234:237], v[168:171], v[80:95]
	v_mfma_f32_32x32x16_bf16 v[16:31], v[234:237], v[172:175], v[16:31]
	ds_read_b128 v[234:237], v205 offset:32
	s_waitcnt lgkmcnt(5)
	v_mfma_f32_32x32x16_bf16 v[64:79], v[238:241], v[168:171], v[64:79]
	v_mfma_f32_32x32x16_bf16 v[0:15], v[238:241], v[172:175], v[0:15]
	ds_read_b128 v[238:241], v205 offset:4640
	s_setprio 0
	global_load_dwordx4 v[168:171], v[194:195], off offset:1920
	global_load_dwordx4 v[172:175], v[196:197], off offset:1920
	s_setprio 1
	s_waitcnt lgkmcnt(1)
	v_mfma_f32_32x32x16_bf16 v[112:127], v[234:237], v[160:163], v[112:127]
	v_mfma_f32_32x32x16_bf16 v[48:63], v[234:237], v[164:167], v[48:63]
	s_waitcnt lgkmcnt(0)
	v_mfma_f32_32x32x16_bf16 v[96:111], v[238:241], v[160:163], v[96:111]
	v_mfma_f32_32x32x16_bf16 v[32:47], v[238:241], v[164:167], v[32:47]
	ds_read_b128 v[234:237], v205 offset:9248
	ds_read_b128 v[238:241], v205 offset:13856
	s_waitcnt vmcnt(7)
	ds_write_b128 v215, v[218:221] offset:18432
	s_waitcnt vmcnt(6)
	ds_write_b128 v215, v[222:225] offset:55296
	ds_read_b128 v[218:221], v208 offset:64
	ds_read_b128 v[222:225], v208 offset:4672
	s_waitcnt lgkmcnt(5)
	v_mfma_f32_32x32x16_bf16 v[80:95], v[234:237], v[160:163], v[80:95]
	v_mfma_f32_32x32x16_bf16 v[16:31], v[234:237], v[164:167], v[16:31]
	ds_read_b128 v[234:237], v205 offset:64
	s_waitcnt lgkmcnt(5)
	v_mfma_f32_32x32x16_bf16 v[64:79], v[238:241], v[160:163], v[64:79]
	v_mfma_f32_32x32x16_bf16 v[0:15], v[238:241], v[164:167], v[0:15]
	ds_read_b128 v[238:241], v205 offset:4672
	s_setprio 0
	global_load_dwordx4 v[160:163], v[184:185], off offset:1920
	global_load_dwordx4 v[164:167], v[186:187], off offset:1920
	s_setprio 1
	s_waitcnt lgkmcnt(1)
	v_mfma_f32_32x32x16_bf16 v[112:127], v[234:237], v[218:221], v[112:127]
	v_mfma_f32_32x32x16_bf16 v[48:63], v[234:237], v[222:225], v[48:63]
	s_waitcnt lgkmcnt(0)
	v_mfma_f32_32x32x16_bf16 v[96:111], v[238:241], v[218:221], v[96:111]
	v_mfma_f32_32x32x16_bf16 v[32:47], v[238:241], v[222:225], v[32:47]
	ds_read_b128 v[234:237], v205 offset:9280
	ds_read_b128 v[238:241], v205 offset:13888
	s_waitcnt vmcnt(7)
	ds_write_b128 v215, v[226:229] offset:27648
	s_waitcnt vmcnt(6)
	ds_write_b128 v215, v[230:233] offset:64512
	ds_read_b128 v[226:229], v208 offset:96
	ds_read_b128 v[230:233], v208 offset:4704
	s_waitcnt lgkmcnt(5)
	v_mfma_f32_32x32x16_bf16 v[80:95], v[234:237], v[218:221], v[80:95]
	v_mfma_f32_32x32x16_bf16 v[16:31], v[234:237], v[222:225], v[16:31]
	ds_read_b128 v[234:237], v205 offset:96
	s_waitcnt lgkmcnt(5)
	v_mfma_f32_32x32x16_bf16 v[64:79], v[238:241], v[218:221], v[64:79]
	v_mfma_f32_32x32x16_bf16 v[0:15], v[238:241], v[222:225], v[0:15]
	ds_read_b128 v[238:241], v205 offset:4704
	s_setprio 0
	global_load_dwordx4 v[218:221], v[198:199], off offset:1920
	global_load_dwordx4 v[222:225], v[200:201], off offset:1920
	s_setprio 1
	s_waitcnt lgkmcnt(1)
	v_mfma_f32_32x32x16_bf16 v[112:127], v[234:237], v[226:229], v[112:127]
	v_mfma_f32_32x32x16_bf16 v[48:63], v[234:237], v[230:233], v[48:63]
	s_waitcnt lgkmcnt(0)
	v_mfma_f32_32x32x16_bf16 v[96:111], v[238:241], v[226:229], v[96:111]
	v_mfma_f32_32x32x16_bf16 v[32:47], v[238:241], v[230:233], v[32:47]
	ds_read_b128 v[234:237], v205 offset:9312
	ds_read_b128 v[238:241], v205 offset:13920
	s_waitcnt lgkmcnt(0)
	s_barrier
; template <bool trans>
; DI void gemm_core(const GTile& tl, const GTile& nx, bool has_next  , bool chain  , bool pre, u32x4 (&ra)[4], u32x4 (&rb)[4], char* smem, f32x16 (&acc)[2][4]) {
;     ...
;   const int nk = K / 64;
;   if (!pre) { G_LOAD(0); G_STORE(0); G_LOAD(1); }
;   for (int kt = 0; kt < nk; ++kt) {
;     __syncthreads();
;     G_COMPUTE(kt & 1, kt);
;   }
	s_waitcnt vmcnt(7)
	ds_write_b128 v209, v[176:179]
	s_waitcnt vmcnt(6)
	ds_write_b128 v210, v[180:183]
	ds_read_b128 v[176:179], v204 offset:36864
	ds_read_b128 v[180:183], v204 offset:41472
	v_mfma_f32_32x32x16_bf16 v[80:95], v[234:237], v[226:229], v[80:95]
	v_mfma_f32_32x32x16_bf16 v[16:31], v[234:237], v[230:233], v[16:31]
	ds_read_b128 v[234:237], v192
	v_mfma_f32_32x32x16_bf16 v[64:79], v[238:241], v[226:229], v[64:79]
	v_mfma_f32_32x32x16_bf16 v[0:15], v[238:241], v[230:233], v[0:15]
	ds_read_b128 v[238:241], v192 offset:4608
	s_setprio 0
	global_load_dwordx4 v[226:229], v[190:191], off offset:2048
	global_load_dwordx4 v[230:233], v[188:189], off offset:2048
	s_setprio 1
	s_waitcnt lgkmcnt(1)
	v_mfma_f32_32x32x16_bf16 v[112:127], v[234:237], v[176:179], v[112:127]
	v_mfma_f32_32x32x16_bf16 v[48:63], v[234:237], v[180:183], v[48:63]
	s_waitcnt lgkmcnt(0)
	v_mfma_f32_32x32x16_bf16 v[96:111], v[238:241], v[176:179], v[96:111]
	v_mfma_f32_32x32x16_bf16 v[32:47], v[238:241], v[180:183], v[32:47]
	ds_read_b128 v[234:237], v192 offset:9216
	ds_read_b128 v[238:241], v192 offset:13824
	s_waitcnt vmcnt(7)
	ds_write_b128 v212, v[168:171]
	s_waitcnt vmcnt(6)
	ds_write_b128 v211, v[172:175]
	ds_read_b128 v[168:171], v204 offset:36896
	ds_read_b128 v[172:175], v204 offset:41504
	s_waitcnt lgkmcnt(5)
	v_mfma_f32_32x32x16_bf16 v[80:95], v[234:237], v[176:179], v[80:95]
	v_mfma_f32_32x32x16_bf16 v[16:31], v[234:237], v[180:183], v[16:31]
	ds_read_b128 v[234:237], v192 offset:32
	s_waitcnt lgkmcnt(5)
	v_mfma_f32_32x32x16_bf16 v[64:79], v[238:241], v[176:179], v[64:79]
	v_mfma_f32_32x32x16_bf16 v[0:15], v[238:241], v[180:183], v[0:15]
	ds_read_b128 v[238:241], v192 offset:4640
	s_setprio 0
	global_load_dwordx4 v[176:179], v[194:195], off offset:2048
	global_load_dwordx4 v[180:183], v[196:197], off offset:2048
	s_setprio 1
	s_waitcnt lgkmcnt(1)
	v_mfma_f32_32x32x16_bf16 v[112:127], v[234:237], v[168:171], v[112:127]
	v_mfma_f32_32x32x16_bf16 v[48:63], v[234:237], v[172:175], v[48:63]
	s_waitcnt lgkmcnt(0)
	v_mfma_f32_32x32x16_bf16 v[96:111], v[238:241], v[168:171], v[96:111]
	v_mfma_f32_32x32x16_bf16 v[32:47], v[238:241], v[172:175], v[32:47]
	ds_read_b128 v[234:237], v192 offset:9248
	ds_read_b128 v[238:241], v192 offset:13856
	s_waitcnt vmcnt(7)
	ds_write_b128 v214, v[160:163]
	s_waitcnt vmcnt(6)
	ds_write_b128 v213, v[164:167]
	ds_read_b128 v[160:163], v204 offset:36928
	ds_read_b128 v[164:167], v204 offset:41536
	s_waitcnt lgkmcnt(5)
	v_mfma_f32_32x32x16_bf16 v[80:95], v[234:237], v[168:171], v[80:95]
	v_mfma_f32_32x32x16_bf16 v[16:31], v[234:237], v[172:175], v[16:31]
	ds_read_b128 v[234:237], v192 offset:64
	s_waitcnt lgkmcnt(5)
	v_mfma_f32_32x32x16_bf16 v[64:79], v[238:241], v[168:171], v[64:79]
	v_mfma_f32_32x32x16_bf16 v[0:15], v[238:241], v[172:175], v[0:15]
	ds_read_b128 v[238:241], v192 offset:4672
	s_setprio 0
	global_load_dwordx4 v[168:171], v[184:185], off offset:2048
	global_load_dwordx4 v[172:175], v[186:187], off offset:2048
	s_setprio 1
	s_waitcnt lgkmcnt(1)
	v_mfma_f32_32x32x16_bf16 v[112:127], v[234:237], v[160:163], v[112:127]
	v_mfma_f32_32x32x16_bf16 v[48:63], v[234:237], v[164:167], v[48:63]
	s_waitcnt lgkmcnt(0)
	v_mfma_f32_32x32x16_bf16 v[96:111], v[238:241], v[160:163], v[96:111]
	v_mfma_f32_32x32x16_bf16 v[32:47], v[238:241], v[164:167], v[32:47]
	ds_read_b128 v[234:237], v192 offset:9280
	ds_read_b128 v[238:241], v192 offset:13888
	s_waitcnt vmcnt(7)
	ds_write_b128 v217, v[218:221]
	s_waitcnt vmcnt(6)
	ds_write_b128 v216, v[222:225]
	ds_read_b128 v[218:221], v204 offset:36960
	ds_read_b128 v[222:225], v204 offset:41568
	s_waitcnt lgkmcnt(5)
	v_mfma_f32_32x32x16_bf16 v[80:95], v[234:237], v[160:163], v[80:95]
	v_mfma_f32_32x32x16_bf16 v[16:31], v[234:237], v[164:167], v[16:31]
	ds_read_b128 v[234:237], v192 offset:96
	s_waitcnt lgkmcnt(5)
	v_mfma_f32_32x32x16_bf16 v[64:79], v[238:241], v[160:163], v[64:79]
	v_mfma_f32_32x32x16_bf16 v[0:15], v[238:241], v[164:167], v[0:15]
	ds_read_b128 v[238:241], v192 offset:4704
	s_setprio 0
	global_load_dwordx4 v[160:163], v[198:199], off offset:2048
	global_load_dwordx4 v[164:167], v[200:201], off offset:2048
	s_setprio 1
	s_waitcnt lgkmcnt(1)
	v_mfma_f32_32x32x16_bf16 v[112:127], v[234:237], v[218:221], v[112:127]
	v_mfma_f32_32x32x16_bf16 v[48:63], v[234:237], v[222:225], v[48:63]
	s_waitcnt lgkmcnt(0)
	v_mfma_f32_32x32x16_bf16 v[96:111], v[238:241], v[218:221], v[96:111]
	v_mfma_f32_32x32x16_bf16 v[32:47], v[238:241], v[222:225], v[32:47]
	ds_read_b128 v[234:237], v192 offset:9312
	ds_read_b128 v[238:241], v192 offset:13920
	s_waitcnt lgkmcnt(0)
	s_barrier
; template <bool trans>
; DI void gemm_core(const GTile& tl, const GTile& nx, bool has_next  , bool chain  , bool pre, u32x4 (&ra)[4], u32x4 (&rb)[4], char* smem, f32x16 (&acc)[2][4]) {
;     ...
;   const int nk = K / 64;
;   if (!pre) { G_LOAD(0); G_STORE(0); G_LOAD(1); }
;   for (int kt = 0; kt < nk; ++kt) {
;     __syncthreads();
;     G_COMPUTE(kt & 1, kt);
;   }
	s_waitcnt vmcnt(7)
	ds_write_b128 v215, v[226:229]
	s_waitcnt vmcnt(6)
	ds_write_b128 v215, v[230:233] offset:36864
	ds_read_b128 v[226:229], v208
	ds_read_b128 v[230:233], v208 offset:4608
	v_mfma_f32_32x32x16_bf16 v[80:95], v[234:237], v[218:221], v[80:95]
	v_mfma_f32_32x32x16_bf16 v[16:31], v[234:237], v[222:225], v[16:31]
	ds_read_b128 v[234:237], v205
	v_mfma_f32_32x32x16_bf16 v[64:79], v[238:241], v[218:221], v[64:79]
	v_mfma_f32_32x32x16_bf16 v[0:15], v[238:241], v[222:225], v[0:15]
	ds_read_b128 v[238:241], v205 offset:4608
	s_setprio 0
	global_load_dwordx4 v[218:221], v[190:191], off offset:2176
	global_load_dwordx4 v[222:225], v[188:189], off offset:2176
	s_setprio 1
	s_waitcnt lgkmcnt(1)
	v_mfma_f32_32x32x16_bf16 v[112:127], v[234:237], v[226:229], v[112:127]
	v_mfma_f32_32x32x16_bf16 v[48:63], v[234:237], v[230:233], v[48:63]
	s_waitcnt lgkmcnt(0)
	v_mfma_f32_32x32x16_bf16 v[96:111], v[238:241], v[226:229], v[96:111]
	v_mfma_f32_32x32x16_bf16 v[32:47], v[238:241], v[230:233], v[32:47]
	ds_read_b128 v[234:237], v205 offset:9216
	ds_read_b128 v[238:241], v205 offset:13824
	s_waitcnt vmcnt(7)
	ds_write_b128 v215, v[176:179] offset:9216
	s_waitcnt vmcnt(6)
	ds_write_b128 v215, v[180:183] offset:46080
	ds_read_b128 v[176:179], v208 offset:32
	ds_read_b128 v[180:183], v208 offset:4640
	s_waitcnt lgkmcnt(5)
	v_mfma_f32_32x32x16_bf16 v[80:95], v[234:237], v[226:229], v[80:95]
	v_mfma_f32_32x32x16_bf16 v[16:31], v[234:237], v[230:233], v[16:31]
	ds_read_b128 v[234:237], v205 offset:32
	s_waitcnt lgkmcnt(5)
	v_mfma_f32_32x32x16_bf16 v[64:79], v[238:241], v[226:229], v[64:79]
	v_mfma_f32_32x32x16_bf16 v[0:15], v[238:241], v[230:233], v[0:15]
	ds_read_b128 v[238:241], v205 offset:4640
	s_setprio 0
	global_load_dwordx4 v[226:229], v[194:195], off offset:2176
	global_load_dwordx4 v[230:233], v[196:197], off offset:2176
	s_setprio 1
	s_waitcnt lgkmcnt(1)
	v_mfma_f32_32x32x16_bf16 v[112:127], v[234:237], v[176:179], v[112:127]
	v_mfma_f32_32x32x16_bf16 v[48:63], v[234:237], v[180:183], v[48:63]
	s_waitcnt lgkmcnt(0)
	v_mfma_f32_32x32x16_bf16 v[96:111], v[238:241], v[176:179], v[96:111]
	v_mfma_f32_32x32x16_bf16 v[32:47], v[238:241], v[180:183], v[32:47]
	ds_read_b128 v[234:237], v205 offset:9248
	ds_read_b128 v[238:241], v205 offset:13856
	s_waitcnt vmcnt(7)
	ds_write_b128 v215, v[168:171] offset:18432
	s_waitcnt vmcnt(6)
	ds_write_b128 v215, v[172:175] offset:55296
	ds_read_b128 v[168:171], v208 offset:64
	ds_read_b128 v[172:175], v208 offset:4672
	s_waitcnt lgkmcnt(5)
	v_mfma_f32_32x32x16_bf16 v[80:95], v[234:237], v[176:179], v[80:95]
	v_mfma_f32_32x32x16_bf16 v[16:31], v[234:237], v[180:183], v[16:31]
	ds_read_b128 v[234:237], v205 offset:64
	s_waitcnt lgkmcnt(5)
	v_mfma_f32_32x32x16_bf16 v[64:79], v[238:241], v[176:179], v[64:79]
	v_mfma_f32_32x32x16_bf16 v[0:15], v[238:241], v[180:183], v[0:15]
	ds_read_b128 v[238:241], v205 offset:4672
	s_setprio 0
	global_load_dwordx4 v[176:179], v[184:185], off offset:2176
	global_load_dwordx4 v[180:183], v[186:187], off offset:2176
	s_setprio 1
	s_waitcnt lgkmcnt(1)
	v_mfma_f32_32x32x16_bf16 v[112:127], v[234:237], v[168:171], v[112:127]
	v_mfma_f32_32x32x16_bf16 v[48:63], v[234:237], v[172:175], v[48:63]
	s_waitcnt lgkmcnt(0)
	v_mfma_f32_32x32x16_bf16 v[96:111], v[238:241], v[168:171], v[96:111]
	v_mfma_f32_32x32x16_bf16 v[32:47], v[238:241], v[172:175], v[32:47]
	ds_read_b128 v[234:237], v205 offset:9280
	ds_read_b128 v[238:241], v205 offset:13888
	s_waitcnt vmcnt(7)
	ds_write_b128 v215, v[160:163] offset:27648
	s_waitcnt vmcnt(6)
	ds_write_b128 v215, v[164:167] offset:64512
	ds_read_b128 v[160:163], v208 offset:96
	ds_read_b128 v[164:167], v208 offset:4704
	s_waitcnt lgkmcnt(5)
	v_mfma_f32_32x32x16_bf16 v[80:95], v[234:237], v[168:171], v[80:95]
	v_mfma_f32_32x32x16_bf16 v[16:31], v[234:237], v[172:175], v[16:31]
	ds_read_b128 v[234:237], v205 offset:96
	s_waitcnt lgkmcnt(5)
	v_mfma_f32_32x32x16_bf16 v[64:79], v[238:241], v[168:171], v[64:79]
	v_mfma_f32_32x32x16_bf16 v[0:15], v[238:241], v[172:175], v[0:15]
	ds_read_b128 v[238:241], v205 offset:4704
	s_setprio 0
	global_load_dwordx4 v[168:171], v[198:199], off offset:2176
	global_load_dwordx4 v[172:175], v[200:201], off offset:2176
	s_setprio 1
	s_waitcnt lgkmcnt(1)
	v_mfma_f32_32x32x16_bf16 v[112:127], v[234:237], v[160:163], v[112:127]
	v_mfma_f32_32x32x16_bf16 v[48:63], v[234:237], v[164:167], v[48:63]
	s_waitcnt lgkmcnt(0)
	v_mfma_f32_32x32x16_bf16 v[96:111], v[238:241], v[160:163], v[96:111]
	v_mfma_f32_32x32x16_bf16 v[32:47], v[238:241], v[164:167], v[32:47]
	ds_read_b128 v[234:237], v205 offset:9312
	ds_read_b128 v[238:241], v205 offset:13920
	s_waitcnt lgkmcnt(0)
	s_barrier
; template <bool trans>
; DI void gemm_core(const GTile& tl, const GTile& nx, bool has_next  , bool chain  , bool pre, u32x4 (&ra)[4], u32x4 (&rb)[4], char* smem, f32x16 (&acc)[2][4]) {
;     ...
;   const int nk = K / 64;
;   if (!pre) { G_LOAD(0); G_STORE(0); G_LOAD(1); }
;   for (int kt = 0; kt < nk; ++kt) {
;     __syncthreads();
;     G_COMPUTE(kt & 1, kt);
;   }
	s_waitcnt vmcnt(7)
	ds_write_b128 v209, v[218:221]
	s_waitcnt vmcnt(6)
	ds_write_b128 v210, v[222:225]
	ds_read_b128 v[218:221], v204 offset:36864
	ds_read_b128 v[222:225], v204 offset:41472
	v_mfma_f32_32x32x16_bf16 v[80:95], v[234:237], v[160:163], v[80:95]
	v_mfma_f32_32x32x16_bf16 v[16:31], v[234:237], v[164:167], v[16:31]
	ds_read_b128 v[234:237], v192
	v_mfma_f32_32x32x16_bf16 v[64:79], v[238:241], v[160:163], v[64:79]
	v_mfma_f32_32x32x16_bf16 v[0:15], v[238:241], v[164:167], v[0:15]
	ds_read_b128 v[238:241], v192 offset:4608
	s_setprio 0
	global_load_dwordx4 v[160:163], v[190:191], off offset:2304
	global_load_dwordx4 v[164:167], v[188:189], off offset:2304
	s_setprio 1
	s_waitcnt lgkmcnt(1)
	v_mfma_f32_32x32x16_bf16 v[112:127], v[234:237], v[218:221], v[112:127]
	v_mfma_f32_32x32x16_bf16 v[48:63], v[234:237], v[222:225], v[48:63]
	s_waitcnt lgkmcnt(0)
	v_mfma_f32_32x32x16_bf16 v[96:111], v[238:241], v[218:221], v[96:111]
	v_mfma_f32_32x32x16_bf16 v[32:47], v[238:241], v[222:225], v[32:47]
	ds_read_b128 v[234:237], v192 offset:9216
	ds_read_b128 v[238:241], v192 offset:13824
	s_waitcnt vmcnt(7)
	ds_write_b128 v212, v[226:229]
	s_waitcnt vmcnt(6)
	ds_write_b128 v211, v[230:233]
	ds_read_b128 v[226:229], v204 offset:36896
	ds_read_b128 v[230:233], v204 offset:41504
	s_waitcnt lgkmcnt(5)
	v_mfma_f32_32x32x16_bf16 v[80:95], v[234:237], v[218:221], v[80:95]
	v_mfma_f32_32x32x16_bf16 v[16:31], v[234:237], v[222:225], v[16:31]
	ds_read_b128 v[234:237], v192 offset:32
	s_waitcnt lgkmcnt(5)
	v_mfma_f32_32x32x16_bf16 v[64:79], v[238:241], v[218:221], v[64:79]
	v_mfma_f32_32x32x16_bf16 v[0:15], v[238:241], v[222:225], v[0:15]
	ds_read_b128 v[238:241], v192 offset:4640
	s_setprio 0
	global_load_dwordx4 v[218:221], v[194:195], off offset:2304
	global_load_dwordx4 v[222:225], v[196:197], off offset:2304
	s_setprio 1
	s_waitcnt lgkmcnt(1)
	v_mfma_f32_32x32x16_bf16 v[112:127], v[234:237], v[226:229], v[112:127]
	v_mfma_f32_32x32x16_bf16 v[48:63], v[234:237], v[230:233], v[48:63]
	s_waitcnt lgkmcnt(0)
	v_mfma_f32_32x32x16_bf16 v[96:111], v[238:241], v[226:229], v[96:111]
	v_mfma_f32_32x32x16_bf16 v[32:47], v[238:241], v[230:233], v[32:47]
	ds_read_b128 v[234:237], v192 offset:9248
	ds_read_b128 v[238:241], v192 offset:13856
	s_waitcnt vmcnt(7)
	ds_write_b128 v214, v[176:179]
	s_waitcnt vmcnt(6)
	ds_write_b128 v213, v[180:183]
	ds_read_b128 v[176:179], v204 offset:36928
	ds_read_b128 v[180:183], v204 offset:41536
	s_waitcnt lgkmcnt(5)
	v_mfma_f32_32x32x16_bf16 v[80:95], v[234:237], v[226:229], v[80:95]
	v_mfma_f32_32x32x16_bf16 v[16:31], v[234:237], v[230:233], v[16:31]
	ds_read_b128 v[234:237], v192 offset:64
	s_waitcnt lgkmcnt(5)
	v_mfma_f32_32x32x16_bf16 v[64:79], v[238:241], v[226:229], v[64:79]
	v_mfma_f32_32x32x16_bf16 v[0:15], v[238:241], v[230:233], v[0:15]
	ds_read_b128 v[238:241], v192 offset:4672
	s_setprio 0
	global_load_dwordx4 v[226:229], v[184:185], off offset:2304
	global_load_dwordx4 v[230:233], v[186:187], off offset:2304
	s_setprio 1
	s_waitcnt lgkmcnt(1)
	v_mfma_f32_32x32x16_bf16 v[112:127], v[234:237], v[176:179], v[112:127]
	v_mfma_f32_32x32x16_bf16 v[48:63], v[234:237], v[180:183], v[48:63]
	s_waitcnt lgkmcnt(0)
	v_mfma_f32_32x32x16_bf16 v[96:111], v[238:241], v[176:179], v[96:111]
	v_mfma_f32_32x32x16_bf16 v[32:47], v[238:241], v[180:183], v[32:47]
	ds_read_b128 v[234:237], v192 offset:9280
	ds_read_b128 v[238:241], v192 offset:13888
	s_waitcnt vmcnt(7)
	ds_write_b128 v217, v[168:171]
	s_waitcnt vmcnt(6)
	ds_write_b128 v216, v[172:175]
	ds_read_b128 v[168:171], v204 offset:36960
	ds_read_b128 v[172:175], v204 offset:41568
	s_waitcnt lgkmcnt(5)
	v_mfma_f32_32x32x16_bf16 v[80:95], v[234:237], v[176:179], v[80:95]
	v_mfma_f32_32x32x16_bf16 v[16:31], v[234:237], v[180:183], v[16:31]
	ds_read_b128 v[234:237], v192 offset:96
	s_waitcnt lgkmcnt(5)
	v_mfma_f32_32x32x16_bf16 v[64:79], v[238:241], v[176:179], v[64:79]
	v_mfma_f32_32x32x16_bf16 v[0:15], v[238:241], v[180:183], v[0:15]
	ds_read_b128 v[238:241], v192 offset:4704
	s_setprio 0
	global_load_dwordx4 v[176:179], v[198:199], off offset:2304
	global_load_dwordx4 v[180:183], v[200:201], off offset:2304
	s_setprio 1
	s_waitcnt lgkmcnt(1)
	v_mfma_f32_32x32x16_bf16 v[112:127], v[234:237], v[168:171], v[112:127]
	v_mfma_f32_32x32x16_bf16 v[48:63], v[234:237], v[172:175], v[48:63]
	s_waitcnt lgkmcnt(0)
	v_mfma_f32_32x32x16_bf16 v[96:111], v[238:241], v[168:171], v[96:111]
	v_mfma_f32_32x32x16_bf16 v[32:47], v[238:241], v[172:175], v[32:47]
	ds_read_b128 v[234:237], v192 offset:9312
	ds_read_b128 v[238:241], v192 offset:13920
	s_waitcnt lgkmcnt(0)
	s_barrier
; template <bool trans>
; DI void gemm_core(const GTile& tl, const GTile& nx, bool has_next  , bool chain  , bool pre, u32x4 (&ra)[4], u32x4 (&rb)[4], char* smem, f32x16 (&acc)[2][4]) {
;     ...
;   const int nk = K / 64;
;   if (!pre) { G_LOAD(0); G_STORE(0); G_LOAD(1); }
;   for (int kt = 0; kt < nk; ++kt) {
;     __syncthreads();
;     G_COMPUTE(kt & 1, kt);
;   }
	s_waitcnt vmcnt(7)
	ds_write_b128 v215, v[160:163]
	s_waitcnt vmcnt(6)
	ds_write_b128 v215, v[164:167] offset:36864
	ds_read_b128 v[160:163], v208
	ds_read_b128 v[164:167], v208 offset:4608
	v_mfma_f32_32x32x16_bf16 v[80:95], v[234:237], v[168:171], v[80:95]
	v_mfma_f32_32x32x16_bf16 v[16:31], v[234:237], v[172:175], v[16:31]
	ds_read_b128 v[234:237], v205
	v_mfma_f32_32x32x16_bf16 v[64:79], v[238:241], v[168:171], v[64:79]
	v_mfma_f32_32x32x16_bf16 v[0:15], v[238:241], v[172:175], v[0:15]
	ds_read_b128 v[238:241], v205 offset:4608
	s_setprio 0
	global_load_dwordx4 v[168:171], v[190:191], off offset:2432
	global_load_dwordx4 v[172:175], v[188:189], off offset:2432
	s_setprio 1
	s_waitcnt lgkmcnt(1)
	v_mfma_f32_32x32x16_bf16 v[112:127], v[234:237], v[160:163], v[112:127]
	v_mfma_f32_32x32x16_bf16 v[48:63], v[234:237], v[164:167], v[48:63]
	s_waitcnt lgkmcnt(0)
	v_mfma_f32_32x32x16_bf16 v[96:111], v[238:241], v[160:163], v[96:111]
	v_mfma_f32_32x32x16_bf16 v[32:47], v[238:241], v[164:167], v[32:47]
	ds_read_b128 v[234:237], v205 offset:9216
	ds_read_b128 v[238:241], v205 offset:13824
	s_waitcnt vmcnt(7)
	ds_write_b128 v215, v[218:221] offset:9216
	s_waitcnt vmcnt(6)
	ds_write_b128 v215, v[222:225] offset:46080
	ds_read_b128 v[218:221], v208 offset:32
	ds_read_b128 v[222:225], v208 offset:4640
	s_waitcnt lgkmcnt(5)
	v_mfma_f32_32x32x16_bf16 v[80:95], v[234:237], v[160:163], v[80:95]
	v_mfma_f32_32x32x16_bf16 v[16:31], v[234:237], v[164:167], v[16:31]
	ds_read_b128 v[234:237], v205 offset:32
	s_waitcnt lgkmcnt(5)
	v_mfma_f32_32x32x16_bf16 v[64:79], v[238:241], v[160:163], v[64:79]
	v_mfma_f32_32x32x16_bf16 v[0:15], v[238:241], v[164:167], v[0:15]
	ds_read_b128 v[238:241], v205 offset:4640
	s_setprio 0
	global_load_dwordx4 v[160:163], v[194:195], off offset:2432
	global_load_dwordx4 v[164:167], v[196:197], off offset:2432
	s_setprio 1
	s_waitcnt lgkmcnt(1)
	v_mfma_f32_32x32x16_bf16 v[112:127], v[234:237], v[218:221], v[112:127]
	v_mfma_f32_32x32x16_bf16 v[48:63], v[234:237], v[222:225], v[48:63]
	s_waitcnt lgkmcnt(0)
	v_mfma_f32_32x32x16_bf16 v[96:111], v[238:241], v[218:221], v[96:111]
	v_mfma_f32_32x32x16_bf16 v[32:47], v[238:241], v[222:225], v[32:47]
	ds_read_b128 v[234:237], v205 offset:9248
	ds_read_b128 v[238:241], v205 offset:13856
	s_waitcnt vmcnt(7)
	ds_write_b128 v215, v[226:229] offset:18432
	s_waitcnt vmcnt(6)
	ds_write_b128 v215, v[230:233] offset:55296
	ds_read_b128 v[226:229], v208 offset:64
	ds_read_b128 v[230:233], v208 offset:4672
	s_waitcnt lgkmcnt(5)
	v_mfma_f32_32x32x16_bf16 v[80:95], v[234:237], v[218:221], v[80:95]
	v_mfma_f32_32x32x16_bf16 v[16:31], v[234:237], v[222:225], v[16:31]
	ds_read_b128 v[234:237], v205 offset:64
	s_waitcnt lgkmcnt(5)
	v_mfma_f32_32x32x16_bf16 v[64:79], v[238:241], v[218:221], v[64:79]
	v_mfma_f32_32x32x16_bf16 v[0:15], v[238:241], v[222:225], v[0:15]
	ds_read_b128 v[238:241], v205 offset:4672
	s_setprio 0
	global_load_dwordx4 v[218:221], v[184:185], off offset:2432
	global_load_dwordx4 v[222:225], v[186:187], off offset:2432
	s_setprio 1
	s_waitcnt lgkmcnt(1)
	v_mfma_f32_32x32x16_bf16 v[112:127], v[234:237], v[226:229], v[112:127]
	v_mfma_f32_32x32x16_bf16 v[48:63], v[234:237], v[230:233], v[48:63]
	s_waitcnt lgkmcnt(0)
	v_mfma_f32_32x32x16_bf16 v[96:111], v[238:241], v[226:229], v[96:111]
	v_mfma_f32_32x32x16_bf16 v[32:47], v[238:241], v[230:233], v[32:47]
	ds_read_b128 v[234:237], v205 offset:9280
	ds_read_b128 v[238:241], v205 offset:13888
	s_waitcnt vmcnt(7)
	ds_write_b128 v215, v[176:179] offset:27648
	s_waitcnt vmcnt(6)
	ds_write_b128 v215, v[180:183] offset:64512
	ds_read_b128 v[176:179], v208 offset:96
	ds_read_b128 v[180:183], v208 offset:4704
	s_waitcnt lgkmcnt(5)
	v_mfma_f32_32x32x16_bf16 v[80:95], v[234:237], v[226:229], v[80:95]
	v_mfma_f32_32x32x16_bf16 v[16:31], v[234:237], v[230:233], v[16:31]
	ds_read_b128 v[234:237], v205 offset:96
	s_waitcnt lgkmcnt(5)
	v_mfma_f32_32x32x16_bf16 v[64:79], v[238:241], v[226:229], v[64:79]
	v_mfma_f32_32x32x16_bf16 v[0:15], v[238:241], v[230:233], v[0:15]
	ds_read_b128 v[238:241], v205 offset:4704
	s_setprio 0
	global_load_dwordx4 v[226:229], v[198:199], off offset:2432
	global_load_dwordx4 v[230:233], v[200:201], off offset:2432
	s_setprio 1
	s_waitcnt lgkmcnt(1)
	v_mfma_f32_32x32x16_bf16 v[112:127], v[234:237], v[176:179], v[112:127]
	v_mfma_f32_32x32x16_bf16 v[48:63], v[234:237], v[180:183], v[48:63]
	s_waitcnt lgkmcnt(0)
	v_mfma_f32_32x32x16_bf16 v[96:111], v[238:241], v[176:179], v[96:111]
	v_mfma_f32_32x32x16_bf16 v[32:47], v[238:241], v[180:183], v[32:47]
	ds_read_b128 v[234:237], v205 offset:9312
	ds_read_b128 v[238:241], v205 offset:13920
	s_waitcnt lgkmcnt(0)
	s_barrier
; template <bool trans>
; DI void gemm_core(const GTile& tl, const GTile& nx, bool has_next  , bool chain  , bool pre, u32x4 (&ra)[4], u32x4 (&rb)[4], char* smem, f32x16 (&acc)[2][4]) {
;     ...
;   const int nk = K / 64;
;   if (!pre) { G_LOAD(0); G_STORE(0); G_LOAD(1); }
;   for (int kt = 0; kt < nk; ++kt) {
;     __syncthreads();
;     G_COMPUTE(kt & 1, kt);
;   }
	s_waitcnt vmcnt(7)
	ds_write_b128 v209, v[168:171]
	s_waitcnt vmcnt(6)
	ds_write_b128 v210, v[172:175]
	ds_read_b128 v[168:171], v204 offset:36864
	ds_read_b128 v[172:175], v204 offset:41472
	v_mfma_f32_32x32x16_bf16 v[80:95], v[234:237], v[176:179], v[80:95]
	v_mfma_f32_32x32x16_bf16 v[16:31], v[234:237], v[180:183], v[16:31]
	ds_read_b128 v[234:237], v192
	v_mfma_f32_32x32x16_bf16 v[64:79], v[238:241], v[176:179], v[64:79]
	v_mfma_f32_32x32x16_bf16 v[0:15], v[238:241], v[180:183], v[0:15]
	ds_read_b128 v[238:241], v192 offset:4608
	s_setprio 0
	global_load_dwordx4 v[176:179], v[190:191], off offset:2560
	global_load_dwordx4 v[180:183], v[188:189], off offset:2560
	s_setprio 1
	s_waitcnt lgkmcnt(1)
	v_mfma_f32_32x32x16_bf16 v[112:127], v[234:237], v[168:171], v[112:127]
	v_mfma_f32_32x32x16_bf16 v[48:63], v[234:237], v[172:175], v[48:63]
	s_waitcnt lgkmcnt(0)
	v_mfma_f32_32x32x16_bf16 v[96:111], v[238:241], v[168:171], v[96:111]
	v_mfma_f32_32x32x16_bf16 v[32:47], v[238:241], v[172:175], v[32:47]
	ds_read_b128 v[234:237], v192 offset:9216
	ds_read_b128 v[238:241], v192 offset:13824
	s_waitcnt vmcnt(7)
	ds_write_b128 v212, v[160:163]
	s_waitcnt vmcnt(6)
	ds_write_b128 v211, v[164:167]
	ds_read_b128 v[160:163], v204 offset:36896
	ds_read_b128 v[164:167], v204 offset:41504
	s_waitcnt lgkmcnt(5)
	v_mfma_f32_32x32x16_bf16 v[80:95], v[234:237], v[168:171], v[80:95]
	v_mfma_f32_32x32x16_bf16 v[16:31], v[234:237], v[172:175], v[16:31]
	ds_read_b128 v[234:237], v192 offset:32
	s_waitcnt lgkmcnt(5)
	v_mfma_f32_32x32x16_bf16 v[64:79], v[238:241], v[168:171], v[64:79]
	v_mfma_f32_32x32x16_bf16 v[0:15], v[238:241], v[172:175], v[0:15]
	ds_read_b128 v[238:241], v192 offset:4640
	s_setprio 0
	global_load_dwordx4 v[168:171], v[194:195], off offset:2560
	global_load_dwordx4 v[172:175], v[196:197], off offset:2560
	s_setprio 1
	s_waitcnt lgkmcnt(1)
	v_mfma_f32_32x32x16_bf16 v[112:127], v[234:237], v[160:163], v[112:127]
	v_mfma_f32_32x32x16_bf16 v[48:63], v[234:237], v[164:167], v[48:63]
	s_waitcnt lgkmcnt(0)
	v_mfma_f32_32x32x16_bf16 v[96:111], v[238:241], v[160:163], v[96:111]
	v_mfma_f32_32x32x16_bf16 v[32:47], v[238:241], v[164:167], v[32:47]
	ds_read_b128 v[234:237], v192 offset:9248
	ds_read_b128 v[238:241], v192 offset:13856
	s_waitcnt vmcnt(7)
	ds_write_b128 v214, v[218:221]
	s_waitcnt vmcnt(6)
	ds_write_b128 v213, v[222:225]
	ds_read_b128 v[218:221], v204 offset:36928
	ds_read_b128 v[222:225], v204 offset:41536
	s_waitcnt lgkmcnt(5)
	v_mfma_f32_32x32x16_bf16 v[80:95], v[234:237], v[160:163], v[80:95]
	v_mfma_f32_32x32x16_bf16 v[16:31], v[234:237], v[164:167], v[16:31]
	ds_read_b128 v[234:237], v192 offset:64
	s_waitcnt lgkmcnt(5)
	v_mfma_f32_32x32x16_bf16 v[64:79], v[238:241], v[160:163], v[64:79]
	v_mfma_f32_32x32x16_bf16 v[0:15], v[238:241], v[164:167], v[0:15]
	ds_read_b128 v[238:241], v192 offset:4672
	s_setprio 0
	global_load_dwordx4 v[160:163], v[184:185], off offset:2560
	global_load_dwordx4 v[164:167], v[186:187], off offset:2560
	s_setprio 1
	s_waitcnt lgkmcnt(1)
	v_mfma_f32_32x32x16_bf16 v[112:127], v[234:237], v[218:221], v[112:127]
	v_mfma_f32_32x32x16_bf16 v[48:63], v[234:237], v[222:225], v[48:63]
	s_waitcnt lgkmcnt(0)
	v_mfma_f32_32x32x16_bf16 v[96:111], v[238:241], v[218:221], v[96:111]
	v_mfma_f32_32x32x16_bf16 v[32:47], v[238:241], v[222:225], v[32:47]
	ds_read_b128 v[234:237], v192 offset:9280
	ds_read_b128 v[238:241], v192 offset:13888
	s_waitcnt vmcnt(7)
	ds_write_b128 v217, v[226:229]
	s_waitcnt vmcnt(6)
	ds_write_b128 v216, v[230:233]
	ds_read_b128 v[226:229], v204 offset:36960
	ds_read_b128 v[230:233], v204 offset:41568
	s_waitcnt lgkmcnt(5)
	v_mfma_f32_32x32x16_bf16 v[80:95], v[234:237], v[218:221], v[80:95]
	v_mfma_f32_32x32x16_bf16 v[16:31], v[234:237], v[222:225], v[16:31]
	ds_read_b128 v[234:237], v192 offset:96
	s_waitcnt lgkmcnt(5)
	v_mfma_f32_32x32x16_bf16 v[64:79], v[238:241], v[218:221], v[64:79]
	v_mfma_f32_32x32x16_bf16 v[0:15], v[238:241], v[222:225], v[0:15]
	ds_read_b128 v[238:241], v192 offset:4704
	s_setprio 0
	global_load_dwordx4 v[218:221], v[198:199], off offset:2560
	global_load_dwordx4 v[222:225], v[200:201], off offset:2560
	s_setprio 1
	s_waitcnt lgkmcnt(1)
	v_mfma_f32_32x32x16_bf16 v[112:127], v[234:237], v[226:229], v[112:127]
	v_mfma_f32_32x32x16_bf16 v[48:63], v[234:237], v[230:233], v[48:63]
	s_waitcnt lgkmcnt(0)
	v_mfma_f32_32x32x16_bf16 v[96:111], v[238:241], v[226:229], v[96:111]
	v_mfma_f32_32x32x16_bf16 v[32:47], v[238:241], v[230:233], v[32:47]
	ds_read_b128 v[234:237], v192 offset:9312
	ds_read_b128 v[238:241], v192 offset:13920
	s_waitcnt lgkmcnt(0)
	s_barrier
; template <bool trans>
; DI void gemm_core(const GTile& tl, const GTile& nx, bool has_next  , bool chain  , bool pre, u32x4 (&ra)[4], u32x4 (&rb)[4], char* smem, f32x16 (&acc)[2][4]) {
;     ...
;   const int nk = K / 64;
;   if (!pre) { G_LOAD(0); G_STORE(0); G_LOAD(1); }
;   for (int kt = 0; kt < nk; ++kt) {
;     __syncthreads();
;     G_COMPUTE(kt & 1, kt);
;   }
	s_waitcnt vmcnt(7)
	ds_write_b128 v215, v[176:179]
	s_waitcnt vmcnt(6)
	ds_write_b128 v215, v[180:183] offset:36864
	ds_read_b128 v[176:179], v208
	ds_read_b128 v[180:183], v208 offset:4608
	v_mfma_f32_32x32x16_bf16 v[80:95], v[234:237], v[226:229], v[80:95]
	v_mfma_f32_32x32x16_bf16 v[16:31], v[234:237], v[230:233], v[16:31]
	ds_read_b128 v[234:237], v205
	v_mfma_f32_32x32x16_bf16 v[64:79], v[238:241], v[226:229], v[64:79]
	v_mfma_f32_32x32x16_bf16 v[0:15], v[238:241], v[230:233], v[0:15]
	ds_read_b128 v[238:241], v205 offset:4608
	s_setprio 0
	global_load_dwordx4 v[226:229], v[190:191], off offset:2688
	global_load_dwordx4 v[230:233], v[188:189], off offset:2688
	s_setprio 1
	s_waitcnt lgkmcnt(1)
	v_mfma_f32_32x32x16_bf16 v[112:127], v[234:237], v[176:179], v[112:127]
	v_mfma_f32_32x32x16_bf16 v[48:63], v[234:237], v[180:183], v[48:63]
	s_waitcnt lgkmcnt(0)
	v_mfma_f32_32x32x16_bf16 v[96:111], v[238:241], v[176:179], v[96:111]
	v_mfma_f32_32x32x16_bf16 v[32:47], v[238:241], v[180:183], v[32:47]
	ds_read_b128 v[234:237], v205 offset:9216
	ds_read_b128 v[238:241], v205 offset:13824
	s_waitcnt vmcnt(7)
	ds_write_b128 v215, v[168:171] offset:9216
	s_waitcnt vmcnt(6)
	ds_write_b128 v215, v[172:175] offset:46080
	ds_read_b128 v[168:171], v208 offset:32
	ds_read_b128 v[172:175], v208 offset:4640
	s_waitcnt lgkmcnt(5)
	v_mfma_f32_32x32x16_bf16 v[80:95], v[234:237], v[176:179], v[80:95]
	v_mfma_f32_32x32x16_bf16 v[16:31], v[234:237], v[180:183], v[16:31]
	ds_read_b128 v[234:237], v205 offset:32
	s_waitcnt lgkmcnt(5)
	v_mfma_f32_32x32x16_bf16 v[64:79], v[238:241], v[176:179], v[64:79]
	v_mfma_f32_32x32x16_bf16 v[0:15], v[238:241], v[180:183], v[0:15]
	ds_read_b128 v[238:241], v205 offset:4640
	s_setprio 0
	global_load_dwordx4 v[176:179], v[194:195], off offset:2688
	global_load_dwordx4 v[180:183], v[196:197], off offset:2688
	s_setprio 1
	s_waitcnt lgkmcnt(1)
	v_mfma_f32_32x32x16_bf16 v[112:127], v[234:237], v[168:171], v[112:127]
	v_mfma_f32_32x32x16_bf16 v[48:63], v[234:237], v[172:175], v[48:63]
	s_waitcnt lgkmcnt(0)
	v_mfma_f32_32x32x16_bf16 v[96:111], v[238:241], v[168:171], v[96:111]
	v_mfma_f32_32x32x16_bf16 v[32:47], v[238:241], v[172:175], v[32:47]
	ds_read_b128 v[234:237], v205 offset:9248
	ds_read_b128 v[238:241], v205 offset:13856
	s_waitcnt vmcnt(7)
	ds_write_b128 v215, v[160:163] offset:18432
	s_waitcnt vmcnt(6)
	ds_write_b128 v215, v[164:167] offset:55296
	ds_read_b128 v[160:163], v208 offset:64
	ds_read_b128 v[164:167], v208 offset:4672
	s_waitcnt lgkmcnt(5)
	v_mfma_f32_32x32x16_bf16 v[80:95], v[234:237], v[168:171], v[80:95]
	v_mfma_f32_32x32x16_bf16 v[16:31], v[234:237], v[172:175], v[16:31]
	ds_read_b128 v[234:237], v205 offset:64
	s_waitcnt lgkmcnt(5)
	v_mfma_f32_32x32x16_bf16 v[64:79], v[238:241], v[168:171], v[64:79]
	v_mfma_f32_32x32x16_bf16 v[0:15], v[238:241], v[172:175], v[0:15]
	ds_read_b128 v[238:241], v205 offset:4672
	s_setprio 0
	global_load_dwordx4 v[168:171], v[184:185], off offset:2688
	global_load_dwordx4 v[172:175], v[186:187], off offset:2688
	s_setprio 1
	s_waitcnt lgkmcnt(1)
	v_mfma_f32_32x32x16_bf16 v[112:127], v[234:237], v[160:163], v[112:127]
	v_mfma_f32_32x32x16_bf16 v[48:63], v[234:237], v[164:167], v[48:63]
	s_waitcnt lgkmcnt(0)
	v_mfma_f32_32x32x16_bf16 v[96:111], v[238:241], v[160:163], v[96:111]
	v_mfma_f32_32x32x16_bf16 v[32:47], v[238:241], v[164:167], v[32:47]
	ds_read_b128 v[234:237], v205 offset:9280
	ds_read_b128 v[238:241], v205 offset:13888
	s_waitcnt vmcnt(7)
	ds_write_b128 v215, v[218:221] offset:27648
	s_waitcnt vmcnt(6)
	ds_write_b128 v215, v[222:225] offset:64512
	ds_read_b128 v[218:221], v208 offset:96
	ds_read_b128 v[222:225], v208 offset:4704
	s_waitcnt lgkmcnt(5)
	v_mfma_f32_32x32x16_bf16 v[80:95], v[234:237], v[160:163], v[80:95]
	v_mfma_f32_32x32x16_bf16 v[16:31], v[234:237], v[164:167], v[16:31]
	ds_read_b128 v[234:237], v205 offset:96
	s_waitcnt lgkmcnt(5)
	v_mfma_f32_32x32x16_bf16 v[64:79], v[238:241], v[160:163], v[64:79]
	v_mfma_f32_32x32x16_bf16 v[0:15], v[238:241], v[164:167], v[0:15]
	ds_read_b128 v[238:241], v205 offset:4704
	s_setprio 0
	global_load_dwordx4 v[160:163], v[198:199], off offset:2688
	global_load_dwordx4 v[164:167], v[200:201], off offset:2688
	s_setprio 1
	s_waitcnt lgkmcnt(1)
	v_mfma_f32_32x32x16_bf16 v[112:127], v[234:237], v[218:221], v[112:127]
	v_mfma_f32_32x32x16_bf16 v[48:63], v[234:237], v[222:225], v[48:63]
	s_waitcnt lgkmcnt(0)
	v_mfma_f32_32x32x16_bf16 v[96:111], v[238:241], v[218:221], v[96:111]
	v_mfma_f32_32x32x16_bf16 v[32:47], v[238:241], v[222:225], v[32:47]
	ds_read_b128 v[234:237], v205 offset:9312
	ds_read_b128 v[238:241], v205 offset:13920
	s_waitcnt lgkmcnt(0)
	s_barrier
; template <bool trans>
; DI void gemm_core(const GTile& tl, const GTile& nx, bool has_next  , bool chain  , bool pre, u32x4 (&ra)[4], u32x4 (&rb)[4], char* smem, f32x16 (&acc)[2][4]) {
;     ...
;   const int nk = K / 64;
;   if (!pre) { G_LOAD(0); G_STORE(0); G_LOAD(1); }
;   for (int kt = 0; kt < nk; ++kt) {
;     __syncthreads();
;     G_COMPUTE(kt & 1, kt);
;   }
	s_waitcnt vmcnt(7)
	ds_write_b128 v209, v[226:229]
	s_waitcnt vmcnt(6)
	ds_write_b128 v210, v[230:233]
	ds_read_b128 v[226:229], v204 offset:36864
	ds_read_b128 v[230:233], v204 offset:41472
	v_mfma_f32_32x32x16_bf16 v[80:95], v[234:237], v[218:221], v[80:95]
	v_mfma_f32_32x32x16_bf16 v[16:31], v[234:237], v[222:225], v[16:31]
	ds_read_b128 v[234:237], v192
	v_mfma_f32_32x32x16_bf16 v[64:79], v[238:241], v[218:221], v[64:79]
	v_mfma_f32_32x32x16_bf16 v[0:15], v[238:241], v[222:225], v[0:15]
	ds_read_b128 v[238:241], v192 offset:4608
	s_setprio 0
	global_load_dwordx4 v[218:221], v[190:191], off offset:2816
	global_load_dwordx4 v[222:225], v[188:189], off offset:2816
	s_setprio 1
	s_waitcnt lgkmcnt(1)
	v_mfma_f32_32x32x16_bf16 v[112:127], v[234:237], v[226:229], v[112:127]
	v_mfma_f32_32x32x16_bf16 v[48:63], v[234:237], v[230:233], v[48:63]
	s_waitcnt lgkmcnt(0)
	v_mfma_f32_32x32x16_bf16 v[96:111], v[238:241], v[226:229], v[96:111]
	v_mfma_f32_32x32x16_bf16 v[32:47], v[238:241], v[230:233], v[32:47]
	ds_read_b128 v[234:237], v192 offset:9216
	ds_read_b128 v[238:241], v192 offset:13824
	s_waitcnt vmcnt(7)
	ds_write_b128 v212, v[176:179]
	s_waitcnt vmcnt(6)
	ds_write_b128 v211, v[180:183]
	ds_read_b128 v[176:179], v204 offset:36896
	ds_read_b128 v[180:183], v204 offset:41504
	s_waitcnt lgkmcnt(5)
	v_mfma_f32_32x32x16_bf16 v[80:95], v[234:237], v[226:229], v[80:95]
	v_mfma_f32_32x32x16_bf16 v[16:31], v[234:237], v[230:233], v[16:31]
	ds_read_b128 v[234:237], v192 offset:32
	s_waitcnt lgkmcnt(5)
	v_mfma_f32_32x32x16_bf16 v[64:79], v[238:241], v[226:229], v[64:79]
	v_mfma_f32_32x32x16_bf16 v[0:15], v[238:241], v[230:233], v[0:15]
	ds_read_b128 v[238:241], v192 offset:4640
	s_setprio 0
	global_load_dwordx4 v[226:229], v[194:195], off offset:2816
	global_load_dwordx4 v[230:233], v[196:197], off offset:2816
	s_setprio 1
	s_waitcnt lgkmcnt(1)
	v_mfma_f32_32x32x16_bf16 v[112:127], v[234:237], v[176:179], v[112:127]
	v_mfma_f32_32x32x16_bf16 v[48:63], v[234:237], v[180:183], v[48:63]
	s_waitcnt lgkmcnt(0)
	v_mfma_f32_32x32x16_bf16 v[96:111], v[238:241], v[176:179], v[96:111]
	v_mfma_f32_32x32x16_bf16 v[32:47], v[238:241], v[180:183], v[32:47]
	ds_read_b128 v[234:237], v192 offset:9248
	ds_read_b128 v[238:241], v192 offset:13856
	s_waitcnt vmcnt(7)
	ds_write_b128 v214, v[168:171]
	s_waitcnt vmcnt(6)
	ds_write_b128 v213, v[172:175]
	ds_read_b128 v[168:171], v204 offset:36928
	ds_read_b128 v[172:175], v204 offset:41536
	s_waitcnt lgkmcnt(5)
	v_mfma_f32_32x32x16_bf16 v[80:95], v[234:237], v[176:179], v[80:95]
	v_mfma_f32_32x32x16_bf16 v[16:31], v[234:237], v[180:183], v[16:31]
	ds_read_b128 v[234:237], v192 offset:64
	s_waitcnt lgkmcnt(5)
	v_mfma_f32_32x32x16_bf16 v[64:79], v[238:241], v[176:179], v[64:79]
	v_mfma_f32_32x32x16_bf16 v[0:15], v[238:241], v[180:183], v[0:15]
	ds_read_b128 v[238:241], v192 offset:4672
	s_setprio 0
	global_load_dwordx4 v[176:179], v[184:185], off offset:2816
	global_load_dwordx4 v[180:183], v[186:187], off offset:2816
	s_setprio 1
	s_waitcnt lgkmcnt(1)
	v_mfma_f32_32x32x16_bf16 v[112:127], v[234:237], v[168:171], v[112:127]
	v_mfma_f32_32x32x16_bf16 v[48:63], v[234:237], v[172:175], v[48:63]
	s_waitcnt lgkmcnt(0)
	v_mfma_f32_32x32x16_bf16 v[96:111], v[238:241], v[168:171], v[96:111]
	v_mfma_f32_32x32x16_bf16 v[32:47], v[238:241], v[172:175], v[32:47]
	ds_read_b128 v[234:237], v192 offset:9280
	ds_read_b128 v[238:241], v192 offset:13888
	s_waitcnt vmcnt(7)
	ds_write_b128 v217, v[160:163]
	s_waitcnt vmcnt(6)
	ds_write_b128 v216, v[164:167]
	ds_read_b128 v[160:163], v204 offset:36960
	ds_read_b128 v[164:167], v204 offset:41568
	s_waitcnt lgkmcnt(5)
	v_mfma_f32_32x32x16_bf16 v[80:95], v[234:237], v[168:171], v[80:95]
	v_mfma_f32_32x32x16_bf16 v[16:31], v[234:237], v[172:175], v[16:31]
	ds_read_b128 v[234:237], v192 offset:96
	s_waitcnt lgkmcnt(5)
	v_mfma_f32_32x32x16_bf16 v[64:79], v[238:241], v[168:171], v[64:79]
	v_mfma_f32_32x32x16_bf16 v[0:15], v[238:241], v[172:175], v[0:15]
	ds_read_b128 v[238:241], v192 offset:4704
	s_setprio 0
	global_load_dwordx4 v[168:171], v[198:199], off offset:2816
	global_load_dwordx4 v[172:175], v[200:201], off offset:2816
	s_setprio 1
	s_waitcnt lgkmcnt(1)
	v_mfma_f32_32x32x16_bf16 v[112:127], v[234:237], v[160:163], v[112:127]
	v_mfma_f32_32x32x16_bf16 v[48:63], v[234:237], v[164:167], v[48:63]
	s_waitcnt lgkmcnt(0)
	v_mfma_f32_32x32x16_bf16 v[96:111], v[238:241], v[160:163], v[96:111]
	v_mfma_f32_32x32x16_bf16 v[32:47], v[238:241], v[164:167], v[32:47]
	ds_read_b128 v[234:237], v192 offset:9312
	ds_read_b128 v[238:241], v192 offset:13920
	s_waitcnt lgkmcnt(0)
	s_barrier
; template <bool trans>
; DI void gemm_core(const GTile& tl, const GTile& nx, bool has_next  , bool chain  , bool pre, u32x4 (&ra)[4], u32x4 (&rb)[4], char* smem, f32x16 (&acc)[2][4]) {
;     ...
;   const int nk = K / 64;
;   if (!pre) { G_LOAD(0); G_STORE(0); G_LOAD(1); }
;   for (int kt = 0; kt < nk; ++kt) {
;     __syncthreads();
;     G_COMPUTE(kt & 1, kt);
;   }
	s_waitcnt vmcnt(7)
	ds_write_b128 v215, v[218:221]
	s_waitcnt vmcnt(6)
	ds_write_b128 v215, v[222:225] offset:36864
	ds_read_b128 v[218:221], v208
	ds_read_b128 v[222:225], v208 offset:4608
	v_mfma_f32_32x32x16_bf16 v[80:95], v[234:237], v[160:163], v[80:95]
	v_mfma_f32_32x32x16_bf16 v[16:31], v[234:237], v[164:167], v[16:31]
	ds_read_b128 v[234:237], v205
	v_mfma_f32_32x32x16_bf16 v[64:79], v[238:241], v[160:163], v[64:79]
	v_mfma_f32_32x32x16_bf16 v[0:15], v[238:241], v[164:167], v[0:15]
	ds_read_b128 v[238:241], v205 offset:4608
	s_setprio 0
	global_load_dwordx4 v[160:163], v[190:191], off offset:2944
	global_load_dwordx4 v[164:167], v[188:189], off offset:2944
	s_setprio 1
	s_waitcnt lgkmcnt(1)
	v_mfma_f32_32x32x16_bf16 v[112:127], v[234:237], v[218:221], v[112:127]
	v_mfma_f32_32x32x16_bf16 v[48:63], v[234:237], v[222:225], v[48:63]
	s_waitcnt lgkmcnt(0)
	v_mfma_f32_32x32x16_bf16 v[96:111], v[238:241], v[218:221], v[96:111]
	v_mfma_f32_32x32x16_bf16 v[32:47], v[238:241], v[222:225], v[32:47]
	ds_read_b128 v[234:237], v205 offset:9216
	ds_read_b128 v[238:241], v205 offset:13824
	s_waitcnt vmcnt(7)
	ds_write_b128 v215, v[226:229] offset:9216
	s_waitcnt vmcnt(6)
	ds_write_b128 v215, v[230:233] offset:46080
	ds_read_b128 v[226:229], v208 offset:32
	ds_read_b128 v[230:233], v208 offset:4640
	s_waitcnt lgkmcnt(5)
	v_mfma_f32_32x32x16_bf16 v[80:95], v[234:237], v[218:221], v[80:95]
	v_mfma_f32_32x32x16_bf16 v[16:31], v[234:237], v[222:225], v[16:31]
	ds_read_b128 v[234:237], v205 offset:32
	s_waitcnt lgkmcnt(5)
	v_mfma_f32_32x32x16_bf16 v[64:79], v[238:241], v[218:221], v[64:79]
	v_mfma_f32_32x32x16_bf16 v[0:15], v[238:241], v[222:225], v[0:15]
	ds_read_b128 v[238:241], v205 offset:4640
	s_setprio 0
	global_load_dwordx4 v[218:221], v[194:195], off offset:2944
	global_load_dwordx4 v[222:225], v[196:197], off offset:2944
	s_setprio 1
	s_waitcnt lgkmcnt(1)
	v_mfma_f32_32x32x16_bf16 v[112:127], v[234:237], v[226:229], v[112:127]
	v_mfma_f32_32x32x16_bf16 v[48:63], v[234:237], v[230:233], v[48:63]
	s_waitcnt lgkmcnt(0)
	v_mfma_f32_32x32x16_bf16 v[96:111], v[238:241], v[226:229], v[96:111]
	v_mfma_f32_32x32x16_bf16 v[32:47], v[238:241], v[230:233], v[32:47]
	ds_read_b128 v[234:237], v205 offset:9248
	ds_read_b128 v[238:241], v205 offset:13856
	s_waitcnt vmcnt(7)
	ds_write_b128 v215, v[176:179] offset:18432
	s_waitcnt vmcnt(6)
	ds_write_b128 v215, v[180:183] offset:55296
	ds_read_b128 v[176:179], v208 offset:64
	ds_read_b128 v[180:183], v208 offset:4672
	s_waitcnt lgkmcnt(5)
	v_mfma_f32_32x32x16_bf16 v[80:95], v[234:237], v[226:229], v[80:95]
	v_mfma_f32_32x32x16_bf16 v[16:31], v[234:237], v[230:233], v[16:31]
	ds_read_b128 v[234:237], v205 offset:64
	s_waitcnt lgkmcnt(5)
	v_mfma_f32_32x32x16_bf16 v[64:79], v[238:241], v[226:229], v[64:79]
	v_mfma_f32_32x32x16_bf16 v[0:15], v[238:241], v[230:233], v[0:15]
	ds_read_b128 v[238:241], v205 offset:4672
	s_setprio 0
	global_load_dwordx4 v[226:229], v[184:185], off offset:2944
	global_load_dwordx4 v[230:233], v[186:187], off offset:2944
	s_setprio 1
	s_waitcnt lgkmcnt(1)
	v_mfma_f32_32x32x16_bf16 v[112:127], v[234:237], v[176:179], v[112:127]
	v_mfma_f32_32x32x16_bf16 v[48:63], v[234:237], v[180:183], v[48:63]
	s_waitcnt lgkmcnt(0)
	v_mfma_f32_32x32x16_bf16 v[96:111], v[238:241], v[176:179], v[96:111]
	v_mfma_f32_32x32x16_bf16 v[32:47], v[238:241], v[180:183], v[32:47]
	ds_read_b128 v[234:237], v205 offset:9280
	ds_read_b128 v[238:241], v205 offset:13888
	s_waitcnt vmcnt(7)
	ds_write_b128 v215, v[168:171] offset:27648
	s_waitcnt vmcnt(6)
	ds_write_b128 v215, v[172:175] offset:64512
	ds_read_b128 v[168:171], v208 offset:96
	ds_read_b128 v[172:175], v208 offset:4704
	s_waitcnt lgkmcnt(5)
	v_mfma_f32_32x32x16_bf16 v[80:95], v[234:237], v[176:179], v[80:95]
	v_mfma_f32_32x32x16_bf16 v[16:31], v[234:237], v[180:183], v[16:31]
	ds_read_b128 v[234:237], v205 offset:96
	s_waitcnt lgkmcnt(5)
	v_mfma_f32_32x32x16_bf16 v[64:79], v[238:241], v[176:179], v[64:79]
	v_mfma_f32_32x32x16_bf16 v[0:15], v[238:241], v[180:183], v[0:15]
	ds_read_b128 v[238:241], v205 offset:4704
	s_setprio 0
	global_load_dwordx4 v[176:179], v[198:199], off offset:2944
	global_load_dwordx4 v[180:183], v[200:201], off offset:2944
	s_setprio 1
	s_waitcnt lgkmcnt(1)
	v_mfma_f32_32x32x16_bf16 v[112:127], v[234:237], v[168:171], v[112:127]
	v_mfma_f32_32x32x16_bf16 v[48:63], v[234:237], v[172:175], v[48:63]
	s_waitcnt lgkmcnt(0)
	v_mfma_f32_32x32x16_bf16 v[96:111], v[238:241], v[168:171], v[96:111]
	v_mfma_f32_32x32x16_bf16 v[32:47], v[238:241], v[172:175], v[32:47]
	ds_read_b128 v[234:237], v205 offset:9312
	ds_read_b128 v[238:241], v205 offset:13920
	s_waitcnt lgkmcnt(0)
	s_barrier
; template <bool trans>
; DI void gemm_core(const GTile& tl, const GTile& nx, bool has_next  , bool chain  , bool pre, u32x4 (&ra)[4], u32x4 (&rb)[4], char* smem, f32x16 (&acc)[2][4]) {
;     ...
;   const int nk = K / 64;
;   if (!pre) { G_LOAD(0); G_STORE(0); G_LOAD(1); }
;   for (int kt = 0; kt < nk; ++kt) {
;     __syncthreads();
;     G_COMPUTE(kt & 1, kt);
;   }
	s_waitcnt vmcnt(7)
	ds_write_b128 v209, v[160:163]
	s_waitcnt vmcnt(6)
	ds_write_b128 v210, v[164:167]
	ds_read_b128 v[160:163], v204 offset:36864
	ds_read_b128 v[164:167], v204 offset:41472
	v_mfma_f32_32x32x16_bf16 v[80:95], v[234:237], v[168:171], v[80:95]
	v_mfma_f32_32x32x16_bf16 v[16:31], v[234:237], v[172:175], v[16:31]
	ds_read_b128 v[234:237], v192
	v_mfma_f32_32x32x16_bf16 v[64:79], v[238:241], v[168:171], v[64:79]
	v_mfma_f32_32x32x16_bf16 v[0:15], v[238:241], v[172:175], v[0:15]
	ds_read_b128 v[238:241], v192 offset:4608
	s_setprio 0
	global_load_dwordx4 v[168:171], v[190:191], off offset:3072
	global_load_dwordx4 v[172:175], v[188:189], off offset:3072
	s_setprio 1
	s_waitcnt lgkmcnt(1)
	v_mfma_f32_32x32x16_bf16 v[112:127], v[234:237], v[160:163], v[112:127]
	v_mfma_f32_32x32x16_bf16 v[48:63], v[234:237], v[164:167], v[48:63]
	s_waitcnt lgkmcnt(0)
	v_mfma_f32_32x32x16_bf16 v[96:111], v[238:241], v[160:163], v[96:111]
	v_mfma_f32_32x32x16_bf16 v[32:47], v[238:241], v[164:167], v[32:47]
	ds_read_b128 v[234:237], v192 offset:9216
	ds_read_b128 v[238:241], v192 offset:13824
	s_waitcnt vmcnt(7)
	ds_write_b128 v212, v[218:221]
	s_waitcnt vmcnt(6)
	ds_write_b128 v211, v[222:225]
	ds_read_b128 v[218:221], v204 offset:36896
	ds_read_b128 v[222:225], v204 offset:41504
	s_waitcnt lgkmcnt(5)
	v_mfma_f32_32x32x16_bf16 v[80:95], v[234:237], v[160:163], v[80:95]
	v_mfma_f32_32x32x16_bf16 v[16:31], v[234:237], v[164:167], v[16:31]
	ds_read_b128 v[234:237], v192 offset:32
	s_waitcnt lgkmcnt(5)
	v_mfma_f32_32x32x16_bf16 v[64:79], v[238:241], v[160:163], v[64:79]
	v_mfma_f32_32x32x16_bf16 v[0:15], v[238:241], v[164:167], v[0:15]
	ds_read_b128 v[238:241], v192 offset:4640
	s_setprio 0
	global_load_dwordx4 v[160:163], v[194:195], off offset:3072
	global_load_dwordx4 v[164:167], v[196:197], off offset:3072
	s_setprio 1
	s_waitcnt lgkmcnt(1)
	v_mfma_f32_32x32x16_bf16 v[112:127], v[234:237], v[218:221], v[112:127]
	v_mfma_f32_32x32x16_bf16 v[48:63], v[234:237], v[222:225], v[48:63]
	s_waitcnt lgkmcnt(0)
	v_mfma_f32_32x32x16_bf16 v[96:111], v[238:241], v[218:221], v[96:111]
	v_mfma_f32_32x32x16_bf16 v[32:47], v[238:241], v[222:225], v[32:47]
	ds_read_b128 v[234:237], v192 offset:9248
	ds_read_b128 v[238:241], v192 offset:13856
	s_waitcnt vmcnt(7)
	ds_write_b128 v214, v[226:229]
	s_waitcnt vmcnt(6)
	ds_write_b128 v213, v[230:233]
	ds_read_b128 v[226:229], v204 offset:36928
	ds_read_b128 v[230:233], v204 offset:41536
	s_waitcnt lgkmcnt(5)
	v_mfma_f32_32x32x16_bf16 v[80:95], v[234:237], v[218:221], v[80:95]
	v_mfma_f32_32x32x16_bf16 v[16:31], v[234:237], v[222:225], v[16:31]
	ds_read_b128 v[234:237], v192 offset:64
	s_waitcnt lgkmcnt(5)
	v_mfma_f32_32x32x16_bf16 v[64:79], v[238:241], v[218:221], v[64:79]
	v_mfma_f32_32x32x16_bf16 v[0:15], v[238:241], v[222:225], v[0:15]
	ds_read_b128 v[238:241], v192 offset:4672
	s_setprio 0
	global_load_dwordx4 v[218:221], v[184:185], off offset:3072
	global_load_dwordx4 v[222:225], v[186:187], off offset:3072
	s_setprio 1
	s_waitcnt lgkmcnt(1)
	v_mfma_f32_32x32x16_bf16 v[112:127], v[234:237], v[226:229], v[112:127]
	v_mfma_f32_32x32x16_bf16 v[48:63], v[234:237], v[230:233], v[48:63]
	s_waitcnt lgkmcnt(0)
	v_mfma_f32_32x32x16_bf16 v[96:111], v[238:241], v[226:229], v[96:111]
	v_mfma_f32_32x32x16_bf16 v[32:47], v[238:241], v[230:233], v[32:47]
	ds_read_b128 v[234:237], v192 offset:9280
	ds_read_b128 v[238:241], v192 offset:13888
	s_waitcnt vmcnt(7)
	ds_write_b128 v217, v[176:179]
	s_waitcnt vmcnt(6)
	ds_write_b128 v216, v[180:183]
	ds_read_b128 v[176:179], v204 offset:36960
	ds_read_b128 v[180:183], v204 offset:41568
	s_waitcnt lgkmcnt(5)
	v_mfma_f32_32x32x16_bf16 v[80:95], v[234:237], v[226:229], v[80:95]
	v_mfma_f32_32x32x16_bf16 v[16:31], v[234:237], v[230:233], v[16:31]
	ds_read_b128 v[234:237], v192 offset:96
	s_waitcnt lgkmcnt(5)
	v_mfma_f32_32x32x16_bf16 v[64:79], v[238:241], v[226:229], v[64:79]
	v_mfma_f32_32x32x16_bf16 v[0:15], v[238:241], v[230:233], v[0:15]
	ds_read_b128 v[238:241], v192 offset:4704
	s_setprio 0
	global_load_dwordx4 v[226:229], v[198:199], off offset:3072
	global_load_dwordx4 v[230:233], v[200:201], off offset:3072
	s_setprio 1
	s_waitcnt lgkmcnt(1)
	v_mfma_f32_32x32x16_bf16 v[112:127], v[234:237], v[176:179], v[112:127]
	v_mfma_f32_32x32x16_bf16 v[48:63], v[234:237], v[180:183], v[48:63]
	s_waitcnt lgkmcnt(0)
	v_mfma_f32_32x32x16_bf16 v[96:111], v[238:241], v[176:179], v[96:111]
	v_mfma_f32_32x32x16_bf16 v[32:47], v[238:241], v[180:183], v[32:47]
	ds_read_b128 v[234:237], v192 offset:9312
	ds_read_b128 v[238:241], v192 offset:13920
	s_waitcnt lgkmcnt(0)
	s_barrier
; template <bool trans>
; DI void gemm_core(const GTile& tl, const GTile& nx, bool has_next  , bool chain  , bool pre, u32x4 (&ra)[4], u32x4 (&rb)[4], char* smem, f32x16 (&acc)[2][4]) {
;     ...
;   const int nk = K / 64;
;   if (!pre) { G_LOAD(0); G_STORE(0); G_LOAD(1); }
;   for (int kt = 0; kt < nk; ++kt) {
;     __syncthreads();
;     G_COMPUTE(kt & 1, kt);
;   }
	s_waitcnt vmcnt(7)
	ds_write_b128 v215, v[168:171]
	s_waitcnt vmcnt(6)
	ds_write_b128 v215, v[172:175] offset:36864
	ds_read_b128 v[168:171], v208
	ds_read_b128 v[172:175], v208 offset:4608
	v_mfma_f32_32x32x16_bf16 v[80:95], v[234:237], v[176:179], v[80:95]
	v_mfma_f32_32x32x16_bf16 v[16:31], v[234:237], v[180:183], v[16:31]
	ds_read_b128 v[234:237], v205
	v_mfma_f32_32x32x16_bf16 v[64:79], v[238:241], v[176:179], v[64:79]
	v_mfma_f32_32x32x16_bf16 v[0:15], v[238:241], v[180:183], v[0:15]
	ds_read_b128 v[238:241], v205 offset:4608
	s_setprio 0
	global_load_dwordx4 v[176:179], v[190:191], off offset:3200
	global_load_dwordx4 v[180:183], v[188:189], off offset:3200
	s_setprio 1
	s_waitcnt lgkmcnt(1)
	v_mfma_f32_32x32x16_bf16 v[112:127], v[234:237], v[168:171], v[112:127]
	v_mfma_f32_32x32x16_bf16 v[48:63], v[234:237], v[172:175], v[48:63]
	s_waitcnt lgkmcnt(0)
	v_mfma_f32_32x32x16_bf16 v[96:111], v[238:241], v[168:171], v[96:111]
	v_mfma_f32_32x32x16_bf16 v[32:47], v[238:241], v[172:175], v[32:47]
	ds_read_b128 v[234:237], v205 offset:9216
	ds_read_b128 v[238:241], v205 offset:13824
	s_waitcnt vmcnt(7)
	ds_write_b128 v215, v[160:163] offset:9216
	s_waitcnt vmcnt(6)
	ds_write_b128 v215, v[164:167] offset:46080
	ds_read_b128 v[160:163], v208 offset:32
	ds_read_b128 v[164:167], v208 offset:4640
	s_waitcnt lgkmcnt(5)
	v_mfma_f32_32x32x16_bf16 v[80:95], v[234:237], v[168:171], v[80:95]
	v_mfma_f32_32x32x16_bf16 v[16:31], v[234:237], v[172:175], v[16:31]
	ds_read_b128 v[234:237], v205 offset:32
	s_waitcnt lgkmcnt(5)
	v_mfma_f32_32x32x16_bf16 v[64:79], v[238:241], v[168:171], v[64:79]
	v_mfma_f32_32x32x16_bf16 v[0:15], v[238:241], v[172:175], v[0:15]
	ds_read_b128 v[238:241], v205 offset:4640
	s_setprio 0
	global_load_dwordx4 v[168:171], v[194:195], off offset:3200
	global_load_dwordx4 v[172:175], v[196:197], off offset:3200
	s_setprio 1
	s_waitcnt lgkmcnt(1)
	v_mfma_f32_32x32x16_bf16 v[112:127], v[234:237], v[160:163], v[112:127]
	v_mfma_f32_32x32x16_bf16 v[48:63], v[234:237], v[164:167], v[48:63]
	s_waitcnt lgkmcnt(0)
	v_mfma_f32_32x32x16_bf16 v[96:111], v[238:241], v[160:163], v[96:111]
	v_mfma_f32_32x32x16_bf16 v[32:47], v[238:241], v[164:167], v[32:47]
	ds_read_b128 v[234:237], v205 offset:9248
	ds_read_b128 v[238:241], v205 offset:13856
	s_waitcnt vmcnt(7)
	ds_write_b128 v215, v[218:221] offset:18432
	s_waitcnt vmcnt(6)
	ds_write_b128 v215, v[222:225] offset:55296
	ds_read_b128 v[218:221], v208 offset:64
	ds_read_b128 v[222:225], v208 offset:4672
	s_waitcnt lgkmcnt(5)
	v_mfma_f32_32x32x16_bf16 v[80:95], v[234:237], v[160:163], v[80:95]
	v_mfma_f32_32x32x16_bf16 v[16:31], v[234:237], v[164:167], v[16:31]
	ds_read_b128 v[234:237], v205 offset:64
	s_waitcnt lgkmcnt(5)
	v_mfma_f32_32x32x16_bf16 v[64:79], v[238:241], v[160:163], v[64:79]
	v_mfma_f32_32x32x16_bf16 v[0:15], v[238:241], v[164:167], v[0:15]
	ds_read_b128 v[238:241], v205 offset:4672
	s_setprio 0
	global_load_dwordx4 v[160:163], v[184:185], off offset:3200
	global_load_dwordx4 v[164:167], v[186:187], off offset:3200
	s_setprio 1
	s_waitcnt lgkmcnt(1)
	v_mfma_f32_32x32x16_bf16 v[112:127], v[234:237], v[218:221], v[112:127]
	v_mfma_f32_32x32x16_bf16 v[48:63], v[234:237], v[222:225], v[48:63]
	s_waitcnt lgkmcnt(0)
	v_mfma_f32_32x32x16_bf16 v[96:111], v[238:241], v[218:221], v[96:111]
	v_mfma_f32_32x32x16_bf16 v[32:47], v[238:241], v[222:225], v[32:47]
	ds_read_b128 v[234:237], v205 offset:9280
	ds_read_b128 v[238:241], v205 offset:13888
	s_waitcnt vmcnt(7)
	ds_write_b128 v215, v[226:229] offset:27648
	s_waitcnt vmcnt(6)
	ds_write_b128 v215, v[230:233] offset:64512
	ds_read_b128 v[226:229], v208 offset:96
	ds_read_b128 v[230:233], v208 offset:4704
	s_waitcnt lgkmcnt(5)
	v_mfma_f32_32x32x16_bf16 v[80:95], v[234:237], v[218:221], v[80:95]
	v_mfma_f32_32x32x16_bf16 v[16:31], v[234:237], v[222:225], v[16:31]
	ds_read_b128 v[234:237], v205 offset:96
	s_waitcnt lgkmcnt(5)
	v_mfma_f32_32x32x16_bf16 v[64:79], v[238:241], v[218:221], v[64:79]
	v_mfma_f32_32x32x16_bf16 v[0:15], v[238:241], v[222:225], v[0:15]
	ds_read_b128 v[238:241], v205 offset:4704
	s_setprio 0
	global_load_dwordx4 v[218:221], v[198:199], off offset:3200
	global_load_dwordx4 v[222:225], v[200:201], off offset:3200
	s_setprio 1
	s_waitcnt lgkmcnt(1)
	v_mfma_f32_32x32x16_bf16 v[112:127], v[234:237], v[226:229], v[112:127]
	v_mfma_f32_32x32x16_bf16 v[48:63], v[234:237], v[230:233], v[48:63]
	s_waitcnt lgkmcnt(0)
	v_mfma_f32_32x32x16_bf16 v[96:111], v[238:241], v[226:229], v[96:111]
	v_mfma_f32_32x32x16_bf16 v[32:47], v[238:241], v[230:233], v[32:47]
	ds_read_b128 v[234:237], v205 offset:9312
	ds_read_b128 v[238:241], v205 offset:13920
	s_waitcnt lgkmcnt(0)
	s_barrier
; template <bool trans>
; DI void gemm_core(const GTile& tl, const GTile& nx, bool has_next  , bool chain  , bool pre, u32x4 (&ra)[4], u32x4 (&rb)[4], char* smem, f32x16 (&acc)[2][4]) {
;     ...
;   const int nk = K / 64;
;   if (!pre) { G_LOAD(0); G_STORE(0); G_LOAD(1); }
;   for (int kt = 0; kt < nk; ++kt) {
;     __syncthreads();
;     G_COMPUTE(kt & 1, kt);
;   }
	s_waitcnt vmcnt(7)
	ds_write_b128 v209, v[176:179]
	s_waitcnt vmcnt(6)
	ds_write_b128 v210, v[180:183]
	ds_read_b128 v[176:179], v204 offset:36864
	ds_read_b128 v[180:183], v204 offset:41472
	v_mfma_f32_32x32x16_bf16 v[80:95], v[234:237], v[226:229], v[80:95]
	v_mfma_f32_32x32x16_bf16 v[16:31], v[234:237], v[230:233], v[16:31]
	ds_read_b128 v[234:237], v192
	v_mfma_f32_32x32x16_bf16 v[64:79], v[238:241], v[226:229], v[64:79]
	v_mfma_f32_32x32x16_bf16 v[0:15], v[238:241], v[230:233], v[0:15]
	ds_read_b128 v[238:241], v192 offset:4608
	s_setprio 0
	global_load_dwordx4 v[226:229], v[190:191], off offset:3328
	global_load_dwordx4 v[230:233], v[188:189], off offset:3328
	s_setprio 1
	s_waitcnt lgkmcnt(1)
	v_mfma_f32_32x32x16_bf16 v[112:127], v[234:237], v[176:179], v[112:127]
	v_mfma_f32_32x32x16_bf16 v[48:63], v[234:237], v[180:183], v[48:63]
	s_waitcnt lgkmcnt(0)
	v_mfma_f32_32x32x16_bf16 v[96:111], v[238:241], v[176:179], v[96:111]
	v_mfma_f32_32x32x16_bf16 v[32:47], v[238:241], v[180:183], v[32:47]
	ds_read_b128 v[234:237], v192 offset:9216
	ds_read_b128 v[238:241], v192 offset:13824
	s_waitcnt vmcnt(7)
	ds_write_b128 v212, v[168:171]
	s_waitcnt vmcnt(6)
	ds_write_b128 v211, v[172:175]
	ds_read_b128 v[168:171], v204 offset:36896
	ds_read_b128 v[172:175], v204 offset:41504
	s_waitcnt lgkmcnt(5)
	v_mfma_f32_32x32x16_bf16 v[80:95], v[234:237], v[176:179], v[80:95]
	v_mfma_f32_32x32x16_bf16 v[16:31], v[234:237], v[180:183], v[16:31]
	ds_read_b128 v[234:237], v192 offset:32
	s_waitcnt lgkmcnt(5)
	v_mfma_f32_32x32x16_bf16 v[64:79], v[238:241], v[176:179], v[64:79]
	v_mfma_f32_32x32x16_bf16 v[0:15], v[238:241], v[180:183], v[0:15]
	ds_read_b128 v[238:241], v192 offset:4640
	s_setprio 0
	global_load_dwordx4 v[176:179], v[194:195], off offset:3328
	global_load_dwordx4 v[180:183], v[196:197], off offset:3328
	s_setprio 1
	s_waitcnt lgkmcnt(1)
	v_mfma_f32_32x32x16_bf16 v[112:127], v[234:237], v[168:171], v[112:127]
	v_mfma_f32_32x32x16_bf16 v[48:63], v[234:237], v[172:175], v[48:63]
	s_waitcnt lgkmcnt(0)
	v_mfma_f32_32x32x16_bf16 v[96:111], v[238:241], v[168:171], v[96:111]
	v_mfma_f32_32x32x16_bf16 v[32:47], v[238:241], v[172:175], v[32:47]
	ds_read_b128 v[234:237], v192 offset:9248
	ds_read_b128 v[238:241], v192 offset:13856
	s_waitcnt vmcnt(7)
	ds_write_b128 v214, v[160:163]
	s_waitcnt vmcnt(6)
	ds_write_b128 v213, v[164:167]
	ds_read_b128 v[160:163], v204 offset:36928
	ds_read_b128 v[164:167], v204 offset:41536
	s_waitcnt lgkmcnt(5)
	v_mfma_f32_32x32x16_bf16 v[80:95], v[234:237], v[168:171], v[80:95]
	v_mfma_f32_32x32x16_bf16 v[16:31], v[234:237], v[172:175], v[16:31]
	ds_read_b128 v[234:237], v192 offset:64
	s_waitcnt lgkmcnt(5)
	v_mfma_f32_32x32x16_bf16 v[64:79], v[238:241], v[168:171], v[64:79]
	v_mfma_f32_32x32x16_bf16 v[0:15], v[238:241], v[172:175], v[0:15]
	ds_read_b128 v[238:241], v192 offset:4672
	s_setprio 0
	global_load_dwordx4 v[168:171], v[184:185], off offset:3328
	global_load_dwordx4 v[172:175], v[186:187], off offset:3328
	s_setprio 1
	s_waitcnt lgkmcnt(1)
	v_mfma_f32_32x32x16_bf16 v[112:127], v[234:237], v[160:163], v[112:127]
	v_mfma_f32_32x32x16_bf16 v[48:63], v[234:237], v[164:167], v[48:63]
	s_waitcnt lgkmcnt(0)
	v_mfma_f32_32x32x16_bf16 v[96:111], v[238:241], v[160:163], v[96:111]
	v_mfma_f32_32x32x16_bf16 v[32:47], v[238:241], v[164:167], v[32:47]
	ds_read_b128 v[234:237], v192 offset:9280
	ds_read_b128 v[238:241], v192 offset:13888
	s_waitcnt vmcnt(7)
	ds_write_b128 v217, v[218:221]
	s_waitcnt vmcnt(6)
	ds_write_b128 v216, v[222:225]
	ds_read_b128 v[218:221], v204 offset:36960
	ds_read_b128 v[222:225], v204 offset:41568
	s_waitcnt lgkmcnt(5)
	v_mfma_f32_32x32x16_bf16 v[80:95], v[234:237], v[160:163], v[80:95]
	v_mfma_f32_32x32x16_bf16 v[16:31], v[234:237], v[164:167], v[16:31]
	ds_read_b128 v[234:237], v192 offset:96
	s_waitcnt lgkmcnt(5)
	v_mfma_f32_32x32x16_bf16 v[64:79], v[238:241], v[160:163], v[64:79]
	v_mfma_f32_32x32x16_bf16 v[0:15], v[238:241], v[164:167], v[0:15]
	ds_read_b128 v[238:241], v192 offset:4704
	s_setprio 0
	global_load_dwordx4 v[160:163], v[198:199], off offset:3328
	global_load_dwordx4 v[164:167], v[200:201], off offset:3328
	s_setprio 1
	s_waitcnt lgkmcnt(1)
	v_mfma_f32_32x32x16_bf16 v[112:127], v[234:237], v[218:221], v[112:127]
	v_mfma_f32_32x32x16_bf16 v[48:63], v[234:237], v[222:225], v[48:63]
	s_waitcnt lgkmcnt(0)
	v_mfma_f32_32x32x16_bf16 v[96:111], v[238:241], v[218:221], v[96:111]
	v_mfma_f32_32x32x16_bf16 v[32:47], v[238:241], v[222:225], v[32:47]
	ds_read_b128 v[234:237], v192 offset:9312
	ds_read_b128 v[238:241], v192 offset:13920
	s_waitcnt lgkmcnt(0)
	s_barrier
; template <bool trans>
; DI void gemm_core(const GTile& tl, const GTile& nx, bool has_next  , bool chain  , bool pre, u32x4 (&ra)[4], u32x4 (&rb)[4], char* smem, f32x16 (&acc)[2][4]) {
;     ...
;   const int nk = K / 64;
;   if (!pre) { G_LOAD(0); G_STORE(0); G_LOAD(1); }
;   for (int kt = 0; kt < nk; ++kt) {
;     __syncthreads();
;     G_COMPUTE(kt & 1, kt);
;   }
	s_waitcnt vmcnt(7)
	ds_write_b128 v215, v[226:229]
	s_waitcnt vmcnt(6)
	ds_write_b128 v215, v[230:233] offset:36864
	ds_read_b128 v[226:229], v208
	ds_read_b128 v[230:233], v208 offset:4608
	v_mfma_f32_32x32x16_bf16 v[80:95], v[234:237], v[218:221], v[80:95]
	v_mfma_f32_32x32x16_bf16 v[16:31], v[234:237], v[222:225], v[16:31]
	ds_read_b128 v[234:237], v205
	v_mfma_f32_32x32x16_bf16 v[64:79], v[238:241], v[218:221], v[64:79]
	v_mfma_f32_32x32x16_bf16 v[0:15], v[238:241], v[222:225], v[0:15]
	ds_read_b128 v[238:241], v205 offset:4608
	s_setprio 0
	global_load_dwordx4 v[218:221], v[190:191], off offset:3456
	global_load_dwordx4 v[222:225], v[188:189], off offset:3456
	s_setprio 1
	s_waitcnt lgkmcnt(1)
	v_mfma_f32_32x32x16_bf16 v[112:127], v[234:237], v[226:229], v[112:127]
	v_mfma_f32_32x32x16_bf16 v[48:63], v[234:237], v[230:233], v[48:63]
	s_waitcnt lgkmcnt(0)
	v_mfma_f32_32x32x16_bf16 v[96:111], v[238:241], v[226:229], v[96:111]
	v_mfma_f32_32x32x16_bf16 v[32:47], v[238:241], v[230:233], v[32:47]
	ds_read_b128 v[234:237], v205 offset:9216
	ds_read_b128 v[238:241], v205 offset:13824
	s_waitcnt vmcnt(7)
	ds_write_b128 v215, v[176:179] offset:9216
	s_waitcnt vmcnt(6)
	ds_write_b128 v215, v[180:183] offset:46080
	ds_read_b128 v[176:179], v208 offset:32
	ds_read_b128 v[180:183], v208 offset:4640
	s_waitcnt lgkmcnt(5)
	v_mfma_f32_32x32x16_bf16 v[80:95], v[234:237], v[226:229], v[80:95]
	v_mfma_f32_32x32x16_bf16 v[16:31], v[234:237], v[230:233], v[16:31]
	ds_read_b128 v[234:237], v205 offset:32
	s_waitcnt lgkmcnt(5)
	v_mfma_f32_32x32x16_bf16 v[64:79], v[238:241], v[226:229], v[64:79]
	v_mfma_f32_32x32x16_bf16 v[0:15], v[238:241], v[230:233], v[0:15]
	ds_read_b128 v[238:241], v205 offset:4640
	s_setprio 0
	global_load_dwordx4 v[226:229], v[194:195], off offset:3456
	global_load_dwordx4 v[230:233], v[196:197], off offset:3456
	s_setprio 1
	s_waitcnt lgkmcnt(1)
	v_mfma_f32_32x32x16_bf16 v[112:127], v[234:237], v[176:179], v[112:127]
	v_mfma_f32_32x32x16_bf16 v[48:63], v[234:237], v[180:183], v[48:63]
	s_waitcnt lgkmcnt(0)
	v_mfma_f32_32x32x16_bf16 v[96:111], v[238:241], v[176:179], v[96:111]
	v_mfma_f32_32x32x16_bf16 v[32:47], v[238:241], v[180:183], v[32:47]
	ds_read_b128 v[234:237], v205 offset:9248
	ds_read_b128 v[238:241], v205 offset:13856
	s_waitcnt vmcnt(7)
	ds_write_b128 v215, v[168:171] offset:18432
	s_waitcnt vmcnt(6)
	ds_write_b128 v215, v[172:175] offset:55296
	ds_read_b128 v[168:171], v208 offset:64
	ds_read_b128 v[172:175], v208 offset:4672
	s_waitcnt lgkmcnt(5)
	v_mfma_f32_32x32x16_bf16 v[80:95], v[234:237], v[176:179], v[80:95]
	v_mfma_f32_32x32x16_bf16 v[16:31], v[234:237], v[180:183], v[16:31]
	ds_read_b128 v[234:237], v205 offset:64
	s_waitcnt lgkmcnt(5)
	v_mfma_f32_32x32x16_bf16 v[64:79], v[238:241], v[176:179], v[64:79]
	v_mfma_f32_32x32x16_bf16 v[0:15], v[238:241], v[180:183], v[0:15]
	ds_read_b128 v[238:241], v205 offset:4672
	s_setprio 0
	global_load_dwordx4 v[176:179], v[184:185], off offset:3456
	global_load_dwordx4 v[180:183], v[186:187], off offset:3456
	s_setprio 1
	s_waitcnt lgkmcnt(1)
	v_mfma_f32_32x32x16_bf16 v[112:127], v[234:237], v[168:171], v[112:127]
	v_mfma_f32_32x32x16_bf16 v[48:63], v[234:237], v[172:175], v[48:63]
	s_waitcnt lgkmcnt(0)
	v_mfma_f32_32x32x16_bf16 v[96:111], v[238:241], v[168:171], v[96:111]
	v_mfma_f32_32x32x16_bf16 v[32:47], v[238:241], v[172:175], v[32:47]
	ds_read_b128 v[234:237], v205 offset:9280
	ds_read_b128 v[238:241], v205 offset:13888
	s_waitcnt vmcnt(7)
	ds_write_b128 v215, v[160:163] offset:27648
	s_waitcnt vmcnt(6)
	ds_write_b128 v215, v[164:167] offset:64512
	ds_read_b128 v[160:163], v208 offset:96
	ds_read_b128 v[164:167], v208 offset:4704
	s_waitcnt lgkmcnt(5)
	v_mfma_f32_32x32x16_bf16 v[80:95], v[234:237], v[168:171], v[80:95]
	v_mfma_f32_32x32x16_bf16 v[16:31], v[234:237], v[172:175], v[16:31]
	ds_read_b128 v[234:237], v205 offset:96
	s_waitcnt lgkmcnt(5)
	v_mfma_f32_32x32x16_bf16 v[64:79], v[238:241], v[168:171], v[64:79]
	v_mfma_f32_32x32x16_bf16 v[0:15], v[238:241], v[172:175], v[0:15]
	ds_read_b128 v[238:241], v205 offset:4704
	s_setprio 0
	global_load_dwordx4 v[168:171], v[198:199], off offset:3456
	global_load_dwordx4 v[172:175], v[200:201], off offset:3456
	s_setprio 1
	s_waitcnt lgkmcnt(1)
	v_mfma_f32_32x32x16_bf16 v[112:127], v[234:237], v[160:163], v[112:127]
	v_mfma_f32_32x32x16_bf16 v[48:63], v[234:237], v[164:167], v[48:63]
	s_waitcnt lgkmcnt(0)
	v_mfma_f32_32x32x16_bf16 v[96:111], v[238:241], v[160:163], v[96:111]
	v_mfma_f32_32x32x16_bf16 v[32:47], v[238:241], v[164:167], v[32:47]
	ds_read_b128 v[234:237], v205 offset:9312
	ds_read_b128 v[238:241], v205 offset:13920
	s_waitcnt lgkmcnt(0)
	s_barrier
; template <bool trans>
; DI void gemm_core(const GTile& tl, const GTile& nx, bool has_next  , bool chain  , bool pre, u32x4 (&ra)[4], u32x4 (&rb)[4], char* smem, f32x16 (&acc)[2][4]) {
;     ...
;   const int nk = K / 64;
;   if (!pre) { G_LOAD(0); G_STORE(0); G_LOAD(1); }
;   for (int kt = 0; kt < nk; ++kt) {
;     __syncthreads();
;     G_COMPUTE(kt & 1, kt);
;   }
	s_waitcnt vmcnt(7)
	ds_write_b128 v209, v[218:221]
	s_waitcnt vmcnt(6)
	ds_write_b128 v210, v[222:225]
	ds_read_b128 v[218:221], v204 offset:36864
	ds_read_b128 v[222:225], v204 offset:41472
	v_mfma_f32_32x32x16_bf16 v[80:95], v[234:237], v[160:163], v[80:95]
	v_mfma_f32_32x32x16_bf16 v[16:31], v[234:237], v[164:167], v[16:31]
	ds_read_b128 v[234:237], v192
	v_mfma_f32_32x32x16_bf16 v[64:79], v[238:241], v[160:163], v[64:79]
	v_mfma_f32_32x32x16_bf16 v[0:15], v[238:241], v[164:167], v[0:15]
	ds_read_b128 v[238:241], v192 offset:4608
	s_setprio 0
	global_load_dwordx4 v[160:163], v[190:191], off offset:3584
	global_load_dwordx4 v[164:167], v[188:189], off offset:3584
	s_setprio 1
	s_waitcnt lgkmcnt(1)
	v_mfma_f32_32x32x16_bf16 v[112:127], v[234:237], v[218:221], v[112:127]
	v_mfma_f32_32x32x16_bf16 v[48:63], v[234:237], v[222:225], v[48:63]
	s_waitcnt lgkmcnt(0)
	v_mfma_f32_32x32x16_bf16 v[96:111], v[238:241], v[218:221], v[96:111]
	v_mfma_f32_32x32x16_bf16 v[32:47], v[238:241], v[222:225], v[32:47]
	ds_read_b128 v[234:237], v192 offset:9216
	ds_read_b128 v[238:241], v192 offset:13824
	s_waitcnt vmcnt(7)
	ds_write_b128 v212, v[226:229]
	s_waitcnt vmcnt(6)
	ds_write_b128 v211, v[230:233]
	ds_read_b128 v[226:229], v204 offset:36896
	ds_read_b128 v[230:233], v204 offset:41504
	s_waitcnt lgkmcnt(5)
	v_mfma_f32_32x32x16_bf16 v[80:95], v[234:237], v[218:221], v[80:95]
	v_mfma_f32_32x32x16_bf16 v[16:31], v[234:237], v[222:225], v[16:31]
	ds_read_b128 v[234:237], v192 offset:32
	s_waitcnt lgkmcnt(5)
	v_mfma_f32_32x32x16_bf16 v[64:79], v[238:241], v[218:221], v[64:79]
	v_mfma_f32_32x32x16_bf16 v[0:15], v[238:241], v[222:225], v[0:15]
	ds_read_b128 v[238:241], v192 offset:4640
	s_setprio 0
	global_load_dwordx4 v[218:221], v[194:195], off offset:3584
	global_load_dwordx4 v[222:225], v[196:197], off offset:3584
	s_setprio 1
	s_waitcnt lgkmcnt(1)
	v_mfma_f32_32x32x16_bf16 v[112:127], v[234:237], v[226:229], v[112:127]
	v_mfma_f32_32x32x16_bf16 v[48:63], v[234:237], v[230:233], v[48:63]
	s_waitcnt lgkmcnt(0)
	v_mfma_f32_32x32x16_bf16 v[96:111], v[238:241], v[226:229], v[96:111]
	v_mfma_f32_32x32x16_bf16 v[32:47], v[238:241], v[230:233], v[32:47]
	ds_read_b128 v[234:237], v192 offset:9248
	ds_read_b128 v[238:241], v192 offset:13856
	s_waitcnt vmcnt(7)
	ds_write_b128 v214, v[176:179]
	s_waitcnt vmcnt(6)
	ds_write_b128 v213, v[180:183]
	ds_read_b128 v[176:179], v204 offset:36928
	ds_read_b128 v[180:183], v204 offset:41536
	s_waitcnt lgkmcnt(5)
	v_mfma_f32_32x32x16_bf16 v[80:95], v[234:237], v[226:229], v[80:95]
	v_mfma_f32_32x32x16_bf16 v[16:31], v[234:237], v[230:233], v[16:31]
	ds_read_b128 v[234:237], v192 offset:64
	s_waitcnt lgkmcnt(5)
	v_mfma_f32_32x32x16_bf16 v[64:79], v[238:241], v[226:229], v[64:79]
	v_mfma_f32_32x32x16_bf16 v[0:15], v[238:241], v[230:233], v[0:15]
	ds_read_b128 v[238:241], v192 offset:4672
	s_setprio 0
	global_load_dwordx4 v[226:229], v[184:185], off offset:3584
	global_load_dwordx4 v[230:233], v[186:187], off offset:3584
	s_setprio 1
	s_waitcnt lgkmcnt(1)
	v_mfma_f32_32x32x16_bf16 v[112:127], v[234:237], v[176:179], v[112:127]
	v_mfma_f32_32x32x16_bf16 v[48:63], v[234:237], v[180:183], v[48:63]
	s_waitcnt lgkmcnt(0)
	v_mfma_f32_32x32x16_bf16 v[96:111], v[238:241], v[176:179], v[96:111]
	v_mfma_f32_32x32x16_bf16 v[32:47], v[238:241], v[180:183], v[32:47]
	ds_read_b128 v[234:237], v192 offset:9280
	ds_read_b128 v[238:241], v192 offset:13888
	s_waitcnt vmcnt(7)
	ds_write_b128 v217, v[168:171]
	s_waitcnt vmcnt(6)
	ds_write_b128 v216, v[172:175]
	ds_read_b128 v[168:171], v204 offset:36960
	ds_read_b128 v[172:175], v204 offset:41568
	s_waitcnt lgkmcnt(5)
	v_mfma_f32_32x32x16_bf16 v[80:95], v[234:237], v[176:179], v[80:95]
	v_mfma_f32_32x32x16_bf16 v[16:31], v[234:237], v[180:183], v[16:31]
	ds_read_b128 v[234:237], v192 offset:96
	s_waitcnt lgkmcnt(5)
	v_mfma_f32_32x32x16_bf16 v[64:79], v[238:241], v[176:179], v[64:79]
	v_mfma_f32_32x32x16_bf16 v[0:15], v[238:241], v[180:183], v[0:15]
	ds_read_b128 v[238:241], v192 offset:4704
	s_setprio 0
	global_load_dwordx4 v[176:179], v[198:199], off offset:3584
	global_load_dwordx4 v[180:183], v[200:201], off offset:3584
	s_setprio 1
	s_waitcnt lgkmcnt(1)
	v_mfma_f32_32x32x16_bf16 v[112:127], v[234:237], v[168:171], v[112:127]
	v_mfma_f32_32x32x16_bf16 v[48:63], v[234:237], v[172:175], v[48:63]
	s_waitcnt lgkmcnt(0)
	v_mfma_f32_32x32x16_bf16 v[96:111], v[238:241], v[168:171], v[96:111]
	v_mfma_f32_32x32x16_bf16 v[32:47], v[238:241], v[172:175], v[32:47]
	ds_read_b128 v[234:237], v192 offset:9312
	ds_read_b128 v[238:241], v192 offset:13920
	s_waitcnt lgkmcnt(0)
	s_barrier
; template <bool trans>
; DI void gemm_core(const GTile& tl, const GTile& nx, bool has_next  , bool chain  , bool pre, u32x4 (&ra)[4], u32x4 (&rb)[4], char* smem, f32x16 (&acc)[2][4]) {
;     ...
;   const int nk = K / 64;
;   if (!pre) { G_LOAD(0); G_STORE(0); G_LOAD(1); }
;   for (int kt = 0; kt < nk; ++kt) {
;     __syncthreads();
;     G_COMPUTE(kt & 1, kt);
;   }
	s_waitcnt vmcnt(7)
	ds_write_b128 v215, v[160:163]
	s_waitcnt vmcnt(6)
	ds_write_b128 v215, v[164:167] offset:36864
	ds_read_b128 v[160:163], v208
	ds_read_b128 v[164:167], v208 offset:4608
	v_mfma_f32_32x32x16_bf16 v[80:95], v[234:237], v[168:171], v[80:95]
	v_mfma_f32_32x32x16_bf16 v[16:31], v[234:237], v[172:175], v[16:31]
	ds_read_b128 v[234:237], v205
	v_mfma_f32_32x32x16_bf16 v[64:79], v[238:241], v[168:171], v[64:79]
	v_mfma_f32_32x32x16_bf16 v[0:15], v[238:241], v[172:175], v[0:15]
	ds_read_b128 v[238:241], v205 offset:4608
	s_setprio 0
	global_load_dwordx4 v[168:171], v[190:191], off offset:3712
	global_load_dwordx4 v[172:175], v[188:189], off offset:3712
	s_setprio 1
	s_waitcnt lgkmcnt(1)
	v_mfma_f32_32x32x16_bf16 v[112:127], v[234:237], v[160:163], v[112:127]
	v_mfma_f32_32x32x16_bf16 v[48:63], v[234:237], v[164:167], v[48:63]
	s_waitcnt lgkmcnt(0)
	v_mfma_f32_32x32x16_bf16 v[96:111], v[238:241], v[160:163], v[96:111]
	v_mfma_f32_32x32x16_bf16 v[32:47], v[238:241], v[164:167], v[32:47]
	ds_read_b128 v[234:237], v205 offset:9216
	ds_read_b128 v[238:241], v205 offset:13824
	s_waitcnt vmcnt(7)
	ds_write_b128 v215, v[218:221] offset:9216
	s_waitcnt vmcnt(6)
	ds_write_b128 v215, v[222:225] offset:46080
	ds_read_b128 v[218:221], v208 offset:32
	ds_read_b128 v[222:225], v208 offset:4640
	s_waitcnt lgkmcnt(5)
	v_mfma_f32_32x32x16_bf16 v[80:95], v[234:237], v[160:163], v[80:95]
	v_mfma_f32_32x32x16_bf16 v[16:31], v[234:237], v[164:167], v[16:31]
	ds_read_b128 v[234:237], v205 offset:32
	s_waitcnt lgkmcnt(5)
	v_mfma_f32_32x32x16_bf16 v[64:79], v[238:241], v[160:163], v[64:79]
	v_mfma_f32_32x32x16_bf16 v[0:15], v[238:241], v[164:167], v[0:15]
	ds_read_b128 v[238:241], v205 offset:4640
	s_setprio 0
	global_load_dwordx4 v[160:163], v[194:195], off offset:3712
	global_load_dwordx4 v[164:167], v[196:197], off offset:3712
	s_setprio 1
	s_waitcnt lgkmcnt(1)
	v_mfma_f32_32x32x16_bf16 v[112:127], v[234:237], v[218:221], v[112:127]
	v_mfma_f32_32x32x16_bf16 v[48:63], v[234:237], v[222:225], v[48:63]
	s_waitcnt lgkmcnt(0)
	v_mfma_f32_32x32x16_bf16 v[96:111], v[238:241], v[218:221], v[96:111]
	v_mfma_f32_32x32x16_bf16 v[32:47], v[238:241], v[222:225], v[32:47]
	ds_read_b128 v[234:237], v205 offset:9248
	ds_read_b128 v[238:241], v205 offset:13856
	s_waitcnt vmcnt(7)
	ds_write_b128 v215, v[226:229] offset:18432
	s_waitcnt vmcnt(6)
	ds_write_b128 v215, v[230:233] offset:55296
	ds_read_b128 v[226:229], v208 offset:64
	ds_read_b128 v[230:233], v208 offset:4672
	s_waitcnt lgkmcnt(5)
	v_mfma_f32_32x32x16_bf16 v[80:95], v[234:237], v[218:221], v[80:95]
	v_mfma_f32_32x32x16_bf16 v[16:31], v[234:237], v[222:225], v[16:31]
	ds_read_b128 v[234:237], v205 offset:64
	s_waitcnt lgkmcnt(5)
	v_mfma_f32_32x32x16_bf16 v[64:79], v[238:241], v[218:221], v[64:79]
	v_mfma_f32_32x32x16_bf16 v[0:15], v[238:241], v[222:225], v[0:15]
	ds_read_b128 v[238:241], v205 offset:4672
	s_setprio 0
	global_load_dwordx4 v[218:221], v[184:185], off offset:3712
	global_load_dwordx4 v[222:225], v[186:187], off offset:3712
	s_setprio 1
	s_waitcnt lgkmcnt(1)
	v_mfma_f32_32x32x16_bf16 v[112:127], v[234:237], v[226:229], v[112:127]
	v_mfma_f32_32x32x16_bf16 v[48:63], v[234:237], v[230:233], v[48:63]
	s_waitcnt lgkmcnt(0)
	v_mfma_f32_32x32x16_bf16 v[96:111], v[238:241], v[226:229], v[96:111]
	v_mfma_f32_32x32x16_bf16 v[32:47], v[238:241], v[230:233], v[32:47]
	ds_read_b128 v[234:237], v205 offset:9280
	ds_read_b128 v[238:241], v205 offset:13888
	s_waitcnt vmcnt(7)
	ds_write_b128 v215, v[176:179] offset:27648
	s_waitcnt vmcnt(6)
	ds_write_b128 v215, v[180:183] offset:64512
	ds_read_b128 v[176:179], v208 offset:96
	ds_read_b128 v[180:183], v208 offset:4704
	s_waitcnt lgkmcnt(5)
	v_mfma_f32_32x32x16_bf16 v[80:95], v[234:237], v[226:229], v[80:95]
	v_mfma_f32_32x32x16_bf16 v[16:31], v[234:237], v[230:233], v[16:31]
	ds_read_b128 v[234:237], v205 offset:96
	s_waitcnt lgkmcnt(5)
	v_mfma_f32_32x32x16_bf16 v[64:79], v[238:241], v[226:229], v[64:79]
	v_mfma_f32_32x32x16_bf16 v[0:15], v[238:241], v[230:233], v[0:15]
	ds_read_b128 v[238:241], v205 offset:4704
	s_setprio 0
	global_load_dwordx4 v[226:229], v[198:199], off offset:3712
	global_load_dwordx4 v[230:233], v[200:201], off offset:3712
	s_setprio 1
	s_waitcnt lgkmcnt(1)
	v_mfma_f32_32x32x16_bf16 v[112:127], v[234:237], v[176:179], v[112:127]
	v_mfma_f32_32x32x16_bf16 v[48:63], v[234:237], v[180:183], v[48:63]
	s_waitcnt lgkmcnt(0)
	v_mfma_f32_32x32x16_bf16 v[96:111], v[238:241], v[176:179], v[96:111]
	v_mfma_f32_32x32x16_bf16 v[32:47], v[238:241], v[180:183], v[32:47]
	ds_read_b128 v[234:237], v205 offset:9312
	ds_read_b128 v[238:241], v205 offset:13920
	s_waitcnt lgkmcnt(0)
	s_barrier
; template <bool trans>
; DI void gemm_core(const GTile& tl, const GTile& nx, bool has_next  , bool chain  , bool pre, u32x4 (&ra)[4], u32x4 (&rb)[4], char* smem, f32x16 (&acc)[2][4]) {
;     ...
;   const int nk = K / 64;
;   if (!pre) { G_LOAD(0); G_STORE(0); G_LOAD(1); }
;   for (int kt = 0; kt < nk; ++kt) {
;     __syncthreads();
;     G_COMPUTE(kt & 1, kt);
;   }
	s_waitcnt vmcnt(7)
	ds_write_b128 v209, v[168:171]
	s_waitcnt vmcnt(6)
	ds_write_b128 v210, v[172:175]
	ds_read_b128 v[168:171], v204 offset:36864
	ds_read_b128 v[172:175], v204 offset:41472
	v_mfma_f32_32x32x16_bf16 v[80:95], v[234:237], v[176:179], v[80:95]
	v_mfma_f32_32x32x16_bf16 v[16:31], v[234:237], v[180:183], v[16:31]
	ds_read_b128 v[234:237], v192
	v_mfma_f32_32x32x16_bf16 v[64:79], v[238:241], v[176:179], v[64:79]
	v_mfma_f32_32x32x16_bf16 v[0:15], v[238:241], v[180:183], v[0:15]
	ds_read_b128 v[238:241], v192 offset:4608
	s_setprio 0
	global_load_dwordx4 v[176:179], v[190:191], off offset:3840
	global_load_dwordx4 v[180:183], v[188:189], off offset:3840
	s_setprio 1
	s_waitcnt lgkmcnt(1)
	v_mfma_f32_32x32x16_bf16 v[112:127], v[234:237], v[168:171], v[112:127]
	v_mfma_f32_32x32x16_bf16 v[48:63], v[234:237], v[172:175], v[48:63]
	s_waitcnt lgkmcnt(0)
	v_mfma_f32_32x32x16_bf16 v[96:111], v[238:241], v[168:171], v[96:111]
	v_mfma_f32_32x32x16_bf16 v[32:47], v[238:241], v[172:175], v[32:47]
	ds_read_b128 v[234:237], v192 offset:9216
	ds_read_b128 v[238:241], v192 offset:13824
	s_waitcnt lgkmcnt(1)
	v_mfma_f32_32x32x16_bf16 v[80:95], v[234:237], v[168:171], v[80:95]
	v_mfma_f32_32x32x16_bf16 v[16:31], v[234:237], v[172:175], v[16:31]
	s_waitcnt lgkmcnt(0)
	v_mfma_f32_32x32x16_bf16 v[64:79], v[238:241], v[168:171], v[64:79]
	v_mfma_f32_32x32x16_bf16 v[0:15], v[238:241], v[172:175], v[0:15]
	s_setprio 0
	global_load_dwordx4 v[234:237], v[194:195], off offset:3840
	global_load_dwordx4 v[238:241], v[196:197], off offset:3840
	s_waitcnt vmcnt(9)
	ds_write_b128 v212, v[160:163]
	s_waitcnt vmcnt(8)
	ds_write_b128 v211, v[164:167]
	ds_read_b128 v[160:163], v204 offset:36896
	ds_read_b128 v[164:167], v204 offset:41504
	ds_read_b128 v[168:171], v192 offset:32
	ds_read_b128 v[172:175], v192 offset:4640
	s_setprio 1
	s_waitcnt lgkmcnt(1)
	v_mfma_f32_32x32x16_bf16 v[112:127], v[168:171], v[160:163], v[112:127]
	v_mfma_f32_32x32x16_bf16 v[48:63], v[168:171], v[164:167], v[48:63]
	s_waitcnt lgkmcnt(0)
	v_mfma_f32_32x32x16_bf16 v[96:111], v[172:175], v[160:163], v[96:111]
	v_mfma_f32_32x32x16_bf16 v[32:47], v[172:175], v[164:167], v[32:47]
	ds_read_b128 v[168:171], v192 offset:9248
	ds_read_b128 v[172:175], v192 offset:13856
	s_waitcnt lgkmcnt(1)
	v_mfma_f32_32x32x16_bf16 v[80:95], v[168:171], v[160:163], v[80:95]
	v_mfma_f32_32x32x16_bf16 v[16:31], v[168:171], v[164:167], v[16:31]
	s_waitcnt lgkmcnt(0)
	v_mfma_f32_32x32x16_bf16 v[64:79], v[172:175], v[160:163], v[64:79]
	v_mfma_f32_32x32x16_bf16 v[0:15], v[172:175], v[164:167], v[0:15]
	s_setprio 0
	global_load_dwordx4 v[242:245], v[184:185], off offset:3840
	global_load_dwordx4 v[246:249], v[186:187], off offset:3840
	s_waitcnt vmcnt(9)
	ds_write_b128 v214, v[218:221]
	s_waitcnt vmcnt(8)
	ds_write_b128 v213, v[222:225]
	ds_read_b128 v[160:163], v204 offset:36928
	ds_read_b128 v[164:167], v204 offset:41536
	ds_read_b128 v[168:171], v192 offset:64
	ds_read_b128 v[172:175], v192 offset:4672
	s_setprio 1
	s_waitcnt lgkmcnt(1)
	v_mfma_f32_32x32x16_bf16 v[112:127], v[168:171], v[160:163], v[112:127]
	v_mfma_f32_32x32x16_bf16 v[48:63], v[168:171], v[164:167], v[48:63]
	s_waitcnt lgkmcnt(0)
	v_mfma_f32_32x32x16_bf16 v[96:111], v[172:175], v[160:163], v[96:111]
	v_mfma_f32_32x32x16_bf16 v[32:47], v[172:175], v[164:167], v[32:47]
	ds_read_b128 v[168:171], v192 offset:9280
	ds_read_b128 v[172:175], v192 offset:13888
	s_waitcnt lgkmcnt(1)
	v_mfma_f32_32x32x16_bf16 v[80:95], v[168:171], v[160:163], v[80:95]
	v_mfma_f32_32x32x16_bf16 v[16:31], v[168:171], v[164:167], v[16:31]
	s_waitcnt lgkmcnt(0)
	v_mfma_f32_32x32x16_bf16 v[64:79], v[172:175], v[160:163], v[64:79]
	v_mfma_f32_32x32x16_bf16 v[0:15], v[172:175], v[164:167], v[0:15]
	s_setprio 0
	global_load_dwordx4 v[218:221], v[198:199], off offset:3840
	global_load_dwordx4 v[222:225], v[200:201], off offset:3840
	s_waitcnt vmcnt(9)
	ds_write_b128 v217, v[226:229]
	s_waitcnt vmcnt(8)
	ds_write_b128 v216, v[230:233]
	ds_read_b128 v[160:163], v204 offset:36960
	ds_read_b128 v[164:167], v204 offset:41568
	ds_read_b128 v[168:171], v192 offset:96
	ds_read_b128 v[172:175], v192 offset:4704
	s_setprio 1
	s_waitcnt lgkmcnt(1)
	v_mfma_f32_32x32x16_bf16 v[112:127], v[168:171], v[160:163], v[112:127]
	v_mfma_f32_32x32x16_bf16 v[48:63], v[168:171], v[164:167], v[48:63]
	s_waitcnt lgkmcnt(0)
	v_mfma_f32_32x32x16_bf16 v[96:111], v[172:175], v[160:163], v[96:111]
	v_mfma_f32_32x32x16_bf16 v[32:47], v[172:175], v[164:167], v[32:47]
	ds_read_b128 v[168:171], v192 offset:9312
	ds_read_b128 v[172:175], v192 offset:13920
	s_waitcnt lgkmcnt(1)
	v_mfma_f32_32x32x16_bf16 v[80:95], v[168:171], v[160:163], v[80:95]
	v_mfma_f32_32x32x16_bf16 v[16:31], v[168:171], v[164:167], v[16:31]
	s_waitcnt lgkmcnt(0)
	v_mfma_f32_32x32x16_bf16 v[64:79], v[172:175], v[160:163], v[64:79]
	v_mfma_f32_32x32x16_bf16 v[0:15], v[172:175], v[164:167], v[0:15]
	s_setprio 0
	global_load_dwordx4 v[160:163], v[190:191], off offset:3968
	global_load_dwordx4 v[164:167], v[188:189], off offset:3968
	s_barrier
; template <bool trans>
; DI void gemm_core(const GTile& tl, const GTile& nx, bool has_next  , bool chain  , bool pre, u32x4 (&ra)[4], u32x4 (&rb)[4], char* smem, f32x16 (&acc)[2][4]) {
;     ...
;   const int nk = K / 64;
;   if (!pre) { G_LOAD(0); G_STORE(0); G_LOAD(1); }
;   for (int kt = 0; kt < nk; ++kt) {
;     __syncthreads();
;     G_COMPUTE(kt & 1, kt);
;   }
	s_waitcnt vmcnt(9)
	ds_write_b128 v215, v[176:179]
	s_waitcnt vmcnt(8)
	ds_write_b128 v215, v[180:183] offset:36864
	ds_read_b128 v[168:171], v208
	ds_read_b128 v[172:175], v208 offset:4608
	ds_read_b128 v[176:179], v205
	ds_read_b128 v[180:183], v205 offset:4608
	s_setprio 1
	s_waitcnt lgkmcnt(1)
	v_mfma_f32_32x32x16_bf16 v[112:127], v[176:179], v[168:171], v[112:127]
	v_mfma_f32_32x32x16_bf16 v[48:63], v[176:179], v[172:175], v[48:63]
	s_waitcnt lgkmcnt(0)
	v_mfma_f32_32x32x16_bf16 v[96:111], v[180:183], v[168:171], v[96:111]
	v_mfma_f32_32x32x16_bf16 v[32:47], v[180:183], v[172:175], v[32:47]
	ds_read_b128 v[176:179], v205 offset:9216
	ds_read_b128 v[180:183], v205 offset:13824
	s_waitcnt lgkmcnt(1)
	v_mfma_f32_32x32x16_bf16 v[80:95], v[176:179], v[168:171], v[80:95]
	v_mfma_f32_32x32x16_bf16 v[16:31], v[176:179], v[172:175], v[16:31]
	s_waitcnt lgkmcnt(0)
	v_mfma_f32_32x32x16_bf16 v[64:79], v[180:183], v[168:171], v[64:79]
	v_mfma_f32_32x32x16_bf16 v[0:15], v[180:183], v[172:175], v[0:15]
	s_setprio 0
	global_load_dwordx4 v[168:171], v[194:195], off offset:3968
	global_load_dwordx4 v[172:175], v[196:197], off offset:3968
	s_waitcnt vmcnt(9)
	ds_write_b128 v215, v[234:237] offset:9216
	s_waitcnt vmcnt(8)
	ds_write_b128 v215, v[238:241] offset:46080
	ds_read_b128 v[176:179], v208 offset:32
	ds_read_b128 v[180:183], v208 offset:4640
	ds_read_b128 v[188:191], v205 offset:32
	ds_read_b128 v[194:197], v205 offset:4640
	s_setprio 1
	s_waitcnt lgkmcnt(1)
	v_mfma_f32_32x32x16_bf16 v[112:127], v[188:191], v[176:179], v[112:127]
	v_mfma_f32_32x32x16_bf16 v[48:63], v[188:191], v[180:183], v[48:63]
	s_waitcnt lgkmcnt(0)
	v_mfma_f32_32x32x16_bf16 v[96:111], v[194:197], v[176:179], v[96:111]
	v_mfma_f32_32x32x16_bf16 v[32:47], v[194:197], v[180:183], v[32:47]
	ds_read_b128 v[188:191], v205 offset:9248
	ds_read_b128 v[194:197], v205 offset:13856
	s_waitcnt lgkmcnt(1)
	v_mfma_f32_32x32x16_bf16 v[80:95], v[188:191], v[176:179], v[80:95]
	v_mfma_f32_32x32x16_bf16 v[16:31], v[188:191], v[180:183], v[16:31]
	s_waitcnt lgkmcnt(0)
	v_mfma_f32_32x32x16_bf16 v[64:79], v[194:197], v[176:179], v[64:79]
	v_mfma_f32_32x32x16_bf16 v[0:15], v[194:197], v[180:183], v[0:15]
	s_setprio 0
	global_load_dwordx4 v[176:179], v[184:185], off offset:3968
	global_load_dwordx4 v[180:183], v[186:187], off offset:3968
	s_waitcnt vmcnt(9)
	ds_write_b128 v215, v[242:245] offset:18432
	s_waitcnt vmcnt(8)
	ds_write_b128 v215, v[246:249] offset:55296
	ds_read_b128 v[184:187], v208 offset:64
	ds_read_b128 v[188:191], v208 offset:4672
	ds_read_b128 v[194:197], v205 offset:64
	ds_read_b128 v[226:229], v205 offset:4672
	s_setprio 1
	s_waitcnt lgkmcnt(1)
	v_mfma_f32_32x32x16_bf16 v[112:127], v[194:197], v[184:187], v[112:127]
	v_mfma_f32_32x32x16_bf16 v[48:63], v[194:197], v[188:191], v[48:63]
	s_waitcnt lgkmcnt(0)
	v_mfma_f32_32x32x16_bf16 v[96:111], v[226:229], v[184:187], v[96:111]
	v_mfma_f32_32x32x16_bf16 v[32:47], v[226:229], v[188:191], v[32:47]
	ds_read_b128 v[194:197], v205 offset:9280
	ds_read_b128 v[226:229], v205 offset:13888
	s_waitcnt lgkmcnt(1)
	v_mfma_f32_32x32x16_bf16 v[80:95], v[194:197], v[184:187], v[80:95]
	v_mfma_f32_32x32x16_bf16 v[16:31], v[194:197], v[188:191], v[16:31]
	s_waitcnt lgkmcnt(0)
	v_mfma_f32_32x32x16_bf16 v[64:79], v[226:229], v[184:187], v[64:79]
	v_mfma_f32_32x32x16_bf16 v[0:15], v[226:229], v[188:191], v[0:15]
	s_setprio 0
	global_load_dwordx4 v[184:187], v[198:199], off offset:3968
	global_load_dwordx4 v[188:191], v[200:201], off offset:3968
	s_waitcnt vmcnt(9)
	ds_write_b128 v215, v[218:221] offset:27648
	s_waitcnt vmcnt(8)
	ds_write_b128 v215, v[222:225] offset:64512
	ds_read_b128 v[194:197], v208 offset:96
	ds_read_b128 v[198:201], v208 offset:4704
	ds_read_b128 v[218:221], v205 offset:96
	ds_read_b128 v[222:225], v205 offset:4704
	s_setprio 1
	s_waitcnt lgkmcnt(1)
	v_mfma_f32_32x32x16_bf16 v[112:127], v[218:221], v[194:197], v[112:127]
	v_mfma_f32_32x32x16_bf16 v[48:63], v[218:221], v[198:201], v[48:63]
	s_waitcnt lgkmcnt(0)
	v_mfma_f32_32x32x16_bf16 v[96:111], v[222:225], v[194:197], v[96:111]
	v_mfma_f32_32x32x16_bf16 v[32:47], v[222:225], v[198:201], v[32:47]
	ds_read_b128 v[218:221], v205 offset:9312
	ds_read_b128 v[222:225], v205 offset:13920
	s_waitcnt lgkmcnt(1)
	v_mfma_f32_32x32x16_bf16 v[80:95], v[218:221], v[194:197], v[80:95]
	v_mfma_f32_32x32x16_bf16 v[16:31], v[218:221], v[198:201], v[16:31]
	s_waitcnt lgkmcnt(0)
	v_mfma_f32_32x32x16_bf16 v[64:79], v[222:225], v[194:197], v[64:79]
	v_mfma_f32_32x32x16_bf16 v[0:15], v[222:225], v[198:201], v[0:15]
	s_setprio 0
	s_barrier
; template <bool trans>
; DI void gemm_core(const GTile& tl, const GTile& nx, bool has_next  , bool chain  , bool pre, u32x4 (&ra)[4], u32x4 (&rb)[4], char* smem, f32x16 (&acc)[2][4]) {
;     ...
;   const int nk = K / 64;
;   if (!pre) { G_LOAD(0); G_STORE(0); G_LOAD(1); }
;   for (int kt = 0; kt < nk; ++kt) {
;     __syncthreads();
;     G_COMPUTE(kt & 1, kt);
;   }
	s_waitcnt vmcnt(7)
	ds_write_b128 v209, v[160:163]
	s_waitcnt vmcnt(6)
	ds_write_b128 v210, v[164:167]
	ds_read_b128 v[194:197], v204 offset:36864
	ds_read_b128 v[198:201], v204 offset:41472
	ds_read_b128 v[218:221], v192
	ds_read_b128 v[222:225], v192 offset:4608
	s_setprio 1
	s_waitcnt lgkmcnt(1)
	v_mfma_f32_32x32x16_bf16 v[112:127], v[218:221], v[194:197], v[112:127]
	v_mfma_f32_32x32x16_bf16 v[48:63], v[218:221], v[198:201], v[48:63]
	s_waitcnt lgkmcnt(0)
	v_mfma_f32_32x32x16_bf16 v[96:111], v[222:225], v[194:197], v[96:111]
	v_mfma_f32_32x32x16_bf16 v[32:47], v[222:225], v[198:201], v[32:47]
	ds_read_b128 v[218:221], v192 offset:9216
	ds_read_b128 v[222:225], v192 offset:13824
	s_waitcnt lgkmcnt(1)
	v_mfma_f32_32x32x16_bf16 v[80:95], v[218:221], v[194:197], v[80:95]
	v_mfma_f32_32x32x16_bf16 v[16:31], v[218:221], v[198:201], v[16:31]
	s_waitcnt lgkmcnt(0)
	v_mfma_f32_32x32x16_bf16 v[64:79], v[222:225], v[194:197], v[64:79]
	v_mfma_f32_32x32x16_bf16 v[0:15], v[222:225], v[198:201], v[0:15]
	s_setprio 0
	s_waitcnt vmcnt(5)
	ds_write_b128 v212, v[168:171]
	s_waitcnt vmcnt(4)
	ds_write_b128 v211, v[172:175]
	ds_read_b128 v[194:197], v204 offset:36896
	ds_read_b128 v[198:201], v204 offset:41504
	ds_read_b128 v[218:221], v192 offset:32
	ds_read_b128 v[222:225], v192 offset:4640
	s_setprio 1
	s_waitcnt lgkmcnt(1)
	v_mfma_f32_32x32x16_bf16 v[112:127], v[218:221], v[194:197], v[112:127]
	v_mfma_f32_32x32x16_bf16 v[48:63], v[218:221], v[198:201], v[48:63]
	s_waitcnt lgkmcnt(0)
	v_mfma_f32_32x32x16_bf16 v[96:111], v[222:225], v[194:197], v[96:111]
	v_mfma_f32_32x32x16_bf16 v[32:47], v[222:225], v[198:201], v[32:47]
	ds_read_b128 v[218:221], v192 offset:9248
	ds_read_b128 v[222:225], v192 offset:13856
	s_waitcnt lgkmcnt(1)
	v_mfma_f32_32x32x16_bf16 v[80:95], v[218:221], v[194:197], v[80:95]
	v_mfma_f32_32x32x16_bf16 v[16:31], v[218:221], v[198:201], v[16:31]
	s_waitcnt lgkmcnt(0)
	v_mfma_f32_32x32x16_bf16 v[64:79], v[222:225], v[194:197], v[64:79]
	v_mfma_f32_32x32x16_bf16 v[0:15], v[222:225], v[198:201], v[0:15]
	s_setprio 0
	s_waitcnt vmcnt(3)
	ds_write_b128 v214, v[176:179]
	s_waitcnt vmcnt(2)
	ds_write_b128 v213, v[180:183]
	ds_read_b128 v[194:197], v204 offset:36928
	ds_read_b128 v[198:201], v204 offset:41536
	ds_read_b128 v[210:213], v192 offset:64
	ds_read_b128 v[218:221], v192 offset:4672
	s_setprio 1
	s_waitcnt lgkmcnt(1)
	v_mfma_f32_32x32x16_bf16 v[112:127], v[210:213], v[194:197], v[112:127]
	v_mfma_f32_32x32x16_bf16 v[48:63], v[210:213], v[198:201], v[48:63]
	s_waitcnt lgkmcnt(0)
	v_mfma_f32_32x32x16_bf16 v[96:111], v[218:221], v[194:197], v[96:111]
	v_mfma_f32_32x32x16_bf16 v[32:47], v[218:221], v[198:201], v[32:47]
	ds_read_b128 v[210:213], v192 offset:9280
	ds_read_b128 v[218:221], v192 offset:13888
	s_waitcnt lgkmcnt(1)
	v_mfma_f32_32x32x16_bf16 v[80:95], v[210:213], v[194:197], v[80:95]
	v_mfma_f32_32x32x16_bf16 v[16:31], v[210:213], v[198:201], v[16:31]
	s_waitcnt lgkmcnt(0)
	v_mfma_f32_32x32x16_bf16 v[64:79], v[218:221], v[194:197], v[64:79]
	v_mfma_f32_32x32x16_bf16 v[0:15], v[218:221], v[198:201], v[0:15]
	s_setprio 0
	s_waitcnt vmcnt(1)
	ds_write_b128 v217, v[184:187]
	s_waitcnt vmcnt(0)
	ds_write_b128 v216, v[188:191]
	ds_read_b128 v[194:197], v204 offset:36960
	ds_read_b128 v[198:201], v204 offset:41568
	ds_read_b128 v[210:213], v192 offset:96
	ds_read_b128 v[214:217], v192 offset:4704
	s_setprio 1
	s_waitcnt lgkmcnt(1)
	v_mfma_f32_32x32x16_bf16 v[112:127], v[210:213], v[194:197], v[112:127]
	v_mfma_f32_32x32x16_bf16 v[48:63], v[210:213], v[198:201], v[48:63]
	s_waitcnt lgkmcnt(0)
	v_mfma_f32_32x32x16_bf16 v[96:111], v[214:217], v[194:197], v[96:111]
	v_mfma_f32_32x32x16_bf16 v[32:47], v[214:217], v[198:201], v[32:47]
	ds_read_b128 v[210:213], v192 offset:9312
	ds_read_b128 v[214:217], v192 offset:13920
	s_waitcnt lgkmcnt(1)
	v_mfma_f32_32x32x16_bf16 v[80:95], v[210:213], v[194:197], v[80:95]
	v_mfma_f32_32x32x16_bf16 v[16:31], v[210:213], v[198:201], v[16:31]
	s_waitcnt lgkmcnt(0)
	v_mfma_f32_32x32x16_bf16 v[64:79], v[214:217], v[194:197], v[64:79]
	v_mfma_f32_32x32x16_bf16 v[0:15], v[214:217], v[198:201], v[0:15]
	s_setprio 0
	s_barrier
; template <bool trans>
; DI void gemm_core(const GTile& tl, const GTile& nx, bool has_next  , bool chain  , bool pre, u32x4 (&ra)[4], u32x4 (&rb)[4], char* smem, f32x16 (&acc)[2][4]) {
;     ...
;   const int nk = K / 64;
;   if (!pre) { G_LOAD(0); G_STORE(0); G_LOAD(1); }
;   for (int kt = 0; kt < nk; ++kt) {
;     __syncthreads();
;     G_COMPUTE(kt & 1, kt);
;   }
;   if (!has_next) __syncthreads();
	ds_read_b128 v[194:197], v208
	ds_read_b128 v[198:201], v208 offset:4608
	ds_read_b128 v[210:213], v205
	ds_read_b128 v[214:217], v205 offset:4608
	s_setprio 1
	s_waitcnt lgkmcnt(1)
	v_mfma_f32_32x32x16_bf16 v[112:127], v[210:213], v[194:197], v[112:127]
	v_mfma_f32_32x32x16_bf16 v[48:63], v[210:213], v[198:201], v[48:63]
	s_waitcnt lgkmcnt(0)
	v_mfma_f32_32x32x16_bf16 v[96:111], v[214:217], v[194:197], v[96:111]
	v_mfma_f32_32x32x16_bf16 v[32:47], v[214:217], v[198:201], v[32:47]
	ds_read_b128 v[210:213], v205 offset:9216
	ds_read_b128 v[214:217], v205 offset:13824
	s_waitcnt lgkmcnt(1)
	v_mfma_f32_32x32x16_bf16 v[80:95], v[210:213], v[194:197], v[80:95]
	v_mfma_f32_32x32x16_bf16 v[16:31], v[210:213], v[198:201], v[16:31]
	s_waitcnt lgkmcnt(0)
	v_mfma_f32_32x32x16_bf16 v[64:79], v[214:217], v[194:197], v[64:79]
	v_mfma_f32_32x32x16_bf16 v[0:15], v[214:217], v[198:201], v[0:15]
	s_setprio 0
	ds_read_b128 v[194:197], v208 offset:32
	ds_read_b128 v[198:201], v208 offset:4640
	ds_read_b128 v[210:213], v205 offset:32
	ds_read_b128 v[214:217], v205 offset:4640
	s_setprio 1
	s_waitcnt lgkmcnt(1)
	v_mfma_f32_32x32x16_bf16 v[112:127], v[210:213], v[194:197], v[112:127]
	v_mfma_f32_32x32x16_bf16 v[48:63], v[210:213], v[198:201], v[48:63]
	s_waitcnt lgkmcnt(0)
	v_mfma_f32_32x32x16_bf16 v[96:111], v[214:217], v[194:197], v[96:111]
	v_mfma_f32_32x32x16_bf16 v[32:47], v[214:217], v[198:201], v[32:47]
	ds_read_b128 v[210:213], v205 offset:9248
	ds_read_b128 v[214:217], v205 offset:13856
	s_waitcnt lgkmcnt(1)
	v_mfma_f32_32x32x16_bf16 v[80:95], v[210:213], v[194:197], v[80:95]
	v_mfma_f32_32x32x16_bf16 v[16:31], v[210:213], v[198:201], v[16:31]
	s_waitcnt lgkmcnt(0)
	v_mfma_f32_32x32x16_bf16 v[64:79], v[214:217], v[194:197], v[64:79]
	v_mfma_f32_32x32x16_bf16 v[0:15], v[214:217], v[198:201], v[0:15]
	s_setprio 0
	ds_read_b128 v[194:197], v208 offset:64
	ds_read_b128 v[198:201], v208 offset:4672
	ds_read_b128 v[210:213], v205 offset:64
	ds_read_b128 v[214:217], v205 offset:4672
	s_setprio 1
	s_waitcnt lgkmcnt(1)
	v_mfma_f32_32x32x16_bf16 v[112:127], v[210:213], v[194:197], v[112:127]
	v_mfma_f32_32x32x16_bf16 v[48:63], v[210:213], v[198:201], v[48:63]
	s_waitcnt lgkmcnt(0)
	v_mfma_f32_32x32x16_bf16 v[96:111], v[214:217], v[194:197], v[96:111]
	v_mfma_f32_32x32x16_bf16 v[32:47], v[214:217], v[198:201], v[32:47]
	ds_read_b128 v[210:213], v205 offset:9280
	ds_read_b128 v[214:217], v205 offset:13888
	s_waitcnt lgkmcnt(1)
	v_mfma_f32_32x32x16_bf16 v[80:95], v[210:213], v[194:197], v[80:95]
	v_mfma_f32_32x32x16_bf16 v[16:31], v[210:213], v[198:201], v[16:31]
	s_waitcnt lgkmcnt(0)
	v_mfma_f32_32x32x16_bf16 v[64:79], v[214:217], v[194:197], v[64:79]
	v_mfma_f32_32x32x16_bf16 v[0:15], v[214:217], v[198:201], v[0:15]
	s_setprio 0
	ds_read_b128 v[194:197], v208 offset:96
	ds_read_b128 v[198:201], v208 offset:4704
	ds_read_b128 v[208:211], v205 offset:96
	ds_read_b128 v[212:215], v205 offset:4704
	s_setprio 1
	s_waitcnt lgkmcnt(1)
	v_mfma_f32_32x32x16_bf16 v[112:127], v[208:211], v[194:197], v[112:127]
	v_mfma_f32_32x32x16_bf16 v[48:63], v[208:211], v[198:201], v[48:63]
	s_waitcnt lgkmcnt(0)
	v_mfma_f32_32x32x16_bf16 v[96:111], v[212:215], v[194:197], v[96:111]
	v_mfma_f32_32x32x16_bf16 v[32:47], v[212:215], v[198:201], v[32:47]
	ds_read_b128 v[208:211], v205 offset:9312
	ds_read_b128 v[212:215], v205 offset:13920
	s_waitcnt lgkmcnt(1)
	v_mfma_f32_32x32x16_bf16 v[80:95], v[208:211], v[194:197], v[80:95]
	v_mfma_f32_32x32x16_bf16 v[16:31], v[208:211], v[198:201], v[16:31]
	s_waitcnt lgkmcnt(0)
	v_mfma_f32_32x32x16_bf16 v[64:79], v[212:215], v[194:197], v[64:79]
	v_mfma_f32_32x32x16_bf16 v[0:15], v[212:215], v[198:201], v[0:15]
	s_setprio 0
	s_andn2_b64 vcc, exec, s[30:31]
	s_barrier

;   DI bf16_t* z() const { return (bf16_t*)(ws + OFF_Z); }
; template <bool trans>
; DI void gemm_core(const GTile& tl, const GTile& nx, bool has_next  , bool chain  , bool pre, u32x4 (&ra)[4], u32x4 (&rb)[4], char* smem, f32x16 (&acc)[2][4]) {
;     ...
;   const int nk = K / 64;
;   if (!pre) { G_LOAD(0); G_STORE(0); G_LOAD(1); }
;   for (int kt = 0; kt < nk; ++kt) {
;     __syncthreads();
;     G_COMPUTE(kt & 1, kt);
;   }
;   if (!has_next) __syncthreads();
; DI void phase_gemm_in1(const Params& p, char* smem) {
;     ...
;     else { f32x16 acc[2][4]; gemm_core<false>(tl, nx, has_next, has_next, pre, ra, rb, smem, acc);
;       if (nt == 25) { EpiRopeK e{&p}; e(acc, mbase, nbase, l32_, g_); }
;       else { EpiRowBf16 e{p.z(), LDZ1}; e(acc, mbase, nbase, l32_, g_); } }
.LBB0_906:
	ds_read_b128 v[128:131], v150 offset:96
	ds_read_b128 v[132:135], v150 offset:4704
	ds_read_b128 v[136:139], v149 offset:96
	ds_read_b128 v[140:143], v149 offset:4704
	s_setprio 1
	s_waitcnt lgkmcnt(1)
	v_mfma_f32_32x32x16_bf16 v[96:111], v[128:131], v[136:139], v[96:111]
	v_mfma_f32_32x32x16_bf16 v[112:127], v[132:135], v[136:139], v[112:127]
	s_waitcnt lgkmcnt(0)
	v_mfma_f32_32x32x16_bf16 v[64:79], v[128:131], v[140:143], v[64:79]
	v_mfma_f32_32x32x16_bf16 v[80:95], v[132:135], v[140:143], v[80:95]
	ds_read_b128 v[136:139], v149 offset:9312
	ds_read_b128 v[140:143], v149 offset:13920
	s_waitcnt lgkmcnt(1)
	v_mfma_f32_32x32x16_bf16 v[32:47], v[128:131], v[136:139], v[32:47]
	v_mfma_f32_32x32x16_bf16 v[48:63], v[132:135], v[136:139], v[48:63]
	s_waitcnt lgkmcnt(0)
	v_mfma_f32_32x32x16_bf16 v[0:15], v[128:131], v[140:143], v[0:15]
	v_mfma_f32_32x32x16_bf16 v[16:31], v[132:135], v[140:143], v[16:31]
	s_setprio 0
	s_andn2_b64 vcc, exec, s[30:31]
	s_cbranch_vccz .LBB0_909
	s_barrier
	s_mov_b64 s[2:3], -1
	s_and_b64 vcc, exec, s[42:43]
	s_cbranch_vccnz .LBB0_910

; DI void store_bf8_pair(bf16_t* rowp  , int g, u32x2 a  , u32x2 b  ) {
;   auto rx = __builtin_amdgcn_permlane32_swap(a.x, b.x, false, false);
;   auto ry = __builtin_amdgcn_permlane32_swap(a.y, b.y, false, false);
;   u32x4 v = {rx[0], ry[0], rx[1], ry[1]};
;   *(u32x4*)(rowp + 8 * g) = v;
; }
;   DI void operator()(const f32x16 (&acc)[2][4], int mbase, int nbase, int l32, int g) const {
; #pragma unroll
;     for (int nb = 0; nb < 2; ++nb)
; #pragma unroll
;       for (int mb = 0; mb < 4; ++mb) {
;         const size_t tok = mbase + 32 * mb + l32;
;         const f32x16& c = acc[nb][mb];
; #pragma unroll
;         for (int j = 0; j < 4; j += 2) {
;           u32x2 a, b;
;           a.x = pk_bf16(c[4 * j], c[4 * j + 1]); a.y = pk_bf16(c[4 * j + 2], c[4 * j + 3]);
;           b.x = pk_bf16(c[4 * j + 4], c[4 * j + 5]); b.y = pk_bf16(c[4 * j + 6], c[4 * j + 7]);
;           store_bf8_pair(O + tok * ld + nbase + 32 * nb + 8 * j, g, a, b);
;         }
;       }
;   }
.LBB0_910:
	s_ashr_i32 s39, s38, 31
	s_lshl_b64 s[2:3], s[38:39], 1
	s_add_u32 s2, s41, s2
	s_addc_u32 s3, s46, s3
	s_mul_i32 s99, s57, 0x3300
	s_add_u32 s100, s2, s99
	s_addc_u32 s101, s3, 0
	v_and_b32_e32 v128, 63, v206
	v_lshrrev_b32_e32 v129, 3, v128
	v_and_b32_e32 v130, 7, v128
	v_lshlrev_b32_e32 v130, 4, v130
	v_mov_b32_e32 v133, 0x3300
	v_mad_u32_u24 v131, v129, v133, v130
	v_lshrrev_b32_e32 v132, 6, v206
	v_mov_b32_e32 v133, 0x1200
	v_mul_u32_u24_e32 v132, v132, v133
	v_add_u32_e32 v132, 0x12000, v132
	v_mov_b32_e32 v133, 0x90
	v_mad_u32_u24 v129, v129, v133, v132
	v_add_u32_e32 v129, v129, v130
	v_mad_u32_u24 v130, v203, v133, v132
	v_lshl_add_u32 v130, v202, 4, v130
	v_cvt_pk_bf16_f32 v96, v96, v97
	v_cvt_pk_bf16_f32 v97, v98, v99
	v_cvt_pk_bf16_f32 v98, v100, v101
	v_cvt_pk_bf16_f32 v99, v102, v103
	v_cvt_pk_bf16_f32 v104, v104, v105
	v_cvt_pk_bf16_f32 v105, v106, v107
	v_cvt_pk_bf16_f32 v106, v108, v109
	v_cvt_pk_bf16_f32 v107, v110, v111
	v_cvt_pk_bf16_f32 v112, v112, v113
	v_cvt_pk_bf16_f32 v113, v114, v115
	v_cvt_pk_bf16_f32 v114, v116, v117
	v_cvt_pk_bf16_f32 v115, v118, v119
	v_cvt_pk_bf16_f32 v120, v120, v121
	v_cvt_pk_bf16_f32 v121, v122, v123
	v_cvt_pk_bf16_f32 v122, v124, v125
	v_cvt_pk_bf16_f32 v123, v126, v127
	s_nop 1
	v_permlane32_swap_b32_e32 v96, v98
	v_permlane32_swap_b32_e32 v97, v99
	v_permlane32_swap_b32_e32 v104, v106
	v_permlane32_swap_b32_e32 v105, v107
	v_permlane32_swap_b32_e32 v112, v114
	v_permlane32_swap_b32_e32 v113, v115
	v_permlane32_swap_b32_e32 v120, v122
	v_permlane32_swap_b32_e32 v121, v123
	ds_write_b128 v130, v[96:99]
	ds_write_b128 v130, v[104:107] offset:32
	ds_write_b128 v130, v[112:115] offset:64
	ds_write_b128 v130, v[120:123] offset:96
	ds_read_b128 v[100:103], v129
	ds_read_b128 v[108:111], v129 offset:1152
	ds_read_b128 v[116:119], v129 offset:2304
	ds_read_b128 v[124:127], v129 offset:3456
	v_cvt_pk_bf16_f32 v64, v64, v65
	v_cvt_pk_bf16_f32 v65, v66, v67
	v_cvt_pk_bf16_f32 v66, v68, v69
	v_cvt_pk_bf16_f32 v67, v70, v71
	v_cvt_pk_bf16_f32 v72, v72, v73
	v_cvt_pk_bf16_f32 v73, v74, v75
	v_cvt_pk_bf16_f32 v74, v76, v77
	v_cvt_pk_bf16_f32 v75, v78, v79
	v_cvt_pk_bf16_f32 v80, v80, v81
	v_cvt_pk_bf16_f32 v81, v82, v83
	v_cvt_pk_bf16_f32 v82, v84, v85
	v_cvt_pk_bf16_f32 v83, v86, v87
	v_cvt_pk_bf16_f32 v88, v88, v89
	v_cvt_pk_bf16_f32 v89, v90, v91
	v_cvt_pk_bf16_f32 v90, v92, v93
	v_cvt_pk_bf16_f32 v91, v94, v95
	s_nop 1
	v_permlane32_swap_b32_e32 v64, v66
	v_permlane32_swap_b32_e32 v65, v67
	v_permlane32_swap_b32_e32 v72, v74
	v_permlane32_swap_b32_e32 v73, v75
	v_permlane32_swap_b32_e32 v80, v82
	v_permlane32_swap_b32_e32 v81, v83
	v_permlane32_swap_b32_e32 v88, v90
	v_permlane32_swap_b32_e32 v89, v91
	s_waitcnt lgkmcnt(3)
	global_store_dwordx4 v131, v[100:103], s[100:101]
	s_add_u32 s100, s100, 0x19800
	s_addc_u32 s101, s101, 0
	s_waitcnt lgkmcnt(2)
	global_store_dwordx4 v131, v[108:111], s[100:101]
	s_add_u32 s100, s100, 0x19800
	s_addc_u32 s101, s101, 0
	s_waitcnt lgkmcnt(1)
	global_store_dwordx4 v131, v[116:119], s[100:101]
	s_add_u32 s100, s100, 0x19800
	s_addc_u32 s101, s101, 0
	s_waitcnt lgkmcnt(0)
; DI void store_bf8_pair(bf16_t* rowp  , int g, u32x2 a  , u32x2 b  ) {
;   auto rx = __builtin_amdgcn_permlane32_swap(a.x, b.x, false, false);
;   auto ry = __builtin_amdgcn_permlane32_swap(a.y, b.y, false, false);
;   u32x4 v = {rx[0], ry[0], rx[1], ry[1]};
;   *(u32x4*)(rowp + 8 * g) = v;
; }
;   DI void operator()(const f32x16 (&acc)[2][4], int mbase, int nbase, int l32, int g) const {
; #pragma unroll
;     for (int nb = 0; nb < 2; ++nb)
; #pragma unroll
;       for (int mb = 0; mb < 4; ++mb) {
;         const size_t tok = mbase + 32 * mb + l32;
;         const f32x16& c = acc[nb][mb];
; #pragma unroll
;         for (int j = 0; j < 4; j += 2) {
;           u32x2 a, b;
;           a.x = pk_bf16(c[4 * j], c[4 * j + 1]); a.y = pk_bf16(c[4 * j + 2], c[4 * j + 3]);
;           b.x = pk_bf16(c[4 * j + 4], c[4 * j + 5]); b.y = pk_bf16(c[4 * j + 6], c[4 * j + 7]);
;           store_bf8_pair(O + tok * ld + nbase + 32 * nb + 8 * j, g, a, b);
;         }
;       }
;   }
	global_store_dwordx4 v131, v[124:127], s[100:101]
	s_add_u32 s100, s100, 0x19800
	s_addc_u32 s101, s101, 0
	ds_write_b128 v130, v[64:67]
	ds_write_b128 v130, v[72:75] offset:32
	ds_write_b128 v130, v[80:83] offset:64
	ds_write_b128 v130, v[88:91] offset:96
	ds_read_b128 v[68:71], v129
	ds_read_b128 v[76:79], v129 offset:1152
	ds_read_b128 v[84:87], v129 offset:2304
	ds_read_b128 v[92:95], v129 offset:3456
	v_cvt_pk_bf16_f32 v32, v32, v33
	v_cvt_pk_bf16_f32 v33, v34, v35
	v_cvt_pk_bf16_f32 v34, v36, v37
	v_cvt_pk_bf16_f32 v35, v38, v39
	v_cvt_pk_bf16_f32 v40, v40, v41
	v_cvt_pk_bf16_f32 v41, v42, v43
	v_cvt_pk_bf16_f32 v42, v44, v45
	v_cvt_pk_bf16_f32 v43, v46, v47
	v_cvt_pk_bf16_f32 v48, v48, v49
	v_cvt_pk_bf16_f32 v49, v50, v51
	v_cvt_pk_bf16_f32 v50, v52, v53
	v_cvt_pk_bf16_f32 v51, v54, v55
	v_cvt_pk_bf16_f32 v56, v56, v57
	v_cvt_pk_bf16_f32 v57, v58, v59
	v_cvt_pk_bf16_f32 v58, v60, v61
	v_cvt_pk_bf16_f32 v59, v62, v63
	s_nop 1
	v_permlane32_swap_b32_e32 v32, v34
	v_permlane32_swap_b32_e32 v33, v35
	v_permlane32_swap_b32_e32 v40, v42
	v_permlane32_swap_b32_e32 v41, v43
	v_permlane32_swap_b32_e32 v48, v50
	v_permlane32_swap_b32_e32 v49, v51
	v_permlane32_swap_b32_e32 v56, v58
	v_permlane32_swap_b32_e32 v57, v59
	s_waitcnt lgkmcnt(3)
	global_store_dwordx4 v131, v[68:71], s[100:101]
	s_add_u32 s100, s100, 0x19800
	s_addc_u32 s101, s101, 0
	s_waitcnt lgkmcnt(2)
	global_store_dwordx4 v131, v[76:79], s[100:101]
	s_add_u32 s100, s100, 0x19800
	s_addc_u32 s101, s101, 0
	s_waitcnt lgkmcnt(1)
	global_store_dwordx4 v131, v[84:87], s[100:101]
	s_add_u32 s100, s100, 0x19800
	s_addc_u32 s101, s101, 0
	s_waitcnt lgkmcnt(0)
	global_store_dwordx4 v131, v[92:95], s[100:101]
	s_add_u32 s100, s100, 0x19800
	s_addc_u32 s101, s101, 0
	ds_write_b128 v130, v[32:35]
	ds_write_b128 v130, v[40:43] offset:32
	ds_write_b128 v130, v[48:51] offset:64
	ds_write_b128 v130, v[56:59] offset:96
	ds_read_b128 v[36:39], v129
	ds_read_b128 v[44:47], v129 offset:1152
	ds_read_b128 v[52:55], v129 offset:2304
	ds_read_b128 v[60:63], v129 offset:3456
	v_cvt_pk_bf16_f32 v0, v0, v1
	v_cvt_pk_bf16_f32 v1, v2, v3
	v_cvt_pk_bf16_f32 v2, v4, v5
	v_cvt_pk_bf16_f32 v3, v6, v7
	v_cvt_pk_bf16_f32 v8, v8, v9
	v_cvt_pk_bf16_f32 v9, v10, v11
	v_cvt_pk_bf16_f32 v10, v12, v13
	v_cvt_pk_bf16_f32 v11, v14, v15
	v_cvt_pk_bf16_f32 v16, v16, v17
	v_cvt_pk_bf16_f32 v17, v18, v19
	v_cvt_pk_bf16_f32 v18, v20, v21
	v_cvt_pk_bf16_f32 v19, v22, v23
	v_cvt_pk_bf16_f32 v24, v24, v25
	v_cvt_pk_bf16_f32 v25, v26, v27
	v_cvt_pk_bf16_f32 v26, v28, v29
	v_cvt_pk_bf16_f32 v27, v30, v31
	s_nop 1
	v_permlane32_swap_b32_e32 v0, v2
	v_permlane32_swap_b32_e32 v1, v3
	v_permlane32_swap_b32_e32 v8, v10
	v_permlane32_swap_b32_e32 v9, v11
	v_permlane32_swap_b32_e32 v16, v18
	v_permlane32_swap_b32_e32 v17, v19
	v_permlane32_swap_b32_e32 v24, v26
	v_permlane32_swap_b32_e32 v25, v27
	s_waitcnt lgkmcnt(3)
	global_store_dwordx4 v131, v[36:39], s[100:101]
	s_add_u32 s100, s100, 0x19800
	s_addc_u32 s101, s101, 0
	s_waitcnt lgkmcnt(2)
	global_store_dwordx4 v131, v[44:47], s[100:101]
	s_add_u32 s100, s100, 0x19800
	s_addc_u32 s101, s101, 0
	s_waitcnt lgkmcnt(1)
	global_store_dwordx4 v131, v[52:55], s[100:101]
	s_add_u32 s100, s100, 0x19800
	s_addc_u32 s101, s101, 0
	s_waitcnt lgkmcnt(0)
	global_store_dwordx4 v131, v[60:63], s[100:101]
	s_add_u32 s100, s100, 0x19800
	s_addc_u32 s101, s101, 0
	ds_write_b128 v130, v[0:3]
	ds_write_b128 v130, v[8:11] offset:32
	ds_write_b128 v130, v[16:19] offset:64
	ds_write_b128 v130, v[24:27] offset:96
	ds_read_b128 v[4:7], v129
	ds_read_b128 v[12:15], v129 offset:1152
	ds_read_b128 v[20:23], v129 offset:2304
	ds_read_b128 v[28:31], v129 offset:3456
	s_waitcnt lgkmcnt(3)
	global_store_dwordx4 v131, v[4:7], s[100:101]
	s_add_u32 s100, s100, 0x19800
	s_addc_u32 s101, s101, 0
	s_waitcnt lgkmcnt(2)
	global_store_dwordx4 v131, v[12:15], s[100:101]
	s_add_u32 s100, s100, 0x19800
	s_addc_u32 s101, s101, 0
	s_waitcnt lgkmcnt(1)
	global_store_dwordx4 v131, v[20:23], s[100:101]
	s_add_u32 s100, s100, 0x19800
	s_addc_u32 s101, s101, 0
	s_waitcnt lgkmcnt(0)
	global_store_dwordx4 v131, v[28:31], s[100:101]
	s_add_u32 s100, s100, 0x19800
	s_addc_u32 s101, s101, 0
	s_cbranch_execnz .LBB0_876
